# speedup vs baseline: 1.0064x; 1.0064x over previous
; #define STAGE(P, GP, ktrel) do { const GAS char* _g = (GP) + (ktrel) * (BK * 2); \
;     __builtin_amdgcn_global_load_lds((const GAS unsigned*)(_g + so0), (unsigned*)((char*)(P) + tid_ * 16), 16, 0, 0); \
;     __builtin_amdgcn_global_load_lds((const GAS unsigned*)(_g + so1), (unsigned*)((char*)(P) + tid_ * 16 + 8192), 16, 0, 0); } while (0)
; #define WAIT_V(n) asm volatile("s_waitcnt vmcnt(" #n ")" ::: "memory")
; #define WAIT_L(n) asm volatile("s_waitcnt lgkmcnt(" #n ")" ::: "memory")
; #define BAR __builtin_amdgcn_s_barrier()
; #define SCHED __builtin_amdgcn_sched_barrier(0)
; #define LDA(dst, b, h) for (int m = 0; m < 4; ++m) for (int k = 0; k < 2; ++k) \
;     dst[m][k] = *reinterpret_cast<const bf16x8*>((char*)SA(b, h) + lds_byte(wr * 64 + m * 16 + fr, k * 32 + fq * 8))
; #define LDB(dst, b, h) for (int n = 0; n < 2; ++n) for (int k = 0; k < 2; ++k) \
;     dst[n][k] = *reinterpret_cast<const bf16x8*>((char*)SB(b, h) + lds_byte(wc * 32 + n * 16 + fr, k * 32 + fq * 8))
; #define MMA(ai, bj, At_, Bt_) do { __builtin_amdgcn_s_setprio(1); \
;     for (int m = 0; m < 4; ++m) for (int n = 0; n < 2; ++n) for (int k = 0; k < 2; ++k) \
;       acc[ai][bj][m][n] = __builtin_amdgcn_mfma_f32_16x16x32_bf16(At_[m][k], Bt_[n][k], acc[ai][bj][m][n], 0, 0, 0); \
;     __builtin_amdgcn_s_setprio(0); } while (0)
; template <int K, int LD = K>
; __device__ __forceinline__ void gemm_main(const GAS bf16* A, const GAS bf16* Bt, int brow, int bcol, f32x4 (&acc)[2][2][4][2]) {
;     ...
;   for (int t = 0; t < nt - 2; t += 2) {
;     LDB(B0, 0, 0); SCHED; LDA(At, 0, 0); STAGE(SA(1, 1), pA1, 1);
;     WAIT_L(8); BAR; WAIT_L(0); MMA(0, 0, At, B0); BAR; SCHED;
;     LDB(B1, 0, 1); STAGE(SB(0, 0), pB0, 2);
;     BAR; WAIT_L(0); MMA(0, 1, At, B1); BAR;
;     LDA(At, 0, 1); STAGE(SA(0, 0), pA0, 2);
;     BAR; WAIT_L(0); MMA(1, 0, At, B0); BAR; SCHED;
;     STAGE(SB(0, 1), pB1, 2);
;     WAIT_V(6); BAR; MMA(1, 1, At, B1); BAR;
;     LDB(B0, 1, 0); SCHED; LDA(At, 1, 0); STAGE(SA(0, 1), pA1, 2);
;     WAIT_L(8); BAR; WAIT_L(0); MMA(0, 0, At, B0); BAR; SCHED;
.LBB0_89:
	ds_read_b128 v[162:165], v144
	ds_read_b128 v[166:169], v144 offset:1024
	ds_read_b128 v[174:177], v144 offset:2048
	ds_read_b128 v[178:181], v144 offset:3072
	v_lshl_add_u64 v[230:231], s[14:15], 0, v[130:131]
	v_readfirstlane_b32 s24, v151
	v_lshl_add_u64 v[214:215], v[230:231], 0, s[8:9]
	s_mov_b32 m0, s24
	v_lshl_add_u64 v[232:233], s[14:15], 0, v[132:133]
	v_readfirstlane_b32 s24, v150
	ds_read_b128 v[182:185], v140
	ds_read_b128 v[186:189], v140 offset:1024
	ds_read_b128 v[190:193], v139
	ds_read_b128 v[194:197], v139 offset:1024
	ds_read_b128 v[198:201], v138
	ds_read_b128 v[202:205], v138 offset:1024
	ds_read_b128 v[206:209], v137
	ds_read_b128 v[210:213], v137 offset:1024
	global_load_lds_dwordx4 v[214:215], off
	v_lshl_add_u64 v[214:215], v[232:233], 0, s[8:9]
	s_mov_b32 m0, s24
	s_nop 0
	global_load_lds_dwordx4 v[214:215], off
	s_waitcnt lgkmcnt(8)
	s_waitcnt vmcnt(10)
	s_barrier
	s_waitcnt lgkmcnt(0)
	s_waitcnt lgkmcnt(0)
	v_mfma_f32_16x16x32_bf16 v[126:129], v[182:185], v[162:165], v[126:129]
	v_mfma_f32_16x16x32_bf16 v[122:125], v[182:185], v[174:177], v[122:125]
	v_mfma_f32_16x16x32_bf16 v[118:121], v[190:193], v[162:165], v[118:121]
	v_mfma_f32_16x16x32_bf16 v[114:117], v[190:193], v[174:177], v[114:117]
	v_mfma_f32_16x16x32_bf16 v[110:113], v[198:201], v[162:165], v[110:113]
	v_mfma_f32_16x16x32_bf16 v[106:109], v[198:201], v[174:177], v[106:109]
	v_mfma_f32_16x16x32_bf16 v[102:105], v[206:209], v[162:165], v[102:105]
	v_mfma_f32_16x16x32_bf16 v[98:101], v[206:209], v[174:177], v[98:101]
	v_mfma_f32_16x16x32_bf16 v[126:129], v[186:189], v[166:169], v[126:129]
	v_mfma_f32_16x16x32_bf16 v[122:125], v[186:189], v[178:181], v[122:125]
	v_mfma_f32_16x16x32_bf16 v[118:121], v[194:197], v[166:169], v[118:121]
	v_mfma_f32_16x16x32_bf16 v[114:117], v[194:197], v[178:181], v[114:117]
	v_mfma_f32_16x16x32_bf16 v[110:113], v[202:205], v[166:169], v[110:113]
	v_mfma_f32_16x16x32_bf16 v[106:109], v[202:205], v[178:181], v[106:109]
	v_mfma_f32_16x16x32_bf16 v[102:105], v[210:213], v[166:169], v[102:105]
	v_mfma_f32_16x16x32_bf16 v[98:101], v[210:213], v[178:181], v[98:101]
	s_barrier
	v_lshl_add_u64 v[234:235], s[22:23], 0, v[130:131]
	v_readfirstlane_b32 s24, v146
	v_lshl_add_u64 v[236:237], v[234:235], 0, s[10:11]
	s_mov_b32 m0, s24
	ds_read_b128 v[214:217], v143
	ds_read_b128 v[218:221], v143 offset:1024
	ds_read_b128 v[222:225], v143 offset:2048
	ds_read_b128 v[226:229], v143 offset:3072
	global_load_lds_dwordx4 v[236:237], off
	v_lshl_add_u64 v[236:237], s[22:23], 0, v[132:133]
	v_readfirstlane_b32 s24, v157
	v_lshl_add_u64 v[238:239], v[236:237], 0, s[10:11]
	s_mov_b32 m0, s24
	s_add_u32 s22, s22, 0x100
	global_load_lds_dwordx4 v[238:239], off
	s_waitcnt vmcnt(10)
	s_barrier
	s_waitcnt lgkmcnt(0)
	s_addc_u32 s23, s23, 0
	s_waitcnt lgkmcnt(0)
	v_mfma_f32_16x16x32_bf16 v[94:97], v[182:185], v[214:217], v[94:97]
	v_mfma_f32_16x16x32_bf16 v[90:93], v[182:185], v[222:225], v[90:93]
	v_mfma_f32_16x16x32_bf16 v[86:89], v[190:193], v[214:217], v[86:89]
	v_mfma_f32_16x16x32_bf16 v[82:85], v[190:193], v[222:225], v[82:85]
	v_mfma_f32_16x16x32_bf16 v[78:81], v[198:201], v[214:217], v[78:81]
	v_mfma_f32_16x16x32_bf16 v[74:77], v[198:201], v[222:225], v[74:77]
	v_mfma_f32_16x16x32_bf16 v[70:73], v[206:209], v[214:217], v[70:73]
	v_mfma_f32_16x16x32_bf16 v[66:69], v[206:209], v[222:225], v[66:69]
	v_mfma_f32_16x16x32_bf16 v[94:97], v[186:189], v[218:221], v[94:97]
	v_mfma_f32_16x16x32_bf16 v[90:93], v[186:189], v[226:229], v[90:93]
	v_mfma_f32_16x16x32_bf16 v[86:89], v[194:197], v[218:221], v[86:89]
	v_mfma_f32_16x16x32_bf16 v[82:85], v[194:197], v[226:229], v[82:85]
	v_mfma_f32_16x16x32_bf16 v[78:81], v[202:205], v[218:221], v[78:81]
	v_mfma_f32_16x16x32_bf16 v[74:77], v[202:205], v[226:229], v[74:77]
	v_mfma_f32_16x16x32_bf16 v[70:73], v[210:213], v[218:221], v[70:73]
	v_mfma_f32_16x16x32_bf16 v[66:69], v[210:213], v[226:229], v[66:69]
	v_lshl_add_u64 v[238:239], s[20:21], 0, v[130:131]
	v_readfirstlane_b32 s24, v145
	v_lshl_add_u64 v[240:241], v[238:239], 0, s[10:11]
	s_mov_b32 m0, s24
	s_barrier
	ds_read_b128 v[182:185], v140 offset:16384
	ds_read_b128 v[186:189], v140 offset:17408
	ds_read_b128 v[190:193], v139 offset:16384
	ds_read_b128 v[194:197], v139 offset:17408
	ds_read_b128 v[198:201], v138 offset:16384
	ds_read_b128 v[202:205], v138 offset:17408
	ds_read_b128 v[206:209], v137 offset:16384
	ds_read_b128 v[210:213], v137 offset:17408
	global_load_lds_dwordx4 v[240:241], off
	v_lshl_add_u64 v[240:241], s[20:21], 0, v[132:133]
	v_readfirstlane_b32 s24, v152
	v_lshl_add_u64 v[242:243], v[240:241], 0, s[10:11]
	s_mov_b32 m0, s24
	s_add_u32 s20, s20, 0x100
	global_load_lds_dwordx4 v[242:243], off
	s_barrier
	s_waitcnt lgkmcnt(0)
	s_addc_u32 s21, s21, 0
	s_waitcnt lgkmcnt(0)
	v_mfma_f32_16x16x32_bf16 v[62:65], v[182:185], v[162:165], v[62:65]
	v_mfma_f32_16x16x32_bf16 v[58:61], v[182:185], v[174:177], v[58:61]
	v_mfma_f32_16x16x32_bf16 v[54:57], v[190:193], v[162:165], v[54:57]
	v_mfma_f32_16x16x32_bf16 v[50:53], v[190:193], v[174:177], v[50:53]
	v_mfma_f32_16x16x32_bf16 v[46:49], v[198:201], v[162:165], v[46:49]
	v_mfma_f32_16x16x32_bf16 v[42:45], v[198:201], v[174:177], v[42:45]
	v_mfma_f32_16x16x32_bf16 v[38:41], v[206:209], v[162:165], v[38:41]
	v_mfma_f32_16x16x32_bf16 v[34:37], v[206:209], v[174:177], v[34:37]
	v_mfma_f32_16x16x32_bf16 v[62:65], v[186:189], v[166:169], v[62:65]
	v_mfma_f32_16x16x32_bf16 v[58:61], v[186:189], v[178:181], v[58:61]
	v_mfma_f32_16x16x32_bf16 v[54:57], v[194:197], v[166:169], v[54:57]
	v_mfma_f32_16x16x32_bf16 v[50:53], v[194:197], v[178:181], v[50:53]
	v_mfma_f32_16x16x32_bf16 v[46:49], v[202:205], v[166:169], v[46:49]
	v_mfma_f32_16x16x32_bf16 v[42:45], v[202:205], v[178:181], v[42:45]
	v_mfma_f32_16x16x32_bf16 v[38:41], v[210:213], v[166:169], v[38:41]
	v_mfma_f32_16x16x32_bf16 v[34:37], v[210:213], v[178:181], v[34:37]
	s_barrier
; #define STAGE(P, GP, ktrel) do { const GAS char* _g = (GP) + (ktrel) * (BK * 2); \
;     __builtin_amdgcn_global_load_lds((const GAS unsigned*)(_g + so0), (unsigned*)((char*)(P) + tid_ * 16), 16, 0, 0); \
;     __builtin_amdgcn_global_load_lds((const GAS unsigned*)(_g + so1), (unsigned*)((char*)(P) + tid_ * 16 + 8192), 16, 0, 0); } while (0)
; #define WAIT_V(n) asm volatile("s_waitcnt vmcnt(" #n ")" ::: "memory")
; #define WAIT_L(n) asm volatile("s_waitcnt lgkmcnt(" #n ")" ::: "memory")
; #define BAR __builtin_amdgcn_s_barrier()
; #define SCHED __builtin_amdgcn_sched_barrier(0)
; #define LDA(dst, b, h) for (int m = 0; m < 4; ++m) for (int k = 0; k < 2; ++k) \
;     dst[m][k] = *reinterpret_cast<const bf16x8*>((char*)SA(b, h) + lds_byte(wr * 64 + m * 16 + fr, k * 32 + fq * 8))
; #define LDB(dst, b, h) for (int n = 0; n < 2; ++n) for (int k = 0; k < 2; ++k) \
;     dst[n][k] = *reinterpret_cast<const bf16x8*>((char*)SB(b, h) + lds_byte(wc * 32 + n * 16 + fr, k * 32 + fq * 8))
; #define MMA(ai, bj, At_, Bt_) do { __builtin_amdgcn_s_setprio(1); \
;     for (int m = 0; m < 4; ++m) for (int n = 0; n < 2; ++n) for (int k = 0; k < 2; ++k) \
;       acc[ai][bj][m][n] = __builtin_amdgcn_mfma_f32_16x16x32_bf16(At_[m][k], Bt_[n][k], acc[ai][bj][m][n], 0, 0, 0); \
;     __builtin_amdgcn_s_setprio(0); } while (0)
; template <int K, int LD = K>
; __device__ __forceinline__ void gemm_main(const GAS bf16* A, const GAS bf16* Bt, int brow, int bcol, f32x4 (&acc)[2][2][4][2]) {
;     ...
;     STAGE(SB(0, 1), pB1, 2);
;     WAIT_V(6); BAR; MMA(1, 1, At, B1); BAR;
;     LDB(B0, 1, 0); SCHED; LDA(At, 1, 0); STAGE(SA(0, 1), pA1, 2);
;     WAIT_L(8); BAR; WAIT_L(0); MMA(0, 0, At, B0); BAR; SCHED;
;     LDB(B1, 1, 1); STAGE(SB(1, 0), pB0, 3);
;     BAR; WAIT_L(0); MMA(0, 1, At, B1); BAR;
	v_lshl_add_u64 v[242:243], s[18:19], 0, v[130:131]
	v_readfirstlane_b32 s24, v147
	v_lshl_add_u64 v[162:163], v[242:243], 0, s[10:11]
	s_mov_b32 m0, s24
	v_lshl_add_u64 v[244:245], s[18:19], 0, v[132:133]
	v_readfirstlane_b32 s24, v158
	global_load_lds_dwordx4 v[162:163], off
	v_lshl_add_u64 v[162:163], v[244:245], 0, s[10:11]
	s_mov_b32 m0, s24
	s_add_u32 s18, s18, 0x100
	global_load_lds_dwordx4 v[162:163], off
	s_waitcnt vmcnt(10)
	s_addc_u32 s19, s19, 0
	s_barrier
	v_mfma_f32_16x16x32_bf16 v[30:33], v[182:185], v[214:217], v[30:33]
	v_mfma_f32_16x16x32_bf16 v[26:29], v[182:185], v[222:225], v[26:29]
	v_mfma_f32_16x16x32_bf16 v[22:25], v[190:193], v[214:217], v[22:25]
	v_mfma_f32_16x16x32_bf16 v[18:21], v[190:193], v[222:225], v[18:21]
	v_mfma_f32_16x16x32_bf16 v[14:17], v[198:201], v[214:217], v[14:17]
	v_mfma_f32_16x16x32_bf16 v[10:13], v[198:201], v[222:225], v[10:13]
	v_mfma_f32_16x16x32_bf16 v[6:9], v[206:209], v[214:217], v[6:9]
	v_mfma_f32_16x16x32_bf16 v[2:5], v[206:209], v[222:225], v[2:5]
	v_mfma_f32_16x16x32_bf16 v[30:33], v[186:189], v[218:221], v[30:33]
	v_mfma_f32_16x16x32_bf16 v[26:29], v[186:189], v[226:229], v[26:29]
	v_mfma_f32_16x16x32_bf16 v[22:25], v[194:197], v[218:221], v[22:25]
	v_mfma_f32_16x16x32_bf16 v[18:21], v[194:197], v[226:229], v[18:21]
	v_mfma_f32_16x16x32_bf16 v[14:17], v[202:205], v[218:221], v[14:17]
	v_mfma_f32_16x16x32_bf16 v[10:13], v[202:205], v[226:229], v[10:13]
	v_mfma_f32_16x16x32_bf16 v[6:9], v[210:213], v[218:221], v[6:9]
	v_mfma_f32_16x16x32_bf16 v[2:5], v[210:213], v[226:229], v[2:5]
	s_barrier
	ds_read_b128 v[162:165], v142
	ds_read_b128 v[166:169], v142 offset:1024
	ds_read_b128 v[174:177], v142 offset:2048
	ds_read_b128 v[178:181], v142 offset:3072
	v_readfirstlane_b32 s24, v153
	v_lshl_add_u64 v[214:215], v[230:231], 0, s[10:11]
	s_mov_b32 m0, s24
	v_readfirstlane_b32 s24, v154
	ds_read_b128 v[182:185], v140 offset:32768
	ds_read_b128 v[186:189], v140 offset:33792
	ds_read_b128 v[190:193], v139 offset:32768
	ds_read_b128 v[194:197], v139 offset:33792
	ds_read_b128 v[198:201], v138 offset:32768
	ds_read_b128 v[202:205], v138 offset:33792
	ds_read_b128 v[206:209], v137 offset:32768
	ds_read_b128 v[210:213], v137 offset:33792
	global_load_lds_dwordx4 v[214:215], off
	v_lshl_add_u64 v[214:215], v[232:233], 0, s[10:11]
	s_mov_b32 m0, s24
	s_add_u32 s14, s14, 0x100
	global_load_lds_dwordx4 v[214:215], off
	s_waitcnt lgkmcnt(8)
	s_waitcnt vmcnt(10)
	s_barrier
	s_waitcnt lgkmcnt(0)
	s_addc_u32 s15, s15, 0
	s_waitcnt lgkmcnt(0)
	v_mfma_f32_16x16x32_bf16 v[126:129], v[182:185], v[162:165], v[126:129]
	v_mfma_f32_16x16x32_bf16 v[122:125], v[182:185], v[174:177], v[122:125]
	v_mfma_f32_16x16x32_bf16 v[118:121], v[190:193], v[162:165], v[118:121]
	v_mfma_f32_16x16x32_bf16 v[114:117], v[190:193], v[174:177], v[114:117]
	v_mfma_f32_16x16x32_bf16 v[110:113], v[198:201], v[162:165], v[110:113]
	v_mfma_f32_16x16x32_bf16 v[106:109], v[198:201], v[174:177], v[106:109]
	v_mfma_f32_16x16x32_bf16 v[102:105], v[206:209], v[162:165], v[102:105]
	v_mfma_f32_16x16x32_bf16 v[98:101], v[206:209], v[174:177], v[98:101]
	v_mfma_f32_16x16x32_bf16 v[126:129], v[186:189], v[166:169], v[126:129]
	v_mfma_f32_16x16x32_bf16 v[122:125], v[186:189], v[178:181], v[122:125]
	v_mfma_f32_16x16x32_bf16 v[118:121], v[194:197], v[166:169], v[118:121]
	v_mfma_f32_16x16x32_bf16 v[114:117], v[194:197], v[178:181], v[114:117]
	v_mfma_f32_16x16x32_bf16 v[110:113], v[202:205], v[166:169], v[110:113]
	v_mfma_f32_16x16x32_bf16 v[106:109], v[202:205], v[178:181], v[106:109]
	v_mfma_f32_16x16x32_bf16 v[102:105], v[210:213], v[166:169], v[102:105]
	v_mfma_f32_16x16x32_bf16 v[98:101], v[210:213], v[178:181], v[98:101]
	s_barrier
	v_readfirstlane_b32 s24, v148
	v_lshl_add_u64 v[230:231], v[234:235], 0, s[12:13]
	s_mov_b32 m0, s24
	v_readfirstlane_b32 s24, v159
	ds_read_b128 v[214:217], v141
	ds_read_b128 v[218:221], v141 offset:1024
	ds_read_b128 v[222:225], v141 offset:2048
	ds_read_b128 v[226:229], v141 offset:3072
	global_load_lds_dwordx4 v[230:231], off
	v_lshl_add_u64 v[230:231], v[236:237], 0, s[12:13]
	s_mov_b32 m0, s24
	s_nop 0
	global_load_lds_dwordx4 v[230:231], off
	s_waitcnt vmcnt(10)
	s_barrier
	s_waitcnt lgkmcnt(0)
	s_waitcnt lgkmcnt(0)
	v_mfma_f32_16x16x32_bf16 v[94:97], v[182:185], v[214:217], v[94:97]
	v_mfma_f32_16x16x32_bf16 v[90:93], v[182:185], v[222:225], v[90:93]
	v_mfma_f32_16x16x32_bf16 v[86:89], v[190:193], v[214:217], v[86:89]
	v_mfma_f32_16x16x32_bf16 v[82:85], v[190:193], v[222:225], v[82:85]
	v_mfma_f32_16x16x32_bf16 v[78:81], v[198:201], v[214:217], v[78:81]
	v_mfma_f32_16x16x32_bf16 v[74:77], v[198:201], v[222:225], v[74:77]
	v_mfma_f32_16x16x32_bf16 v[70:73], v[206:209], v[214:217], v[70:73]
	v_mfma_f32_16x16x32_bf16 v[66:69], v[206:209], v[222:225], v[66:69]
	v_mfma_f32_16x16x32_bf16 v[94:97], v[186:189], v[218:221], v[94:97]
	v_mfma_f32_16x16x32_bf16 v[90:93], v[186:189], v[226:229], v[90:93]
	v_mfma_f32_16x16x32_bf16 v[86:89], v[194:197], v[218:221], v[86:89]
	v_mfma_f32_16x16x32_bf16 v[82:85], v[194:197], v[226:229], v[82:85]
	v_mfma_f32_16x16x32_bf16 v[78:81], v[202:205], v[218:221], v[78:81]
	v_mfma_f32_16x16x32_bf16 v[74:77], v[202:205], v[226:229], v[74:77]
	v_mfma_f32_16x16x32_bf16 v[70:73], v[210:213], v[218:221], v[70:73]
	v_mfma_f32_16x16x32_bf16 v[66:69], v[210:213], v[226:229], v[66:69]
	v_readfirstlane_b32 s24, v155
	v_lshl_add_u64 v[230:231], v[238:239], 0, s[12:13]
	s_mov_b32 m0, s24
	v_readfirstlane_b32 s24, v156
	s_barrier
; #define STAGE(P, GP, ktrel) do { const GAS char* _g = (GP) + (ktrel) * (BK * 2); \
;     __builtin_amdgcn_global_load_lds((const GAS unsigned*)(_g + so0), (unsigned*)((char*)(P) + tid_ * 16), 16, 0, 0); \
;     __builtin_amdgcn_global_load_lds((const GAS unsigned*)(_g + so1), (unsigned*)((char*)(P) + tid_ * 16 + 8192), 16, 0, 0); } while (0)
; #define WAIT_V(n) asm volatile("s_waitcnt vmcnt(" #n ")" ::: "memory")
; #define WAIT_L(n) asm volatile("s_waitcnt lgkmcnt(" #n ")" ::: "memory")
; #define BAR __builtin_amdgcn_s_barrier()
; #define SCHED __builtin_amdgcn_sched_barrier(0)
; #define LDA(dst, b, h) for (int m = 0; m < 4; ++m) for (int k = 0; k < 2; ++k) \
;     dst[m][k] = *reinterpret_cast<const bf16x8*>((char*)SA(b, h) + lds_byte(wr * 64 + m * 16 + fr, k * 32 + fq * 8))
; #define LDB(dst, b, h) for (int n = 0; n < 2; ++n) for (int k = 0; k < 2; ++k) \
;     dst[n][k] = *reinterpret_cast<const bf16x8*>((char*)SB(b, h) + lds_byte(wc * 32 + n * 16 + fr, k * 32 + fq * 8))
; #define MMA(ai, bj, At_, Bt_) do { __builtin_amdgcn_s_setprio(1); \
;     for (int m = 0; m < 4; ++m) for (int n = 0; n < 2; ++n) for (int k = 0; k < 2; ++k) \
;       acc[ai][bj][m][n] = __builtin_amdgcn_mfma_f32_16x16x32_bf16(At_[m][k], Bt_[n][k], acc[ai][bj][m][n], 0, 0, 0); \
;     __builtin_amdgcn_s_setprio(0); } while (0)
; template <int K, int LD = K>
; __device__ __forceinline__ void gemm_main(const GAS bf16* A, const GAS bf16* Bt, int brow, int bcol, f32x4 (&acc)[2][2][4][2]) {
;     ...
;     LDA(At, 1, 1); STAGE(SA(1, 0), pA0, 3);
;     BAR; WAIT_L(0); MMA(1, 0, At, B0); BAR; SCHED;
;     STAGE(SB(1, 1), pB1, 3);
;     WAIT_V(6); BAR; MMA(1, 1, At, B1); BAR;
;     pA0 += 4 * BK; pA1 += 4 * BK; pB0 += 4 * BK; pB1 += 4 * BK;
;     asm volatile("" : "+s"(pA0), "+s"(pA1), "+s"(pB0), "+s"(pB1));
;   }
;   { LDB(B0, 0, 0); LDA(At, 0, 0); STAGE(SA(1, 1), pA1, 1);
;     BAR; WAIT_L(0); MMA(0, 0, At, B0); BAR;
	ds_read_b128 v[182:185], v140 offset:49152
	ds_read_b128 v[186:189], v140 offset:50176
	ds_read_b128 v[190:193], v139 offset:49152
	ds_read_b128 v[194:197], v139 offset:50176
	ds_read_b128 v[198:201], v138 offset:49152
	ds_read_b128 v[202:205], v138 offset:50176
	ds_read_b128 v[206:209], v137 offset:49152
	ds_read_b128 v[210:213], v137 offset:50176
	global_load_lds_dwordx4 v[230:231], off
	v_lshl_add_u64 v[230:231], v[240:241], 0, s[12:13]
	s_mov_b32 m0, s24
	s_nop 0
	global_load_lds_dwordx4 v[230:231], off
	s_barrier
	s_waitcnt lgkmcnt(0)
	s_waitcnt lgkmcnt(0)
	v_mfma_f32_16x16x32_bf16 v[62:65], v[182:185], v[162:165], v[62:65]
	v_mfma_f32_16x16x32_bf16 v[58:61], v[182:185], v[174:177], v[58:61]
	v_mfma_f32_16x16x32_bf16 v[54:57], v[190:193], v[162:165], v[54:57]
	v_mfma_f32_16x16x32_bf16 v[50:53], v[190:193], v[174:177], v[50:53]
	v_mfma_f32_16x16x32_bf16 v[46:49], v[198:201], v[162:165], v[46:49]
	v_mfma_f32_16x16x32_bf16 v[42:45], v[198:201], v[174:177], v[42:45]
	v_mfma_f32_16x16x32_bf16 v[38:41], v[206:209], v[162:165], v[38:41]
	v_mfma_f32_16x16x32_bf16 v[34:37], v[206:209], v[174:177], v[34:37]
	v_mfma_f32_16x16x32_bf16 v[62:65], v[186:189], v[166:169], v[62:65]
	v_mfma_f32_16x16x32_bf16 v[58:61], v[186:189], v[178:181], v[58:61]
	v_mfma_f32_16x16x32_bf16 v[54:57], v[194:197], v[166:169], v[54:57]
	v_mfma_f32_16x16x32_bf16 v[50:53], v[194:197], v[178:181], v[50:53]
	v_mfma_f32_16x16x32_bf16 v[46:49], v[202:205], v[166:169], v[46:49]
	v_mfma_f32_16x16x32_bf16 v[42:45], v[202:205], v[178:181], v[42:45]
	v_mfma_f32_16x16x32_bf16 v[38:41], v[210:213], v[166:169], v[38:41]
	v_mfma_f32_16x16x32_bf16 v[34:37], v[210:213], v[178:181], v[34:37]
	s_barrier
	v_readfirstlane_b32 s24, v149
	v_lshl_add_u64 v[162:163], v[242:243], 0, s[12:13]
	s_mov_b32 m0, s24
	v_readfirstlane_b32 s24, v160
	global_load_lds_dwordx4 v[162:163], off
	v_lshl_add_u64 v[162:163], v[244:245], 0, s[12:13]
	s_mov_b32 m0, s24
	s_nop 0
	global_load_lds_dwordx4 v[162:163], off
	s_waitcnt vmcnt(10)
	s_barrier
	v_mfma_f32_16x16x32_bf16 v[30:33], v[182:185], v[214:217], v[30:33]
	v_mfma_f32_16x16x32_bf16 v[26:29], v[182:185], v[222:225], v[26:29]
	v_mfma_f32_16x16x32_bf16 v[22:25], v[190:193], v[214:217], v[22:25]
	v_mfma_f32_16x16x32_bf16 v[18:21], v[190:193], v[222:225], v[18:21]
	v_mfma_f32_16x16x32_bf16 v[14:17], v[198:201], v[214:217], v[14:17]
	v_mfma_f32_16x16x32_bf16 v[10:13], v[198:201], v[222:225], v[10:13]
	v_mfma_f32_16x16x32_bf16 v[6:9], v[206:209], v[214:217], v[6:9]
	v_mfma_f32_16x16x32_bf16 v[2:5], v[206:209], v[222:225], v[2:5]
	v_mfma_f32_16x16x32_bf16 v[30:33], v[186:189], v[218:221], v[30:33]
	v_mfma_f32_16x16x32_bf16 v[26:29], v[186:189], v[226:229], v[26:29]
	v_mfma_f32_16x16x32_bf16 v[22:25], v[194:197], v[218:221], v[22:25]
	v_mfma_f32_16x16x32_bf16 v[18:21], v[194:197], v[226:229], v[18:21]
	v_mfma_f32_16x16x32_bf16 v[14:17], v[202:205], v[218:221], v[14:17]
	v_mfma_f32_16x16x32_bf16 v[10:13], v[202:205], v[226:229], v[10:13]
	v_mfma_f32_16x16x32_bf16 v[6:9], v[210:213], v[218:221], v[6:9]
	v_mfma_f32_16x16x32_bf16 v[2:5], v[210:213], v[226:229], v[2:5]
	s_add_i32 s17, s17, 2
	s_cmp_lt_u32 s17, 12
	s_barrier
	s_cbranch_scc1 .LBB0_89
	ds_read_b128 v[146:149], v144
	ds_read_b128 v[152:155], v144 offset:1024
	ds_read_b128 v[156:159], v144 offset:2048
	ds_read_b128 v[160:163], v144 offset:3072
	ds_read_b128 v[164:167], v140
	ds_read_b128 v[174:177], v140 offset:1024
	ds_read_b128 v[178:181], v139
	ds_read_b128 v[182:185], v139 offset:1024
	ds_read_b128 v[186:189], v138
	ds_read_b128 v[190:193], v138 offset:1024
	ds_read_b128 v[194:197], v137
	ds_read_b128 v[198:201], v137 offset:1024
	v_lshl_add_u64 v[144:145], s[14:15], 0, v[130:131]
	v_readfirstlane_b32 s17, v151
	v_lshl_add_u64 v[144:145], v[144:145], 0, s[8:9]
	s_mov_b32 m0, s17
	v_lshl_add_u64 v[132:133], s[14:15], 0, v[132:133]
	v_readfirstlane_b32 s14, v150
	global_load_lds_dwordx4 v[144:145], off
	v_lshl_add_u64 v[132:133], v[132:133], 0, s[8:9]
	s_mov_b32 m0, s14
	s_nop 0
	global_load_lds_dwordx4 v[132:133], off
	s_waitcnt vmcnt(10)
	s_barrier
	s_waitcnt lgkmcnt(0)
	s_waitcnt lgkmcnt(0)
	v_mfma_f32_16x16x32_bf16 v[126:129], v[164:167], v[146:149], v[126:129]
	v_mfma_f32_16x16x32_bf16 v[122:125], v[164:167], v[156:159], v[122:125]
	v_mfma_f32_16x16x32_bf16 v[110:113], v[186:189], v[146:149], v[110:113]
	v_mfma_f32_16x16x32_bf16 v[106:109], v[186:189], v[156:159], v[106:109]
	v_mfma_f32_16x16x32_bf16 v[126:129], v[174:177], v[152:155], v[126:129]
	v_mfma_f32_16x16x32_bf16 v[122:125], v[174:177], v[160:163], v[122:125]
	v_mfma_f32_16x16x32_bf16 v[118:121], v[178:181], v[146:149], v[118:121]
	v_mfma_f32_16x16x32_bf16 v[114:117], v[178:181], v[156:159], v[114:117]
	v_mfma_f32_16x16x32_bf16 v[110:113], v[190:193], v[152:155], v[110:113]
	v_mfma_f32_16x16x32_bf16 v[106:109], v[190:193], v[160:163], v[106:109]
	v_mfma_f32_16x16x32_bf16 v[102:105], v[194:197], v[146:149], v[102:105]
	v_mfma_f32_16x16x32_bf16 v[98:101], v[194:197], v[156:159], v[98:101]
	v_mfma_f32_16x16x32_bf16 v[202:205], v[182:185], v[152:155], v[118:121]
	v_mfma_f32_16x16x32_bf16 v[206:209], v[182:185], v[160:163], v[114:117]
	v_mfma_f32_16x16x32_bf16 v[210:213], v[198:201], v[152:155], v[102:105]
	v_mfma_f32_16x16x32_bf16 v[214:217], v[198:201], v[160:163], v[98:101]
	s_barrier
	s_nop 1
	ds_read_b128 v[98:101], v143
	ds_read_b128 v[102:105], v143 offset:1024
	ds_read_b128 v[114:117], v143 offset:2048
	ds_read_b128 v[118:121], v143 offset:3072
	s_waitcnt vmcnt(8)
	s_barrier
; #define WAIT_V(n) asm volatile("s_waitcnt vmcnt(" #n ")" ::: "memory")
; #define WAIT_L(n) asm volatile("s_waitcnt lgkmcnt(" #n ")" ::: "memory")
; #define BAR __builtin_amdgcn_s_barrier()
; #define LDA(dst, b, h) for (int m = 0; m < 4; ++m) for (int k = 0; k < 2; ++k) \
;     dst[m][k] = *reinterpret_cast<const bf16x8*>((char*)SA(b, h) + lds_byte(wr * 64 + m * 16 + fr, k * 32 + fq * 8))
; #define LDB(dst, b, h) for (int n = 0; n < 2; ++n) for (int k = 0; k < 2; ++k) \
;     dst[n][k] = *reinterpret_cast<const bf16x8*>((char*)SB(b, h) + lds_byte(wc * 32 + n * 16 + fr, k * 32 + fq * 8))
; #define MMA(ai, bj, At_, Bt_) do { __builtin_amdgcn_s_setprio(1); \
;     for (int m = 0; m < 4; ++m) for (int n = 0; n < 2; ++n) for (int k = 0; k < 2; ++k) \
;       acc[ai][bj][m][n] = __builtin_amdgcn_mfma_f32_16x16x32_bf16(At_[m][k], Bt_[n][k], acc[ai][bj][m][n], 0, 0, 0); \
;     __builtin_amdgcn_s_setprio(0); } while (0)
; template <int K, int LD = K>
; __device__ __forceinline__ void gemm_main(const GAS bf16* A, const GAS bf16* Bt, int brow, int bcol, f32x4 (&acc)[2][2][4][2]) {
;     ...
;     LDB(B1, 0, 1); BAR; WAIT_L(0); MMA(0, 1, At, B1); BAR;
;     LDA(At, 0, 1); WAIT_V(4); BAR; WAIT_L(0); MMA(1, 0, At, B0); MMA(1, 1, At, B1); BAR; }
;   { LDB(B0, 1, 0); LDA(At, 1, 0); WAIT_V(2); BAR; WAIT_L(0); MMA(0, 0, At, B0); BAR;
	s_waitcnt lgkmcnt(0)
	s_waitcnt lgkmcnt(0)
	v_mfma_f32_16x16x32_bf16 v[94:97], v[164:167], v[98:101], v[94:97]
	v_mfma_f32_16x16x32_bf16 v[90:93], v[164:167], v[114:117], v[90:93]
	v_mfma_f32_16x16x32_bf16 v[78:81], v[186:189], v[98:101], v[78:81]
	v_mfma_f32_16x16x32_bf16 v[74:77], v[186:189], v[114:117], v[74:77]
	v_mfma_f32_16x16x32_bf16 v[94:97], v[174:177], v[102:105], v[94:97]
	v_mfma_f32_16x16x32_bf16 v[90:93], v[174:177], v[118:121], v[90:93]
	v_mfma_f32_16x16x32_bf16 v[86:89], v[178:181], v[98:101], v[86:89]
	v_mfma_f32_16x16x32_bf16 v[82:85], v[178:181], v[114:117], v[82:85]
	v_mfma_f32_16x16x32_bf16 v[78:81], v[190:193], v[102:105], v[78:81]
	v_mfma_f32_16x16x32_bf16 v[74:77], v[190:193], v[118:121], v[74:77]
	v_mfma_f32_16x16x32_bf16 v[70:73], v[194:197], v[98:101], v[70:73]
	v_mfma_f32_16x16x32_bf16 v[66:69], v[194:197], v[114:117], v[66:69]
	v_mfma_f32_16x16x32_bf16 v[164:167], v[182:185], v[102:105], v[86:89]
	v_mfma_f32_16x16x32_bf16 v[174:177], v[182:185], v[118:121], v[82:85]
	v_mfma_f32_16x16x32_bf16 v[178:181], v[198:201], v[102:105], v[70:73]
	v_mfma_f32_16x16x32_bf16 v[182:185], v[198:201], v[118:121], v[66:69]
	s_barrier
	s_nop 1
	ds_read_b128 v[66:69], v140 offset:16384
	ds_read_b128 v[70:73], v140 offset:17408
	ds_read_b128 v[82:85], v139 offset:16384
	ds_read_b128 v[86:89], v139 offset:17408
	ds_read_b128 v[186:189], v138 offset:16384
	ds_read_b128 v[190:193], v138 offset:17408
	ds_read_b128 v[194:197], v137 offset:16384
	ds_read_b128 v[198:201], v137 offset:17408
	s_waitcnt vmcnt(4)
	s_barrier
	s_waitcnt lgkmcnt(0)
	s_waitcnt lgkmcnt(0)
	v_mfma_f32_16x16x32_bf16 v[62:65], v[66:69], v[146:149], v[62:65]
	v_mfma_f32_16x16x32_bf16 v[58:61], v[66:69], v[156:159], v[58:61]
	v_mfma_f32_16x16x32_bf16 v[46:49], v[186:189], v[146:149], v[46:49]
	v_mfma_f32_16x16x32_bf16 v[38:41], v[194:197], v[146:149], v[38:41]
	v_mfma_f32_16x16x32_bf16 v[62:65], v[70:73], v[152:155], v[62:65]
	v_mfma_f32_16x16x32_bf16 v[58:61], v[70:73], v[160:163], v[58:61]
	v_mfma_f32_16x16x32_bf16 v[54:57], v[82:85], v[146:149], v[54:57]
	v_mfma_f32_16x16x32_bf16 v[50:53], v[82:85], v[156:159], v[50:53]
	v_mfma_f32_16x16x32_bf16 v[46:49], v[190:193], v[152:155], v[46:49]
	v_mfma_f32_16x16x32_bf16 v[42:45], v[186:189], v[156:159], v[42:45]
	v_mfma_f32_16x16x32_bf16 v[38:41], v[198:201], v[152:155], v[38:41]
	v_mfma_f32_16x16x32_bf16 v[34:37], v[194:197], v[156:159], v[34:37]
	v_mfma_f32_16x16x32_bf16 v[218:221], v[86:89], v[152:155], v[54:57]
	v_mfma_f32_16x16x32_bf16 v[222:225], v[86:89], v[160:163], v[50:53]
	v_mfma_f32_16x16x32_bf16 v[226:229], v[190:193], v[160:163], v[42:45]
	v_mfma_f32_16x16x32_bf16 v[144:147], v[198:201], v[160:163], v[34:37]
	v_mfma_f32_16x16x32_bf16 v[30:33], v[66:69], v[98:101], v[30:33]
	v_mfma_f32_16x16x32_bf16 v[26:29], v[66:69], v[114:117], v[26:29]
	v_mfma_f32_16x16x32_bf16 v[14:17], v[186:189], v[98:101], v[14:17]
	v_mfma_f32_16x16x32_bf16 v[6:9], v[194:197], v[98:101], v[6:9]
	v_mfma_f32_16x16x32_bf16 v[30:33], v[70:73], v[102:105], v[30:33]
	v_mfma_f32_16x16x32_bf16 v[26:29], v[70:73], v[118:121], v[26:29]
	v_mfma_f32_16x16x32_bf16 v[22:25], v[82:85], v[98:101], v[22:25]
	v_mfma_f32_16x16x32_bf16 v[18:21], v[82:85], v[114:117], v[18:21]
	v_mfma_f32_16x16x32_bf16 v[14:17], v[190:193], v[102:105], v[14:17]
	v_mfma_f32_16x16x32_bf16 v[10:13], v[186:189], v[114:117], v[10:13]
	v_mfma_f32_16x16x32_bf16 v[6:9], v[198:201], v[102:105], v[6:9]
	v_mfma_f32_16x16x32_bf16 v[2:5], v[194:197], v[114:117], v[2:5]
	v_mfma_f32_16x16x32_bf16 v[148:151], v[86:89], v[102:105], v[22:25]
	v_mfma_f32_16x16x32_bf16 v[152:155], v[86:89], v[118:121], v[18:21]
	v_mfma_f32_16x16x32_bf16 v[156:159], v[190:193], v[118:121], v[10:13]
	v_mfma_f32_16x16x32_bf16 v[160:163], v[198:201], v[118:121], v[2:5]
	s_barrier
	s_nop 1
	ds_read_b128 v[2:5], v142
	ds_read_b128 v[10:13], v142 offset:1024
	ds_read_b128 v[186:189], v142 offset:2048
	ds_read_b128 v[190:193], v142 offset:3072
	ds_read_b128 v[18:21], v140 offset:32768
	ds_read_b128 v[22:25], v140 offset:33792
	ds_read_b128 v[34:37], v139 offset:32768
	ds_read_b128 v[42:45], v139 offset:33792
	ds_read_b128 v[50:53], v138 offset:32768
	ds_read_b128 v[54:57], v138 offset:33792
	ds_read_b128 v[194:197], v137 offset:32768
	ds_read_b128 v[198:201], v137 offset:33792
	s_waitcnt vmcnt(2)
	s_barrier
; #define WAIT_V(n) asm volatile("s_waitcnt vmcnt(" #n ")" ::: "memory")
; #define WAIT_L(n) asm volatile("s_waitcnt lgkmcnt(" #n ")" ::: "memory")
; #define BAR __builtin_amdgcn_s_barrier()
; #define LDA(dst, b, h) for (int m = 0; m < 4; ++m) for (int k = 0; k < 2; ++k) \
;     dst[m][k] = *reinterpret_cast<const bf16x8*>((char*)SA(b, h) + lds_byte(wr * 64 + m * 16 + fr, k * 32 + fq * 8))
; #define LDB(dst, b, h) for (int n = 0; n < 2; ++n) for (int k = 0; k < 2; ++k) \
;     dst[n][k] = *reinterpret_cast<const bf16x8*>((char*)SB(b, h) + lds_byte(wc * 32 + n * 16 + fr, k * 32 + fq * 8))
; #define MMA(ai, bj, At_, Bt_) do { __builtin_amdgcn_s_setprio(1); \
;     for (int m = 0; m < 4; ++m) for (int n = 0; n < 2; ++n) for (int k = 0; k < 2; ++k) \
;       acc[ai][bj][m][n] = __builtin_amdgcn_mfma_f32_16x16x32_bf16(At_[m][k], Bt_[n][k], acc[ai][bj][m][n], 0, 0, 0); \
;     __builtin_amdgcn_s_setprio(0); } while (0)
; template <int K, int LD = K>
; __device__ __forceinline__ void gemm_main(const GAS bf16* A, const GAS bf16* Bt, int brow, int bcol, f32x4 (&acc)[2][2][4][2]) {
;     ...
;   { LDB(B0, 1, 0); LDA(At, 1, 0); WAIT_V(2); BAR; WAIT_L(0); MMA(0, 0, At, B0); BAR;
;     LDB(B1, 1, 1); WAIT_V(0); BAR; WAIT_L(0); MMA(0, 1, At, B1); BAR;
;     LDA(At, 1, 1); BAR; WAIT_L(0); MMA(1, 0, At, B0); MMA(1, 1, At, B1); BAR; }
;   if (wr == 0) BAR;
	s_waitcnt lgkmcnt(0)
	s_waitcnt lgkmcnt(0)
	v_mfma_f32_16x16x32_bf16 v[66:69], v[18:21], v[2:5], v[126:129]
	v_mfma_f32_16x16x32_bf16 v[118:121], v[22:25], v[10:13], v[66:69]
	v_mfma_f32_16x16x32_bf16 v[66:69], v[18:21], v[186:189], v[122:125]
	v_mfma_f32_16x16x32_bf16 v[114:117], v[22:25], v[190:193], v[66:69]
	v_mfma_f32_16x16x32_bf16 v[66:69], v[34:37], v[2:5], v[202:205]
	v_mfma_f32_16x16x32_bf16 v[102:105], v[42:45], v[10:13], v[66:69]
	v_mfma_f32_16x16x32_bf16 v[66:69], v[34:37], v[186:189], v[206:209]
	v_mfma_f32_16x16x32_bf16 v[98:101], v[42:45], v[190:193], v[66:69]
	v_mfma_f32_16x16x32_bf16 v[66:69], v[50:53], v[2:5], v[110:113]
	v_mfma_f32_16x16x32_bf16 v[86:89], v[54:57], v[10:13], v[66:69]
	v_mfma_f32_16x16x32_bf16 v[66:69], v[50:53], v[186:189], v[106:109]
	v_mfma_f32_16x16x32_bf16 v[82:85], v[54:57], v[190:193], v[66:69]
	v_mfma_f32_16x16x32_bf16 v[66:69], v[194:197], v[2:5], v[210:213]
	v_mfma_f32_16x16x32_bf16 v[70:73], v[198:201], v[10:13], v[66:69]
	v_mfma_f32_16x16x32_bf16 v[66:69], v[194:197], v[186:189], v[214:217]
	v_mfma_f32_16x16x32_bf16 v[66:69], v[198:201], v[190:193], v[66:69]
	s_barrier
	ds_read_b128 v[202:205], v141
	ds_read_b128 v[206:209], v141 offset:1024
	ds_read_b128 v[210:213], v141 offset:2048
	ds_read_b128 v[214:217], v141 offset:3072
	s_waitcnt vmcnt(0)
	s_barrier
	s_waitcnt lgkmcnt(0)
	s_waitcnt lgkmcnt(0)
	v_mfma_f32_16x16x32_bf16 v[94:97], v[18:21], v[202:205], v[94:97]
	v_mfma_f32_16x16x32_bf16 v[18:21], v[18:21], v[210:213], v[90:93]
	v_mfma_f32_16x16x32_bf16 v[122:125], v[22:25], v[214:217], v[18:21]
	v_mfma_f32_16x16x32_bf16 v[18:21], v[34:37], v[202:205], v[164:167]
	v_mfma_f32_16x16x32_bf16 v[110:113], v[42:45], v[206:209], v[18:21]
	v_mfma_f32_16x16x32_bf16 v[18:21], v[34:37], v[210:213], v[174:177]
	v_mfma_f32_16x16x32_bf16 v[106:109], v[42:45], v[214:217], v[18:21]
	v_mfma_f32_16x16x32_bf16 v[18:21], v[50:53], v[202:205], v[78:81]
	v_mfma_f32_16x16x32_bf16 v[126:129], v[22:25], v[206:209], v[94:97]
	v_mfma_f32_16x16x32_bf16 v[94:97], v[54:57], v[206:209], v[18:21]
	v_mfma_f32_16x16x32_bf16 v[18:21], v[50:53], v[210:213], v[74:77]
	v_mfma_f32_16x16x32_bf16 v[90:93], v[54:57], v[214:217], v[18:21]
	v_mfma_f32_16x16x32_bf16 v[18:21], v[194:197], v[202:205], v[178:181]
	v_mfma_f32_16x16x32_bf16 v[78:81], v[198:201], v[206:209], v[18:21]
	v_mfma_f32_16x16x32_bf16 v[18:21], v[194:197], v[210:213], v[182:185]
	v_mfma_f32_16x16x32_bf16 v[74:77], v[198:201], v[214:217], v[18:21]
	s_barrier
	ds_read_b128 v[164:167], v140 offset:49152
	ds_read_b128 v[140:143], v140 offset:50176
	ds_read_b128 v[174:177], v139 offset:49152
	ds_read_b128 v[178:181], v139 offset:50176
	ds_read_b128 v[182:185], v138 offset:49152
	ds_read_b128 v[194:197], v138 offset:50176
	ds_read_b128 v[198:201], v137 offset:49152
	ds_read_b128 v[230:233], v137 offset:50176
	s_barrier
	s_waitcnt lgkmcnt(0)
	s_waitcnt lgkmcnt(0)
	v_mfma_f32_16x16x32_bf16 v[18:21], v[164:167], v[2:5], v[62:65]
	v_mfma_f32_16x16x32_bf16 v[54:57], v[140:143], v[10:13], v[18:21]
	v_mfma_f32_16x16x32_bf16 v[18:21], v[164:167], v[186:189], v[58:61]
	v_mfma_f32_16x16x32_bf16 v[50:53], v[140:143], v[190:193], v[18:21]
	v_mfma_f32_16x16x32_bf16 v[18:21], v[174:177], v[2:5], v[218:221]
	v_mfma_f32_16x16x32_bf16 v[42:45], v[178:181], v[10:13], v[18:21]
	v_mfma_f32_16x16x32_bf16 v[18:21], v[174:177], v[186:189], v[222:225]
	v_mfma_f32_16x16x32_bf16 v[34:37], v[178:181], v[190:193], v[18:21]
	v_mfma_f32_16x16x32_bf16 v[18:21], v[182:185], v[2:5], v[46:49]
	v_mfma_f32_16x16x32_bf16 v[2:5], v[198:201], v[2:5], v[38:41]
	v_mfma_f32_16x16x32_bf16 v[22:25], v[194:197], v[10:13], v[18:21]
	v_mfma_f32_16x16x32_bf16 v[18:21], v[182:185], v[186:189], v[226:229]
	v_mfma_f32_16x16x32_bf16 v[10:13], v[230:233], v[10:13], v[2:5]
	v_mfma_f32_16x16x32_bf16 v[2:5], v[198:201], v[186:189], v[144:147]
	v_mfma_f32_16x16x32_bf16 v[18:21], v[194:197], v[190:193], v[18:21]
	v_mfma_f32_16x16x32_bf16 v[2:5], v[230:233], v[190:193], v[2:5]
	v_mfma_f32_16x16x32_bf16 v[26:29], v[164:167], v[210:213], v[26:29]
	v_mfma_f32_16x16x32_bf16 v[30:33], v[164:167], v[202:205], v[30:33]
	v_mfma_f32_16x16x32_bf16 v[58:61], v[140:143], v[214:217], v[26:29]
	v_mfma_f32_16x16x32_bf16 v[26:29], v[174:177], v[202:205], v[148:151]
	v_mfma_f32_16x16x32_bf16 v[14:17], v[182:185], v[202:205], v[14:17]
	v_mfma_f32_16x16x32_bf16 v[62:65], v[140:143], v[206:209], v[30:33]
	v_mfma_f32_16x16x32_bf16 v[46:49], v[178:181], v[206:209], v[26:29]
	v_mfma_f32_16x16x32_bf16 v[26:29], v[174:177], v[210:213], v[152:155]
	v_mfma_f32_16x16x32_bf16 v[30:33], v[194:197], v[206:209], v[14:17]
	v_mfma_f32_16x16x32_bf16 v[14:17], v[182:185], v[210:213], v[156:159]
	v_mfma_f32_16x16x32_bf16 v[6:9], v[198:201], v[202:205], v[6:9]
	v_mfma_f32_16x16x32_bf16 v[38:41], v[178:181], v[214:217], v[26:29]
	v_mfma_f32_16x16x32_bf16 v[26:29], v[194:197], v[214:217], v[14:17]
	v_mfma_f32_16x16x32_bf16 v[14:17], v[230:233], v[206:209], v[6:9]
	v_mfma_f32_16x16x32_bf16 v[6:9], v[198:201], v[210:213], v[160:163]
	v_mfma_f32_16x16x32_bf16 v[6:9], v[230:233], v[214:217], v[6:9]
	v_cmp_gt_u32_e32 vcc, s34, v136
	s_barrier
	s_and_saveexec_b64 s[14:15], vcc
	s_cbranch_execz .LBB0_92
	s_barrier

; #define STAGE(P, GP, ktrel) do { const GAS char* _g = (GP) + (ktrel) * (BK * 2); \
;     __builtin_amdgcn_global_load_lds((const GAS unsigned*)(_g + so0), (unsigned*)((char*)(P) + tid_ * 16), 16, 0, 0); \
;     __builtin_amdgcn_global_load_lds((const GAS unsigned*)(_g + so1), (unsigned*)((char*)(P) + tid_ * 16 + 8192), 16, 0, 0); } while (0)
; #define WAIT_V(n) asm volatile("s_waitcnt vmcnt(" #n ")" ::: "memory")
; #define WAIT_L(n) asm volatile("s_waitcnt lgkmcnt(" #n ")" ::: "memory")
; #define BAR __builtin_amdgcn_s_barrier()
; #define SCHED __builtin_amdgcn_sched_barrier(0)
; #define LDA(dst, b, h) for (int m = 0; m < 4; ++m) for (int k = 0; k < 2; ++k) \
;     dst[m][k] = *reinterpret_cast<const bf16x8*>((char*)SA(b, h) + lds_byte(wr * 64 + m * 16 + fr, k * 32 + fq * 8))
; #define LDB(dst, b, h) for (int n = 0; n < 2; ++n) for (int k = 0; k < 2; ++k) \
;     dst[n][k] = *reinterpret_cast<const bf16x8*>((char*)SB(b, h) + lds_byte(wc * 32 + n * 16 + fr, k * 32 + fq * 8))
; #define MMA(ai, bj, At_, Bt_) do { __builtin_amdgcn_s_setprio(1); \
;     for (int m = 0; m < 4; ++m) for (int n = 0; n < 2; ++n) for (int k = 0; k < 2; ++k) \
;       acc[ai][bj][m][n] = __builtin_amdgcn_mfma_f32_16x16x32_bf16(At_[m][k], Bt_[n][k], acc[ai][bj][m][n], 0, 0, 0); \
;     __builtin_amdgcn_s_setprio(0); } while (0)
; template <int K, int LD = K>
; __device__ __forceinline__ void gemm_main(const GAS bf16* A, const GAS bf16* Bt, int brow, int bcol, f32x4 (&acc)[2][2][4][2]) {
;     ...
;   for (int t = 0; t < nt - 2; t += 2) {
;     LDB(B0, 0, 0); SCHED; LDA(At, 0, 0); STAGE(SA(1, 1), pA1, 1);
;     WAIT_L(8); BAR; WAIT_L(0); MMA(0, 0, At, B0); BAR; SCHED;
;     LDB(B1, 0, 1); STAGE(SB(0, 0), pB0, 2);
;     BAR; WAIT_L(0); MMA(0, 1, At, B1); BAR;
;     LDA(At, 0, 1); STAGE(SA(0, 0), pA0, 2);
;     BAR; WAIT_L(0); MMA(1, 0, At, B0); BAR; SCHED;
;     STAGE(SB(0, 1), pB1, 2);
;     WAIT_V(6); BAR; MMA(1, 1, At, B1); BAR;
;     LDB(B0, 1, 0); SCHED; LDA(At, 1, 0); STAGE(SA(0, 1), pA1, 2);
;     WAIT_L(8); BAR; WAIT_L(0); MMA(0, 0, At, B0); BAR; SCHED;
.LBB0_230:
	ds_read_b128 v[160:163], v144
	ds_read_b128 v[164:167], v144 offset:1024
	ds_read_b128 v[174:177], v144 offset:2048
	ds_read_b128 v[178:181], v144 offset:3072
	v_lshl_add_u64 v[168:169], s[12:13], 0, v[130:131]
	v_readfirstlane_b32 s23, v143
	v_lshl_add_u64 v[214:215], v[168:169], 0, s[6:7]
	s_mov_b32 m0, s23
	v_lshl_add_u64 v[230:231], s[12:13], 0, v[132:133]
	v_readfirstlane_b32 s23, v142
	ds_read_b128 v[182:185], v138
	ds_read_b128 v[186:189], v138 offset:1024
	ds_read_b128 v[190:193], v137
	ds_read_b128 v[194:197], v137 offset:1024
	ds_read_b128 v[198:201], v136
	ds_read_b128 v[202:205], v136 offset:1024
	ds_read_b128 v[206:209], v135
	ds_read_b128 v[210:213], v135 offset:1024
	global_load_lds_dwordx4 v[214:215], off
	v_lshl_add_u64 v[214:215], v[230:231], 0, s[6:7]
	s_mov_b32 m0, s23
	s_nop 0
	global_load_lds_dwordx4 v[214:215], off
	s_waitcnt lgkmcnt(8)
	s_waitcnt vmcnt(10)
	s_barrier
	s_waitcnt lgkmcnt(0)
	s_waitcnt lgkmcnt(0)
	v_mfma_f32_16x16x32_bf16 v[126:129], v[182:185], v[160:163], v[126:129]
	v_mfma_f32_16x16x32_bf16 v[122:125], v[182:185], v[174:177], v[122:125]
	v_mfma_f32_16x16x32_bf16 v[118:121], v[190:193], v[160:163], v[118:121]
	v_mfma_f32_16x16x32_bf16 v[114:117], v[190:193], v[174:177], v[114:117]
	v_mfma_f32_16x16x32_bf16 v[110:113], v[198:201], v[160:163], v[110:113]
	v_mfma_f32_16x16x32_bf16 v[106:109], v[198:201], v[174:177], v[106:109]
	v_mfma_f32_16x16x32_bf16 v[102:105], v[206:209], v[160:163], v[102:105]
	v_mfma_f32_16x16x32_bf16 v[98:101], v[206:209], v[174:177], v[98:101]
	v_mfma_f32_16x16x32_bf16 v[126:129], v[186:189], v[164:167], v[126:129]
	v_mfma_f32_16x16x32_bf16 v[122:125], v[186:189], v[178:181], v[122:125]
	v_mfma_f32_16x16x32_bf16 v[118:121], v[194:197], v[164:167], v[118:121]
	v_mfma_f32_16x16x32_bf16 v[114:117], v[194:197], v[178:181], v[114:117]
	v_mfma_f32_16x16x32_bf16 v[110:113], v[202:205], v[164:167], v[110:113]
	v_mfma_f32_16x16x32_bf16 v[106:109], v[202:205], v[178:181], v[106:109]
	v_mfma_f32_16x16x32_bf16 v[102:105], v[210:213], v[164:167], v[102:105]
	v_mfma_f32_16x16x32_bf16 v[98:101], v[210:213], v[178:181], v[98:101]
	s_barrier
	v_lshl_add_u64 v[232:233], s[20:21], 0, v[130:131]
	v_readfirstlane_b32 s23, v151
	v_lshl_add_u64 v[234:235], v[232:233], 0, s[8:9]
	s_mov_b32 m0, s23
	ds_read_b128 v[214:217], v141
	ds_read_b128 v[218:221], v141 offset:1024
	ds_read_b128 v[222:225], v141 offset:2048
	ds_read_b128 v[226:229], v141 offset:3072
	global_load_lds_dwordx4 v[234:235], off
	v_lshl_add_u64 v[234:235], s[20:21], 0, v[132:133]
	v_readfirstlane_b32 s23, v152
	v_lshl_add_u64 v[236:237], v[234:235], 0, s[8:9]
	s_mov_b32 m0, s23
	s_add_u32 s20, s20, 0x100
	global_load_lds_dwordx4 v[236:237], off
	s_waitcnt vmcnt(10)
	s_barrier
	s_waitcnt lgkmcnt(0)
	s_addc_u32 s21, s21, 0
	s_waitcnt lgkmcnt(0)
	v_mfma_f32_16x16x32_bf16 v[94:97], v[182:185], v[214:217], v[94:97]
	v_mfma_f32_16x16x32_bf16 v[90:93], v[182:185], v[222:225], v[90:93]
	v_mfma_f32_16x16x32_bf16 v[86:89], v[190:193], v[214:217], v[86:89]
	v_mfma_f32_16x16x32_bf16 v[82:85], v[190:193], v[222:225], v[82:85]
	v_mfma_f32_16x16x32_bf16 v[78:81], v[198:201], v[214:217], v[78:81]
	v_mfma_f32_16x16x32_bf16 v[74:77], v[198:201], v[222:225], v[74:77]
	v_mfma_f32_16x16x32_bf16 v[70:73], v[206:209], v[214:217], v[70:73]
	v_mfma_f32_16x16x32_bf16 v[66:69], v[206:209], v[222:225], v[66:69]
	v_mfma_f32_16x16x32_bf16 v[94:97], v[186:189], v[218:221], v[94:97]
	v_mfma_f32_16x16x32_bf16 v[90:93], v[186:189], v[226:229], v[90:93]
	v_mfma_f32_16x16x32_bf16 v[86:89], v[194:197], v[218:221], v[86:89]
	v_mfma_f32_16x16x32_bf16 v[82:85], v[194:197], v[226:229], v[82:85]
	v_mfma_f32_16x16x32_bf16 v[78:81], v[202:205], v[218:221], v[78:81]
	v_mfma_f32_16x16x32_bf16 v[74:77], v[202:205], v[226:229], v[74:77]
	v_mfma_f32_16x16x32_bf16 v[70:73], v[210:213], v[218:221], v[70:73]
	v_mfma_f32_16x16x32_bf16 v[66:69], v[210:213], v[226:229], v[66:69]
	v_lshl_add_u64 v[236:237], s[18:19], 0, v[130:131]
	v_readfirstlane_b32 s23, v145
	v_lshl_add_u64 v[238:239], v[236:237], 0, s[8:9]
	s_mov_b32 m0, s23
	s_barrier
	ds_read_b128 v[182:185], v138 offset:16384
	ds_read_b128 v[186:189], v138 offset:17408
	ds_read_b128 v[190:193], v137 offset:16384
	ds_read_b128 v[194:197], v137 offset:17408
	ds_read_b128 v[198:201], v136 offset:16384
	ds_read_b128 v[202:205], v136 offset:17408
	ds_read_b128 v[206:209], v135 offset:16384
	ds_read_b128 v[210:213], v135 offset:17408
	global_load_lds_dwordx4 v[238:239], off
	v_lshl_add_u64 v[238:239], s[18:19], 0, v[132:133]
	v_readfirstlane_b32 s23, v146
	v_lshl_add_u64 v[240:241], v[238:239], 0, s[8:9]
	s_mov_b32 m0, s23
	s_add_u32 s18, s18, 0x100
	global_load_lds_dwordx4 v[240:241], off
	s_barrier
	s_waitcnt lgkmcnt(0)
	s_addc_u32 s19, s19, 0
	s_waitcnt lgkmcnt(0)
	v_mfma_f32_16x16x32_bf16 v[62:65], v[182:185], v[160:163], v[62:65]
	v_mfma_f32_16x16x32_bf16 v[58:61], v[182:185], v[174:177], v[58:61]
	v_mfma_f32_16x16x32_bf16 v[54:57], v[190:193], v[160:163], v[54:57]
	v_mfma_f32_16x16x32_bf16 v[50:53], v[190:193], v[174:177], v[50:53]
	v_mfma_f32_16x16x32_bf16 v[46:49], v[198:201], v[160:163], v[46:49]
	v_mfma_f32_16x16x32_bf16 v[42:45], v[198:201], v[174:177], v[42:45]
	v_mfma_f32_16x16x32_bf16 v[38:41], v[206:209], v[160:163], v[38:41]
	v_mfma_f32_16x16x32_bf16 v[34:37], v[206:209], v[174:177], v[34:37]
	v_mfma_f32_16x16x32_bf16 v[62:65], v[186:189], v[164:167], v[62:65]
	v_mfma_f32_16x16x32_bf16 v[58:61], v[186:189], v[178:181], v[58:61]
	v_mfma_f32_16x16x32_bf16 v[54:57], v[194:197], v[164:167], v[54:57]
	v_mfma_f32_16x16x32_bf16 v[50:53], v[194:197], v[178:181], v[50:53]
	v_mfma_f32_16x16x32_bf16 v[46:49], v[202:205], v[164:167], v[46:49]
	v_mfma_f32_16x16x32_bf16 v[42:45], v[202:205], v[178:181], v[42:45]
	v_mfma_f32_16x16x32_bf16 v[38:41], v[210:213], v[164:167], v[38:41]
	v_mfma_f32_16x16x32_bf16 v[34:37], v[210:213], v[178:181], v[34:37]
	s_barrier
; #define STAGE(P, GP, ktrel) do { const GAS char* _g = (GP) + (ktrel) * (BK * 2); \
;     __builtin_amdgcn_global_load_lds((const GAS unsigned*)(_g + so0), (unsigned*)((char*)(P) + tid_ * 16), 16, 0, 0); \
;     __builtin_amdgcn_global_load_lds((const GAS unsigned*)(_g + so1), (unsigned*)((char*)(P) + tid_ * 16 + 8192), 16, 0, 0); } while (0)
; #define WAIT_V(n) asm volatile("s_waitcnt vmcnt(" #n ")" ::: "memory")
; #define WAIT_L(n) asm volatile("s_waitcnt lgkmcnt(" #n ")" ::: "memory")
; #define BAR __builtin_amdgcn_s_barrier()
; #define SCHED __builtin_amdgcn_sched_barrier(0)
; #define LDA(dst, b, h) for (int m = 0; m < 4; ++m) for (int k = 0; k < 2; ++k) \
;     dst[m][k] = *reinterpret_cast<const bf16x8*>((char*)SA(b, h) + lds_byte(wr * 64 + m * 16 + fr, k * 32 + fq * 8))
; #define LDB(dst, b, h) for (int n = 0; n < 2; ++n) for (int k = 0; k < 2; ++k) \
;     dst[n][k] = *reinterpret_cast<const bf16x8*>((char*)SB(b, h) + lds_byte(wc * 32 + n * 16 + fr, k * 32 + fq * 8))
; #define MMA(ai, bj, At_, Bt_) do { __builtin_amdgcn_s_setprio(1); \
;     for (int m = 0; m < 4; ++m) for (int n = 0; n < 2; ++n) for (int k = 0; k < 2; ++k) \
;       acc[ai][bj][m][n] = __builtin_amdgcn_mfma_f32_16x16x32_bf16(At_[m][k], Bt_[n][k], acc[ai][bj][m][n], 0, 0, 0); \
;     __builtin_amdgcn_s_setprio(0); } while (0)
; template <int K, int LD = K>
; __device__ __forceinline__ void gemm_main(const GAS bf16* A, const GAS bf16* Bt, int brow, int bcol, f32x4 (&acc)[2][2][4][2]) {
;     ...
;     STAGE(SB(0, 1), pB1, 2);
;     WAIT_V(6); BAR; MMA(1, 1, At, B1); BAR;
;     LDB(B0, 1, 0); SCHED; LDA(At, 1, 0); STAGE(SA(0, 1), pA1, 2);
;     WAIT_L(8); BAR; WAIT_L(0); MMA(0, 0, At, B0); BAR; SCHED;
;     LDB(B1, 1, 1); STAGE(SB(1, 0), pB0, 3);
;     BAR; WAIT_L(0); MMA(0, 1, At, B1); BAR;
	v_lshl_add_u64 v[240:241], s[16:17], 0, v[130:131]
	v_readfirstlane_b32 s23, v153
	v_lshl_add_u64 v[160:161], v[240:241], 0, s[8:9]
	s_mov_b32 m0, s23
	v_lshl_add_u64 v[242:243], s[16:17], 0, v[132:133]
	v_readfirstlane_b32 s23, v155
	global_load_lds_dwordx4 v[160:161], off
	v_lshl_add_u64 v[160:161], v[242:243], 0, s[8:9]
	s_mov_b32 m0, s23
	s_add_u32 s16, s16, 0x100
	global_load_lds_dwordx4 v[160:161], off
	s_waitcnt vmcnt(10)
	s_addc_u32 s17, s17, 0
	s_barrier
	v_mfma_f32_16x16x32_bf16 v[30:33], v[182:185], v[214:217], v[30:33]
	v_mfma_f32_16x16x32_bf16 v[26:29], v[182:185], v[222:225], v[26:29]
	v_mfma_f32_16x16x32_bf16 v[22:25], v[190:193], v[214:217], v[22:25]
	v_mfma_f32_16x16x32_bf16 v[18:21], v[190:193], v[222:225], v[18:21]
	v_mfma_f32_16x16x32_bf16 v[14:17], v[198:201], v[214:217], v[14:17]
	v_mfma_f32_16x16x32_bf16 v[10:13], v[198:201], v[222:225], v[10:13]
	v_mfma_f32_16x16x32_bf16 v[6:9], v[206:209], v[214:217], v[6:9]
	v_mfma_f32_16x16x32_bf16 v[2:5], v[206:209], v[222:225], v[2:5]
	v_mfma_f32_16x16x32_bf16 v[30:33], v[186:189], v[218:221], v[30:33]
	v_mfma_f32_16x16x32_bf16 v[26:29], v[186:189], v[226:229], v[26:29]
	v_mfma_f32_16x16x32_bf16 v[22:25], v[194:197], v[218:221], v[22:25]
	v_mfma_f32_16x16x32_bf16 v[18:21], v[194:197], v[226:229], v[18:21]
	v_mfma_f32_16x16x32_bf16 v[14:17], v[202:205], v[218:221], v[14:17]
	v_mfma_f32_16x16x32_bf16 v[10:13], v[202:205], v[226:229], v[10:13]
	v_mfma_f32_16x16x32_bf16 v[6:9], v[210:213], v[218:221], v[6:9]
	v_mfma_f32_16x16x32_bf16 v[2:5], v[210:213], v[226:229], v[2:5]
	s_barrier
	ds_read_b128 v[160:163], v140
	ds_read_b128 v[164:167], v140 offset:1024
	ds_read_b128 v[174:177], v140 offset:2048
	ds_read_b128 v[178:181], v140 offset:3072
	v_readfirstlane_b32 s23, v147
	v_lshl_add_u64 v[168:169], v[168:169], 0, s[8:9]
	s_mov_b32 m0, s23
	v_readfirstlane_b32 s23, v148
	ds_read_b128 v[182:185], v138 offset:32768
	ds_read_b128 v[186:189], v138 offset:33792
	ds_read_b128 v[190:193], v137 offset:32768
	ds_read_b128 v[194:197], v137 offset:33792
	ds_read_b128 v[198:201], v136 offset:32768
	ds_read_b128 v[202:205], v136 offset:33792
	ds_read_b128 v[206:209], v135 offset:32768
	ds_read_b128 v[210:213], v135 offset:33792
	global_load_lds_dwordx4 v[168:169], off
	v_lshl_add_u64 v[168:169], v[230:231], 0, s[8:9]
	s_mov_b32 m0, s23
	s_add_u32 s12, s12, 0x100
	global_load_lds_dwordx4 v[168:169], off
	s_waitcnt lgkmcnt(8)
	s_waitcnt vmcnt(10)
	s_barrier
	s_waitcnt lgkmcnt(0)
	s_addc_u32 s13, s13, 0
	s_waitcnt lgkmcnt(0)
	v_mfma_f32_16x16x32_bf16 v[126:129], v[182:185], v[160:163], v[126:129]
	v_mfma_f32_16x16x32_bf16 v[122:125], v[182:185], v[174:177], v[122:125]
	v_mfma_f32_16x16x32_bf16 v[118:121], v[190:193], v[160:163], v[118:121]
	v_mfma_f32_16x16x32_bf16 v[114:117], v[190:193], v[174:177], v[114:117]
	v_mfma_f32_16x16x32_bf16 v[110:113], v[198:201], v[160:163], v[110:113]
	v_mfma_f32_16x16x32_bf16 v[106:109], v[198:201], v[174:177], v[106:109]
	v_mfma_f32_16x16x32_bf16 v[102:105], v[206:209], v[160:163], v[102:105]
	v_mfma_f32_16x16x32_bf16 v[98:101], v[206:209], v[174:177], v[98:101]
	v_mfma_f32_16x16x32_bf16 v[126:129], v[186:189], v[164:167], v[126:129]
	v_mfma_f32_16x16x32_bf16 v[122:125], v[186:189], v[178:181], v[122:125]
	v_mfma_f32_16x16x32_bf16 v[118:121], v[194:197], v[164:167], v[118:121]
	v_mfma_f32_16x16x32_bf16 v[114:117], v[194:197], v[178:181], v[114:117]
	v_mfma_f32_16x16x32_bf16 v[110:113], v[202:205], v[164:167], v[110:113]
	v_mfma_f32_16x16x32_bf16 v[106:109], v[202:205], v[178:181], v[106:109]
	v_mfma_f32_16x16x32_bf16 v[102:105], v[210:213], v[164:167], v[102:105]
	v_mfma_f32_16x16x32_bf16 v[98:101], v[210:213], v[178:181], v[98:101]
	s_barrier
	v_readfirstlane_b32 s23, v156
	v_lshl_add_u64 v[168:169], v[232:233], 0, s[10:11]
	s_mov_b32 m0, s23
	v_readfirstlane_b32 s23, v157
	ds_read_b128 v[214:217], v139
	ds_read_b128 v[218:221], v139 offset:1024
	ds_read_b128 v[222:225], v139 offset:2048
	ds_read_b128 v[226:229], v139 offset:3072
	global_load_lds_dwordx4 v[168:169], off
	v_lshl_add_u64 v[168:169], v[234:235], 0, s[10:11]
	s_mov_b32 m0, s23
	s_nop 0
	global_load_lds_dwordx4 v[168:169], off
	s_waitcnt vmcnt(10)
	s_barrier
	s_waitcnt lgkmcnt(0)
	s_waitcnt lgkmcnt(0)
	v_mfma_f32_16x16x32_bf16 v[94:97], v[182:185], v[214:217], v[94:97]
	v_mfma_f32_16x16x32_bf16 v[90:93], v[182:185], v[222:225], v[90:93]
	v_mfma_f32_16x16x32_bf16 v[86:89], v[190:193], v[214:217], v[86:89]
	v_mfma_f32_16x16x32_bf16 v[82:85], v[190:193], v[222:225], v[82:85]
	v_mfma_f32_16x16x32_bf16 v[78:81], v[198:201], v[214:217], v[78:81]
	v_mfma_f32_16x16x32_bf16 v[74:77], v[198:201], v[222:225], v[74:77]
	v_mfma_f32_16x16x32_bf16 v[70:73], v[206:209], v[214:217], v[70:73]
	v_mfma_f32_16x16x32_bf16 v[66:69], v[206:209], v[222:225], v[66:69]
	v_mfma_f32_16x16x32_bf16 v[94:97], v[186:189], v[218:221], v[94:97]
	v_mfma_f32_16x16x32_bf16 v[90:93], v[186:189], v[226:229], v[90:93]
	v_mfma_f32_16x16x32_bf16 v[86:89], v[194:197], v[218:221], v[86:89]
	v_mfma_f32_16x16x32_bf16 v[82:85], v[194:197], v[226:229], v[82:85]
	v_mfma_f32_16x16x32_bf16 v[78:81], v[202:205], v[218:221], v[78:81]
	v_mfma_f32_16x16x32_bf16 v[74:77], v[202:205], v[226:229], v[74:77]
	v_mfma_f32_16x16x32_bf16 v[70:73], v[210:213], v[218:221], v[70:73]
	v_mfma_f32_16x16x32_bf16 v[66:69], v[210:213], v[226:229], v[66:69]
	v_readfirstlane_b32 s23, v149
	v_lshl_add_u64 v[168:169], v[236:237], 0, s[10:11]
	s_mov_b32 m0, s23
	v_readfirstlane_b32 s23, v150
	s_barrier
; #define STAGE(P, GP, ktrel) do { const GAS char* _g = (GP) + (ktrel) * (BK * 2); \
;     __builtin_amdgcn_global_load_lds((const GAS unsigned*)(_g + so0), (unsigned*)((char*)(P) + tid_ * 16), 16, 0, 0); \
;     __builtin_amdgcn_global_load_lds((const GAS unsigned*)(_g + so1), (unsigned*)((char*)(P) + tid_ * 16 + 8192), 16, 0, 0); } while (0)
; #define WAIT_V(n) asm volatile("s_waitcnt vmcnt(" #n ")" ::: "memory")
; #define WAIT_L(n) asm volatile("s_waitcnt lgkmcnt(" #n ")" ::: "memory")
; #define BAR __builtin_amdgcn_s_barrier()
; #define SCHED __builtin_amdgcn_sched_barrier(0)
; #define LDA(dst, b, h) for (int m = 0; m < 4; ++m) for (int k = 0; k < 2; ++k) \
;     dst[m][k] = *reinterpret_cast<const bf16x8*>((char*)SA(b, h) + lds_byte(wr * 64 + m * 16 + fr, k * 32 + fq * 8))
; #define LDB(dst, b, h) for (int n = 0; n < 2; ++n) for (int k = 0; k < 2; ++k) \
;     dst[n][k] = *reinterpret_cast<const bf16x8*>((char*)SB(b, h) + lds_byte(wc * 32 + n * 16 + fr, k * 32 + fq * 8))
; #define MMA(ai, bj, At_, Bt_) do { __builtin_amdgcn_s_setprio(1); \
;     for (int m = 0; m < 4; ++m) for (int n = 0; n < 2; ++n) for (int k = 0; k < 2; ++k) \
;       acc[ai][bj][m][n] = __builtin_amdgcn_mfma_f32_16x16x32_bf16(At_[m][k], Bt_[n][k], acc[ai][bj][m][n], 0, 0, 0); \
;     __builtin_amdgcn_s_setprio(0); } while (0)
; template <int K, int LD = K>
; __device__ __forceinline__ void gemm_main(const GAS bf16* A, const GAS bf16* Bt, int brow, int bcol, f32x4 (&acc)[2][2][4][2]) {
;     ...
;     LDA(At, 1, 1); STAGE(SA(1, 0), pA0, 3);
;     BAR; WAIT_L(0); MMA(1, 0, At, B0); BAR; SCHED;
;     STAGE(SB(1, 1), pB1, 3);
;     WAIT_V(6); BAR; MMA(1, 1, At, B1); BAR;
;     pA0 += 4 * BK; pA1 += 4 * BK; pB0 += 4 * BK; pB1 += 4 * BK;
;     asm volatile("" : "+s"(pA0), "+s"(pA1), "+s"(pB0), "+s"(pB1));
;   }
;   { LDB(B0, 0, 0); LDA(At, 0, 0); STAGE(SA(1, 1), pA1, 1);
;     BAR; WAIT_L(0); MMA(0, 0, At, B0); BAR;
	ds_read_b128 v[182:185], v138 offset:49152
	ds_read_b128 v[186:189], v138 offset:50176
	ds_read_b128 v[190:193], v137 offset:49152
	ds_read_b128 v[194:197], v137 offset:50176
	ds_read_b128 v[198:201], v136 offset:49152
	ds_read_b128 v[202:205], v136 offset:50176
	ds_read_b128 v[206:209], v135 offset:49152
	ds_read_b128 v[210:213], v135 offset:50176
	global_load_lds_dwordx4 v[168:169], off
	v_lshl_add_u64 v[168:169], v[238:239], 0, s[10:11]
	s_mov_b32 m0, s23
	s_nop 0
	global_load_lds_dwordx4 v[168:169], off
	s_barrier
	s_waitcnt lgkmcnt(0)
	s_waitcnt lgkmcnt(0)
	v_mfma_f32_16x16x32_bf16 v[62:65], v[182:185], v[160:163], v[62:65]
	v_mfma_f32_16x16x32_bf16 v[58:61], v[182:185], v[174:177], v[58:61]
	v_mfma_f32_16x16x32_bf16 v[54:57], v[190:193], v[160:163], v[54:57]
	v_mfma_f32_16x16x32_bf16 v[50:53], v[190:193], v[174:177], v[50:53]
	v_mfma_f32_16x16x32_bf16 v[46:49], v[198:201], v[160:163], v[46:49]
	v_mfma_f32_16x16x32_bf16 v[42:45], v[198:201], v[174:177], v[42:45]
	v_mfma_f32_16x16x32_bf16 v[38:41], v[206:209], v[160:163], v[38:41]
	v_mfma_f32_16x16x32_bf16 v[34:37], v[206:209], v[174:177], v[34:37]
	v_mfma_f32_16x16x32_bf16 v[62:65], v[186:189], v[164:167], v[62:65]
	v_mfma_f32_16x16x32_bf16 v[58:61], v[186:189], v[178:181], v[58:61]
	v_mfma_f32_16x16x32_bf16 v[54:57], v[194:197], v[164:167], v[54:57]
	v_mfma_f32_16x16x32_bf16 v[50:53], v[194:197], v[178:181], v[50:53]
	v_mfma_f32_16x16x32_bf16 v[46:49], v[202:205], v[164:167], v[46:49]
	v_mfma_f32_16x16x32_bf16 v[42:45], v[202:205], v[178:181], v[42:45]
	v_mfma_f32_16x16x32_bf16 v[38:41], v[210:213], v[164:167], v[38:41]
	v_mfma_f32_16x16x32_bf16 v[34:37], v[210:213], v[178:181], v[34:37]
	s_barrier
	v_readfirstlane_b32 s23, v158
	v_lshl_add_u64 v[160:161], v[240:241], 0, s[10:11]
	s_mov_b32 m0, s23
	v_readfirstlane_b32 s23, v159
	global_load_lds_dwordx4 v[160:161], off
	v_lshl_add_u64 v[160:161], v[242:243], 0, s[10:11]
	s_mov_b32 m0, s23
	s_nop 0
	global_load_lds_dwordx4 v[160:161], off
	s_waitcnt vmcnt(10)
	s_barrier
	v_mfma_f32_16x16x32_bf16 v[30:33], v[182:185], v[214:217], v[30:33]
	v_mfma_f32_16x16x32_bf16 v[26:29], v[182:185], v[222:225], v[26:29]
	v_mfma_f32_16x16x32_bf16 v[22:25], v[190:193], v[214:217], v[22:25]
	v_mfma_f32_16x16x32_bf16 v[18:21], v[190:193], v[222:225], v[18:21]
	v_mfma_f32_16x16x32_bf16 v[14:17], v[198:201], v[214:217], v[14:17]
	v_mfma_f32_16x16x32_bf16 v[10:13], v[198:201], v[222:225], v[10:13]
	v_mfma_f32_16x16x32_bf16 v[6:9], v[206:209], v[214:217], v[6:9]
	v_mfma_f32_16x16x32_bf16 v[2:5], v[206:209], v[222:225], v[2:5]
	v_mfma_f32_16x16x32_bf16 v[30:33], v[186:189], v[218:221], v[30:33]
	v_mfma_f32_16x16x32_bf16 v[26:29], v[186:189], v[226:229], v[26:29]
	v_mfma_f32_16x16x32_bf16 v[22:25], v[194:197], v[218:221], v[22:25]
	v_mfma_f32_16x16x32_bf16 v[18:21], v[194:197], v[226:229], v[18:21]
	v_mfma_f32_16x16x32_bf16 v[14:17], v[202:205], v[218:221], v[14:17]
	v_mfma_f32_16x16x32_bf16 v[10:13], v[202:205], v[226:229], v[10:13]
	v_mfma_f32_16x16x32_bf16 v[6:9], v[210:213], v[218:221], v[6:9]
	v_mfma_f32_16x16x32_bf16 v[2:5], v[210:213], v[226:229], v[2:5]
	s_add_i32 s22, s22, 2
	s_cmp_lt_u32 s22, 40
	s_barrier
	s_cbranch_scc1 .LBB0_230
	ds_read_b128 v[146:149], v144
	ds_read_b128 v[150:153], v144 offset:1024
	ds_read_b128 v[156:159], v144 offset:2048
	ds_read_b128 v[160:163], v144 offset:3072
	ds_read_b128 v[164:167], v138
	ds_read_b128 v[174:177], v138 offset:1024
	ds_read_b128 v[178:181], v137
	ds_read_b128 v[182:185], v137 offset:1024
	ds_read_b128 v[186:189], v136
	ds_read_b128 v[190:193], v136 offset:1024
	ds_read_b128 v[194:197], v135
	ds_read_b128 v[198:201], v135 offset:1024
	v_lshl_add_u64 v[144:145], s[12:13], 0, v[130:131]
	v_readfirstlane_b32 s16, v143
	v_lshl_add_u64 v[144:145], v[144:145], 0, s[6:7]
	s_mov_b32 m0, s16
	v_lshl_add_u64 v[132:133], s[12:13], 0, v[132:133]
	v_readfirstlane_b32 s12, v142
	global_load_lds_dwordx4 v[144:145], off
	v_lshl_add_u64 v[132:133], v[132:133], 0, s[6:7]
	s_mov_b32 m0, s12
	s_nop 0
	global_load_lds_dwordx4 v[132:133], off
	s_waitcnt vmcnt(10)
	s_barrier
	s_waitcnt lgkmcnt(0)
	s_waitcnt lgkmcnt(0)
	v_mfma_f32_16x16x32_bf16 v[126:129], v[164:167], v[146:149], v[126:129]
	v_mfma_f32_16x16x32_bf16 v[122:125], v[164:167], v[156:159], v[122:125]
	v_mfma_f32_16x16x32_bf16 v[110:113], v[186:189], v[146:149], v[110:113]
	v_mfma_f32_16x16x32_bf16 v[106:109], v[186:189], v[156:159], v[106:109]
	v_mfma_f32_16x16x32_bf16 v[126:129], v[174:177], v[150:153], v[126:129]
	v_mfma_f32_16x16x32_bf16 v[122:125], v[174:177], v[160:163], v[122:125]
	v_mfma_f32_16x16x32_bf16 v[118:121], v[178:181], v[146:149], v[118:121]
	v_mfma_f32_16x16x32_bf16 v[114:117], v[178:181], v[156:159], v[114:117]
	v_mfma_f32_16x16x32_bf16 v[110:113], v[190:193], v[150:153], v[110:113]
	v_mfma_f32_16x16x32_bf16 v[106:109], v[190:193], v[160:163], v[106:109]
	v_mfma_f32_16x16x32_bf16 v[102:105], v[194:197], v[146:149], v[102:105]
	v_mfma_f32_16x16x32_bf16 v[98:101], v[194:197], v[156:159], v[98:101]
	v_mfma_f32_16x16x32_bf16 v[142:145], v[182:185], v[150:153], v[118:121]
	v_mfma_f32_16x16x32_bf16 v[202:205], v[182:185], v[160:163], v[114:117]
	v_mfma_f32_16x16x32_bf16 v[206:209], v[198:201], v[150:153], v[102:105]
	v_mfma_f32_16x16x32_bf16 v[210:213], v[198:201], v[160:163], v[98:101]
	s_barrier
	s_nop 1
	ds_read_b128 v[98:101], v141
	ds_read_b128 v[102:105], v141 offset:1024
	ds_read_b128 v[114:117], v141 offset:2048
	ds_read_b128 v[118:121], v141 offset:3072
	s_waitcnt vmcnt(8)
	s_barrier
; #define WAIT_V(n) asm volatile("s_waitcnt vmcnt(" #n ")" ::: "memory")
; #define WAIT_L(n) asm volatile("s_waitcnt lgkmcnt(" #n ")" ::: "memory")
; #define BAR __builtin_amdgcn_s_barrier()
; #define LDA(dst, b, h) for (int m = 0; m < 4; ++m) for (int k = 0; k < 2; ++k) \
;     dst[m][k] = *reinterpret_cast<const bf16x8*>((char*)SA(b, h) + lds_byte(wr * 64 + m * 16 + fr, k * 32 + fq * 8))
; #define LDB(dst, b, h) for (int n = 0; n < 2; ++n) for (int k = 0; k < 2; ++k) \
;     dst[n][k] = *reinterpret_cast<const bf16x8*>((char*)SB(b, h) + lds_byte(wc * 32 + n * 16 + fr, k * 32 + fq * 8))
; #define MMA(ai, bj, At_, Bt_) do { __builtin_amdgcn_s_setprio(1); \
;     for (int m = 0; m < 4; ++m) for (int n = 0; n < 2; ++n) for (int k = 0; k < 2; ++k) \
;       acc[ai][bj][m][n] = __builtin_amdgcn_mfma_f32_16x16x32_bf16(At_[m][k], Bt_[n][k], acc[ai][bj][m][n], 0, 0, 0); \
;     __builtin_amdgcn_s_setprio(0); } while (0)
; template <int K, int LD = K>
; __device__ __forceinline__ void gemm_main(const GAS bf16* A, const GAS bf16* Bt, int brow, int bcol, f32x4 (&acc)[2][2][4][2]) {
;     ...
;     LDB(B1, 0, 1); BAR; WAIT_L(0); MMA(0, 1, At, B1); BAR;
;     LDA(At, 0, 1); WAIT_V(4); BAR; WAIT_L(0); MMA(1, 0, At, B0); MMA(1, 1, At, B1); BAR; }
;   { LDB(B0, 1, 0); LDA(At, 1, 0); WAIT_V(2); BAR; WAIT_L(0); MMA(0, 0, At, B0); BAR;
	s_waitcnt lgkmcnt(0)
	s_waitcnt lgkmcnt(0)
	v_mfma_f32_16x16x32_bf16 v[94:97], v[164:167], v[98:101], v[94:97]
	v_mfma_f32_16x16x32_bf16 v[90:93], v[164:167], v[114:117], v[90:93]
	v_mfma_f32_16x16x32_bf16 v[78:81], v[186:189], v[98:101], v[78:81]
	v_mfma_f32_16x16x32_bf16 v[74:77], v[186:189], v[114:117], v[74:77]
	v_mfma_f32_16x16x32_bf16 v[94:97], v[174:177], v[102:105], v[94:97]
	v_mfma_f32_16x16x32_bf16 v[90:93], v[174:177], v[118:121], v[90:93]
	v_mfma_f32_16x16x32_bf16 v[86:89], v[178:181], v[98:101], v[86:89]
	v_mfma_f32_16x16x32_bf16 v[82:85], v[178:181], v[114:117], v[82:85]
	v_mfma_f32_16x16x32_bf16 v[78:81], v[190:193], v[102:105], v[78:81]
	v_mfma_f32_16x16x32_bf16 v[74:77], v[190:193], v[118:121], v[74:77]
	v_mfma_f32_16x16x32_bf16 v[70:73], v[194:197], v[98:101], v[70:73]
	v_mfma_f32_16x16x32_bf16 v[66:69], v[194:197], v[114:117], v[66:69]
	v_mfma_f32_16x16x32_bf16 v[164:167], v[182:185], v[102:105], v[86:89]
	v_mfma_f32_16x16x32_bf16 v[174:177], v[182:185], v[118:121], v[82:85]
	v_mfma_f32_16x16x32_bf16 v[178:181], v[198:201], v[102:105], v[70:73]
	v_mfma_f32_16x16x32_bf16 v[182:185], v[198:201], v[118:121], v[66:69]
	s_barrier
	s_nop 1
	ds_read_b128 v[66:69], v138 offset:16384
	ds_read_b128 v[70:73], v138 offset:17408
	ds_read_b128 v[82:85], v137 offset:16384
	ds_read_b128 v[86:89], v137 offset:17408
	ds_read_b128 v[186:189], v136 offset:16384
	ds_read_b128 v[190:193], v136 offset:17408
	ds_read_b128 v[194:197], v135 offset:16384
	ds_read_b128 v[198:201], v135 offset:17408
	s_waitcnt vmcnt(4)
	s_barrier
	s_waitcnt lgkmcnt(0)
	s_waitcnt lgkmcnt(0)
	v_mfma_f32_16x16x32_bf16 v[62:65], v[66:69], v[146:149], v[62:65]
	v_mfma_f32_16x16x32_bf16 v[58:61], v[66:69], v[156:159], v[58:61]
	v_mfma_f32_16x16x32_bf16 v[46:49], v[186:189], v[146:149], v[46:49]
	v_mfma_f32_16x16x32_bf16 v[42:45], v[186:189], v[156:159], v[42:45]
	v_mfma_f32_16x16x32_bf16 v[62:65], v[70:73], v[150:153], v[62:65]
	v_mfma_f32_16x16x32_bf16 v[58:61], v[70:73], v[160:163], v[58:61]
	v_mfma_f32_16x16x32_bf16 v[54:57], v[82:85], v[146:149], v[54:57]
	v_mfma_f32_16x16x32_bf16 v[50:53], v[82:85], v[156:159], v[50:53]
	v_mfma_f32_16x16x32_bf16 v[46:49], v[190:193], v[150:153], v[46:49]
	v_mfma_f32_16x16x32_bf16 v[42:45], v[190:193], v[160:163], v[42:45]
	v_mfma_f32_16x16x32_bf16 v[38:41], v[194:197], v[146:149], v[38:41]
	v_mfma_f32_16x16x32_bf16 v[34:37], v[194:197], v[156:159], v[34:37]
	v_mfma_f32_16x16x32_bf16 v[214:217], v[86:89], v[150:153], v[54:57]
	v_mfma_f32_16x16x32_bf16 v[218:221], v[86:89], v[160:163], v[50:53]
	v_mfma_f32_16x16x32_bf16 v[146:149], v[198:201], v[150:153], v[38:41]
	v_mfma_f32_16x16x32_bf16 v[150:153], v[198:201], v[160:163], v[34:37]
	v_mfma_f32_16x16x32_bf16 v[30:33], v[66:69], v[98:101], v[30:33]
	v_mfma_f32_16x16x32_bf16 v[26:29], v[66:69], v[114:117], v[26:29]
	v_mfma_f32_16x16x32_bf16 v[14:17], v[186:189], v[98:101], v[14:17]
	v_mfma_f32_16x16x32_bf16 v[10:13], v[186:189], v[114:117], v[10:13]
	v_mfma_f32_16x16x32_bf16 v[30:33], v[70:73], v[102:105], v[30:33]
	v_mfma_f32_16x16x32_bf16 v[26:29], v[70:73], v[118:121], v[26:29]
	v_mfma_f32_16x16x32_bf16 v[22:25], v[82:85], v[98:101], v[22:25]
	v_mfma_f32_16x16x32_bf16 v[18:21], v[82:85], v[114:117], v[18:21]
	v_mfma_f32_16x16x32_bf16 v[14:17], v[190:193], v[102:105], v[14:17]
	v_mfma_f32_16x16x32_bf16 v[10:13], v[190:193], v[118:121], v[10:13]
	v_mfma_f32_16x16x32_bf16 v[6:9], v[194:197], v[98:101], v[6:9]
	v_mfma_f32_16x16x32_bf16 v[2:5], v[194:197], v[114:117], v[2:5]
	v_mfma_f32_16x16x32_bf16 v[156:159], v[86:89], v[102:105], v[22:25]
	v_mfma_f32_16x16x32_bf16 v[160:163], v[86:89], v[118:121], v[18:21]
	v_mfma_f32_16x16x32_bf16 v[186:189], v[198:201], v[102:105], v[6:9]
	v_mfma_f32_16x16x32_bf16 v[190:193], v[198:201], v[118:121], v[2:5]
	s_barrier
	s_nop 1
	ds_read_b128 v[2:5], v140
	ds_read_b128 v[6:9], v140 offset:1024
	ds_read_b128 v[194:197], v140 offset:2048
	ds_read_b128 v[198:201], v140 offset:3072
	ds_read_b128 v[18:21], v138 offset:32768
	ds_read_b128 v[22:25], v138 offset:33792
	ds_read_b128 v[34:37], v137 offset:32768
	ds_read_b128 v[38:41], v137 offset:33792
	ds_read_b128 v[50:53], v136 offset:32768
	ds_read_b128 v[54:57], v136 offset:33792
	ds_read_b128 v[222:225], v135 offset:32768
	ds_read_b128 v[226:229], v135 offset:33792
	s_waitcnt vmcnt(2)
	s_barrier
; #define WAIT_V(n) asm volatile("s_waitcnt vmcnt(" #n ")" ::: "memory")
; #define WAIT_L(n) asm volatile("s_waitcnt lgkmcnt(" #n ")" ::: "memory")
; #define BAR __builtin_amdgcn_s_barrier()
; #define LDA(dst, b, h) for (int m = 0; m < 4; ++m) for (int k = 0; k < 2; ++k) \
;     dst[m][k] = *reinterpret_cast<const bf16x8*>((char*)SA(b, h) + lds_byte(wr * 64 + m * 16 + fr, k * 32 + fq * 8))
; #define LDB(dst, b, h) for (int n = 0; n < 2; ++n) for (int k = 0; k < 2; ++k) \
;     dst[n][k] = *reinterpret_cast<const bf16x8*>((char*)SB(b, h) + lds_byte(wc * 32 + n * 16 + fr, k * 32 + fq * 8))
; #define MMA(ai, bj, At_, Bt_) do { __builtin_amdgcn_s_setprio(1); \
;     for (int m = 0; m < 4; ++m) for (int n = 0; n < 2; ++n) for (int k = 0; k < 2; ++k) \
;       acc[ai][bj][m][n] = __builtin_amdgcn_mfma_f32_16x16x32_bf16(At_[m][k], Bt_[n][k], acc[ai][bj][m][n], 0, 0, 0); \
;     __builtin_amdgcn_s_setprio(0); } while (0)
; template <int K, int LD = K>
; __device__ __forceinline__ void gemm_main(const GAS bf16* A, const GAS bf16* Bt, int brow, int bcol, f32x4 (&acc)[2][2][4][2]) {
;     ...
;   { LDB(B0, 1, 0); LDA(At, 1, 0); WAIT_V(2); BAR; WAIT_L(0); MMA(0, 0, At, B0); BAR;
;     LDB(B1, 1, 1); WAIT_V(0); BAR; WAIT_L(0); MMA(0, 1, At, B1); BAR;
;     LDA(At, 1, 1); BAR; WAIT_L(0); MMA(1, 0, At, B0); MMA(1, 1, At, B1); BAR; }
;   if (wr == 0) BAR;
	s_waitcnt lgkmcnt(0)
	s_waitcnt lgkmcnt(0)
	v_mfma_f32_16x16x32_bf16 v[66:69], v[18:21], v[2:5], v[126:129]
	v_mfma_f32_16x16x32_bf16 v[118:121], v[22:25], v[6:9], v[66:69]
	v_mfma_f32_16x16x32_bf16 v[66:69], v[18:21], v[194:197], v[122:125]
	v_mfma_f32_16x16x32_bf16 v[114:117], v[22:25], v[198:201], v[66:69]
	v_mfma_f32_16x16x32_bf16 v[66:69], v[34:37], v[2:5], v[142:145]
	v_mfma_f32_16x16x32_bf16 v[102:105], v[38:41], v[6:9], v[66:69]
	v_mfma_f32_16x16x32_bf16 v[66:69], v[34:37], v[194:197], v[202:205]
	v_mfma_f32_16x16x32_bf16 v[98:101], v[38:41], v[198:201], v[66:69]
	v_mfma_f32_16x16x32_bf16 v[66:69], v[50:53], v[2:5], v[110:113]
	v_mfma_f32_16x16x32_bf16 v[86:89], v[54:57], v[6:9], v[66:69]
	v_mfma_f32_16x16x32_bf16 v[66:69], v[50:53], v[194:197], v[106:109]
	v_mfma_f32_16x16x32_bf16 v[82:85], v[54:57], v[198:201], v[66:69]
	v_mfma_f32_16x16x32_bf16 v[66:69], v[222:225], v[2:5], v[206:209]
	v_mfma_f32_16x16x32_bf16 v[70:73], v[226:229], v[6:9], v[66:69]
	v_mfma_f32_16x16x32_bf16 v[66:69], v[222:225], v[194:197], v[210:213]
	v_mfma_f32_16x16x32_bf16 v[66:69], v[226:229], v[198:201], v[66:69]
	s_barrier
	ds_read_b128 v[140:143], v139
	ds_read_b128 v[202:205], v139 offset:1024
	ds_read_b128 v[206:209], v139 offset:2048
	ds_read_b128 v[210:213], v139 offset:3072
	s_waitcnt vmcnt(0)
	s_barrier
	s_waitcnt lgkmcnt(0)
	s_waitcnt lgkmcnt(0)
	v_mfma_f32_16x16x32_bf16 v[94:97], v[18:21], v[140:143], v[94:97]
	v_mfma_f32_16x16x32_bf16 v[18:21], v[18:21], v[206:209], v[90:93]
	v_mfma_f32_16x16x32_bf16 v[122:125], v[22:25], v[210:213], v[18:21]
	v_mfma_f32_16x16x32_bf16 v[18:21], v[34:37], v[140:143], v[164:167]
	v_mfma_f32_16x16x32_bf16 v[110:113], v[38:41], v[202:205], v[18:21]
	v_mfma_f32_16x16x32_bf16 v[18:21], v[34:37], v[206:209], v[174:177]
	v_mfma_f32_16x16x32_bf16 v[106:109], v[38:41], v[210:213], v[18:21]
	v_mfma_f32_16x16x32_bf16 v[18:21], v[50:53], v[140:143], v[78:81]
	v_mfma_f32_16x16x32_bf16 v[126:129], v[22:25], v[202:205], v[94:97]
	v_mfma_f32_16x16x32_bf16 v[94:97], v[54:57], v[202:205], v[18:21]
	v_mfma_f32_16x16x32_bf16 v[18:21], v[50:53], v[206:209], v[74:77]
	v_mfma_f32_16x16x32_bf16 v[90:93], v[54:57], v[210:213], v[18:21]
	v_mfma_f32_16x16x32_bf16 v[18:21], v[222:225], v[140:143], v[178:181]
	v_mfma_f32_16x16x32_bf16 v[78:81], v[226:229], v[202:205], v[18:21]
	v_mfma_f32_16x16x32_bf16 v[18:21], v[222:225], v[206:209], v[182:185]
	v_mfma_f32_16x16x32_bf16 v[74:77], v[226:229], v[210:213], v[18:21]
	s_barrier
	ds_read_b128 v[164:167], v138 offset:49152
	ds_read_b128 v[174:177], v138 offset:50176
	ds_read_b128 v[178:181], v137 offset:49152
	ds_read_b128 v[182:185], v137 offset:50176
	ds_read_b128 v[222:225], v136 offset:49152
	ds_read_b128 v[136:139], v136 offset:50176
	ds_read_b128 v[226:229], v135 offset:49152
	ds_read_b128 v[230:233], v135 offset:50176
	s_barrier
	s_waitcnt lgkmcnt(0)
	s_waitcnt lgkmcnt(0)
	v_mfma_f32_16x16x32_bf16 v[18:21], v[164:167], v[2:5], v[62:65]
	v_mfma_f32_16x16x32_bf16 v[54:57], v[174:177], v[6:9], v[18:21]
	v_mfma_f32_16x16x32_bf16 v[18:21], v[164:167], v[194:197], v[58:61]
	v_mfma_f32_16x16x32_bf16 v[50:53], v[174:177], v[198:201], v[18:21]
	v_mfma_f32_16x16x32_bf16 v[18:21], v[178:181], v[2:5], v[214:217]
	v_mfma_f32_16x16x32_bf16 v[38:41], v[182:185], v[6:9], v[18:21]
	v_mfma_f32_16x16x32_bf16 v[18:21], v[178:181], v[194:197], v[218:221]
	v_mfma_f32_16x16x32_bf16 v[34:37], v[182:185], v[198:201], v[18:21]
	v_mfma_f32_16x16x32_bf16 v[18:21], v[222:225], v[2:5], v[46:49]
	v_mfma_f32_16x16x32_bf16 v[2:5], v[226:229], v[2:5], v[146:149]
	v_mfma_f32_16x16x32_bf16 v[22:25], v[136:139], v[6:9], v[18:21]
	v_mfma_f32_16x16x32_bf16 v[18:21], v[222:225], v[194:197], v[42:45]
	v_mfma_f32_16x16x32_bf16 v[6:9], v[230:233], v[6:9], v[2:5]
	v_mfma_f32_16x16x32_bf16 v[2:5], v[226:229], v[194:197], v[150:153]
	v_mfma_f32_16x16x32_bf16 v[18:21], v[136:139], v[198:201], v[18:21]
	v_mfma_f32_16x16x32_bf16 v[2:5], v[230:233], v[198:201], v[2:5]
	v_mfma_f32_16x16x32_bf16 v[26:29], v[164:167], v[206:209], v[26:29]
	v_mfma_f32_16x16x32_bf16 v[58:61], v[174:177], v[210:213], v[26:29]
	v_mfma_f32_16x16x32_bf16 v[26:29], v[178:181], v[140:143], v[156:159]
	v_mfma_f32_16x16x32_bf16 v[46:49], v[182:185], v[202:205], v[26:29]
	v_mfma_f32_16x16x32_bf16 v[26:29], v[178:181], v[206:209], v[160:163]
	v_mfma_f32_16x16x32_bf16 v[10:13], v[222:225], v[206:209], v[10:13]
	v_mfma_f32_16x16x32_bf16 v[30:33], v[164:167], v[140:143], v[30:33]
	v_mfma_f32_16x16x32_bf16 v[42:45], v[182:185], v[210:213], v[26:29]
	v_mfma_f32_16x16x32_bf16 v[14:17], v[222:225], v[140:143], v[14:17]
	v_mfma_f32_16x16x32_bf16 v[26:29], v[136:139], v[210:213], v[10:13]
	v_mfma_f32_16x16x32_bf16 v[10:13], v[226:229], v[140:143], v[186:189]
	v_mfma_f32_16x16x32_bf16 v[62:65], v[174:177], v[202:205], v[30:33]
	v_mfma_f32_16x16x32_bf16 v[30:33], v[136:139], v[202:205], v[14:17]
	v_mfma_f32_16x16x32_bf16 v[14:17], v[230:233], v[202:205], v[10:13]
	v_mfma_f32_16x16x32_bf16 v[10:13], v[226:229], v[206:209], v[190:193]
	v_mfma_f32_16x16x32_bf16 v[10:13], v[230:233], v[210:213], v[10:13]
	v_cmp_gt_u32_e32 vcc, s35, v134
	s_barrier
	s_and_saveexec_b64 s[12:13], vcc
	s_cbranch_execz .LBB0_233
	s_barrier

; #define STAGE(P, GP, ktrel) do { const GAS char* _g = (GP) + (ktrel) * (BK * 2); \
;     __builtin_amdgcn_global_load_lds((const GAS unsigned*)(_g + so0), (unsigned*)((char*)(P) + tid_ * 16), 16, 0, 0); \
;     __builtin_amdgcn_global_load_lds((const GAS unsigned*)(_g + so1), (unsigned*)((char*)(P) + tid_ * 16 + 8192), 16, 0, 0); } while (0)
; #define WAIT_L(n) asm volatile("s_waitcnt lgkmcnt(" #n ")" ::: "memory")
; #define BAR __builtin_amdgcn_s_barrier()
; #define SCHED __builtin_amdgcn_sched_barrier(0)
; #define LDA(dst, b, h) for (int m = 0; m < 4; ++m) for (int k = 0; k < 2; ++k) \
;     dst[m][k] = *reinterpret_cast<const bf16x8*>((char*)SA(b, h) + lds_byte(wr * 64 + m * 16 + fr, k * 32 + fq * 8))
; #define LDB(dst, b, h) for (int n = 0; n < 2; ++n) for (int k = 0; k < 2; ++k) \
;     dst[n][k] = *reinterpret_cast<const bf16x8*>((char*)SB(b, h) + lds_byte(wc * 32 + n * 16 + fr, k * 32 + fq * 8))
; #define MMA(ai, bj, At_, Bt_) do { __builtin_amdgcn_s_setprio(1); \
;     for (int m = 0; m < 4; ++m) for (int n = 0; n < 2; ++n) for (int k = 0; k < 2; ++k) \
;       acc[ai][bj][m][n] = __builtin_amdgcn_mfma_f32_16x16x32_bf16(At_[m][k], Bt_[n][k], acc[ai][bj][m][n], 0, 0, 0); \
;     __builtin_amdgcn_s_setprio(0); } while (0)
; template <int K, int LD = K>
; __device__ __forceinline__ void gemm_main(const GAS bf16* A, const GAS bf16* Bt, int brow, int bcol, f32x4 (&acc)[2][2][4][2]) {
;     ...
;   for (int t = 0; t < nt - 2; t += 2) {
;     LDB(B0, 0, 0); SCHED; LDA(At, 0, 0); STAGE(SA(1, 1), pA1, 1);
;     WAIT_L(8); BAR; WAIT_L(0); MMA(0, 0, At, B0); BAR; SCHED;
;     LDB(B1, 0, 1); STAGE(SB(0, 0), pB0, 2);
;     BAR; WAIT_L(0); MMA(0, 1, At, B1); BAR;
;     LDA(At, 0, 1); STAGE(SA(0, 0), pA0, 2);
;     BAR; WAIT_L(0); MMA(1, 0, At, B0); BAR; SCHED;
.LBB0_346:
	ds_read_b128 v[162:165], v146
	ds_read_b128 v[166:169], v146 offset:1024
	ds_read_b128 v[174:177], v146 offset:2048
	ds_read_b128 v[178:181], v146 offset:3072
	v_lshl_add_u64 v[230:231], s[26:27], 0, v[130:131]
	v_readfirstlane_b32 s20, v143
	v_lshl_add_u64 v[214:215], v[230:231], 0, s[14:15]
	s_mov_b32 m0, s20
	v_lshl_add_u64 v[232:233], s[26:27], 0, v[132:133]
	v_readfirstlane_b32 s20, v142
	ds_read_b128 v[182:185], v138
	ds_read_b128 v[186:189], v138 offset:1024
	ds_read_b128 v[190:193], v137
	ds_read_b128 v[194:197], v137 offset:1024
	ds_read_b128 v[198:201], v136
	ds_read_b128 v[202:205], v136 offset:1024
	ds_read_b128 v[206:209], v135
	ds_read_b128 v[210:213], v135 offset:1024
	global_load_lds_dwordx4 v[214:215], off
	v_lshl_add_u64 v[214:215], v[232:233], 0, s[14:15]
	s_mov_b32 m0, s20
	s_nop 0
	global_load_lds_dwordx4 v[214:215], off
	s_waitcnt lgkmcnt(8)
	s_waitcnt vmcnt(10)
	s_barrier
	s_waitcnt lgkmcnt(0)
	s_waitcnt lgkmcnt(0)
	v_mfma_f32_16x16x32_bf16 v[126:129], v[182:185], v[162:165], v[126:129]
	v_mfma_f32_16x16x32_bf16 v[122:125], v[182:185], v[174:177], v[122:125]
	v_mfma_f32_16x16x32_bf16 v[118:121], v[190:193], v[162:165], v[118:121]
	v_mfma_f32_16x16x32_bf16 v[114:117], v[190:193], v[174:177], v[114:117]
	v_mfma_f32_16x16x32_bf16 v[110:113], v[198:201], v[162:165], v[110:113]
	v_mfma_f32_16x16x32_bf16 v[106:109], v[198:201], v[174:177], v[106:109]
	v_mfma_f32_16x16x32_bf16 v[102:105], v[206:209], v[162:165], v[102:105]
	v_mfma_f32_16x16x32_bf16 v[98:101], v[206:209], v[174:177], v[98:101]
	v_mfma_f32_16x16x32_bf16 v[126:129], v[186:189], v[166:169], v[126:129]
	v_mfma_f32_16x16x32_bf16 v[122:125], v[186:189], v[178:181], v[122:125]
	v_mfma_f32_16x16x32_bf16 v[118:121], v[194:197], v[166:169], v[118:121]
	v_mfma_f32_16x16x32_bf16 v[114:117], v[194:197], v[178:181], v[114:117]
	v_mfma_f32_16x16x32_bf16 v[110:113], v[202:205], v[166:169], v[110:113]
	v_mfma_f32_16x16x32_bf16 v[106:109], v[202:205], v[178:181], v[106:109]
	v_mfma_f32_16x16x32_bf16 v[102:105], v[210:213], v[166:169], v[102:105]
	v_mfma_f32_16x16x32_bf16 v[98:101], v[210:213], v[178:181], v[98:101]
	s_barrier
	v_lshl_add_u64 v[234:235], s[36:37], 0, v[130:131]
	v_readfirstlane_b32 s20, v153
	v_lshl_add_u64 v[236:237], v[234:235], 0, s[22:23]
	s_mov_b32 m0, s20
	ds_read_b128 v[214:217], v141
	ds_read_b128 v[218:221], v141 offset:1024
	ds_read_b128 v[222:225], v141 offset:2048
	ds_read_b128 v[226:229], v141 offset:3072
	global_load_lds_dwordx4 v[236:237], off
	v_lshl_add_u64 v[236:237], s[36:37], 0, v[132:133]
	v_readfirstlane_b32 s20, v154
	v_lshl_add_u64 v[238:239], v[236:237], 0, s[22:23]
	s_mov_b32 m0, s20
	s_add_u32 s36, s36, 0x100
	global_load_lds_dwordx4 v[238:239], off
	s_waitcnt vmcnt(10)
	s_barrier
	s_waitcnt lgkmcnt(0)
	s_addc_u32 s37, s37, 0
	s_waitcnt lgkmcnt(0)
	v_mfma_f32_16x16x32_bf16 v[94:97], v[182:185], v[214:217], v[94:97]
	v_mfma_f32_16x16x32_bf16 v[90:93], v[182:185], v[222:225], v[90:93]
	v_mfma_f32_16x16x32_bf16 v[86:89], v[190:193], v[214:217], v[86:89]
	v_mfma_f32_16x16x32_bf16 v[82:85], v[190:193], v[222:225], v[82:85]
	v_mfma_f32_16x16x32_bf16 v[78:81], v[198:201], v[214:217], v[78:81]
	v_mfma_f32_16x16x32_bf16 v[74:77], v[198:201], v[222:225], v[74:77]
	v_mfma_f32_16x16x32_bf16 v[70:73], v[206:209], v[214:217], v[70:73]
	v_mfma_f32_16x16x32_bf16 v[66:69], v[206:209], v[222:225], v[66:69]
	v_mfma_f32_16x16x32_bf16 v[94:97], v[186:189], v[218:221], v[94:97]
	v_mfma_f32_16x16x32_bf16 v[90:93], v[186:189], v[226:229], v[90:93]
	v_mfma_f32_16x16x32_bf16 v[86:89], v[194:197], v[218:221], v[86:89]
	v_mfma_f32_16x16x32_bf16 v[82:85], v[194:197], v[226:229], v[82:85]
	v_mfma_f32_16x16x32_bf16 v[78:81], v[202:205], v[218:221], v[78:81]
	v_mfma_f32_16x16x32_bf16 v[74:77], v[202:205], v[226:229], v[74:77]
	v_mfma_f32_16x16x32_bf16 v[70:73], v[210:213], v[218:221], v[70:73]
	v_mfma_f32_16x16x32_bf16 v[66:69], v[210:213], v[226:229], v[66:69]
	v_lshl_add_u64 v[238:239], s[34:35], 0, v[130:131]
	v_readfirstlane_b32 s20, v147
	v_lshl_add_u64 v[240:241], v[238:239], 0, s[22:23]
	s_mov_b32 m0, s20
	s_barrier
	ds_read_b128 v[182:185], v138 offset:16384
	ds_read_b128 v[186:189], v138 offset:17408
	ds_read_b128 v[190:193], v137 offset:16384
	ds_read_b128 v[194:197], v137 offset:17408
	ds_read_b128 v[198:201], v136 offset:16384
	ds_read_b128 v[202:205], v136 offset:17408
	ds_read_b128 v[206:209], v135 offset:16384
	ds_read_b128 v[210:213], v135 offset:17408
	global_load_lds_dwordx4 v[240:241], off
	v_lshl_add_u64 v[240:241], s[34:35], 0, v[132:133]
	v_readfirstlane_b32 s20, v148
	v_lshl_add_u64 v[242:243], v[240:241], 0, s[22:23]
	s_mov_b32 m0, s20
	s_add_u32 s34, s34, 0x100
	global_load_lds_dwordx4 v[242:243], off
	s_barrier
	s_waitcnt lgkmcnt(0)
	s_addc_u32 s35, s35, 0
	s_waitcnt lgkmcnt(0)
	v_mfma_f32_16x16x32_bf16 v[62:65], v[182:185], v[162:165], v[62:65]
	v_mfma_f32_16x16x32_bf16 v[58:61], v[182:185], v[174:177], v[58:61]
	v_mfma_f32_16x16x32_bf16 v[54:57], v[190:193], v[162:165], v[54:57]
	v_mfma_f32_16x16x32_bf16 v[50:53], v[190:193], v[174:177], v[50:53]
	v_mfma_f32_16x16x32_bf16 v[46:49], v[198:201], v[162:165], v[46:49]
	v_mfma_f32_16x16x32_bf16 v[42:45], v[198:201], v[174:177], v[42:45]
	v_mfma_f32_16x16x32_bf16 v[38:41], v[206:209], v[162:165], v[38:41]
	v_mfma_f32_16x16x32_bf16 v[34:37], v[206:209], v[174:177], v[34:37]
	v_mfma_f32_16x16x32_bf16 v[62:65], v[186:189], v[166:169], v[62:65]
	v_mfma_f32_16x16x32_bf16 v[58:61], v[186:189], v[178:181], v[58:61]
	v_mfma_f32_16x16x32_bf16 v[54:57], v[194:197], v[166:169], v[54:57]
	v_mfma_f32_16x16x32_bf16 v[50:53], v[194:197], v[178:181], v[50:53]
	v_mfma_f32_16x16x32_bf16 v[46:49], v[202:205], v[166:169], v[46:49]
	v_mfma_f32_16x16x32_bf16 v[42:45], v[202:205], v[178:181], v[42:45]
	v_mfma_f32_16x16x32_bf16 v[38:41], v[210:213], v[166:169], v[38:41]
	v_mfma_f32_16x16x32_bf16 v[34:37], v[210:213], v[178:181], v[34:37]
	s_barrier
; #define STAGE(P, GP, ktrel) do { const GAS char* _g = (GP) + (ktrel) * (BK * 2); \
;     __builtin_amdgcn_global_load_lds((const GAS unsigned*)(_g + so0), (unsigned*)((char*)(P) + tid_ * 16), 16, 0, 0); \
;     __builtin_amdgcn_global_load_lds((const GAS unsigned*)(_g + so1), (unsigned*)((char*)(P) + tid_ * 16 + 8192), 16, 0, 0); } while (0)
; #define WAIT_V(n) asm volatile("s_waitcnt vmcnt(" #n ")" ::: "memory")
; #define WAIT_L(n) asm volatile("s_waitcnt lgkmcnt(" #n ")" ::: "memory")
; #define BAR __builtin_amdgcn_s_barrier()
; #define SCHED __builtin_amdgcn_sched_barrier(0)
; #define LDA(dst, b, h) for (int m = 0; m < 4; ++m) for (int k = 0; k < 2; ++k) \
;     dst[m][k] = *reinterpret_cast<const bf16x8*>((char*)SA(b, h) + lds_byte(wr * 64 + m * 16 + fr, k * 32 + fq * 8))
; #define LDB(dst, b, h) for (int n = 0; n < 2; ++n) for (int k = 0; k < 2; ++k) \
;     dst[n][k] = *reinterpret_cast<const bf16x8*>((char*)SB(b, h) + lds_byte(wc * 32 + n * 16 + fr, k * 32 + fq * 8))
; #define MMA(ai, bj, At_, Bt_) do { __builtin_amdgcn_s_setprio(1); \
;     for (int m = 0; m < 4; ++m) for (int n = 0; n < 2; ++n) for (int k = 0; k < 2; ++k) \
;       acc[ai][bj][m][n] = __builtin_amdgcn_mfma_f32_16x16x32_bf16(At_[m][k], Bt_[n][k], acc[ai][bj][m][n], 0, 0, 0); \
;     __builtin_amdgcn_s_setprio(0); } while (0)
; template <int K, int LD = K>
; __device__ __forceinline__ void gemm_main(const GAS bf16* A, const GAS bf16* Bt, int brow, int bcol, f32x4 (&acc)[2][2][4][2]) {
;     ...
;     STAGE(SB(0, 1), pB1, 2);
;     WAIT_V(6); BAR; MMA(1, 1, At, B1); BAR;
;     LDB(B0, 1, 0); SCHED; LDA(At, 1, 0); STAGE(SA(0, 1), pA1, 2);
;     WAIT_L(8); BAR; WAIT_L(0); MMA(0, 0, At, B0); BAR; SCHED;
;     LDB(B1, 1, 1); STAGE(SB(1, 0), pB0, 3);
;     BAR; WAIT_L(0); MMA(0, 1, At, B1); BAR;
;     LDA(At, 1, 1); STAGE(SA(1, 0), pA0, 3);
	v_lshl_add_u64 v[242:243], s[28:29], 0, v[130:131]
	v_readfirstlane_b32 s20, v155
	v_lshl_add_u64 v[162:163], v[242:243], 0, s[22:23]
	s_mov_b32 m0, s20
	v_lshl_add_u64 v[244:245], s[28:29], 0, v[132:133]
	v_readfirstlane_b32 s20, v156
	global_load_lds_dwordx4 v[162:163], off
	v_lshl_add_u64 v[162:163], v[244:245], 0, s[22:23]
	s_mov_b32 m0, s20
	s_add_u32 s28, s28, 0x100
	global_load_lds_dwordx4 v[162:163], off
	s_waitcnt vmcnt(10)
	s_addc_u32 s29, s29, 0
	s_barrier
	v_mfma_f32_16x16x32_bf16 v[30:33], v[182:185], v[214:217], v[30:33]
	v_mfma_f32_16x16x32_bf16 v[26:29], v[182:185], v[222:225], v[26:29]
	v_mfma_f32_16x16x32_bf16 v[22:25], v[190:193], v[214:217], v[22:25]
	v_mfma_f32_16x16x32_bf16 v[18:21], v[190:193], v[222:225], v[18:21]
	v_mfma_f32_16x16x32_bf16 v[14:17], v[198:201], v[214:217], v[14:17]
	v_mfma_f32_16x16x32_bf16 v[10:13], v[198:201], v[222:225], v[10:13]
	v_mfma_f32_16x16x32_bf16 v[6:9], v[206:209], v[214:217], v[6:9]
	v_mfma_f32_16x16x32_bf16 v[2:5], v[206:209], v[222:225], v[2:5]
	v_mfma_f32_16x16x32_bf16 v[30:33], v[186:189], v[218:221], v[30:33]
	v_mfma_f32_16x16x32_bf16 v[26:29], v[186:189], v[226:229], v[26:29]
	v_mfma_f32_16x16x32_bf16 v[22:25], v[194:197], v[218:221], v[22:25]
	v_mfma_f32_16x16x32_bf16 v[18:21], v[194:197], v[226:229], v[18:21]
	v_mfma_f32_16x16x32_bf16 v[14:17], v[202:205], v[218:221], v[14:17]
	v_mfma_f32_16x16x32_bf16 v[10:13], v[202:205], v[226:229], v[10:13]
	v_mfma_f32_16x16x32_bf16 v[6:9], v[210:213], v[218:221], v[6:9]
	v_mfma_f32_16x16x32_bf16 v[2:5], v[210:213], v[226:229], v[2:5]
	s_barrier
	ds_read_b128 v[162:165], v140
	ds_read_b128 v[166:169], v140 offset:1024
	ds_read_b128 v[174:177], v140 offset:2048
	ds_read_b128 v[178:181], v140 offset:3072
	v_readfirstlane_b32 s20, v149
	v_lshl_add_u64 v[214:215], v[230:231], 0, s[22:23]
	s_mov_b32 m0, s20
	v_readfirstlane_b32 s20, v150
	ds_read_b128 v[182:185], v138 offset:32768
	ds_read_b128 v[186:189], v138 offset:33792
	ds_read_b128 v[190:193], v137 offset:32768
	ds_read_b128 v[194:197], v137 offset:33792
	ds_read_b128 v[198:201], v136 offset:32768
	ds_read_b128 v[202:205], v136 offset:33792
	ds_read_b128 v[206:209], v135 offset:32768
	ds_read_b128 v[210:213], v135 offset:33792
	global_load_lds_dwordx4 v[214:215], off
	v_lshl_add_u64 v[214:215], v[232:233], 0, s[22:23]
	s_mov_b32 m0, s20
	s_add_u32 s26, s26, 0x100
	global_load_lds_dwordx4 v[214:215], off
	s_waitcnt lgkmcnt(8)
	s_waitcnt vmcnt(10)
	s_barrier
	s_waitcnt lgkmcnt(0)
	s_addc_u32 s27, s27, 0
	s_waitcnt lgkmcnt(0)
	v_mfma_f32_16x16x32_bf16 v[126:129], v[182:185], v[162:165], v[126:129]
	v_mfma_f32_16x16x32_bf16 v[122:125], v[182:185], v[174:177], v[122:125]
	v_mfma_f32_16x16x32_bf16 v[118:121], v[190:193], v[162:165], v[118:121]
	v_mfma_f32_16x16x32_bf16 v[114:117], v[190:193], v[174:177], v[114:117]
	v_mfma_f32_16x16x32_bf16 v[110:113], v[198:201], v[162:165], v[110:113]
	v_mfma_f32_16x16x32_bf16 v[106:109], v[198:201], v[174:177], v[106:109]
	v_mfma_f32_16x16x32_bf16 v[102:105], v[206:209], v[162:165], v[102:105]
	v_mfma_f32_16x16x32_bf16 v[98:101], v[206:209], v[174:177], v[98:101]
	v_mfma_f32_16x16x32_bf16 v[126:129], v[186:189], v[166:169], v[126:129]
	v_mfma_f32_16x16x32_bf16 v[122:125], v[186:189], v[178:181], v[122:125]
	v_mfma_f32_16x16x32_bf16 v[118:121], v[194:197], v[166:169], v[118:121]
	v_mfma_f32_16x16x32_bf16 v[114:117], v[194:197], v[178:181], v[114:117]
	v_mfma_f32_16x16x32_bf16 v[110:113], v[202:205], v[166:169], v[110:113]
	v_mfma_f32_16x16x32_bf16 v[106:109], v[202:205], v[178:181], v[106:109]
	v_mfma_f32_16x16x32_bf16 v[102:105], v[210:213], v[166:169], v[102:105]
	v_mfma_f32_16x16x32_bf16 v[98:101], v[210:213], v[178:181], v[98:101]
	s_barrier
	v_readfirstlane_b32 s20, v157
	v_lshl_add_u64 v[230:231], v[234:235], 0, s[24:25]
	s_mov_b32 m0, s20
	v_readfirstlane_b32 s20, v158
	ds_read_b128 v[214:217], v139
	ds_read_b128 v[218:221], v139 offset:1024
	ds_read_b128 v[222:225], v139 offset:2048
	ds_read_b128 v[226:229], v139 offset:3072
	global_load_lds_dwordx4 v[230:231], off
	v_lshl_add_u64 v[230:231], v[236:237], 0, s[24:25]
	s_mov_b32 m0, s20
	s_nop 0
	global_load_lds_dwordx4 v[230:231], off
	s_waitcnt vmcnt(10)
	s_barrier
	s_waitcnt lgkmcnt(0)
	s_waitcnt lgkmcnt(0)
	v_mfma_f32_16x16x32_bf16 v[94:97], v[182:185], v[214:217], v[94:97]
	v_mfma_f32_16x16x32_bf16 v[90:93], v[182:185], v[222:225], v[90:93]
	v_mfma_f32_16x16x32_bf16 v[86:89], v[190:193], v[214:217], v[86:89]
	v_mfma_f32_16x16x32_bf16 v[82:85], v[190:193], v[222:225], v[82:85]
	v_mfma_f32_16x16x32_bf16 v[78:81], v[198:201], v[214:217], v[78:81]
	v_mfma_f32_16x16x32_bf16 v[74:77], v[198:201], v[222:225], v[74:77]
	v_mfma_f32_16x16x32_bf16 v[70:73], v[206:209], v[214:217], v[70:73]
	v_mfma_f32_16x16x32_bf16 v[66:69], v[206:209], v[222:225], v[66:69]
	v_mfma_f32_16x16x32_bf16 v[94:97], v[186:189], v[218:221], v[94:97]
	v_mfma_f32_16x16x32_bf16 v[90:93], v[186:189], v[226:229], v[90:93]
	v_mfma_f32_16x16x32_bf16 v[86:89], v[194:197], v[218:221], v[86:89]
	v_mfma_f32_16x16x32_bf16 v[82:85], v[194:197], v[226:229], v[82:85]
	v_mfma_f32_16x16x32_bf16 v[78:81], v[202:205], v[218:221], v[78:81]
	v_mfma_f32_16x16x32_bf16 v[74:77], v[202:205], v[226:229], v[74:77]
	v_mfma_f32_16x16x32_bf16 v[70:73], v[210:213], v[218:221], v[70:73]
	v_mfma_f32_16x16x32_bf16 v[66:69], v[210:213], v[226:229], v[66:69]
	v_readfirstlane_b32 s20, v151
	v_lshl_add_u64 v[230:231], v[238:239], 0, s[24:25]
	s_mov_b32 m0, s20
	v_readfirstlane_b32 s20, v152
	s_barrier
; #define STAGE(P, GP, ktrel) do { const GAS char* _g = (GP) + (ktrel) * (BK * 2); \
;     __builtin_amdgcn_global_load_lds((const GAS unsigned*)(_g + so0), (unsigned*)((char*)(P) + tid_ * 16), 16, 0, 0); \
;     __builtin_amdgcn_global_load_lds((const GAS unsigned*)(_g + so1), (unsigned*)((char*)(P) + tid_ * 16 + 8192), 16, 0, 0); } while (0)
; #define WAIT_V(n) asm volatile("s_waitcnt vmcnt(" #n ")" ::: "memory")
; #define WAIT_L(n) asm volatile("s_waitcnt lgkmcnt(" #n ")" ::: "memory")
; #define BAR __builtin_amdgcn_s_barrier()
; #define SCHED __builtin_amdgcn_sched_barrier(0)
; #define LDA(dst, b, h) for (int m = 0; m < 4; ++m) for (int k = 0; k < 2; ++k) \
;     dst[m][k] = *reinterpret_cast<const bf16x8*>((char*)SA(b, h) + lds_byte(wr * 64 + m * 16 + fr, k * 32 + fq * 8))
; #define LDB(dst, b, h) for (int n = 0; n < 2; ++n) for (int k = 0; k < 2; ++k) \
;     dst[n][k] = *reinterpret_cast<const bf16x8*>((char*)SB(b, h) + lds_byte(wc * 32 + n * 16 + fr, k * 32 + fq * 8))
; #define MMA(ai, bj, At_, Bt_) do { __builtin_amdgcn_s_setprio(1); \
;     for (int m = 0; m < 4; ++m) for (int n = 0; n < 2; ++n) for (int k = 0; k < 2; ++k) \
;       acc[ai][bj][m][n] = __builtin_amdgcn_mfma_f32_16x16x32_bf16(At_[m][k], Bt_[n][k], acc[ai][bj][m][n], 0, 0, 0); \
;     __builtin_amdgcn_s_setprio(0); } while (0)
; template <int K, int LD = K>
; __device__ __forceinline__ void gemm_main(const GAS bf16* A, const GAS bf16* Bt, int brow, int bcol, f32x4 (&acc)[2][2][4][2]) {
;     ...
;     LDA(At, 1, 1); STAGE(SA(1, 0), pA0, 3);
;     BAR; WAIT_L(0); MMA(1, 0, At, B0); BAR; SCHED;
;     STAGE(SB(1, 1), pB1, 3);
;     WAIT_V(6); BAR; MMA(1, 1, At, B1); BAR;
;     pA0 += 4 * BK; pA1 += 4 * BK; pB0 += 4 * BK; pB1 += 4 * BK;
;     asm volatile("" : "+s"(pA0), "+s"(pA1), "+s"(pB0), "+s"(pB1));
;   }
;   { LDB(B0, 0, 0); LDA(At, 0, 0); STAGE(SA(1, 1), pA1, 1);
;     BAR; WAIT_L(0); MMA(0, 0, At, B0); BAR;
;     LDB(B1, 0, 1); BAR; WAIT_L(0); MMA(0, 1, At, B1); BAR;
;     LDA(At, 0, 1); WAIT_V(4); BAR; WAIT_L(0); MMA(1, 0, At, B0); MMA(1, 1, At, B1); BAR; }
	ds_read_b128 v[182:185], v138 offset:49152
	ds_read_b128 v[186:189], v138 offset:50176
	ds_read_b128 v[190:193], v137 offset:49152
	ds_read_b128 v[194:197], v137 offset:50176
	ds_read_b128 v[198:201], v136 offset:49152
	ds_read_b128 v[202:205], v136 offset:50176
	ds_read_b128 v[206:209], v135 offset:49152
	ds_read_b128 v[210:213], v135 offset:50176
	global_load_lds_dwordx4 v[230:231], off
	v_lshl_add_u64 v[230:231], v[240:241], 0, s[24:25]
	s_mov_b32 m0, s20
	s_nop 0
	global_load_lds_dwordx4 v[230:231], off
	s_barrier
	s_waitcnt lgkmcnt(0)
	s_waitcnt lgkmcnt(0)
	v_mfma_f32_16x16x32_bf16 v[62:65], v[182:185], v[162:165], v[62:65]
	v_mfma_f32_16x16x32_bf16 v[58:61], v[182:185], v[174:177], v[58:61]
	v_mfma_f32_16x16x32_bf16 v[54:57], v[190:193], v[162:165], v[54:57]
	v_mfma_f32_16x16x32_bf16 v[50:53], v[190:193], v[174:177], v[50:53]
	v_mfma_f32_16x16x32_bf16 v[46:49], v[198:201], v[162:165], v[46:49]
	v_mfma_f32_16x16x32_bf16 v[42:45], v[198:201], v[174:177], v[42:45]
	v_mfma_f32_16x16x32_bf16 v[38:41], v[206:209], v[162:165], v[38:41]
	v_mfma_f32_16x16x32_bf16 v[34:37], v[206:209], v[174:177], v[34:37]
	v_mfma_f32_16x16x32_bf16 v[62:65], v[186:189], v[166:169], v[62:65]
	v_mfma_f32_16x16x32_bf16 v[58:61], v[186:189], v[178:181], v[58:61]
	v_mfma_f32_16x16x32_bf16 v[54:57], v[194:197], v[166:169], v[54:57]
	v_mfma_f32_16x16x32_bf16 v[50:53], v[194:197], v[178:181], v[50:53]
	v_mfma_f32_16x16x32_bf16 v[46:49], v[202:205], v[166:169], v[46:49]
	v_mfma_f32_16x16x32_bf16 v[42:45], v[202:205], v[178:181], v[42:45]
	v_mfma_f32_16x16x32_bf16 v[38:41], v[210:213], v[166:169], v[38:41]
	v_mfma_f32_16x16x32_bf16 v[34:37], v[210:213], v[178:181], v[34:37]
	s_barrier
	v_readfirstlane_b32 s20, v159
	v_lshl_add_u64 v[162:163], v[242:243], 0, s[24:25]
	s_mov_b32 m0, s20
	v_readfirstlane_b32 s20, v160
	global_load_lds_dwordx4 v[162:163], off
	v_lshl_add_u64 v[162:163], v[244:245], 0, s[24:25]
	s_mov_b32 m0, s20
	s_nop 0
	global_load_lds_dwordx4 v[162:163], off
	s_waitcnt vmcnt(10)
	s_barrier
	v_mfma_f32_16x16x32_bf16 v[30:33], v[182:185], v[214:217], v[30:33]
	v_mfma_f32_16x16x32_bf16 v[26:29], v[182:185], v[222:225], v[26:29]
	v_mfma_f32_16x16x32_bf16 v[22:25], v[190:193], v[214:217], v[22:25]
	v_mfma_f32_16x16x32_bf16 v[18:21], v[190:193], v[222:225], v[18:21]
	v_mfma_f32_16x16x32_bf16 v[14:17], v[198:201], v[214:217], v[14:17]
	v_mfma_f32_16x16x32_bf16 v[10:13], v[198:201], v[222:225], v[10:13]
	v_mfma_f32_16x16x32_bf16 v[6:9], v[206:209], v[214:217], v[6:9]
	v_mfma_f32_16x16x32_bf16 v[2:5], v[206:209], v[222:225], v[2:5]
	v_mfma_f32_16x16x32_bf16 v[30:33], v[186:189], v[218:221], v[30:33]
	v_mfma_f32_16x16x32_bf16 v[26:29], v[186:189], v[226:229], v[26:29]
	v_mfma_f32_16x16x32_bf16 v[22:25], v[194:197], v[218:221], v[22:25]
	v_mfma_f32_16x16x32_bf16 v[18:21], v[194:197], v[226:229], v[18:21]
	v_mfma_f32_16x16x32_bf16 v[14:17], v[202:205], v[218:221], v[14:17]
	v_mfma_f32_16x16x32_bf16 v[10:13], v[202:205], v[226:229], v[10:13]
	v_mfma_f32_16x16x32_bf16 v[6:9], v[210:213], v[218:221], v[6:9]
	v_mfma_f32_16x16x32_bf16 v[2:5], v[210:213], v[226:229], v[2:5]
	s_add_i32 s5, s5, 2
	s_cmp_lt_u32 s5, 12
	s_barrier
	s_cbranch_scc1 .LBB0_346
	ds_read_b128 v[148:151], v146
	ds_read_b128 v[152:155], v146 offset:1024
	ds_read_b128 v[156:159], v146 offset:2048
	ds_read_b128 v[160:163], v146 offset:3072
	ds_read_b128 v[164:167], v138
	ds_read_b128 v[174:177], v138 offset:1024
	ds_read_b128 v[178:181], v137
	ds_read_b128 v[182:185], v137 offset:1024
	ds_read_b128 v[186:189], v136
	ds_read_b128 v[190:193], v136 offset:1024
	ds_read_b128 v[194:197], v135
	ds_read_b128 v[198:201], v135 offset:1024
	v_lshl_add_u64 v[146:147], s[26:27], 0, v[130:131]
	v_readfirstlane_b32 s5, v143
	v_lshl_add_u64 v[146:147], v[146:147], 0, s[14:15]
	s_mov_b32 m0, s5
	v_lshl_add_u64 v[132:133], s[26:27], 0, v[132:133]
	v_readfirstlane_b32 s5, v142
	global_load_lds_dwordx4 v[146:147], off
	v_lshl_add_u64 v[132:133], v[132:133], 0, s[14:15]
	s_mov_b32 m0, s5
	s_nop 0
	global_load_lds_dwordx4 v[132:133], off
	s_waitcnt vmcnt(10)
	s_barrier
	s_waitcnt lgkmcnt(0)
	s_waitcnt lgkmcnt(0)
	v_mfma_f32_16x16x32_bf16 v[126:129], v[164:167], v[148:151], v[126:129]
	v_mfma_f32_16x16x32_bf16 v[122:125], v[164:167], v[156:159], v[122:125]
	v_mfma_f32_16x16x32_bf16 v[110:113], v[186:189], v[148:151], v[110:113]
	v_mfma_f32_16x16x32_bf16 v[106:109], v[186:189], v[156:159], v[106:109]
	v_mfma_f32_16x16x32_bf16 v[126:129], v[174:177], v[152:155], v[126:129]
	v_mfma_f32_16x16x32_bf16 v[122:125], v[174:177], v[160:163], v[122:125]
	v_mfma_f32_16x16x32_bf16 v[118:121], v[178:181], v[148:151], v[118:121]
	v_mfma_f32_16x16x32_bf16 v[114:117], v[178:181], v[156:159], v[114:117]
	v_mfma_f32_16x16x32_bf16 v[110:113], v[190:193], v[152:155], v[110:113]
	v_mfma_f32_16x16x32_bf16 v[106:109], v[190:193], v[160:163], v[106:109]
	v_mfma_f32_16x16x32_bf16 v[102:105], v[194:197], v[148:151], v[102:105]
	v_mfma_f32_16x16x32_bf16 v[98:101], v[194:197], v[156:159], v[98:101]
	v_mfma_f32_16x16x32_bf16 v[202:205], v[182:185], v[152:155], v[118:121]
	v_mfma_f32_16x16x32_bf16 v[206:209], v[182:185], v[160:163], v[114:117]
	v_mfma_f32_16x16x32_bf16 v[210:213], v[198:201], v[152:155], v[102:105]
	v_mfma_f32_16x16x32_bf16 v[214:217], v[198:201], v[160:163], v[98:101]
	s_barrier
	s_nop 1
	ds_read_b128 v[98:101], v141
	ds_read_b128 v[102:105], v141 offset:1024
	ds_read_b128 v[114:117], v141 offset:2048
	ds_read_b128 v[118:121], v141 offset:3072
	s_waitcnt vmcnt(8)
	s_barrier
; #define WAIT_V(n) asm volatile("s_waitcnt vmcnt(" #n ")" ::: "memory")
; #define WAIT_L(n) asm volatile("s_waitcnt lgkmcnt(" #n ")" ::: "memory")
; #define BAR __builtin_amdgcn_s_barrier()
; #define LDA(dst, b, h) for (int m = 0; m < 4; ++m) for (int k = 0; k < 2; ++k) \
;     dst[m][k] = *reinterpret_cast<const bf16x8*>((char*)SA(b, h) + lds_byte(wr * 64 + m * 16 + fr, k * 32 + fq * 8))
; #define LDB(dst, b, h) for (int n = 0; n < 2; ++n) for (int k = 0; k < 2; ++k) \
;     dst[n][k] = *reinterpret_cast<const bf16x8*>((char*)SB(b, h) + lds_byte(wc * 32 + n * 16 + fr, k * 32 + fq * 8))
; #define MMA(ai, bj, At_, Bt_) do { __builtin_amdgcn_s_setprio(1); \
;     for (int m = 0; m < 4; ++m) for (int n = 0; n < 2; ++n) for (int k = 0; k < 2; ++k) \
;       acc[ai][bj][m][n] = __builtin_amdgcn_mfma_f32_16x16x32_bf16(At_[m][k], Bt_[n][k], acc[ai][bj][m][n], 0, 0, 0); \
;     __builtin_amdgcn_s_setprio(0); } while (0)
; template <int K, int LD = K>
; __device__ __forceinline__ void gemm_main(const GAS bf16* A, const GAS bf16* Bt, int brow, int bcol, f32x4 (&acc)[2][2][4][2]) {
;     ...
;     LDB(B1, 0, 1); BAR; WAIT_L(0); MMA(0, 1, At, B1); BAR;
;     LDA(At, 0, 1); WAIT_V(4); BAR; WAIT_L(0); MMA(1, 0, At, B0); MMA(1, 1, At, B1); BAR; }
;   { LDB(B0, 1, 0); LDA(At, 1, 0); WAIT_V(2); BAR; WAIT_L(0); MMA(0, 0, At, B0); BAR;
	s_waitcnt lgkmcnt(0)
	s_waitcnt lgkmcnt(0)
	v_mfma_f32_16x16x32_bf16 v[94:97], v[164:167], v[98:101], v[94:97]
	v_mfma_f32_16x16x32_bf16 v[90:93], v[164:167], v[114:117], v[90:93]
	v_mfma_f32_16x16x32_bf16 v[78:81], v[186:189], v[98:101], v[78:81]
	v_mfma_f32_16x16x32_bf16 v[74:77], v[186:189], v[114:117], v[74:77]
	v_mfma_f32_16x16x32_bf16 v[94:97], v[174:177], v[102:105], v[94:97]
	v_mfma_f32_16x16x32_bf16 v[90:93], v[174:177], v[118:121], v[90:93]
	v_mfma_f32_16x16x32_bf16 v[86:89], v[178:181], v[98:101], v[86:89]
	v_mfma_f32_16x16x32_bf16 v[82:85], v[178:181], v[114:117], v[82:85]
	v_mfma_f32_16x16x32_bf16 v[78:81], v[190:193], v[102:105], v[78:81]
	v_mfma_f32_16x16x32_bf16 v[74:77], v[190:193], v[118:121], v[74:77]
	v_mfma_f32_16x16x32_bf16 v[70:73], v[194:197], v[98:101], v[70:73]
	v_mfma_f32_16x16x32_bf16 v[66:69], v[194:197], v[114:117], v[66:69]
	v_mfma_f32_16x16x32_bf16 v[164:167], v[182:185], v[102:105], v[86:89]
	v_mfma_f32_16x16x32_bf16 v[174:177], v[182:185], v[118:121], v[82:85]
	v_mfma_f32_16x16x32_bf16 v[178:181], v[198:201], v[102:105], v[70:73]
	v_mfma_f32_16x16x32_bf16 v[182:185], v[198:201], v[118:121], v[66:69]
	s_barrier
	s_nop 1
	ds_read_b128 v[66:69], v138 offset:16384
	ds_read_b128 v[70:73], v138 offset:17408
	ds_read_b128 v[82:85], v137 offset:16384
	ds_read_b128 v[86:89], v137 offset:17408
	ds_read_b128 v[186:189], v136 offset:16384
	ds_read_b128 v[190:193], v136 offset:17408
	ds_read_b128 v[194:197], v135 offset:16384
	ds_read_b128 v[198:201], v135 offset:17408
	s_waitcnt vmcnt(4)
	s_barrier
	s_waitcnt lgkmcnt(0)
	s_waitcnt lgkmcnt(0)
	v_mfma_f32_16x16x32_bf16 v[62:65], v[66:69], v[148:151], v[62:65]
	v_mfma_f32_16x16x32_bf16 v[58:61], v[66:69], v[156:159], v[58:61]
	v_mfma_f32_16x16x32_bf16 v[46:49], v[186:189], v[148:151], v[46:49]
	v_mfma_f32_16x16x32_bf16 v[42:45], v[186:189], v[156:159], v[42:45]
	v_mfma_f32_16x16x32_bf16 v[62:65], v[70:73], v[152:155], v[62:65]
	v_mfma_f32_16x16x32_bf16 v[58:61], v[70:73], v[160:163], v[58:61]
	v_mfma_f32_16x16x32_bf16 v[54:57], v[82:85], v[148:151], v[54:57]
	v_mfma_f32_16x16x32_bf16 v[50:53], v[82:85], v[156:159], v[50:53]
	v_mfma_f32_16x16x32_bf16 v[46:49], v[190:193], v[152:155], v[46:49]
	v_mfma_f32_16x16x32_bf16 v[42:45], v[190:193], v[160:163], v[42:45]
	v_mfma_f32_16x16x32_bf16 v[38:41], v[194:197], v[148:151], v[38:41]
	v_mfma_f32_16x16x32_bf16 v[34:37], v[194:197], v[156:159], v[34:37]
	v_mfma_f32_16x16x32_bf16 v[218:221], v[86:89], v[152:155], v[54:57]
	v_mfma_f32_16x16x32_bf16 v[222:225], v[86:89], v[160:163], v[50:53]
	v_mfma_f32_16x16x32_bf16 v[146:149], v[198:201], v[152:155], v[38:41]
	v_mfma_f32_16x16x32_bf16 v[150:153], v[198:201], v[160:163], v[34:37]
	v_mfma_f32_16x16x32_bf16 v[30:33], v[66:69], v[98:101], v[30:33]
	v_mfma_f32_16x16x32_bf16 v[26:29], v[66:69], v[114:117], v[26:29]
	v_mfma_f32_16x16x32_bf16 v[14:17], v[186:189], v[98:101], v[14:17]
	v_mfma_f32_16x16x32_bf16 v[10:13], v[186:189], v[114:117], v[10:13]
	v_mfma_f32_16x16x32_bf16 v[30:33], v[70:73], v[102:105], v[30:33]
	v_mfma_f32_16x16x32_bf16 v[26:29], v[70:73], v[118:121], v[26:29]
	v_mfma_f32_16x16x32_bf16 v[22:25], v[82:85], v[98:101], v[22:25]
	v_mfma_f32_16x16x32_bf16 v[18:21], v[82:85], v[114:117], v[18:21]
	v_mfma_f32_16x16x32_bf16 v[14:17], v[190:193], v[102:105], v[14:17]
	v_mfma_f32_16x16x32_bf16 v[10:13], v[190:193], v[118:121], v[10:13]
	v_mfma_f32_16x16x32_bf16 v[6:9], v[194:197], v[98:101], v[6:9]
	v_mfma_f32_16x16x32_bf16 v[2:5], v[194:197], v[114:117], v[2:5]
	v_mfma_f32_16x16x32_bf16 v[154:157], v[86:89], v[102:105], v[22:25]
	v_mfma_f32_16x16x32_bf16 v[158:161], v[86:89], v[118:121], v[18:21]
	v_mfma_f32_16x16x32_bf16 v[186:189], v[198:201], v[102:105], v[6:9]
	v_mfma_f32_16x16x32_bf16 v[190:193], v[198:201], v[118:121], v[2:5]
	s_barrier
	s_nop 1
	ds_read_b128 v[2:5], v140
	ds_read_b128 v[6:9], v140 offset:1024
	ds_read_b128 v[194:197], v140 offset:2048
	ds_read_b128 v[140:143], v140 offset:3072
	ds_read_b128 v[18:21], v138 offset:32768
	ds_read_b128 v[22:25], v138 offset:33792
	ds_read_b128 v[34:37], v137 offset:32768
	ds_read_b128 v[38:41], v137 offset:33792
	ds_read_b128 v[50:53], v136 offset:32768
	ds_read_b128 v[54:57], v136 offset:33792
	ds_read_b128 v[198:201], v135 offset:32768
	ds_read_b128 v[226:229], v135 offset:33792
	s_waitcnt vmcnt(2)
	s_barrier
; #define WAIT_V(n) asm volatile("s_waitcnt vmcnt(" #n ")" ::: "memory")
; #define WAIT_L(n) asm volatile("s_waitcnt lgkmcnt(" #n ")" ::: "memory")
; #define BAR __builtin_amdgcn_s_barrier()
; #define LDA(dst, b, h) for (int m = 0; m < 4; ++m) for (int k = 0; k < 2; ++k) \
;     dst[m][k] = *reinterpret_cast<const bf16x8*>((char*)SA(b, h) + lds_byte(wr * 64 + m * 16 + fr, k * 32 + fq * 8))
; #define LDB(dst, b, h) for (int n = 0; n < 2; ++n) for (int k = 0; k < 2; ++k) \
;     dst[n][k] = *reinterpret_cast<const bf16x8*>((char*)SB(b, h) + lds_byte(wc * 32 + n * 16 + fr, k * 32 + fq * 8))
; #define MMA(ai, bj, At_, Bt_) do { __builtin_amdgcn_s_setprio(1); \
;     for (int m = 0; m < 4; ++m) for (int n = 0; n < 2; ++n) for (int k = 0; k < 2; ++k) \
;       acc[ai][bj][m][n] = __builtin_amdgcn_mfma_f32_16x16x32_bf16(At_[m][k], Bt_[n][k], acc[ai][bj][m][n], 0, 0, 0); \
;     __builtin_amdgcn_s_setprio(0); } while (0)
; template <int K, int LD = K>
; __device__ __forceinline__ void gemm_main(const GAS bf16* A, const GAS bf16* Bt, int brow, int bcol, f32x4 (&acc)[2][2][4][2]) {
;     ...
;   { LDB(B0, 1, 0); LDA(At, 1, 0); WAIT_V(2); BAR; WAIT_L(0); MMA(0, 0, At, B0); BAR;
;     LDB(B1, 1, 1); WAIT_V(0); BAR; WAIT_L(0); MMA(0, 1, At, B1); BAR;
;     LDA(At, 1, 1); BAR; WAIT_L(0); MMA(1, 0, At, B0); MMA(1, 1, At, B1); BAR; }
;   if (wr == 0) BAR;
	s_waitcnt lgkmcnt(0)
	s_waitcnt lgkmcnt(0)
	v_mfma_f32_16x16x32_bf16 v[66:69], v[18:21], v[2:5], v[126:129]
	v_mfma_f32_16x16x32_bf16 v[114:117], v[22:25], v[6:9], v[66:69]
	v_mfma_f32_16x16x32_bf16 v[66:69], v[18:21], v[194:197], v[122:125]
	v_mfma_f32_16x16x32_bf16 v[118:121], v[22:25], v[140:143], v[66:69]
	v_mfma_f32_16x16x32_bf16 v[66:69], v[34:37], v[2:5], v[202:205]
	v_mfma_f32_16x16x32_bf16 v[102:105], v[38:41], v[6:9], v[66:69]
	v_mfma_f32_16x16x32_bf16 v[66:69], v[34:37], v[194:197], v[206:209]
	v_mfma_f32_16x16x32_bf16 v[98:101], v[38:41], v[140:143], v[66:69]
	v_mfma_f32_16x16x32_bf16 v[66:69], v[50:53], v[2:5], v[110:113]
	v_mfma_f32_16x16x32_bf16 v[82:85], v[54:57], v[6:9], v[66:69]
	v_mfma_f32_16x16x32_bf16 v[66:69], v[50:53], v[194:197], v[106:109]
	v_mfma_f32_16x16x32_bf16 v[86:89], v[54:57], v[140:143], v[66:69]
	v_mfma_f32_16x16x32_bf16 v[66:69], v[198:201], v[2:5], v[210:213]
	v_mfma_f32_16x16x32_bf16 v[70:73], v[226:229], v[6:9], v[66:69]
	v_mfma_f32_16x16x32_bf16 v[66:69], v[198:201], v[194:197], v[214:217]
	v_mfma_f32_16x16x32_bf16 v[66:69], v[226:229], v[140:143], v[66:69]
	s_barrier
	ds_read_b128 v[202:205], v139
	ds_read_b128 v[206:209], v139 offset:1024
	ds_read_b128 v[210:213], v139 offset:2048
	ds_read_b128 v[214:217], v139 offset:3072
	s_waitcnt vmcnt(0)
	s_barrier
	s_waitcnt lgkmcnt(0)
	s_waitcnt lgkmcnt(0)
	v_mfma_f32_16x16x32_bf16 v[94:97], v[18:21], v[202:205], v[94:97]
	v_mfma_f32_16x16x32_bf16 v[18:21], v[18:21], v[210:213], v[90:93]
	v_mfma_f32_16x16x32_bf16 v[126:129], v[22:25], v[214:217], v[18:21]
	v_mfma_f32_16x16x32_bf16 v[18:21], v[34:37], v[202:205], v[164:167]
	v_mfma_f32_16x16x32_bf16 v[106:109], v[38:41], v[206:209], v[18:21]
	v_mfma_f32_16x16x32_bf16 v[18:21], v[34:37], v[210:213], v[174:177]
	v_mfma_f32_16x16x32_bf16 v[110:113], v[38:41], v[214:217], v[18:21]
	v_mfma_f32_16x16x32_bf16 v[18:21], v[50:53], v[202:205], v[78:81]
	v_mfma_f32_16x16x32_bf16 v[90:93], v[54:57], v[206:209], v[18:21]
	v_mfma_f32_16x16x32_bf16 v[18:21], v[50:53], v[210:213], v[74:77]
	v_mfma_f32_16x16x32_bf16 v[122:125], v[22:25], v[206:209], v[94:97]
	v_mfma_f32_16x16x32_bf16 v[94:97], v[54:57], v[214:217], v[18:21]
	v_mfma_f32_16x16x32_bf16 v[18:21], v[198:201], v[202:205], v[178:181]
	v_mfma_f32_16x16x32_bf16 v[74:77], v[226:229], v[206:209], v[18:21]
	v_mfma_f32_16x16x32_bf16 v[18:21], v[198:201], v[210:213], v[182:185]
	v_mfma_f32_16x16x32_bf16 v[78:81], v[226:229], v[214:217], v[18:21]
	s_barrier
	ds_read_b128 v[162:165], v138 offset:49152
	ds_read_b128 v[166:169], v138 offset:50176
	ds_read_b128 v[174:177], v137 offset:49152
	ds_read_b128 v[178:181], v137 offset:50176
	ds_read_b128 v[182:185], v136 offset:49152
	ds_read_b128 v[136:139], v136 offset:50176
	ds_read_b128 v[198:201], v135 offset:49152
	ds_read_b128 v[226:229], v135 offset:50176
	s_barrier
	s_waitcnt lgkmcnt(0)
	s_waitcnt lgkmcnt(0)
	v_mfma_f32_16x16x32_bf16 v[18:21], v[162:165], v[2:5], v[62:65]
	v_mfma_f32_16x16x32_bf16 v[50:53], v[166:169], v[6:9], v[18:21]
	v_mfma_f32_16x16x32_bf16 v[18:21], v[162:165], v[194:197], v[58:61]
	v_mfma_f32_16x16x32_bf16 v[54:57], v[166:169], v[140:143], v[18:21]
	v_mfma_f32_16x16x32_bf16 v[18:21], v[174:177], v[2:5], v[218:221]
	v_mfma_f32_16x16x32_bf16 v[38:41], v[178:181], v[6:9], v[18:21]
	v_mfma_f32_16x16x32_bf16 v[18:21], v[174:177], v[194:197], v[222:225]
	v_mfma_f32_16x16x32_bf16 v[34:37], v[178:181], v[140:143], v[18:21]
	v_mfma_f32_16x16x32_bf16 v[18:21], v[182:185], v[2:5], v[46:49]
	v_mfma_f32_16x16x32_bf16 v[2:5], v[198:201], v[2:5], v[146:149]
	v_mfma_f32_16x16x32_bf16 v[18:21], v[136:139], v[6:9], v[18:21]
	v_mfma_f32_16x16x32_bf16 v[22:25], v[182:185], v[194:197], v[42:45]
	v_mfma_f32_16x16x32_bf16 v[6:9], v[226:229], v[6:9], v[2:5]
	v_mfma_f32_16x16x32_bf16 v[2:5], v[198:201], v[194:197], v[150:153]
	v_mfma_f32_16x16x32_bf16 v[22:25], v[136:139], v[140:143], v[22:25]
	v_mfma_f32_16x16x32_bf16 v[2:5], v[226:229], v[140:143], v[2:5]
	v_mfma_f32_16x16x32_bf16 v[26:29], v[162:165], v[210:213], v[26:29]
	v_mfma_f32_16x16x32_bf16 v[62:65], v[166:169], v[214:217], v[26:29]
	v_mfma_f32_16x16x32_bf16 v[26:29], v[174:177], v[202:205], v[154:157]
	v_mfma_f32_16x16x32_bf16 v[30:33], v[162:165], v[202:205], v[30:33]
	v_mfma_f32_16x16x32_bf16 v[42:45], v[178:181], v[206:209], v[26:29]
	v_mfma_f32_16x16x32_bf16 v[26:29], v[174:177], v[210:213], v[158:161]
	v_mfma_f32_16x16x32_bf16 v[14:17], v[182:185], v[202:205], v[14:17]
	v_mfma_f32_16x16x32_bf16 v[10:13], v[182:185], v[210:213], v[10:13]
	v_mfma_f32_16x16x32_bf16 v[58:61], v[166:169], v[206:209], v[30:33]
	v_mfma_f32_16x16x32_bf16 v[46:49], v[178:181], v[214:217], v[26:29]
	v_mfma_f32_16x16x32_bf16 v[26:29], v[136:139], v[206:209], v[14:17]
	v_mfma_f32_16x16x32_bf16 v[30:33], v[136:139], v[214:217], v[10:13]
	v_mfma_f32_16x16x32_bf16 v[10:13], v[198:201], v[202:205], v[186:189]
	v_mfma_f32_16x16x32_bf16 v[14:17], v[198:201], v[210:213], v[190:193]
	v_mfma_f32_16x16x32_bf16 v[10:13], v[226:229], v[206:209], v[10:13]
	v_mfma_f32_16x16x32_bf16 v[14:17], v[226:229], v[214:217], v[14:17]
	v_cmp_gt_u32_e32 vcc, s48, v134
	s_barrier
	s_and_saveexec_b64 s[26:27], vcc
	s_cbranch_execz .LBB0_349
	s_barrier

; __device__ __forceinline__ void sb_unit(GAS unsigned char* ws, int b, int h, int qb) {
;     ...
;     float G[8], Tt[8];
; #pragma unroll
;     for (int g = 0; g < 4; ++g) { G[g] = (l0[4 * g] + l0[4 * g + 1]) + (l0[4 * g + 2] + l0[4 * g + 3]); G[g + 4] = (l1[4 * g] + l1[4 * g + 1]) + (l1[4 * g + 2] + l1[4 * g + 3]); }
; #pragma unroll
;     for (int g = 0; g < 8; ++g) Tt[g] = pair_sum(G[g]);
;     float suf = R;
; #pragma unroll
;     for (int g = 7; g >= 0; --g) {
;       const float base = suf + (hi == 0 ? (Tt[g] - G[g]) : 0.f);
;       if (g < 4) {
;         const float a3 = base, a2 = a3 + l0[4 * g + 3], a1 = a2 + l0[4 * g + 2], a0 = a1 + l0[4 * g + 1];
;         p0[4 * g + 3] = __builtin_amdgcn_exp2f(p0[4 * g + 3] + a3); p0[4 * g + 2] = __builtin_amdgcn_exp2f(p0[4 * g + 2] + a2);
;         p0[4 * g + 1] = __builtin_amdgcn_exp2f(p0[4 * g + 1] + a1); p0[4 * g + 0] = __builtin_amdgcn_exp2f(p0[4 * g + 0] + a0);
;       } else {
;         const int gg = g - 4;
;         const float a3 = base, a2 = a3 + l1[4 * gg + 3], a1 = a2 + l1[4 * gg + 2], a0 = a1 + l1[4 * gg + 1];
;         p1[4 * gg + 3] = __builtin_amdgcn_exp2f(p1[4 * gg + 3] + a3); p1[4 * gg + 2] = __builtin_amdgcn_exp2f(p1[4 * gg + 2] + a2);
;         p1[4 * gg + 1] = __builtin_amdgcn_exp2f(p1[4 * gg + 1] + a1); p1[4 * gg + 0] = __builtin_amdgcn_exp2f(p1[4 * gg + 0] + a0);
;       }
;       suf += Tt[g];
;     }
;     R = suf;
;     bf16x8 pa0, pa1, pa2, pa3;
;     ATT_PK4(p0, 0, pa0); ATT_PK4(p0, 8, pa1); ATT_PK4(p1, 0, pa2); ATT_PK4(p1, 8, pa3);
;     asm volatile("s_waitcnt lgkmcnt(0)" ::: "memory");
.LBB0_426:
	s_or_b64 exec, exec, s[82:83]
	v_mov_b32_e32 v234, v53
	v_mov_b32_e32 v235, v54
	v_mov_b32_e32 v236, v52
	v_mov_b32_e32 v237, v55
	v_pk_add_f32 v[234:235], v[234:235], v[236:237]
	v_mov_b32_e32 v236, v37
	v_mov_b32_e32 v237, v38
	v_mov_b32_e32 v238, v36
	v_mov_b32_e32 v239, v39
	v_pk_add_f32 v[236:237], v[236:237], v[238:239]
	v_mov_b32_e32 v238, v56
	v_add_f32_e32 v2, v236, v237
	v_mov_b32_e32 v236, v57
	v_mov_b32_e32 v237, v58
	v_mov_b32_e32 v239, v59
	v_pk_add_f32 v[236:237], v[236:237], v[238:239]
	v_mov_b32_e32 v238, v41
	v_mov_b32_e32 v239, v42
	v_mov_b32_e32 v240, v40
	v_mov_b32_e32 v241, v43
	v_pk_add_f32 v[238:239], v[238:239], v[240:241]
	v_mov_b32_e32 v240, v61
	v_mov_b32_e32 v241, v62
	v_mov_b32_e32 v242, v60
	v_mov_b32_e32 v243, v63
	v_pk_add_f32 v[240:241], v[240:241], v[242:243]
	v_mov_b32_e32 v242, v44
	v_add_f32_e32 v52, v240, v241
	v_mov_b32_e32 v240, v45
	v_mov_b32_e32 v241, v46
	v_mov_b32_e32 v243, v47
	v_pk_add_f32 v[240:241], v[240:241], v[242:243]
	v_mov_b32_e32 v242, v64
	v_add_f32_e32 v56, v240, v241
	v_mov_b32_e32 v240, v65
	v_mov_b32_e32 v241, v66
	v_mov_b32_e32 v243, v67
	v_pk_add_f32 v[240:241], v[240:241], v[242:243]
	v_mov_b32_e32 v242, v49
	v_mov_b32_e32 v243, v50
	v_mov_b32_e32 v244, v48
	v_mov_b32_e32 v245, v51
	v_mov_b32_e32 v48, v52
	v_mov_b32_e32 v64, v52
	v_pk_add_f32 v[242:243], v[242:243], v[244:245]
	s_nop 0
	v_permlane32_swap_b32_e32 v48, v64
	v_add_f32_e32 v60, v242, v243
	v_add_f32_e32 v243, v48, v64
	v_mov_b32_e32 v64, v2
	v_mov_b32_e32 v233, v2
	s_nop 1
	v_permlane32_swap_b32_e32 v64, v233
	v_add_f32_e32 v245, v64, v233
	v_mov_b32_e32 v64, v56
	v_mov_b32_e32 v233, v56
	s_nop 1
	v_permlane32_swap_b32_e32 v64, v233
	v_add_f32_e32 v247, v64, v233
	v_mov_b32_e32 v64, v60
	v_mov_b32_e32 v233, v60
	s_nop 1
	v_permlane32_swap_b32_e32 v64, v233
	v_add_f32_e32 v64, v64, v233
	v_sub_f32_e32 v60, v64, v60
	v_cndmask_b32_e32 v60, 0, v60, vcc
	v_add_f32_e32 v60, v231, v60
	v_add_f32_e32 v51, v51, v60
	v_add_f32_e32 v50, v50, v51
	v_add_f32_e32 v49, v49, v50
	v_add_f32_e32 v49, v188, v49
	v_exp_f32_e32 v188, v49
	v_sub_f32_e32 v49, v247, v56
	v_add_f32_e32 v249, v231, v64
	v_cndmask_b32_e32 v49, 0, v49, vcc
	v_add_f32_e32 v49, v249, v49
	v_pk_add_f32 v[238:239], v[238:239], v[238:239] op_sel:[0,1] op_sel_hi:[1,0]
	v_add_f32_e32 v47, v47, v49
	v_mov_b32_e32 v246, v238
	v_mov_b32_e32 v248, v238
	v_add_f32_e32 v46, v46, v47
	s_nop 0
	v_permlane32_swap_b32_e32 v246, v248
	v_add_f32_e32 v45, v45, v46
	v_add_f32_e32 v47, v184, v47
	v_add_f32_e32 v46, v181, v46
	v_exp_f32_e32 v64, v47
	v_exp_f32_e32 v181, v46
	v_add_f32_e32 v45, v180, v45
	v_pk_add_f32 v[46:47], v[246:247], v[248:249]
	v_exp_f32_e32 v180, v45
	v_sub_f32_e32 v45, v46, v238
	v_cndmask_b32_e32 v45, 0, v45, vcc
	v_add_f32_e32 v45, v45, v47
	v_add_f32_e32 v43, v43, v45
	v_add_f32_e32 v42, v42, v43
	v_add_f32_e32 v41, v41, v42
	v_add_f32_e32 v43, v176, v43
	v_add_f32_e32 v42, v167, v42
	v_sub_f32_e32 v2, v245, v2
	v_exp_f32_e32 v176, v43
	v_exp_f32_e32 v167, v42
	v_pk_add_f32 v[42:43], v[46:47], v[46:47] op_sel:[0,1] op_sel_hi:[1,0]
	v_cndmask_b32_e32 v2, 0, v2, vcc
	v_add_f32_e32 v2, v2, v42
	v_pk_add_f32 v[240:241], v[240:241], v[240:241] op_sel:[0,1] op_sel_hi:[1,0]
	v_add_f32_e32 v39, v39, v2
	v_mov_b32_e32 v244, v240
	v_mov_b32_e32 v48, v240
	v_add_f32_e32 v49, v185, v49
	v_add_f32_e32 v38, v38, v39
	v_permlane32_swap_b32_e32 v244, v48
	v_exp_f32_e32 v56, v49
	v_add_f32_e32 v37, v37, v38
	v_add_f32_e32 v39, v162, v39
	v_add_f32_e32 v38, v159, v38
	v_mov_b32_e32 v49, v42
	v_exp_f32_e32 v46, v39
	v_exp_f32_e32 v47, v38
	v_add_f32_e32 v37, v158, v37
	v_pk_add_f32 v[38:39], v[244:245], v[48:49]
	v_exp_f32_e32 v158, v37
	v_sub_f32_e32 v37, v38, v240
	v_cndmask_b32_e32 v37, 0, v37, vcc
	v_add_f32_e32 v41, v166, v41
	v_add_f32_e32 v37, v37, v39
	v_exp_f32_e32 v166, v41
	v_add_f32_e32 v41, v67, v37
	v_add_f32_e32 v37, v187, v37
	v_add_f32_e32 v42, v66, v41
	v_exp_f32_e32 v48, v37
	v_add_f32_e32 v37, v186, v41
	v_add_f32_e32 v43, v65, v42
	v_exp_f32_e32 v49, v37
	v_add_f32_e32 v37, v183, v42
	v_exp_f32_e32 v42, v37
	v_add_f32_e32 v37, v182, v43
	v_exp_f32_e32 v43, v37
	v_sub_f32_e32 v37, v243, v52
	v_pk_add_f32 v[38:39], v[38:39], v[38:39] op_sel:[0,1] op_sel_hi:[1,0]
	v_cndmask_b32_e32 v37, 0, v37, vcc
	v_add_f32_e32 v37, v37, v38
	v_add_f32_e32 v39, v63, v37
	v_add_f32_e32 v37, v179, v37
	v_pk_add_f32 v[236:237], v[236:237], v[236:237] op_sel:[0,1] op_sel_hi:[1,0]
	v_add_f32_e32 v45, v177, v45
	v_add_f32_e32 v41, v62, v39
	v_exp_f32_e32 v52, v37
	v_add_f32_e32 v37, v178, v39
	v_mov_b32_e32 v242, v236
	v_mov_b32_e32 v44, v236
	v_exp_f32_e32 v177, v45
	v_add_f32_e32 v45, v61, v41
	v_exp_f32_e32 v61, v37
	v_add_f32_e32 v37, v169, v41
	v_permlane32_swap_b32_e32 v242, v44
	v_exp_f32_e32 v62, v37
	v_add_f32_e32 v37, v168, v45
	v_mov_b32_e32 v45, v38
	v_pk_add_f32 v[38:39], v[242:243], v[44:45]
	v_exp_f32_e32 v63, v37
	v_sub_f32_e32 v37, v38, v236
	v_cndmask_b32_e32 v37, 0, v37, vcc
	v_add_f32_e32 v37, v37, v39
	v_add_f32_e32 v41, v59, v37
	v_add_f32_e32 v44, v58, v41
	v_add_f32_e32 v37, v165, v37
	v_pk_add_f32 v[234:235], v[234:235], v[234:235] op_sel:[0,1] op_sel_hi:[1,0]
	v_add_f32_e32 v45, v57, v44
	v_exp_f32_e32 v57, v37
	v_add_f32_e32 v37, v164, v41
	v_mov_b32_e32 v36, v234
	v_mov_b32_e32 v40, v234
	v_exp_f32_e32 v58, v37
	v_add_f32_e32 v37, v161, v44
	v_permlane32_swap_b32_e32 v36, v40
	v_exp_f32_e32 v44, v37
	v_mov_b32_e32 v37, v38
	v_mov_b32_e32 v41, v39
	v_pk_add_f32 v[36:37], v[36:37], v[40:41]
	v_add_f32_e32 v51, v190, v51
	v_sub_f32_e32 v38, v36, v234
	v_cndmask_b32_e32 v38, 0, v38, vcc
	v_add_f32_e32 v38, v38, v37
	v_add_f32_e32 v39, v55, v38
	v_add_f32_e32 v40, v54, v39
	v_add_f32_e32 v41, v53, v40
	v_add_f32_e32 v50, v189, v50
	v_add_f32_e32 v45, v160, v45
	v_add_f32_e32 v41, v154, v41
	v_add_f32_e32 v38, v157, v38
	v_add_f32_e32 v39, v156, v39
	v_add_f32_e32 v40, v155, v40
	v_add_f32_e32 v60, v191, v60
	v_exp_f32_e32 v51, v51
	v_exp_f32_e32 v50, v50
	v_add_f32_e32 v2, v163, v2
	v_exp_f32_e32 v41, v41
	v_exp_f32_e32 v38, v38
	v_exp_f32_e32 v40, v40
	v_exp_f32_e32 v39, v39
	v_exp_f32_e32 v45, v45
	v_exp_f32_e32 v60, v60
	v_exp_f32_e32 v2, v2
	v_add_f32_e32 v231, v36, v37
	s_nop 1
	v_cvt_pk_bf16_f32 v36, v41, v40
	s_nop 1
	v_cvt_pk_bf16_f32 v37, v39, v38
	s_nop 1
	v_cvt_pk_bf16_f32 v38, v45, v44
	s_nop 1
	v_cvt_pk_bf16_f32 v39, v58, v57
	s_nop 1
	v_cvt_pk_bf16_f32 v40, v63, v62
	s_nop 1
	v_cvt_pk_bf16_f32 v41, v61, v52
	s_nop 1
	v_cvt_pk_bf16_f32 v42, v43, v42
	s_nop 1
	v_cvt_pk_bf16_f32 v43, v49, v48
	s_nop 1
	v_cvt_pk_bf16_f32 v44, v158, v47
	s_nop 1
	v_cvt_pk_bf16_f32 v45, v46, v2
	s_nop 1
	v_cvt_pk_bf16_f32 v46, v166, v167
	s_nop 1
	v_cvt_pk_bf16_f32 v47, v176, v177
	s_nop 1
	v_cvt_pk_bf16_f32 v48, v180, v181
	s_nop 1
	v_cvt_pk_bf16_f32 v49, v64, v56
	s_nop 1
	v_cvt_pk_bf16_f32 v50, v188, v50
	s_nop 1
	v_cvt_pk_bf16_f32 v51, v51, v60
	s_waitcnt lgkmcnt(0)
; #define ATT_SBAR() __builtin_amdgcn_sched_barrier(0)
; __device__ __forceinline__ void att_pv(f32x16* o, int vb, bf16x8 pa0, bf16x8 pa1, bf16x8 pa2, bf16x8 pa3) {
; #pragma unroll
;   for (int d0 = 0; d0 < 2; ++d0) { s16x4 lo[4], hi[4];
; #pragma unroll
;     for (int ks = 0; ks < 4; ++ks) { const int a = vb + d0 * 2048 + (ks >> 1) * 4096 + (ks & 1) * 512;
;       asm volatile("ds_read_b64_tr_b16 %0,%1" : "=&v"(lo[ks]) : "v"(a) : "memory");
;       asm volatile("ds_read_b64_tr_b16 %0,%1 offset:128" : "=&v"(hi[ks]) : "v"(a) : "memory"); }
;     asm volatile("s_waitcnt lgkmcnt(0)" ::: "memory"); ATT_SBAR();
;     ...
;     __builtin_amdgcn_s_setprio(1);
;     o[d0] = __builtin_amdgcn_mfma_f32_32x32x16_bf16(pa0, ATT_PK(0), o[d0], 0, 0, 0);
;     o[d0] = __builtin_amdgcn_mfma_f32_32x32x16_bf16(pa1, ATT_PK(1), o[d0], 0, 0, 0);
;     o[d0] = __builtin_amdgcn_mfma_f32_32x32x16_bf16(pa2, ATT_PK(2), o[d0], 0, 0, 0);
;     o[d0] = __builtin_amdgcn_mfma_f32_32x32x16_bf16(pa3, ATT_PK(3), o[d0], 0, 0, 0);
;     __builtin_amdgcn_s_setprio(0);
;     ...
;   }
; __device__ __forceinline__ void sb_unit(GAS unsigned char* ws, int b, int h, int qb) {
;     ...
;     asm volatile("s_waitcnt lgkmcnt(0)" ::: "memory");
;     att_pv(o, vb0, pa0, pa1, pa2, pa3);
;     if (__all(R < -150.f)) break;
	ds_read_b64_tr_b16 v[52:53],v219
	ds_read_b64_tr_b16 v[54:55],v219 offset:128
	ds_read_b64_tr_b16 v[56:57],v222
	ds_read_b64_tr_b16 v[58:59],v222 offset:128
	ds_read_b64_tr_b16 v[60:61],v223
	ds_read_b64_tr_b16 v[62:63],v223 offset:128
	ds_read_b64_tr_b16 v[64:65],v224
	ds_read_b64_tr_b16 v[66:67],v224 offset:128
	s_waitcnt lgkmcnt(0)
	s_nop 0
	v_permlane32_swap_b32_e32 v36, v38
	v_permlane32_swap_b32_e32 v37, v39
	v_permlane32_swap_b32_e32 v40, v42
	v_permlane32_swap_b32_e32 v41, v43
	v_permlane32_swap_b32_e32 v44, v46
	v_permlane32_swap_b32_e32 v45, v47
	v_permlane32_swap_b32_e32 v48, v50
	v_permlane32_swap_b32_e32 v49, v51
	v_mfma_f32_32x32x16_bf16 v[4:19], v[36:39], v[52:55], v[4:19]
	v_mfma_f32_32x32x16_bf16 v[4:19], v[40:43], v[56:59], v[4:19]
	v_mfma_f32_32x32x16_bf16 v[4:19], v[44:47], v[60:63], v[4:19]
	v_mfma_f32_32x32x16_bf16 v[4:19], v[48:51], v[64:67], v[4:19]
	ds_read_b64_tr_b16 v[52:53],v225
	ds_read_b64_tr_b16 v[54:55],v225 offset:128
	ds_read_b64_tr_b16 v[56:57],v226
	ds_read_b64_tr_b16 v[58:59],v226 offset:128
	ds_read_b64_tr_b16 v[60:61],v227
	ds_read_b64_tr_b16 v[62:63],v227 offset:128
	ds_read_b64_tr_b16 v[64:65],v228
	ds_read_b64_tr_b16 v[66:67],v228 offset:128
	s_waitcnt lgkmcnt(0)
	v_mfma_f32_32x32x16_bf16 v[20:35], v[36:39], v[52:55], v[20:35]
	v_mfma_f32_32x32x16_bf16 v[20:35], v[40:43], v[56:59], v[20:35]
	v_mfma_f32_32x32x16_bf16 v[20:35], v[44:47], v[60:63], v[20:35]
	v_mfma_f32_32x32x16_bf16 v[20:35], v[48:51], v[64:67], v[20:35]
	s_mov_b32 s4, 0xc3160000
	v_cmp_gt_f32_e64 s[4:5], s4, v231
	s_cmp_eq_u64 s[4:5], exec
	s_cselect_b64 s[6:7], -1, 0
	v_cmp_eq_u32_e64 s[4:5], 0, v216
	s_or_b64 s[4:5], s[4:5], s[6:7]
	s_and_b64 s[4:5], exec, s[4:5]
	v_subrev_u32_e32 v229, 64, v229
	s_or_b64 s[80:81], s[4:5], s[80:81]
	v_mov_b32_e32 v216, v232
	s_andn2_b64 exec, exec, s[80:81]
	s_cbranch_execz .LBB0_431

; #define LAS __attribute__((address_space(3)))
; __device__ __forceinline__ void att_qkt(f32x16& p0, f32x16& p1, const LAS unsigned char* Ks, const bf16x8* qr, int r32, int hi) {
;   p0 = f32x16{}; p1 = f32x16{};
; #pragma unroll
;   for (int d0 = 0; d0 < 4; ++d0) { const int cb = (d0 * 16 + hi * 8) * 2;
;     const bf16x8 b0 = *(const LAS bf16x8*)(Ks + ATT_KSWZ(r32, cb));
;     const bf16x8 b1 = *(const LAS bf16x8*)(Ks + ATT_KSWZ(32 + r32, cb));
;     __builtin_amdgcn_s_setprio(1);
;     p0 = __builtin_amdgcn_mfma_f32_32x32x16_bf16(b0, qr[d0], p0, 0, 0, 0);
;     p1 = __builtin_amdgcn_mfma_f32_32x32x16_bf16(b1, qr[d0], p1, 0, 0, 0);
;     __builtin_amdgcn_s_setprio(0); }
.LBB0_533:
	s_or_b64 exec, exec, s[4:5]
	v_add3_u32 v20, v187, s19, 64
	v_ashrrev_i32_e32 v21, 31, v20
	v_lshlrev_b64 v[20:21], 10, v[20:21]
	v_or_b32_e32 v20, v20, v37
	v_lshl_add_u64 v[22:23], s[14:15], 0, v[20:21]
	v_lshl_add_u64 v[20:21], s[12:13], 0, v[20:21]
	global_load_dwordx4 v[146:149], v[22:23], off
	global_load_dwordx4 v[150:153], v[20:21], off
	v_lshlrev_b32_e32 v20, 5, v188
	v_lshlrev_b32_e32 v21, 4, v187
	v_and_b32_e32 v20, 0x600, v20
	v_and_b32_e32 v22, 0x1f0, v21
	v_and_b32_e32 v23, 0x7ffff808, v1
	v_or3_b32 v20, v22, v23, v20
	v_lshl_add_u32 v219, v20, 1, v195
	v_readfirstlane_b32 s27, v2
	ds_write_b128 v219, v[8:11]
	v_lshlrev_b32_e32 v2, 7, v187
	v_and_b32_e32 v8, 0x70, v21
	v_bitop3_b32 v220, v37, v2, v8 bitop3:0xde
	v_lshlrev_b32_e32 v51, 4, v181
	v_add_u32_e32 v221, 0x100, v220
	s_cmp_eq_u32 s27, 0
	v_and_b32_e32 v215, 0x70, v51
	v_or_b32_e32 v218, 32, v178
	v_or_b32_e32 v217, 64, v178
	v_or_b32_e32 v216, 0x60, v178
	ds_write_b128 v221, v[4:7] offset:24576
	ds_write_b128 v219, v[12:15] offset:8192
	ds_write_b128 v221, v[16:19] offset:32768
	s_waitcnt lgkmcnt(0)
	s_barrier
	s_cbranch_scc1 .LBB0_535
	v_lshl_add_u32 v2, v181, 7, v195
	v_xad_u32 v8, v178, v215, v2
	ds_read_b128 v[4:7], v8 offset:24576
	ds_read_b128 v[8:11], v8 offset:28672
	s_waitcnt lgkmcnt(1)
	v_mfma_f32_32x32x16_bf16 v[20:35], v[4:7], v[142:145], 0
	s_waitcnt lgkmcnt(0)
	v_mfma_f32_32x32x16_bf16 v[4:19], v[8:11], v[142:145], 0
	v_xad_u32 v40, v218, v215, v2
	ds_read_b128 v[36:39], v40 offset:24576
	ds_read_b128 v[40:43], v40 offset:28672
	s_waitcnt lgkmcnt(1)
	v_mfma_f32_32x32x16_bf16 v[20:35], v[36:39], v[138:141], v[20:35]
	s_waitcnt lgkmcnt(0)
	v_mfma_f32_32x32x16_bf16 v[4:19], v[40:43], v[138:141], v[4:19]
	v_xad_u32 v40, v217, v215, v2
	ds_read_b128 v[36:39], v40 offset:24576
	ds_read_b128 v[40:43], v40 offset:28672
	s_waitcnt lgkmcnt(1)
	v_mfma_f32_32x32x16_bf16 v[20:35], v[36:39], v[134:137], v[20:35]
	s_waitcnt lgkmcnt(0)
	v_mfma_f32_32x32x16_bf16 v[4:19], v[40:43], v[134:137], v[4:19]
	v_xad_u32 v2, v216, v215, v2
	ds_read_b128 v[36:39], v2 offset:24576
	ds_read_b128 v[40:43], v2 offset:28672
	s_waitcnt lgkmcnt(1)
	v_mfma_f32_32x32x16_bf16 v[20:35], v[36:39], v[130:133], v[20:35]
	s_waitcnt lgkmcnt(0)
	v_mfma_f32_32x32x16_bf16 v[4:19], v[40:43], v[130:133], v[4:19]
	s_lshl_b32 s4, s18, 2
	s_addk_i32 s4, 0x100
	v_add_u32_e32 v2, s4, v178
	v_add_u32_e32 v2, 0x11000, v2
	ds_read_b128 v[36:39], v2
	ds_read_b128 v[40:43], v2 offset:32
	ds_read_b128 v[44:47], v2 offset:64
	ds_read_b128 v[52:55], v2 offset:96
	ds_read_b128 v[56:59], v2 offset:128
	ds_read_b128 v[60:63], v2 offset:160
	ds_read_b128 v[64:67], v2 offset:192
	ds_read_b128 v[68:71], v2 offset:224
	s_waitcnt lgkmcnt(7)
	v_sub_f32_e32 v37, v50, v37
	v_sub_f32_e32 v36, v50, v36
	v_pk_fma_f32 v[20:21], v[20:21], s[76:77], v[36:37] op_sel_hi:[1,0,1]
	s_waitcnt lgkmcnt(3)
	v_sub_f32_e32 v37, v50, v57
	v_sub_f32_e32 v36, v50, v56
	v_lshl_or_b32 v2, v129, 2, s18
	v_pk_fma_f32 v[4:5], v[4:5], s[76:77], v[36:37] op_sel_hi:[1,0,1]
	v_or_b32_e32 v36, 32, v2
	v_cmp_le_i32_e32 vcc, v36, v185
	v_sub_f32_e32 v53, v50, v53
	v_sub_f32_e32 v52, v50, v52
	v_cndmask_b32_e32 v84, v196, v4, vcc
	v_cmp_lt_i32_e32 vcc, v2, v185
	v_sub_f32_e32 v39, v50, v39
	v_sub_f32_e32 v38, v50, v38
	v_cndmask_b32_e32 v4, v196, v21, vcc
	v_cmp_le_i32_e32 vcc, v2, v185
	v_or_b32_e32 v21, 33, v2
	v_pk_fma_f32 v[22:23], v[22:23], s[76:77], v[38:39] op_sel_hi:[1,0,1]
	v_cndmask_b32_e32 v20, v196, v20, vcc
	v_cmp_le_i32_e32 vcc, v21, v185
	v_pk_fma_f32 v[32:33], v[32:33], s[76:77], v[52:53] op_sel_hi:[1,0,1]
	v_sub_f32_e32 v53, v50, v59
	v_cndmask_b32_e32 v85, v196, v5, vcc
	v_or_b32_e32 v5, 2, v2
	v_sub_f32_e32 v52, v50, v58
	v_cmp_le_i32_e32 vcc, v5, v185
	v_or_b32_e32 v21, 34, v2
	v_pk_fma_f32 v[6:7], v[6:7], s[76:77], v[52:53] op_sel_hi:[1,0,1]
	v_cndmask_b32_e32 v5, v196, v22, vcc
	v_cmp_le_i32_e32 vcc, v21, v185
	v_or_b32_e32 v21, 35, v2
	v_sub_f32_e32 v49, v50, v55
	v_cndmask_b32_e32 v86, v196, v6, vcc
	v_or_b32_e32 v6, 3, v2
	v_cmp_le_i32_e32 vcc, v6, v185
	v_sub_f32_e32 v48, v50, v54
	v_sub_f32_e32 v41, v50, v41
	v_cndmask_b32_e32 v6, v196, v23, vcc
	v_cmp_le_i32_e32 vcc, v21, v185
	v_sub_f32_e32 v40, v50, v40
	v_pk_fma_f32 v[24:25], v[24:25], s[76:77], v[40:41] op_sel_hi:[1,0,1]
	v_cndmask_b32_e32 v87, v196, v7, vcc
	v_or_b32_e32 v7, 8, v2
	v_pk_fma_f32 v[34:35], v[34:35], s[76:77], v[48:49] op_sel_hi:[1,0,1]
	s_waitcnt lgkmcnt(2)
	v_sub_f32_e32 v49, v50, v61
	v_sub_f32_e32 v48, v50, v60
	v_cmp_le_i32_e32 vcc, v7, v185
	v_or_b32_e32 v21, 40, v2
	v_pk_fma_f32 v[8:9], v[8:9], s[76:77], v[48:49] op_sel_hi:[1,0,1]
	v_cndmask_b32_e32 v7, v196, v24, vcc
	v_cmp_le_i32_e32 vcc, v21, v185
	v_or_b32_e32 v21, 41, v2
	v_sub_f32_e32 v47, v50, v47
	v_cndmask_b32_e32 v88, v196, v8, vcc
	v_or_b32_e32 v8, 9, v2
	v_cmp_le_i32_e32 vcc, v8, v185
	v_sub_f32_e32 v46, v50, v46
	v_sub_f32_e32 v43, v50, v43
	v_cndmask_b32_e32 v8, v196, v25, vcc
	v_cmp_le_i32_e32 vcc, v21, v185
	v_sub_f32_e32 v42, v50, v42
	v_pk_fma_f32 v[26:27], v[26:27], s[76:77], v[42:43] op_sel_hi:[1,0,1]
	v_cndmask_b32_e32 v89, v196, v9, vcc
	v_or_b32_e32 v9, 10, v2
	v_pk_fma_f32 v[30:31], v[30:31], s[76:77], v[46:47] op_sel_hi:[1,0,1]
	v_sub_f32_e32 v47, v50, v63
	v_sub_f32_e32 v46, v50, v62
	v_cmp_le_i32_e32 vcc, v9, v185
	v_or_b32_e32 v21, 42, v2
	v_pk_fma_f32 v[10:11], v[10:11], s[76:77], v[46:47] op_sel_hi:[1,0,1]
	v_cndmask_b32_e32 v9, v196, v26, vcc
	v_cmp_le_i32_e32 vcc, v21, v185
	v_or_b32_e32 v21, 43, v2
	v_sub_f32_e32 v45, v50, v45
	v_cndmask_b32_e32 v90, v196, v10, vcc
	v_or_b32_e32 v10, 11, v2
	v_cmp_le_i32_e32 vcc, v10, v185
	v_sub_f32_e32 v44, v50, v44
	v_pk_fma_f32 v[28:29], v[28:29], s[76:77], v[44:45] op_sel_hi:[1,0,1]
	v_cndmask_b32_e32 v10, v196, v27, vcc
	v_cmp_le_i32_e32 vcc, v21, v185
	s_waitcnt lgkmcnt(1)
	v_sub_f32_e32 v45, v50, v65
	v_sub_f32_e32 v44, v50, v64
	v_cndmask_b32_e32 v91, v196, v11, vcc
	v_or_b32_e32 v11, 16, v2
	v_cmp_le_i32_e32 vcc, v11, v185
	v_or_b32_e32 v21, 48, v2
	v_pk_fma_f32 v[12:13], v[12:13], s[76:77], v[44:45] op_sel_hi:[1,0,1]
	v_cndmask_b32_e32 v11, v196, v28, vcc
	v_cmp_le_i32_e32 vcc, v21, v185
	v_or_b32_e32 v21, 49, v2
	v_sub_f32_e32 v43, v50, v67
	v_cndmask_b32_e32 v92, v196, v12, vcc
	v_or_b32_e32 v12, 17, v2
	v_cmp_le_i32_e32 vcc, v12, v185
	v_sub_f32_e32 v42, v50, v66
	v_pk_fma_f32 v[14:15], v[14:15], s[76:77], v[42:43] op_sel_hi:[1,0,1]
	v_cndmask_b32_e32 v12, v196, v29, vcc
	v_cmp_le_i32_e32 vcc, v21, v185
	v_or_b32_e32 v21, 50, v2
	s_waitcnt lgkmcnt(0)
	v_sub_f32_e32 v41, v50, v69
	v_cndmask_b32_e32 v93, v196, v13, vcc
	v_or_b32_e32 v13, 18, v2
	v_cmp_le_i32_e32 vcc, v13, v185
	v_sub_f32_e32 v40, v50, v68
	v_pk_fma_f32 v[16:17], v[16:17], s[76:77], v[40:41] op_sel_hi:[1,0,1]
	v_cndmask_b32_e32 v13, v196, v30, vcc
	v_cmp_le_i32_e32 vcc, v21, v185
	v_or_b32_e32 v21, 51, v2
	v_sub_f32_e32 v39, v50, v71
	v_cndmask_b32_e32 v94, v196, v14, vcc
	v_or_b32_e32 v14, 19, v2
	v_cmp_le_i32_e32 vcc, v14, v185
	v_sub_f32_e32 v38, v50, v70
	v_pk_fma_f32 v[18:19], v[18:19], s[76:77], v[38:39] op_sel_hi:[1,0,1]
	v_cndmask_b32_e32 v14, v196, v31, vcc
	v_cmp_le_i32_e32 vcc, v21, v185
	v_or_b32_e32 v21, 56, v2
	s_mov_b32 s4, 0xf149f2ca
	v_cndmask_b32_e32 v95, v196, v15, vcc
	v_or_b32_e32 v15, 24, v2
	v_cmp_le_i32_e32 vcc, v15, v185
	s_nop 1
	v_cndmask_b32_e32 v15, v196, v32, vcc
	v_cmp_le_i32_e32 vcc, v21, v185
	v_or_b32_e32 v21, 57, v2
	s_nop 0
	v_cndmask_b32_e32 v96, v196, v16, vcc
	v_or_b32_e32 v16, 25, v2
	v_cmp_le_i32_e32 vcc, v16, v185
	s_nop 1
	v_cndmask_b32_e32 v16, v196, v33, vcc
	v_cmp_le_i32_e32 vcc, v21, v185
	v_or_b32_e32 v21, 58, v2
	s_nop 0
	v_cndmask_b32_e32 v97, v196, v17, vcc
	v_or_b32_e32 v17, 26, v2
	v_cmp_le_i32_e32 vcc, v17, v185
	s_nop 1
	v_cndmask_b32_e32 v17, v196, v34, vcc
	v_cmp_le_i32_e32 vcc, v21, v185
	v_max_f32_e32 v21, v20, v4
	v_max3_f32 v21, v21, v5, v6
	v_max3_f32 v21, v21, v7, v8
	v_max3_f32 v21, v21, v9, v10
	v_cndmask_b32_e32 v98, v196, v18, vcc
	v_or_b32_e32 v18, 27, v2
	v_max3_f32 v21, v21, v11, v12
	v_cmp_le_i32_e32 vcc, v18, v185
	v_max3_f32 v21, v21, v13, v14
	v_max3_f32 v21, v21, v15, v16
	v_cndmask_b32_e32 v18, v196, v35, vcc
	v_or_b32_e32 v2, 59, v2
	v_max3_f32 v21, v21, v17, v18
	v_cmp_le_i32_e32 vcc, v2, v185
	v_max3_f32 v2, v21, v84, v85
	v_max3_f32 v2, v2, v86, v87
	v_max3_f32 v2, v2, v88, v89
	v_max3_f32 v2, v2, v90, v91
	v_max3_f32 v2, v2, v92, v93
	v_max3_f32 v2, v2, v94, v95
	v_cndmask_b32_e32 v99, v196, v19, vcc
	v_max3_f32 v2, v2, v96, v97
	v_max3_f32 v2, v2, v98, v99
	v_mov_b32_e32 v19, v2
	s_nop 1
	v_permlane32_swap_b32_e32 v2, v19
	v_max3_f32 v233, v2, v19, s4
	v_sub_f32_e32 v4, v4, v233
	v_exp_f32_e32 v101, v4
	v_sub_f32_e32 v4, v5, v233
	v_exp_f32_e32 v102, v4
	v_sub_f32_e32 v4, v6, v233
	v_exp_f32_e32 v103, v4
	v_sub_f32_e32 v4, v7, v233
	v_exp_f32_e32 v104, v4
	v_sub_f32_e32 v4, v8, v233
	v_exp_f32_e32 v105, v4
	v_sub_f32_e32 v4, v9, v233
	v_exp_f32_e32 v106, v4
	v_sub_f32_e32 v4, v10, v233
	v_exp_f32_e32 v107, v4
	v_sub_f32_e32 v4, v11, v233
	v_exp_f32_e32 v108, v4
	v_sub_f32_e32 v4, v12, v233
	v_exp_f32_e32 v109, v4
	v_sub_f32_e32 v4, v13, v233
	v_exp_f32_e32 v110, v4
	v_sub_f32_e32 v4, v14, v233
	v_exp_f32_e32 v111, v4
	v_sub_f32_e32 v4, v15, v233
	v_exp_f32_e32 v112, v4
	v_sub_f32_e32 v4, v16, v233
	v_exp_f32_e32 v113, v4
	v_sub_f32_e32 v4, v17, v233
	v_sub_f32_e32 v2, 0xf149f2ca, v233
	v_sub_f32_e32 v19, v20, v233
	v_exp_f32_e32 v114, v4
	v_sub_f32_e32 v4, v18, v233
	v_exp_f32_e32 v100, v19
	v_exp_f32_e32 v115, v4
	v_exp_f32_e32 v232, v2
	v_mov_b32_e32 v190, v233
	s_branch .LBB0_536

; #define LAS __attribute__((address_space(3)))
; #define ATT_SBAR() __builtin_amdgcn_sched_barrier(0)
; #define WV(t) __builtin_amdgcn_readfirstlane((int)((64 * (t) <= qwmax) && !((dqw - F2[64 * (t) + 63]) < -thr2)))
; __device__ __forceinline__ void att_qkt(f32x16& p0, f32x16& p1, const LAS unsigned char* Ks, const bf16x8* qr, int r32, int hi) {
;   p0 = f32x16{}; p1 = f32x16{};
; #pragma unroll
;   for (int d0 = 0; d0 < 4; ++d0) { const int cb = (d0 * 16 + hi * 8) * 2;
;     const bf16x8 b0 = *(const LAS bf16x8*)(Ks + ATT_KSWZ(r32, cb));
;     const bf16x8 b1 = *(const LAS bf16x8*)(Ks + ATT_KSWZ(32 + r32, cb));
;     __builtin_amdgcn_s_setprio(1);
;     p0 = __builtin_amdgcn_mfma_f32_32x32x16_bf16(b0, qr[d0], p0, 0, 0, 0);
;     p1 = __builtin_amdgcn_mfma_f32_32x32x16_bf16(b1, qr[d0], p1, 0, 0, 0);
;     __builtin_amdgcn_s_setprio(0); }
; __device__ __forceinline__ void fox_unit(GAS unsigned char* ws, int b, int h, int qb, float thr2, bool have_f2) {
;     ...
;   for (int j = js + 1; j + 1 < NT; j += 2) {
;     const int b1 = NXT(bi), b2 = NXT(b1);
;     vB = WV(TI(j));
;     ATT_SBAR(); if (vB) att_qkt(pB0, pB1, K_lds + BUFK(b1), qr, r32, hi);
.LBB0_542:
	s_or_b64 exec, exec, s[6:7]
	s_add_i32 s6, s26, 1
	s_cmp_lg_u32 s26, 2
	s_cselect_b32 s28, s6, 0
	v_readfirstlane_b32 s8, v2
	s_cmp_lg_u32 s8, 0
	s_cselect_b64 s[6:7], -1, 0
	s_cmp_eq_u32 s8, 0
	s_cbranch_scc1 .LBB0_544
	v_lshl_add_u32 v2, s28, 13, v223
	v_add_u32_e32 v8, v2, v224
	ds_read_b128 v[4:7], v8 offset:24576
	ds_read_b128 v[8:11], v8 offset:28672
	s_waitcnt lgkmcnt(1)
	v_mfma_f32_32x32x16_bf16 v[68:83], v[4:7], v[142:145], 0
	s_waitcnt lgkmcnt(0)
	v_mfma_f32_32x32x16_bf16 v[52:67], v[8:11], v[142:145], 0
	v_add_u32_e32 v8, v2, v225
	ds_read_b128 v[4:7], v8 offset:24576
	ds_read_b128 v[8:11], v8 offset:28672
	s_waitcnt lgkmcnt(1)
	v_mfma_f32_32x32x16_bf16 v[68:83], v[4:7], v[138:141], v[68:83]
	s_waitcnt lgkmcnt(0)
	v_mfma_f32_32x32x16_bf16 v[52:67], v[8:11], v[138:141], v[52:67]
	v_add_u32_e32 v8, v2, v226
	ds_read_b128 v[4:7], v8 offset:24576
	ds_read_b128 v[8:11], v8 offset:28672
	s_waitcnt lgkmcnt(1)
	v_mfma_f32_32x32x16_bf16 v[68:83], v[4:7], v[134:137], v[68:83]
	s_waitcnt lgkmcnt(0)
	v_mfma_f32_32x32x16_bf16 v[52:67], v[8:11], v[134:137], v[52:67]
	v_add_u32_e32 v2, v2, v227
	ds_read_b128 v[4:7], v2 offset:24576
	ds_read_b128 v[8:11], v2 offset:28672
	s_waitcnt lgkmcnt(1)
	v_mfma_f32_32x32x16_bf16 v[68:83], v[4:7], v[130:133], v[68:83]
	s_waitcnt lgkmcnt(0)
	v_mfma_f32_32x32x16_bf16 v[52:67], v[8:11], v[130:133], v[52:67]

; #define ATT_SBAR() __builtin_amdgcn_sched_barrier(0)
; __device__ __forceinline__ void att_pv(f32x16* o, int vb, bf16x8 pa0, bf16x8 pa1, bf16x8 pa2, bf16x8 pa3) {
; #pragma unroll
;   for (int d0 = 0; d0 < 2; ++d0) { s16x4 lo[4], hi[4];
; #pragma unroll
;     for (int ks = 0; ks < 4; ++ks) { const int a = vb + d0 * 2048 + (ks >> 1) * 4096 + (ks & 1) * 512;
;       asm volatile("ds_read_b64_tr_b16 %0,%1" : "=&v"(lo[ks]) : "v"(a) : "memory");
;       asm volatile("ds_read_b64_tr_b16 %0,%1 offset:128" : "=&v"(hi[ks]) : "v"(a) : "memory"); }
;     asm volatile("s_waitcnt lgkmcnt(0)" ::: "memory"); ATT_SBAR();
;     ...
;     __builtin_amdgcn_s_setprio(1);
;     o[d0] = __builtin_amdgcn_mfma_f32_32x32x16_bf16(pa0, ATT_PK(0), o[d0], 0, 0, 0);
;     o[d0] = __builtin_amdgcn_mfma_f32_32x32x16_bf16(pa1, ATT_PK(1), o[d0], 0, 0, 0);
;     o[d0] = __builtin_amdgcn_mfma_f32_32x32x16_bf16(pa2, ATT_PK(2), o[d0], 0, 0, 0);
;     o[d0] = __builtin_amdgcn_mfma_f32_32x32x16_bf16(pa3, ATT_PK(3), o[d0], 0, 0, 0);
;     __builtin_amdgcn_s_setprio(0);
;     ...
;   }
; __device__ __forceinline__ void fox_unit(GAS unsigned char* ws, int b, int h, int qb, float thr2, bool have_f2) {
;     ...
;     if (vA) att_pv(o, vb0 + BUFV(bi), pa0, pa1, pa2, pa3);
.LBB0_546:
	s_andn2_b64 vcc, exec, s[8:9]
	s_cbranch_vccnz .LBB0_548
	v_lshl_add_u32 v2, s26, 13, v186
	ds_read_b64_tr_b16 v[4:5],v2
	ds_read_b64_tr_b16 v[6:7],v2 offset:128
	v_add_u32_e32 v12, 0x200, v2
	ds_read_b64_tr_b16 v[8:9],v12
	ds_read_b64_tr_b16 v[10:11],v12 offset:128
	v_add_u32_e32 v16, 0x1000, v2
	ds_read_b64_tr_b16 v[12:13],v16
	ds_read_b64_tr_b16 v[14:15],v16 offset:128
	v_add_u32_e32 v16, 0x1200, v2
	ds_read_b64_tr_b16 v[232:233],v16
	ds_read_b64_tr_b16 v[234:235],v16 offset:128
	s_waitcnt lgkmcnt(0)
	v_mfma_f32_32x32x16_bf16 v[34:49], v[154:157], v[4:7], v[34:49]
	v_mfma_f32_32x32x16_bf16 v[34:49], v[158:161], v[8:11], v[34:49]
	v_mfma_f32_32x32x16_bf16 v[34:49], v[162:165], v[12:15], v[34:49]
	v_mfma_f32_32x32x16_bf16 v[34:49], v[166:169], v[232:235], v[34:49]
	v_add_u32_e32 v8, 0x800, v2
	ds_read_b64_tr_b16 v[4:5],v8
	ds_read_b64_tr_b16 v[6:7],v8 offset:128
	v_add_u32_e32 v12, 0xa00, v2
	ds_read_b64_tr_b16 v[8:9],v12
	ds_read_b64_tr_b16 v[10:11],v12 offset:128
	v_add_u32_e32 v16, 0x1800, v2
	ds_read_b64_tr_b16 v[12:13],v16
	ds_read_b64_tr_b16 v[14:15],v16 offset:128
	v_add_u32_e32 v2, 0x1a00, v2
	ds_read_b64_tr_b16 v[232:233],v2
	ds_read_b64_tr_b16 v[234:235],v2 offset:128
	s_waitcnt lgkmcnt(0)
	v_mfma_f32_32x32x16_bf16 v[18:33], v[154:157], v[4:7], v[18:33]
	v_mfma_f32_32x32x16_bf16 v[18:33], v[158:161], v[8:11], v[18:33]
	v_mfma_f32_32x32x16_bf16 v[18:33], v[162:165], v[12:15], v[18:33]
	v_mfma_f32_32x32x16_bf16 v[18:33], v[166:169], v[232:235], v[18:33]

; #define LAS __attribute__((address_space(3)))
; #define ATT_SBAR() __builtin_amdgcn_sched_barrier(0)
; #define WV(t) __builtin_amdgcn_readfirstlane((int)((64 * (t) <= qwmax) && !((dqw - F2[64 * (t) + 63]) < -thr2)))
; __device__ __forceinline__ void att_qkt(f32x16& p0, f32x16& p1, const LAS unsigned char* Ks, const bf16x8* qr, int r32, int hi) {
;   p0 = f32x16{}; p1 = f32x16{};
; #pragma unroll
;   for (int d0 = 0; d0 < 4; ++d0) { const int cb = (d0 * 16 + hi * 8) * 2;
;     const bf16x8 b0 = *(const LAS bf16x8*)(Ks + ATT_KSWZ(r32, cb));
;     const bf16x8 b1 = *(const LAS bf16x8*)(Ks + ATT_KSWZ(32 + r32, cb));
;     __builtin_amdgcn_s_setprio(1);
;     p0 = __builtin_amdgcn_mfma_f32_32x32x16_bf16(b0, qr[d0], p0, 0, 0, 0);
;     p1 = __builtin_amdgcn_mfma_f32_32x32x16_bf16(b1, qr[d0], p1, 0, 0, 0);
;     __builtin_amdgcn_s_setprio(0); }
; __device__ __forceinline__ void fox_unit(GAS unsigned char* ws, int b, int h, int qb, float thr2, bool have_f2) {
;     ...
;     vA = WV(TI(j + 1));
;     ATT_SBAR(); if (vA) att_qkt(pA0, pA1, K_lds + BUFK(b2), qr, r32, hi);
.LBB0_561:
	s_or_b64 exec, exec, s[20:21]
	v_readfirstlane_b32 s27, v5
	s_cmp_lg_u32 s27, 0
	s_cselect_b64 s[20:21], -1, 0
	s_cmp_eq_u32 s27, 0
	s_cbranch_scc1 .LBB0_563
	v_add_u32_e32 v5, s30, v222
	v_add_u32_e32 v10, v5, v224
	ds_read_b128 v[6:9], v10 offset:24576
	ds_read_b128 v[10:13], v10 offset:28672
	s_waitcnt lgkmcnt(1)
	v_mfma_f32_32x32x16_bf16 v[100:115], v[6:9], v[142:145], 0
	s_waitcnt lgkmcnt(0)
	v_mfma_f32_32x32x16_bf16 v[84:99], v[10:13], v[142:145], 0
	v_add_u32_e32 v10, v5, v225
	ds_read_b128 v[6:9], v10 offset:24576
	ds_read_b128 v[10:13], v10 offset:28672
	s_waitcnt lgkmcnt(1)
	v_mfma_f32_32x32x16_bf16 v[100:115], v[6:9], v[138:141], v[100:115]
	s_waitcnt lgkmcnt(0)
	v_mfma_f32_32x32x16_bf16 v[84:99], v[10:13], v[138:141], v[84:99]
	v_add_u32_e32 v10, v5, v226
	ds_read_b128 v[6:9], v10 offset:24576
	ds_read_b128 v[10:13], v10 offset:28672
	s_waitcnt lgkmcnt(1)
	v_mfma_f32_32x32x16_bf16 v[100:115], v[6:9], v[134:137], v[100:115]
	s_waitcnt lgkmcnt(0)
	v_mfma_f32_32x32x16_bf16 v[84:99], v[10:13], v[134:137], v[84:99]
	v_add_u32_e32 v5, v5, v227
	ds_read_b128 v[6:9], v5 offset:24576
	ds_read_b128 v[10:13], v5 offset:28672
	s_waitcnt lgkmcnt(1)
	v_mfma_f32_32x32x16_bf16 v[100:115], v[6:9], v[130:133], v[100:115]
	s_waitcnt lgkmcnt(0)
	v_mfma_f32_32x32x16_bf16 v[84:99], v[10:13], v[130:133], v[84:99]

; #define ATT_SBAR() __builtin_amdgcn_sched_barrier(0)
; __device__ __forceinline__ void att_pv(f32x16* o, int vb, bf16x8 pa0, bf16x8 pa1, bf16x8 pa2, bf16x8 pa3) {
; #pragma unroll
;   for (int d0 = 0; d0 < 2; ++d0) { s16x4 lo[4], hi[4];
; #pragma unroll
;     for (int ks = 0; ks < 4; ++ks) { const int a = vb + d0 * 2048 + (ks >> 1) * 4096 + (ks & 1) * 512;
;       asm volatile("ds_read_b64_tr_b16 %0,%1" : "=&v"(lo[ks]) : "v"(a) : "memory");
;       asm volatile("ds_read_b64_tr_b16 %0,%1 offset:128" : "=&v"(hi[ks]) : "v"(a) : "memory"); }
;     asm volatile("s_waitcnt lgkmcnt(0)" ::: "memory"); ATT_SBAR();
;     ...
;     __builtin_amdgcn_s_setprio(1);
;     o[d0] = __builtin_amdgcn_mfma_f32_32x32x16_bf16(pa0, ATT_PK(0), o[d0], 0, 0, 0);
;     o[d0] = __builtin_amdgcn_mfma_f32_32x32x16_bf16(pa1, ATT_PK(1), o[d0], 0, 0, 0);
;     o[d0] = __builtin_amdgcn_mfma_f32_32x32x16_bf16(pa2, ATT_PK(2), o[d0], 0, 0, 0);
;     o[d0] = __builtin_amdgcn_mfma_f32_32x32x16_bf16(pa3, ATT_PK(3), o[d0], 0, 0, 0);
;     __builtin_amdgcn_s_setprio(0);
;     ...
;   }
; __device__ __forceinline__ void fox_unit(GAS unsigned char* ws, int b, int h, int qb, float thr2, bool have_f2) {
;     ...
;     if (vB) att_pv(o, vb0 + BUFV(b1), pa0, pa1, pa2, pa3);
.LBB0_565:
	s_and_b64 vcc, exec, s[8:9]
	s_cbranch_vccnz .LBB0_567
	v_lshl_add_u32 v16, s28, 13, v186
	ds_read_b64_tr_b16 v[4:5],v16
	ds_read_b64_tr_b16 v[6:7],v16 offset:128
	v_add_u32_e32 v12, 0x200, v16
	ds_read_b64_tr_b16 v[8:9],v12
	ds_read_b64_tr_b16 v[10:11],v12 offset:128
	v_add_u32_e32 v17, 0x1000, v16
	ds_read_b64_tr_b16 v[12:13],v17
	ds_read_b64_tr_b16 v[14:15],v17 offset:128
	v_add_u32_e32 v17, 0x1200, v16
	ds_read_b64_tr_b16 v[232:233],v17
	ds_read_b64_tr_b16 v[234:235],v17 offset:128
	s_waitcnt lgkmcnt(0)
	v_mfma_f32_32x32x16_bf16 v[34:49], v[154:157], v[4:7], v[34:49]
	v_mfma_f32_32x32x16_bf16 v[34:49], v[158:161], v[8:11], v[34:49]
	v_mfma_f32_32x32x16_bf16 v[34:49], v[162:165], v[12:15], v[34:49]
	v_mfma_f32_32x32x16_bf16 v[34:49], v[166:169], v[232:235], v[34:49]
	v_add_u32_e32 v8, 0x800, v16
	ds_read_b64_tr_b16 v[4:5],v8
	ds_read_b64_tr_b16 v[6:7],v8 offset:128
	v_add_u32_e32 v12, 0xa00, v16
	ds_read_b64_tr_b16 v[8:9],v12
	ds_read_b64_tr_b16 v[10:11],v12 offset:128
	v_add_u32_e32 v17, 0x1800, v16
	ds_read_b64_tr_b16 v[12:13],v17
	ds_read_b64_tr_b16 v[14:15],v17 offset:128
	v_add_u32_e32 v16, 0x1a00, v16
	ds_read_b64_tr_b16 v[232:233],v16
	ds_read_b64_tr_b16 v[234:235],v16 offset:128
	s_waitcnt lgkmcnt(0)
	v_mfma_f32_32x32x16_bf16 v[18:33], v[154:157], v[4:7], v[18:33]
	v_mfma_f32_32x32x16_bf16 v[18:33], v[158:161], v[8:11], v[18:33]
	v_mfma_f32_32x32x16_bf16 v[18:33], v[162:165], v[12:15], v[18:33]
	v_mfma_f32_32x32x16_bf16 v[18:33], v[166:169], v[232:235], v[18:33]

; #define LAS __attribute__((address_space(3)))
; #define ATT_SBAR() __builtin_amdgcn_sched_barrier(0)
; #define WV(t) __builtin_amdgcn_readfirstlane((int)((64 * (t) <= qwmax) && !((dqw - F2[64 * (t) + 63]) < -thr2)))
; __device__ __forceinline__ void att_qkt(f32x16& p0, f32x16& p1, const LAS unsigned char* Ks, const bf16x8* qr, int r32, int hi) {
;   p0 = f32x16{}; p1 = f32x16{};
; #pragma unroll
;   for (int d0 = 0; d0 < 4; ++d0) { const int cb = (d0 * 16 + hi * 8) * 2;
;     const bf16x8 b0 = *(const LAS bf16x8*)(Ks + ATT_KSWZ(r32, cb));
;     const bf16x8 b1 = *(const LAS bf16x8*)(Ks + ATT_KSWZ(32 + r32, cb));
;     __builtin_amdgcn_s_setprio(1);
;     p0 = __builtin_amdgcn_mfma_f32_32x32x16_bf16(b0, qr[d0], p0, 0, 0, 0);
;     p1 = __builtin_amdgcn_mfma_f32_32x32x16_bf16(b1, qr[d0], p1, 0, 0, 0);
;     __builtin_amdgcn_s_setprio(0); }
; __device__ __forceinline__ void fox_unit(GAS unsigned char* ws, int b, int h, int qb, float thr2, bool have_f2) {
;     ...
;   { const int b1 = NXT(bi);
;     vB = WV(TI(NT - 1));
;     ATT_SBAR(); if (vB) att_qkt(pB0, pB1, K_lds + BUFK(b1), qr, r32, hi);
.LBB0_581:
	s_or_b64 exec, exec, s[4:5]
	v_add_u32_e32 v1, 1, v234
	v_cmp_ne_u32_e32 vcc, 2, v234
	v_readfirstlane_b32 s4, v4
	s_nop 0
	v_cndmask_b32_e32 v1, 0, v1, vcc
	s_cmp_lg_u32 s4, 0
	s_cselect_b64 s[6:7], -1, 0
	s_cmp_eq_u32 s4, 0
	s_cbranch_scc1 .LBB0_583
	v_lshlrev_b32_e32 v4, 13, v1
	s_movk_i32 s4, 0x100
	v_add3_u32 v12, s4, v4, v222
	v_xad_u32 v8, v178, v215, v12
	ds_read_b128 v[4:7], v8 offset:24576
	ds_read_b128 v[8:11], v8 offset:28672
	s_waitcnt lgkmcnt(1)
	v_mfma_f32_32x32x16_bf16 v[68:83], v[4:7], v[142:145], 0
	s_waitcnt lgkmcnt(0)
	v_mfma_f32_32x32x16_bf16 v[52:67], v[8:11], v[142:145], 0
	v_xad_u32 v8, v218, v215, v12
	ds_read_b128 v[4:7], v8 offset:24576
	ds_read_b128 v[8:11], v8 offset:28672
	s_waitcnt lgkmcnt(1)
	v_mfma_f32_32x32x16_bf16 v[68:83], v[4:7], v[138:141], v[68:83]
	s_waitcnt lgkmcnt(0)
	v_mfma_f32_32x32x16_bf16 v[52:67], v[8:11], v[138:141], v[52:67]
	v_xad_u32 v8, v217, v215, v12
	ds_read_b128 v[4:7], v8 offset:24576
	ds_read_b128 v[8:11], v8 offset:28672
	s_waitcnt lgkmcnt(1)
	v_mfma_f32_32x32x16_bf16 v[68:83], v[4:7], v[134:137], v[68:83]
	s_waitcnt lgkmcnt(0)
	v_mfma_f32_32x32x16_bf16 v[52:67], v[8:11], v[134:137], v[52:67]
	v_xad_u32 v8, v216, v215, v12
	ds_read_b128 v[4:7], v8 offset:24576
	ds_read_b128 v[8:11], v8 offset:28672
	s_waitcnt lgkmcnt(1)
	v_mfma_f32_32x32x16_bf16 v[68:83], v[4:7], v[130:133], v[68:83]
	s_waitcnt lgkmcnt(0)
	v_mfma_f32_32x32x16_bf16 v[52:67], v[8:11], v[130:133], v[52:67]

; #define ATT_SBAR() __builtin_amdgcn_sched_barrier(0)
; __device__ __forceinline__ void att_pv(f32x16* o, int vb, bf16x8 pa0, bf16x8 pa1, bf16x8 pa2, bf16x8 pa3) {
; #pragma unroll
;   for (int d0 = 0; d0 < 2; ++d0) { s16x4 lo[4], hi[4];
; #pragma unroll
;     for (int ks = 0; ks < 4; ++ks) { const int a = vb + d0 * 2048 + (ks >> 1) * 4096 + (ks & 1) * 512;
;       asm volatile("ds_read_b64_tr_b16 %0,%1" : "=&v"(lo[ks]) : "v"(a) : "memory");
;       asm volatile("ds_read_b64_tr_b16 %0,%1 offset:128" : "=&v"(hi[ks]) : "v"(a) : "memory"); }
;     asm volatile("s_waitcnt lgkmcnt(0)" ::: "memory"); ATT_SBAR();
;     ...
;     __builtin_amdgcn_s_setprio(1);
;     o[d0] = __builtin_amdgcn_mfma_f32_32x32x16_bf16(pa0, ATT_PK(0), o[d0], 0, 0, 0);
;     o[d0] = __builtin_amdgcn_mfma_f32_32x32x16_bf16(pa1, ATT_PK(1), o[d0], 0, 0, 0);
;     o[d0] = __builtin_amdgcn_mfma_f32_32x32x16_bf16(pa2, ATT_PK(2), o[d0], 0, 0, 0);
;     o[d0] = __builtin_amdgcn_mfma_f32_32x32x16_bf16(pa3, ATT_PK(3), o[d0], 0, 0, 0);
;     __builtin_amdgcn_s_setprio(0);
;     ...
;   }
; __device__ __forceinline__ void fox_unit(GAS unsigned char* ws, int b, int h, int qb, float thr2, bool have_f2) {
;     ...
;     if (vA) att_pv(o, vb0 + BUFV(bi), pa0, pa1, pa2, pa3);
.LBB0_585:
	s_or_b64 exec, exec, s[4:5]
	s_and_saveexec_b64 s[4:5], vcc
	s_cbranch_execz .LBB0_587
	v_lshl_add_u32 v16, v234, 13, v186
	ds_read_b64_tr_b16 v[4:5],v16
	ds_read_b64_tr_b16 v[6:7],v16 offset:128
	v_add_u32_e32 v12, 0x200, v16
	ds_read_b64_tr_b16 v[8:9],v12
	ds_read_b64_tr_b16 v[10:11],v12 offset:128
	v_add_u32_e32 v17, 0x1000, v16
	ds_read_b64_tr_b16 v[12:13],v17
	ds_read_b64_tr_b16 v[14:15],v17 offset:128
	v_add_u32_e32 v17, 0x1200, v16
	ds_read_b64_tr_b16 v[84:85],v17
	ds_read_b64_tr_b16 v[86:87],v17 offset:128
	s_waitcnt lgkmcnt(0)
	v_mfma_f32_32x32x16_bf16 v[34:49], v[154:157], v[4:7], v[34:49]
	v_mfma_f32_32x32x16_bf16 v[34:49], v[158:161], v[8:11], v[34:49]
	v_mfma_f32_32x32x16_bf16 v[34:49], v[162:165], v[12:15], v[34:49]
	v_mfma_f32_32x32x16_bf16 v[34:49], v[166:169], v[84:87], v[34:49]
	v_add_u32_e32 v8, 0x800, v16
	ds_read_b64_tr_b16 v[4:5],v8
	ds_read_b64_tr_b16 v[6:7],v8 offset:128
	v_add_u32_e32 v12, 0xa00, v16
	ds_read_b64_tr_b16 v[8:9],v12
	ds_read_b64_tr_b16 v[10:11],v12 offset:128
	v_add_u32_e32 v17, 0x1800, v16
	ds_read_b64_tr_b16 v[12:13],v17
	ds_read_b64_tr_b16 v[14:15],v17 offset:128
	v_add_u32_e32 v16, 0x1a00, v16
	ds_read_b64_tr_b16 v[84:85],v16
	ds_read_b64_tr_b16 v[86:87],v16 offset:128
	s_waitcnt lgkmcnt(0)
	v_mfma_f32_32x32x16_bf16 v[18:33], v[154:157], v[4:7], v[18:33]
	v_mfma_f32_32x32x16_bf16 v[18:33], v[158:161], v[8:11], v[18:33]
	v_mfma_f32_32x32x16_bf16 v[18:33], v[162:165], v[12:15], v[18:33]
	v_mfma_f32_32x32x16_bf16 v[18:33], v[166:169], v[84:87], v[18:33]

; #define ATT_SBAR() __builtin_amdgcn_sched_barrier(0)
; __device__ __forceinline__ void att_pv(f32x16* o, int vb, bf16x8 pa0, bf16x8 pa1, bf16x8 pa2, bf16x8 pa3) {
; #pragma unroll
;   for (int d0 = 0; d0 < 2; ++d0) { s16x4 lo[4], hi[4];
; #pragma unroll
;     for (int ks = 0; ks < 4; ++ks) { const int a = vb + d0 * 2048 + (ks >> 1) * 4096 + (ks & 1) * 512;
;       asm volatile("ds_read_b64_tr_b16 %0,%1" : "=&v"(lo[ks]) : "v"(a) : "memory");
;       asm volatile("ds_read_b64_tr_b16 %0,%1 offset:128" : "=&v"(hi[ks]) : "v"(a) : "memory"); }
;     asm volatile("s_waitcnt lgkmcnt(0)" ::: "memory"); ATT_SBAR();
;     ...
;     __builtin_amdgcn_s_setprio(1);
;     o[d0] = __builtin_amdgcn_mfma_f32_32x32x16_bf16(pa0, ATT_PK(0), o[d0], 0, 0, 0);
;     o[d0] = __builtin_amdgcn_mfma_f32_32x32x16_bf16(pa1, ATT_PK(1), o[d0], 0, 0, 0);
;     o[d0] = __builtin_amdgcn_mfma_f32_32x32x16_bf16(pa2, ATT_PK(2), o[d0], 0, 0, 0);
;     o[d0] = __builtin_amdgcn_mfma_f32_32x32x16_bf16(pa3, ATT_PK(3), o[d0], 0, 0, 0);
;     __builtin_amdgcn_s_setprio(0);
;     ...
;   }
.LBB0_595:
	s_and_b64 vcc, exec, s[4:5]
	s_cbranch_vccnz .LBB0_597
	v_sub_f32_e32 v4, v52, v50
	v_exp_f32_e32 v12, v4
	v_sub_f32_e32 v4, v53, v50
	v_exp_f32_e32 v13, v4
	v_sub_f32_e32 v4, v54, v50
	v_exp_f32_e32 v14, v4
	v_sub_f32_e32 v4, v55, v50
	v_exp_f32_e32 v15, v4
	v_sub_f32_e32 v4, v56, v50
	v_exp_f32_e32 v16, v4
	v_sub_f32_e32 v4, v57, v50
	v_exp_f32_e32 v17, v4
	v_sub_f32_e32 v4, v58, v50
	v_exp_f32_e32 v51, v4
	v_sub_f32_e32 v4, v59, v50
	v_exp_f32_e32 v52, v4
	v_sub_f32_e32 v4, v60, v50
	v_exp_f32_e32 v53, v4
	v_sub_f32_e32 v4, v61, v50
	v_exp_f32_e32 v54, v4
	v_sub_f32_e32 v4, v62, v50
	v_exp_f32_e32 v55, v4
	v_sub_f32_e32 v4, v63, v50
	v_exp_f32_e32 v56, v4
	v_sub_f32_e32 v4, v64, v50
	v_exp_f32_e32 v57, v4
	v_sub_f32_e32 v4, v65, v50
	v_exp_f32_e32 v58, v4
	v_sub_f32_e32 v4, v66, v50
	v_exp_f32_e32 v59, v4
	v_sub_f32_e32 v4, v67, v50
	v_exp_f32_e32 v60, v4
	v_add_f32_e32 v4, 0, v68
	v_add_f32_e32 v4, v69, v4
	v_add_f32_e32 v4, v70, v4
	v_add_f32_e32 v4, v71, v4
	v_add_f32_e32 v4, v72, v4
	v_add_f32_e32 v4, v73, v4
	v_add_f32_e32 v4, v74, v4
	v_add_f32_e32 v4, v75, v4
	v_add_f32_e32 v4, v76, v4
	v_add_f32_e32 v4, v77, v4
	v_add_f32_e32 v4, v78, v4
	v_add_f32_e32 v4, v79, v4
	v_add_f32_e32 v4, v80, v4
	v_add_f32_e32 v4, v81, v4
	v_add_f32_e32 v4, v82, v4
	v_add_f32_e32 v4, v83, v4
	v_add_f32_e32 v4, v12, v4
	v_add_f32_e32 v4, v13, v4
	v_add_f32_e32 v4, v14, v4
	v_add_f32_e32 v4, v15, v4
	v_add_f32_e32 v4, v16, v4
	v_add_f32_e32 v4, v17, v4
	v_add_f32_e32 v4, v51, v4
	v_add_f32_e32 v4, v52, v4
	v_add_f32_e32 v4, v53, v4
	v_add_f32_e32 v4, v54, v4
	v_add_f32_e32 v4, v55, v4
	v_add_f32_e32 v4, v56, v4
	v_add_f32_e32 v4, v57, v4
	v_add_f32_e32 v4, v58, v4
	v_add_f32_e32 v4, v59, v4
	v_add_f32_e32 v4, v60, v4
	v_mov_b32_e32 v5, v4
	s_nop 1
	v_permlane32_swap_b32_e32 v4, v5
	v_add_f32_e32 v84, v4, v5
	s_nop 1
	v_cvt_pk_bf16_f32 v4, v68, v69
	s_nop 1
	v_cvt_pk_bf16_f32 v5, v70, v71
	s_nop 1
	v_cvt_pk_bf16_f32 v6, v72, v73
	s_nop 1
	v_cvt_pk_bf16_f32 v7, v74, v75
	s_nop 1
	v_cvt_pk_bf16_f32 v8, v76, v77
	s_nop 1
	v_cvt_pk_bf16_f32 v9, v78, v79
	s_nop 1
	v_cvt_pk_bf16_f32 v10, v80, v81
	s_nop 1
	v_cvt_pk_bf16_f32 v11, v82, v83
	s_nop 1
	v_cvt_pk_bf16_f32 v12, v12, v13
	s_nop 1
	v_cvt_pk_bf16_f32 v13, v14, v15
	s_nop 1
	v_cvt_pk_bf16_f32 v14, v16, v17
	s_nop 1
	v_cvt_pk_bf16_f32 v15, v51, v52
	s_nop 1
	v_cvt_pk_bf16_f32 v50, v53, v54
	s_nop 1
	v_cvt_pk_bf16_f32 v51, v55, v56
	s_nop 1
	v_cvt_pk_bf16_f32 v52, v57, v58
	s_nop 1
	v_cvt_pk_bf16_f32 v53, v59, v60
	v_fmac_f32_e32 v84, v189, v2
	v_permlane32_swap_b32_e32 v4, v6
	v_permlane32_swap_b32_e32 v5, v7
	v_permlane32_swap_b32_e32 v8, v10
	v_permlane32_swap_b32_e32 v9, v11
	v_permlane32_swap_b32_e32 v12, v14
	v_permlane32_swap_b32_e32 v13, v15
	v_permlane32_swap_b32_e32 v50, v52
	v_permlane32_swap_b32_e32 v51, v53
	v_lshl_add_u32 v1, v1, 13, v186
	ds_read_b64_tr_b16 v[54:55],v1
	ds_read_b64_tr_b16 v[56:57],v1 offset:128
	v_add_u32_e32 v2, 0x200, v1
	ds_read_b64_tr_b16 v[58:59],v2
	ds_read_b64_tr_b16 v[60:61],v2 offset:128
	v_add_u32_e32 v2, 0x1000, v1
	ds_read_b64_tr_b16 v[62:63],v2
	ds_read_b64_tr_b16 v[64:65],v2 offset:128
	v_add_u32_e32 v2, 0x1200, v1
	ds_read_b64_tr_b16 v[66:67],v2
	ds_read_b64_tr_b16 v[68:69],v2 offset:128
	s_waitcnt lgkmcnt(0)
	v_mfma_f32_32x32x16_bf16 v[34:49], v[4:7], v[54:57], v[34:49]
	v_mfma_f32_32x32x16_bf16 v[34:49], v[8:11], v[58:61], v[34:49]
	v_mfma_f32_32x32x16_bf16 v[34:49], v[12:15], v[62:65], v[34:49]
	v_mfma_f32_32x32x16_bf16 v[34:49], v[50:53], v[66:69], v[34:49]
	v_add_u32_e32 v2, 0x800, v1
	ds_read_b64_tr_b16 v[54:55],v2
	ds_read_b64_tr_b16 v[56:57],v2 offset:128
	v_add_u32_e32 v2, 0xa00, v1
	ds_read_b64_tr_b16 v[58:59],v2
	ds_read_b64_tr_b16 v[60:61],v2 offset:128
	v_add_u32_e32 v2, 0x1800, v1
	ds_read_b64_tr_b16 v[62:63],v2
	ds_read_b64_tr_b16 v[64:65],v2 offset:128
	v_add_u32_e32 v1, 0x1a00, v1
	ds_read_b64_tr_b16 v[66:67],v1
	ds_read_b64_tr_b16 v[68:69],v1 offset:128
	s_waitcnt lgkmcnt(0)
	v_mfma_f32_32x32x16_bf16 v[18:33], v[4:7], v[54:57], v[18:33]
	v_mfma_f32_32x32x16_bf16 v[18:33], v[8:11], v[58:61], v[18:33]
	v_mfma_f32_32x32x16_bf16 v[18:33], v[12:15], v[62:65], v[18:33]
	v_mfma_f32_32x32x16_bf16 v[18:33], v[50:53], v[66:69], v[18:33]
	v_mov_b32_e32 v189, v84

; #define STAGE(P, GP, ktrel) do { const GAS char* _g = (GP) + (ktrel) * (BK * 2); \
;     __builtin_amdgcn_global_load_lds((const GAS unsigned*)(_g + so0), (unsigned*)((char*)(P) + tid_ * 16), 16, 0, 0); \
;     __builtin_amdgcn_global_load_lds((const GAS unsigned*)(_g + so1), (unsigned*)((char*)(P) + tid_ * 16 + 8192), 16, 0, 0); } while (0)
; #define WAIT_L(n) asm volatile("s_waitcnt lgkmcnt(" #n ")" ::: "memory")
; #define BAR __builtin_amdgcn_s_barrier()
; #define SCHED __builtin_amdgcn_sched_barrier(0)
; #define LDA(dst, b, h) for (int m = 0; m < 4; ++m) for (int k = 0; k < 2; ++k) \
;     dst[m][k] = *reinterpret_cast<const bf16x8*>((char*)SA(b, h) + lds_byte(wr * 64 + m * 16 + fr, k * 32 + fq * 8))
; #define LDB(dst, b, h) for (int n = 0; n < 2; ++n) for (int k = 0; k < 2; ++k) \
;     dst[n][k] = *reinterpret_cast<const bf16x8*>((char*)SB(b, h) + lds_byte(wc * 32 + n * 16 + fr, k * 32 + fq * 8))
; #define MMA(ai, bj, At_, Bt_) do { __builtin_amdgcn_s_setprio(1); \
;     for (int m = 0; m < 4; ++m) for (int n = 0; n < 2; ++n) for (int k = 0; k < 2; ++k) \
;       acc[ai][bj][m][n] = __builtin_amdgcn_mfma_f32_16x16x32_bf16(At_[m][k], Bt_[n][k], acc[ai][bj][m][n], 0, 0, 0); \
;     __builtin_amdgcn_s_setprio(0); } while (0)
; template <int K, int LD = K>
; __device__ __forceinline__ void gemm_main(const GAS bf16* A, const GAS bf16* Bt, int brow, int bcol, f32x4 (&acc)[2][2][4][2]) {
;     ...
;   for (int t = 0; t < nt - 2; t += 2) {
;     LDB(B0, 0, 0); SCHED; LDA(At, 0, 0); STAGE(SA(1, 1), pA1, 1);
;     WAIT_L(8); BAR; WAIT_L(0); MMA(0, 0, At, B0); BAR; SCHED;
;     LDB(B1, 0, 1); STAGE(SB(0, 0), pB0, 2);
;     BAR; WAIT_L(0); MMA(0, 1, At, B1); BAR;
;     LDA(At, 0, 1); STAGE(SA(0, 0), pA0, 2);
;     BAR; WAIT_L(0); MMA(1, 0, At, B0); BAR; SCHED;
.LBB0_709:
	ds_read_b128 v[146:149], v143
	ds_read_b128 v[150:153], v143 offset:1024
	ds_read_b128 v[154:157], v143 offset:2048
	ds_read_b128 v[158:161], v143 offset:3072
	v_add_u32_e32 v230, 0x100, v141
	v_add_u32_e32 v144, 0xc000, v230
	v_lshl_add_u64 v[214:215], s[20:21], 0, v[130:131]
	v_readfirstlane_b32 s30, v144
	v_add_u32_e32 v145, 0xe000, v230
	v_lshl_add_u64 v[198:199], v[214:215], 0, s[6:7]
	s_mov_b32 m0, s30
	v_lshl_add_u64 v[216:217], s[20:21], 0, v[132:133]
	v_readfirstlane_b32 s30, v145
	ds_read_b128 v[162:165], v138
	ds_read_b128 v[166:169], v138 offset:1024
	ds_read_b128 v[174:177], v137
	ds_read_b128 v[178:181], v137 offset:1024
	ds_read_b128 v[182:185], v136
	ds_read_b128 v[186:189], v136 offset:1024
	ds_read_b128 v[190:193], v135
	ds_read_b128 v[194:197], v135 offset:1024
	global_load_lds_dwordx4 v[198:199], off
	v_lshl_add_u64 v[198:199], v[216:217], 0, s[6:7]
	s_mov_b32 m0, s30
	s_nop 0
	global_load_lds_dwordx4 v[198:199], off
	s_waitcnt lgkmcnt(8)
	s_waitcnt vmcnt(10)
	s_barrier
	s_waitcnt lgkmcnt(0)
	s_waitcnt lgkmcnt(0)
	v_mfma_f32_16x16x32_bf16 v[126:129], v[162:165], v[146:149], v[126:129]
	v_mfma_f32_16x16x32_bf16 v[122:125], v[162:165], v[154:157], v[122:125]
	v_mfma_f32_16x16x32_bf16 v[118:121], v[174:177], v[146:149], v[118:121]
	v_mfma_f32_16x16x32_bf16 v[114:117], v[174:177], v[154:157], v[114:117]
	v_mfma_f32_16x16x32_bf16 v[110:113], v[182:185], v[146:149], v[110:113]
	v_mfma_f32_16x16x32_bf16 v[106:109], v[182:185], v[154:157], v[106:109]
	v_mfma_f32_16x16x32_bf16 v[102:105], v[190:193], v[146:149], v[102:105]
	v_mfma_f32_16x16x32_bf16 v[98:101], v[190:193], v[154:157], v[98:101]
	v_mfma_f32_16x16x32_bf16 v[126:129], v[166:169], v[150:153], v[126:129]
	v_mfma_f32_16x16x32_bf16 v[122:125], v[166:169], v[158:161], v[122:125]
	v_mfma_f32_16x16x32_bf16 v[118:121], v[178:181], v[150:153], v[118:121]
	v_mfma_f32_16x16x32_bf16 v[114:117], v[178:181], v[158:161], v[114:117]
	v_mfma_f32_16x16x32_bf16 v[110:113], v[186:189], v[150:153], v[110:113]
	v_mfma_f32_16x16x32_bf16 v[106:109], v[186:189], v[158:161], v[106:109]
	v_mfma_f32_16x16x32_bf16 v[102:105], v[194:197], v[150:153], v[102:105]
	v_mfma_f32_16x16x32_bf16 v[98:101], v[194:197], v[158:161], v[98:101]
	s_barrier
	v_add_u32_e32 v224, s47, v141
	v_lshl_add_u64 v[218:219], s[28:29], 0, v[130:131]
	v_readfirstlane_b32 s30, v224
	v_lshl_add_u64 v[220:221], v[218:219], 0, s[10:11]
	s_mov_b32 m0, s30
	v_add_u32_e32 v224, 0x2000, v224
	ds_read_b128 v[198:201], v142
	ds_read_b128 v[202:205], v142 offset:1024
	ds_read_b128 v[206:209], v142 offset:2048
	ds_read_b128 v[210:213], v142 offset:3072
	global_load_lds_dwordx4 v[220:221], off
	v_lshl_add_u64 v[220:221], s[28:29], 0, v[132:133]
	v_readfirstlane_b32 s30, v224
	v_lshl_add_u64 v[222:223], v[220:221], 0, s[10:11]
	s_mov_b32 m0, s30
	s_add_u32 s28, s28, 0x100
	global_load_lds_dwordx4 v[222:223], off
	s_waitcnt vmcnt(10)
	s_barrier
	s_waitcnt lgkmcnt(0)
	s_addc_u32 s29, s29, 0
	s_waitcnt lgkmcnt(0)
	v_mfma_f32_16x16x32_bf16 v[94:97], v[162:165], v[198:201], v[94:97]
	v_mfma_f32_16x16x32_bf16 v[90:93], v[162:165], v[206:209], v[90:93]
	v_mfma_f32_16x16x32_bf16 v[86:89], v[174:177], v[198:201], v[86:89]
	v_mfma_f32_16x16x32_bf16 v[82:85], v[174:177], v[206:209], v[82:85]
	v_mfma_f32_16x16x32_bf16 v[78:81], v[182:185], v[198:201], v[78:81]
	v_mfma_f32_16x16x32_bf16 v[74:77], v[182:185], v[206:209], v[74:77]
	v_mfma_f32_16x16x32_bf16 v[70:73], v[190:193], v[198:201], v[70:73]
	v_mfma_f32_16x16x32_bf16 v[66:69], v[190:193], v[206:209], v[66:69]
	v_mfma_f32_16x16x32_bf16 v[94:97], v[166:169], v[202:205], v[94:97]
	v_mfma_f32_16x16x32_bf16 v[90:93], v[166:169], v[210:213], v[90:93]
	v_mfma_f32_16x16x32_bf16 v[86:89], v[178:181], v[202:205], v[86:89]
	v_mfma_f32_16x16x32_bf16 v[82:85], v[178:181], v[210:213], v[82:85]
	v_mfma_f32_16x16x32_bf16 v[78:81], v[186:189], v[202:205], v[78:81]
	v_mfma_f32_16x16x32_bf16 v[74:77], v[186:189], v[210:213], v[74:77]
	v_mfma_f32_16x16x32_bf16 v[70:73], v[194:197], v[202:205], v[70:73]
	v_mfma_f32_16x16x32_bf16 v[66:69], v[194:197], v[210:213], v[66:69]
	v_lshl_add_u64 v[222:223], s[26:27], 0, v[130:131]
	v_readfirstlane_b32 s30, v230
	v_lshl_add_u64 v[224:225], v[222:223], 0, s[10:11]
	s_mov_b32 m0, s30
	v_add_u32_e32 v228, 0x2000, v230
	s_barrier
	ds_read_b128 v[162:165], v138 offset:16384
	ds_read_b128 v[166:169], v138 offset:17408
	ds_read_b128 v[174:177], v137 offset:16384
	ds_read_b128 v[178:181], v137 offset:17408
	ds_read_b128 v[182:185], v136 offset:16384
	ds_read_b128 v[186:189], v136 offset:17408
	ds_read_b128 v[190:193], v135 offset:16384
	ds_read_b128 v[194:197], v135 offset:17408
	global_load_lds_dwordx4 v[224:225], off
	v_lshl_add_u64 v[224:225], s[26:27], 0, v[132:133]
	v_readfirstlane_b32 s30, v228
	v_lshl_add_u64 v[226:227], v[224:225], 0, s[10:11]
	s_mov_b32 m0, s30
	s_add_u32 s26, s26, 0x100
	global_load_lds_dwordx4 v[226:227], off
	s_barrier
	s_waitcnt lgkmcnt(0)
	s_addc_u32 s27, s27, 0
	s_waitcnt lgkmcnt(0)
	v_mfma_f32_16x16x32_bf16 v[62:65], v[162:165], v[146:149], v[62:65]
	v_mfma_f32_16x16x32_bf16 v[58:61], v[162:165], v[154:157], v[58:61]
	v_mfma_f32_16x16x32_bf16 v[54:57], v[174:177], v[146:149], v[54:57]
	v_mfma_f32_16x16x32_bf16 v[50:53], v[174:177], v[154:157], v[50:53]
	v_mfma_f32_16x16x32_bf16 v[46:49], v[182:185], v[146:149], v[46:49]
	v_mfma_f32_16x16x32_bf16 v[42:45], v[182:185], v[154:157], v[42:45]
	v_mfma_f32_16x16x32_bf16 v[38:41], v[190:193], v[146:149], v[38:41]
	v_mfma_f32_16x16x32_bf16 v[34:37], v[190:193], v[154:157], v[34:37]
	v_mfma_f32_16x16x32_bf16 v[62:65], v[166:169], v[150:153], v[62:65]
	v_mfma_f32_16x16x32_bf16 v[58:61], v[166:169], v[158:161], v[58:61]
	v_mfma_f32_16x16x32_bf16 v[54:57], v[178:181], v[150:153], v[54:57]
	v_mfma_f32_16x16x32_bf16 v[50:53], v[178:181], v[158:161], v[50:53]
	v_mfma_f32_16x16x32_bf16 v[46:49], v[186:189], v[150:153], v[46:49]
	v_mfma_f32_16x16x32_bf16 v[42:45], v[186:189], v[158:161], v[42:45]
	v_mfma_f32_16x16x32_bf16 v[38:41], v[194:197], v[150:153], v[38:41]
	v_mfma_f32_16x16x32_bf16 v[34:37], v[194:197], v[158:161], v[34:37]
	s_barrier
; #define STAGE(P, GP, ktrel) do { const GAS char* _g = (GP) + (ktrel) * (BK * 2); \
;     __builtin_amdgcn_global_load_lds((const GAS unsigned*)(_g + so0), (unsigned*)((char*)(P) + tid_ * 16), 16, 0, 0); \
;     __builtin_amdgcn_global_load_lds((const GAS unsigned*)(_g + so1), (unsigned*)((char*)(P) + tid_ * 16 + 8192), 16, 0, 0); } while (0)
; #define WAIT_V(n) asm volatile("s_waitcnt vmcnt(" #n ")" ::: "memory")
; #define WAIT_L(n) asm volatile("s_waitcnt lgkmcnt(" #n ")" ::: "memory")
; #define BAR __builtin_amdgcn_s_barrier()
; #define SCHED __builtin_amdgcn_sched_barrier(0)
; #define LDA(dst, b, h) for (int m = 0; m < 4; ++m) for (int k = 0; k < 2; ++k) \
;     dst[m][k] = *reinterpret_cast<const bf16x8*>((char*)SA(b, h) + lds_byte(wr * 64 + m * 16 + fr, k * 32 + fq * 8))
; #define LDB(dst, b, h) for (int n = 0; n < 2; ++n) for (int k = 0; k < 2; ++k) \
;     dst[n][k] = *reinterpret_cast<const bf16x8*>((char*)SB(b, h) + lds_byte(wc * 32 + n * 16 + fr, k * 32 + fq * 8))
; #define MMA(ai, bj, At_, Bt_) do { __builtin_amdgcn_s_setprio(1); \
;     for (int m = 0; m < 4; ++m) for (int n = 0; n < 2; ++n) for (int k = 0; k < 2; ++k) \
;       acc[ai][bj][m][n] = __builtin_amdgcn_mfma_f32_16x16x32_bf16(At_[m][k], Bt_[n][k], acc[ai][bj][m][n], 0, 0, 0); \
;     __builtin_amdgcn_s_setprio(0); } while (0)
; template <int K, int LD = K>
; __device__ __forceinline__ void gemm_main(const GAS bf16* A, const GAS bf16* Bt, int brow, int bcol, f32x4 (&acc)[2][2][4][2]) {
;     ...
;     STAGE(SB(0, 1), pB1, 2);
;     WAIT_V(6); BAR; MMA(1, 1, At, B1); BAR;
;     LDB(B0, 1, 0); SCHED; LDA(At, 1, 0); STAGE(SA(0, 1), pA1, 2);
;     WAIT_L(8); BAR; WAIT_L(0); MMA(0, 0, At, B0); BAR; SCHED;
;     LDB(B1, 1, 1); STAGE(SB(1, 0), pB0, 3);
;     BAR; WAIT_L(0); MMA(0, 1, At, B1); BAR;
;     LDA(At, 1, 1); STAGE(SA(1, 0), pA0, 3);
	v_add_u32_e32 v148, s48, v141
	v_lshl_add_u64 v[226:227], s[24:25], 0, v[130:131]
	v_readfirstlane_b32 s30, v148
	v_add_u32_e32 v148, 0x2000, v148
	v_lshl_add_u64 v[146:147], v[226:227], 0, s[10:11]
	s_mov_b32 m0, s30
	v_lshl_add_u64 v[228:229], s[24:25], 0, v[132:133]
	v_readfirstlane_b32 s30, v148
	global_load_lds_dwordx4 v[146:147], off
	v_lshl_add_u64 v[146:147], v[228:229], 0, s[10:11]
	s_mov_b32 m0, s30
	s_add_u32 s24, s24, 0x100
	global_load_lds_dwordx4 v[146:147], off
	s_waitcnt vmcnt(10)
	s_addc_u32 s25, s25, 0
	s_barrier
	v_mfma_f32_16x16x32_bf16 v[30:33], v[162:165], v[198:201], v[30:33]
	v_mfma_f32_16x16x32_bf16 v[26:29], v[162:165], v[206:209], v[26:29]
	v_mfma_f32_16x16x32_bf16 v[22:25], v[174:177], v[198:201], v[22:25]
	v_mfma_f32_16x16x32_bf16 v[18:21], v[174:177], v[206:209], v[18:21]
	v_mfma_f32_16x16x32_bf16 v[14:17], v[182:185], v[198:201], v[14:17]
	v_mfma_f32_16x16x32_bf16 v[10:13], v[182:185], v[206:209], v[10:13]
	v_mfma_f32_16x16x32_bf16 v[6:9], v[190:193], v[198:201], v[6:9]
	v_mfma_f32_16x16x32_bf16 v[2:5], v[190:193], v[206:209], v[2:5]
	v_mfma_f32_16x16x32_bf16 v[30:33], v[166:169], v[202:205], v[30:33]
	v_mfma_f32_16x16x32_bf16 v[26:29], v[166:169], v[210:213], v[26:29]
	v_mfma_f32_16x16x32_bf16 v[22:25], v[178:181], v[202:205], v[22:25]
	v_mfma_f32_16x16x32_bf16 v[18:21], v[178:181], v[210:213], v[18:21]
	v_mfma_f32_16x16x32_bf16 v[14:17], v[186:189], v[202:205], v[14:17]
	v_mfma_f32_16x16x32_bf16 v[10:13], v[186:189], v[210:213], v[10:13]
	v_mfma_f32_16x16x32_bf16 v[6:9], v[194:197], v[202:205], v[6:9]
	v_mfma_f32_16x16x32_bf16 v[2:5], v[194:197], v[210:213], v[2:5]
	s_barrier
	ds_read_b128 v[146:149], v140
	ds_read_b128 v[150:153], v140 offset:1024
	ds_read_b128 v[154:157], v140 offset:2048
	ds_read_b128 v[158:161], v140 offset:3072
	v_add_u32_e32 v200, 0x4000, v230
	v_lshl_add_u64 v[198:199], v[214:215], 0, s[10:11]
	v_readfirstlane_b32 s30, v200
	v_add_u32_e32 v200, 0x6000, v230
	s_mov_b32 m0, s30
	v_readfirstlane_b32 s30, v200
	ds_read_b128 v[162:165], v138 offset:32768
	ds_read_b128 v[166:169], v138 offset:33792
	ds_read_b128 v[174:177], v137 offset:32768
	ds_read_b128 v[178:181], v137 offset:33792
	ds_read_b128 v[182:185], v136 offset:32768
	ds_read_b128 v[186:189], v136 offset:33792
	ds_read_b128 v[190:193], v135 offset:32768
	ds_read_b128 v[194:197], v135 offset:33792
	global_load_lds_dwordx4 v[198:199], off
	v_lshl_add_u64 v[198:199], v[216:217], 0, s[10:11]
	s_mov_b32 m0, s30
	s_add_u32 s20, s20, 0x100
	global_load_lds_dwordx4 v[198:199], off
	s_waitcnt lgkmcnt(8)
	s_waitcnt vmcnt(10)
	s_barrier
	s_waitcnt lgkmcnt(0)
	s_addc_u32 s21, s21, 0
	s_waitcnt lgkmcnt(0)
	v_mfma_f32_16x16x32_bf16 v[126:129], v[162:165], v[146:149], v[126:129]
	v_mfma_f32_16x16x32_bf16 v[122:125], v[162:165], v[154:157], v[122:125]
	v_mfma_f32_16x16x32_bf16 v[118:121], v[174:177], v[146:149], v[118:121]
	v_mfma_f32_16x16x32_bf16 v[114:117], v[174:177], v[154:157], v[114:117]
	v_mfma_f32_16x16x32_bf16 v[110:113], v[182:185], v[146:149], v[110:113]
	v_mfma_f32_16x16x32_bf16 v[106:109], v[182:185], v[154:157], v[106:109]
	v_mfma_f32_16x16x32_bf16 v[102:105], v[190:193], v[146:149], v[102:105]
	v_mfma_f32_16x16x32_bf16 v[98:101], v[190:193], v[154:157], v[98:101]
	v_mfma_f32_16x16x32_bf16 v[126:129], v[166:169], v[150:153], v[126:129]
	v_mfma_f32_16x16x32_bf16 v[122:125], v[166:169], v[158:161], v[122:125]
	v_mfma_f32_16x16x32_bf16 v[118:121], v[178:181], v[150:153], v[118:121]
	v_mfma_f32_16x16x32_bf16 v[114:117], v[178:181], v[158:161], v[114:117]
	v_mfma_f32_16x16x32_bf16 v[110:113], v[186:189], v[150:153], v[110:113]
	v_mfma_f32_16x16x32_bf16 v[106:109], v[186:189], v[158:161], v[106:109]
	v_mfma_f32_16x16x32_bf16 v[102:105], v[194:197], v[150:153], v[102:105]
	v_mfma_f32_16x16x32_bf16 v[98:101], v[194:197], v[158:161], v[98:101]
	s_barrier
	v_add_u32_e32 v216, s49, v141
	v_lshl_add_u64 v[214:215], v[218:219], 0, s[12:13]
	v_readfirstlane_b32 s30, v216
	v_add_u32_e32 v216, 0x2000, v216
	s_mov_b32 m0, s30
	v_readfirstlane_b32 s30, v216
	ds_read_b128 v[198:201], v139
	ds_read_b128 v[202:205], v139 offset:1024
	ds_read_b128 v[206:209], v139 offset:2048
	ds_read_b128 v[210:213], v139 offset:3072
	global_load_lds_dwordx4 v[214:215], off
	v_lshl_add_u64 v[214:215], v[220:221], 0, s[12:13]
	s_mov_b32 m0, s30
	s_nop 0
	global_load_lds_dwordx4 v[214:215], off
	s_waitcnt vmcnt(10)
	s_barrier
	s_waitcnt lgkmcnt(0)
	s_waitcnt lgkmcnt(0)
	v_mfma_f32_16x16x32_bf16 v[94:97], v[162:165], v[198:201], v[94:97]
	v_mfma_f32_16x16x32_bf16 v[90:93], v[162:165], v[206:209], v[90:93]
	v_mfma_f32_16x16x32_bf16 v[86:89], v[174:177], v[198:201], v[86:89]
	v_mfma_f32_16x16x32_bf16 v[82:85], v[174:177], v[206:209], v[82:85]
	v_mfma_f32_16x16x32_bf16 v[78:81], v[182:185], v[198:201], v[78:81]
	v_mfma_f32_16x16x32_bf16 v[74:77], v[182:185], v[206:209], v[74:77]
	v_mfma_f32_16x16x32_bf16 v[70:73], v[190:193], v[198:201], v[70:73]
	v_mfma_f32_16x16x32_bf16 v[66:69], v[190:193], v[206:209], v[66:69]
	v_mfma_f32_16x16x32_bf16 v[94:97], v[166:169], v[202:205], v[94:97]
	v_mfma_f32_16x16x32_bf16 v[90:93], v[166:169], v[210:213], v[90:93]
	v_mfma_f32_16x16x32_bf16 v[86:89], v[178:181], v[202:205], v[86:89]
	v_mfma_f32_16x16x32_bf16 v[82:85], v[178:181], v[210:213], v[82:85]
	v_mfma_f32_16x16x32_bf16 v[78:81], v[186:189], v[202:205], v[78:81]
	v_mfma_f32_16x16x32_bf16 v[74:77], v[186:189], v[210:213], v[74:77]
	v_mfma_f32_16x16x32_bf16 v[70:73], v[194:197], v[202:205], v[70:73]
	v_mfma_f32_16x16x32_bf16 v[66:69], v[194:197], v[210:213], v[66:69]
	v_add_u32_e32 v216, 0x8000, v230
	v_lshl_add_u64 v[214:215], v[222:223], 0, s[12:13]
	v_readfirstlane_b32 s30, v216
	v_add_u32_e32 v216, 0xa000, v230
	s_mov_b32 m0, s30
	v_readfirstlane_b32 s30, v216
	s_barrier
; #define STAGE(P, GP, ktrel) do { const GAS char* _g = (GP) + (ktrel) * (BK * 2); \
;     __builtin_amdgcn_global_load_lds((const GAS unsigned*)(_g + so0), (unsigned*)((char*)(P) + tid_ * 16), 16, 0, 0); \
;     __builtin_amdgcn_global_load_lds((const GAS unsigned*)(_g + so1), (unsigned*)((char*)(P) + tid_ * 16 + 8192), 16, 0, 0); } while (0)
; #define WAIT_V(n) asm volatile("s_waitcnt vmcnt(" #n ")" ::: "memory")
; #define WAIT_L(n) asm volatile("s_waitcnt lgkmcnt(" #n ")" ::: "memory")
; #define BAR __builtin_amdgcn_s_barrier()
; #define SCHED __builtin_amdgcn_sched_barrier(0)
; #define LDA(dst, b, h) for (int m = 0; m < 4; ++m) for (int k = 0; k < 2; ++k) \
;     dst[m][k] = *reinterpret_cast<const bf16x8*>((char*)SA(b, h) + lds_byte(wr * 64 + m * 16 + fr, k * 32 + fq * 8))
; #define LDB(dst, b, h) for (int n = 0; n < 2; ++n) for (int k = 0; k < 2; ++k) \
;     dst[n][k] = *reinterpret_cast<const bf16x8*>((char*)SB(b, h) + lds_byte(wc * 32 + n * 16 + fr, k * 32 + fq * 8))
; #define MMA(ai, bj, At_, Bt_) do { __builtin_amdgcn_s_setprio(1); \
;     for (int m = 0; m < 4; ++m) for (int n = 0; n < 2; ++n) for (int k = 0; k < 2; ++k) \
;       acc[ai][bj][m][n] = __builtin_amdgcn_mfma_f32_16x16x32_bf16(At_[m][k], Bt_[n][k], acc[ai][bj][m][n], 0, 0, 0); \
;     __builtin_amdgcn_s_setprio(0); } while (0)
; template <int K, int LD = K>
; __device__ __forceinline__ void gemm_main(const GAS bf16* A, const GAS bf16* Bt, int brow, int bcol, f32x4 (&acc)[2][2][4][2]) {
;     ...
;     LDA(At, 1, 1); STAGE(SA(1, 0), pA0, 3);
;     BAR; WAIT_L(0); MMA(1, 0, At, B0); BAR; SCHED;
;     STAGE(SB(1, 1), pB1, 3);
;     WAIT_V(6); BAR; MMA(1, 1, At, B1); BAR;
;     pA0 += 4 * BK; pA1 += 4 * BK; pB0 += 4 * BK; pB1 += 4 * BK;
;     asm volatile("" : "+s"(pA0), "+s"(pA1), "+s"(pB0), "+s"(pB1));
;   }
;   { LDB(B0, 0, 0); LDA(At, 0, 0); STAGE(SA(1, 1), pA1, 1);
;     BAR; WAIT_L(0); MMA(0, 0, At, B0); BAR;
;     LDB(B1, 0, 1); BAR; WAIT_L(0); MMA(0, 1, At, B1); BAR;
;     LDA(At, 0, 1); WAIT_V(4); BAR; WAIT_L(0); MMA(1, 0, At, B0); MMA(1, 1, At, B1); BAR; }
	ds_read_b128 v[162:165], v138 offset:49152
	ds_read_b128 v[166:169], v138 offset:50176
	ds_read_b128 v[174:177], v137 offset:49152
	ds_read_b128 v[178:181], v137 offset:50176
	ds_read_b128 v[182:185], v136 offset:49152
	ds_read_b128 v[186:189], v136 offset:50176
	ds_read_b128 v[190:193], v135 offset:49152
	ds_read_b128 v[194:197], v135 offset:50176
	global_load_lds_dwordx4 v[214:215], off
	v_lshl_add_u64 v[214:215], v[224:225], 0, s[12:13]
	s_mov_b32 m0, s30
	s_nop 0
	global_load_lds_dwordx4 v[214:215], off
	s_barrier
	s_waitcnt lgkmcnt(0)
	s_waitcnt lgkmcnt(0)
	v_mfma_f32_16x16x32_bf16 v[62:65], v[162:165], v[146:149], v[62:65]
	v_mfma_f32_16x16x32_bf16 v[58:61], v[162:165], v[154:157], v[58:61]
	v_mfma_f32_16x16x32_bf16 v[54:57], v[174:177], v[146:149], v[54:57]
	v_mfma_f32_16x16x32_bf16 v[50:53], v[174:177], v[154:157], v[50:53]
	v_mfma_f32_16x16x32_bf16 v[46:49], v[182:185], v[146:149], v[46:49]
	v_mfma_f32_16x16x32_bf16 v[42:45], v[182:185], v[154:157], v[42:45]
	v_mfma_f32_16x16x32_bf16 v[38:41], v[190:193], v[146:149], v[38:41]
	v_mfma_f32_16x16x32_bf16 v[34:37], v[190:193], v[154:157], v[34:37]
	v_mfma_f32_16x16x32_bf16 v[62:65], v[166:169], v[150:153], v[62:65]
	v_mfma_f32_16x16x32_bf16 v[58:61], v[166:169], v[158:161], v[58:61]
	v_mfma_f32_16x16x32_bf16 v[54:57], v[178:181], v[150:153], v[54:57]
	v_mfma_f32_16x16x32_bf16 v[50:53], v[178:181], v[158:161], v[50:53]
	v_mfma_f32_16x16x32_bf16 v[46:49], v[186:189], v[150:153], v[46:49]
	v_mfma_f32_16x16x32_bf16 v[42:45], v[186:189], v[158:161], v[42:45]
	v_mfma_f32_16x16x32_bf16 v[38:41], v[194:197], v[150:153], v[38:41]
	v_mfma_f32_16x16x32_bf16 v[34:37], v[194:197], v[158:161], v[34:37]
	s_barrier
	v_add_u32_e32 v148, s50, v141
	v_lshl_add_u64 v[146:147], v[226:227], 0, s[12:13]
	v_readfirstlane_b32 s30, v148
	v_add_u32_e32 v148, 0x2000, v148
	s_mov_b32 m0, s30
	v_readfirstlane_b32 s30, v148
	global_load_lds_dwordx4 v[146:147], off
	v_lshl_add_u64 v[146:147], v[228:229], 0, s[12:13]
	s_mov_b32 m0, s30
	s_nop 0
	global_load_lds_dwordx4 v[146:147], off
	s_waitcnt vmcnt(10)
	s_barrier
	v_mfma_f32_16x16x32_bf16 v[30:33], v[162:165], v[198:201], v[30:33]
	v_mfma_f32_16x16x32_bf16 v[26:29], v[162:165], v[206:209], v[26:29]
	v_mfma_f32_16x16x32_bf16 v[22:25], v[174:177], v[198:201], v[22:25]
	v_mfma_f32_16x16x32_bf16 v[18:21], v[174:177], v[206:209], v[18:21]
	v_mfma_f32_16x16x32_bf16 v[14:17], v[182:185], v[198:201], v[14:17]
	v_mfma_f32_16x16x32_bf16 v[10:13], v[182:185], v[206:209], v[10:13]
	v_mfma_f32_16x16x32_bf16 v[6:9], v[190:193], v[198:201], v[6:9]
	v_mfma_f32_16x16x32_bf16 v[2:5], v[190:193], v[206:209], v[2:5]
	v_mfma_f32_16x16x32_bf16 v[30:33], v[166:169], v[202:205], v[30:33]
	v_mfma_f32_16x16x32_bf16 v[26:29], v[166:169], v[210:213], v[26:29]
	v_mfma_f32_16x16x32_bf16 v[22:25], v[178:181], v[202:205], v[22:25]
	v_mfma_f32_16x16x32_bf16 v[18:21], v[178:181], v[210:213], v[18:21]
	v_mfma_f32_16x16x32_bf16 v[14:17], v[186:189], v[202:205], v[14:17]
	v_mfma_f32_16x16x32_bf16 v[10:13], v[186:189], v[210:213], v[10:13]
	v_mfma_f32_16x16x32_bf16 v[6:9], v[194:197], v[202:205], v[6:9]
	v_mfma_f32_16x16x32_bf16 v[2:5], v[194:197], v[210:213], v[2:5]
	s_add_i32 s17, s17, 2
	s_cmp_lt_u32 s17, 4
	s_barrier
	s_cbranch_scc1 .LBB0_709
	v_lshl_add_u64 v[198:199], s[20:21], 0, v[130:131]
	v_readfirstlane_b32 s17, v144
	v_lshl_add_u64 v[198:199], v[198:199], 0, s[6:7]
	s_mov_b32 m0, s17
	v_lshl_add_u64 v[132:133], s[20:21], 0, v[132:133]
	v_readfirstlane_b32 s17, v145
	ds_read_b128 v[146:149], v143
	ds_read_b128 v[150:153], v143 offset:1024
	ds_read_b128 v[154:157], v143 offset:2048
	ds_read_b128 v[158:161], v143 offset:3072
	ds_read_b128 v[162:165], v138
	ds_read_b128 v[166:169], v138 offset:1024
	ds_read_b128 v[174:177], v137
	ds_read_b128 v[178:181], v137 offset:1024
	ds_read_b128 v[182:185], v136
	ds_read_b128 v[186:189], v136 offset:1024
	ds_read_b128 v[190:193], v135
	ds_read_b128 v[194:197], v135 offset:1024
	global_load_lds_dwordx4 v[198:199], off
	v_lshl_add_u64 v[132:133], v[132:133], 0, s[6:7]
	s_mov_b32 m0, s17
	s_nop 0
	global_load_lds_dwordx4 v[132:133], off
	s_waitcnt vmcnt(10)
	s_barrier
	s_waitcnt lgkmcnt(0)
	s_waitcnt lgkmcnt(0)
	v_mfma_f32_16x16x32_bf16 v[126:129], v[162:165], v[146:149], v[126:129]
	v_mfma_f32_16x16x32_bf16 v[122:125], v[162:165], v[154:157], v[122:125]
	v_mfma_f32_16x16x32_bf16 v[110:113], v[182:185], v[146:149], v[110:113]
	v_mfma_f32_16x16x32_bf16 v[106:109], v[182:185], v[154:157], v[106:109]
	v_mfma_f32_16x16x32_bf16 v[126:129], v[166:169], v[150:153], v[126:129]
	v_mfma_f32_16x16x32_bf16 v[122:125], v[166:169], v[158:161], v[122:125]
	v_mfma_f32_16x16x32_bf16 v[118:121], v[174:177], v[146:149], v[118:121]
	v_mfma_f32_16x16x32_bf16 v[114:117], v[174:177], v[154:157], v[114:117]
	v_mfma_f32_16x16x32_bf16 v[110:113], v[186:189], v[150:153], v[110:113]
	v_mfma_f32_16x16x32_bf16 v[106:109], v[186:189], v[158:161], v[106:109]
	v_mfma_f32_16x16x32_bf16 v[102:105], v[190:193], v[146:149], v[102:105]
	v_mfma_f32_16x16x32_bf16 v[98:101], v[190:193], v[154:157], v[98:101]
	v_mfma_f32_16x16x32_bf16 v[198:201], v[178:181], v[150:153], v[118:121]
	v_mfma_f32_16x16x32_bf16 v[202:205], v[178:181], v[158:161], v[114:117]
	v_mfma_f32_16x16x32_bf16 v[206:209], v[194:197], v[150:153], v[102:105]
	v_mfma_f32_16x16x32_bf16 v[210:213], v[194:197], v[158:161], v[98:101]
	s_barrier
	s_nop 1
	ds_read_b128 v[98:101], v142
	ds_read_b128 v[102:105], v142 offset:1024
	ds_read_b128 v[114:117], v142 offset:2048
	ds_read_b128 v[118:121], v142 offset:3072
	s_waitcnt vmcnt(8)
	s_barrier
; #define WAIT_V(n) asm volatile("s_waitcnt vmcnt(" #n ")" ::: "memory")
; #define WAIT_L(n) asm volatile("s_waitcnt lgkmcnt(" #n ")" ::: "memory")
; #define BAR __builtin_amdgcn_s_barrier()
; #define LDA(dst, b, h) for (int m = 0; m < 4; ++m) for (int k = 0; k < 2; ++k) \
;     dst[m][k] = *reinterpret_cast<const bf16x8*>((char*)SA(b, h) + lds_byte(wr * 64 + m * 16 + fr, k * 32 + fq * 8))
; #define LDB(dst, b, h) for (int n = 0; n < 2; ++n) for (int k = 0; k < 2; ++k) \
;     dst[n][k] = *reinterpret_cast<const bf16x8*>((char*)SB(b, h) + lds_byte(wc * 32 + n * 16 + fr, k * 32 + fq * 8))
; #define MMA(ai, bj, At_, Bt_) do { __builtin_amdgcn_s_setprio(1); \
;     for (int m = 0; m < 4; ++m) for (int n = 0; n < 2; ++n) for (int k = 0; k < 2; ++k) \
;       acc[ai][bj][m][n] = __builtin_amdgcn_mfma_f32_16x16x32_bf16(At_[m][k], Bt_[n][k], acc[ai][bj][m][n], 0, 0, 0); \
;     __builtin_amdgcn_s_setprio(0); } while (0)
; template <int K, int LD = K>
; __device__ __forceinline__ void gemm_main(const GAS bf16* A, const GAS bf16* Bt, int brow, int bcol, f32x4 (&acc)[2][2][4][2]) {
;     ...
;     LDB(B1, 0, 1); BAR; WAIT_L(0); MMA(0, 1, At, B1); BAR;
;     LDA(At, 0, 1); WAIT_V(4); BAR; WAIT_L(0); MMA(1, 0, At, B0); MMA(1, 1, At, B1); BAR; }
;   { LDB(B0, 1, 0); LDA(At, 1, 0); WAIT_V(2); BAR; WAIT_L(0); MMA(0, 0, At, B0); BAR;
	s_waitcnt lgkmcnt(0)
	s_waitcnt lgkmcnt(0)
	v_mfma_f32_16x16x32_bf16 v[94:97], v[162:165], v[98:101], v[94:97]
	v_mfma_f32_16x16x32_bf16 v[90:93], v[162:165], v[114:117], v[90:93]
	v_mfma_f32_16x16x32_bf16 v[70:73], v[190:193], v[98:101], v[70:73]
	v_mfma_f32_16x16x32_bf16 v[66:69], v[190:193], v[114:117], v[66:69]
	v_mfma_f32_16x16x32_bf16 v[94:97], v[166:169], v[102:105], v[94:97]
	v_mfma_f32_16x16x32_bf16 v[90:93], v[166:169], v[118:121], v[90:93]
	v_mfma_f32_16x16x32_bf16 v[86:89], v[174:177], v[98:101], v[86:89]
	v_mfma_f32_16x16x32_bf16 v[82:85], v[174:177], v[114:117], v[82:85]
	v_mfma_f32_16x16x32_bf16 v[78:81], v[182:185], v[98:101], v[78:81]
	v_mfma_f32_16x16x32_bf16 v[74:77], v[182:185], v[114:117], v[74:77]
	v_mfma_f32_16x16x32_bf16 v[70:73], v[194:197], v[102:105], v[70:73]
	v_mfma_f32_16x16x32_bf16 v[66:69], v[194:197], v[118:121], v[66:69]
	v_mfma_f32_16x16x32_bf16 v[142:145], v[178:181], v[102:105], v[86:89]
	v_mfma_f32_16x16x32_bf16 v[162:165], v[178:181], v[118:121], v[82:85]
	v_mfma_f32_16x16x32_bf16 v[166:169], v[186:189], v[102:105], v[78:81]
	v_mfma_f32_16x16x32_bf16 v[174:177], v[186:189], v[118:121], v[74:77]
	s_barrier
	s_nop 0
	ds_read_b128 v[74:77], v138 offset:16384
	ds_read_b128 v[78:81], v138 offset:17408
	ds_read_b128 v[82:85], v137 offset:16384
	ds_read_b128 v[86:89], v137 offset:17408
	ds_read_b128 v[178:181], v136 offset:16384
	ds_read_b128 v[182:185], v136 offset:17408
	ds_read_b128 v[186:189], v135 offset:16384
	ds_read_b128 v[190:193], v135 offset:17408
	s_waitcnt vmcnt(4)
	s_barrier
	s_waitcnt lgkmcnt(0)
	s_waitcnt lgkmcnt(0)
	v_mfma_f32_16x16x32_bf16 v[62:65], v[74:77], v[146:149], v[62:65]
	v_mfma_f32_16x16x32_bf16 v[58:61], v[74:77], v[154:157], v[58:61]
	v_mfma_f32_16x16x32_bf16 v[54:57], v[82:85], v[146:149], v[54:57]
	v_mfma_f32_16x16x32_bf16 v[50:53], v[82:85], v[154:157], v[50:53]
	v_mfma_f32_16x16x32_bf16 v[38:41], v[186:189], v[146:149], v[38:41]
	v_mfma_f32_16x16x32_bf16 v[34:37], v[186:189], v[154:157], v[34:37]
	v_mfma_f32_16x16x32_bf16 v[62:65], v[78:81], v[150:153], v[62:65]
	v_mfma_f32_16x16x32_bf16 v[58:61], v[78:81], v[158:161], v[58:61]
	v_mfma_f32_16x16x32_bf16 v[54:57], v[86:89], v[150:153], v[54:57]
	v_mfma_f32_16x16x32_bf16 v[50:53], v[86:89], v[158:161], v[50:53]
	v_mfma_f32_16x16x32_bf16 v[46:49], v[178:181], v[146:149], v[46:49]
	v_mfma_f32_16x16x32_bf16 v[42:45], v[178:181], v[154:157], v[42:45]
	v_mfma_f32_16x16x32_bf16 v[38:41], v[190:193], v[150:153], v[38:41]
	v_mfma_f32_16x16x32_bf16 v[34:37], v[190:193], v[158:161], v[34:37]
	v_mfma_f32_16x16x32_bf16 v[194:197], v[182:185], v[150:153], v[46:49]
	v_mfma_f32_16x16x32_bf16 v[214:217], v[182:185], v[158:161], v[42:45]
	v_mfma_f32_16x16x32_bf16 v[22:25], v[82:85], v[98:101], v[22:25]
	v_mfma_f32_16x16x32_bf16 v[18:21], v[82:85], v[114:117], v[18:21]
	v_mfma_f32_16x16x32_bf16 v[14:17], v[178:181], v[98:101], v[14:17]
	v_mfma_f32_16x16x32_bf16 v[10:13], v[178:181], v[114:117], v[10:13]
	v_mfma_f32_16x16x32_bf16 v[30:33], v[74:77], v[98:101], v[30:33]
	v_mfma_f32_16x16x32_bf16 v[26:29], v[74:77], v[114:117], v[26:29]
	v_mfma_f32_16x16x32_bf16 v[22:25], v[86:89], v[102:105], v[22:25]
	v_mfma_f32_16x16x32_bf16 v[18:21], v[86:89], v[118:121], v[18:21]
	v_mfma_f32_16x16x32_bf16 v[14:17], v[182:185], v[102:105], v[14:17]
	v_mfma_f32_16x16x32_bf16 v[10:13], v[182:185], v[118:121], v[10:13]
	v_mfma_f32_16x16x32_bf16 v[6:9], v[186:189], v[98:101], v[6:9]
	v_mfma_f32_16x16x32_bf16 v[2:5], v[186:189], v[114:117], v[2:5]
	v_mfma_f32_16x16x32_bf16 v[146:149], v[78:81], v[102:105], v[30:33]
	v_mfma_f32_16x16x32_bf16 v[150:153], v[78:81], v[118:121], v[26:29]
	v_mfma_f32_16x16x32_bf16 v[154:157], v[190:193], v[102:105], v[6:9]
	v_mfma_f32_16x16x32_bf16 v[158:161], v[190:193], v[118:121], v[2:5]
	s_barrier
	s_nop 1
	ds_read_b128 v[2:5], v140
	ds_read_b128 v[6:9], v140 offset:1024
	ds_read_b128 v[178:181], v140 offset:2048
	ds_read_b128 v[182:185], v140 offset:3072
	ds_read_b128 v[26:29], v138 offset:32768
	ds_read_b128 v[30:33], v138 offset:33792
	ds_read_b128 v[42:45], v137 offset:32768
	ds_read_b128 v[46:49], v137 offset:33792
	ds_read_b128 v[186:189], v136 offset:32768
	ds_read_b128 v[190:193], v136 offset:33792
	ds_read_b128 v[218:221], v135 offset:32768
	ds_read_b128 v[222:225], v135 offset:33792
	s_waitcnt vmcnt(2)
	s_barrier
; #define WAIT_V(n) asm volatile("s_waitcnt vmcnt(" #n ")" ::: "memory")
; #define WAIT_L(n) asm volatile("s_waitcnt lgkmcnt(" #n ")" ::: "memory")
; #define BAR __builtin_amdgcn_s_barrier()
; #define LDA(dst, b, h) for (int m = 0; m < 4; ++m) for (int k = 0; k < 2; ++k) \
;     dst[m][k] = *reinterpret_cast<const bf16x8*>((char*)SA(b, h) + lds_byte(wr * 64 + m * 16 + fr, k * 32 + fq * 8))
; #define LDB(dst, b, h) for (int n = 0; n < 2; ++n) for (int k = 0; k < 2; ++k) \
;     dst[n][k] = *reinterpret_cast<const bf16x8*>((char*)SB(b, h) + lds_byte(wc * 32 + n * 16 + fr, k * 32 + fq * 8))
; #define MMA(ai, bj, At_, Bt_) do { __builtin_amdgcn_s_setprio(1); \
;     for (int m = 0; m < 4; ++m) for (int n = 0; n < 2; ++n) for (int k = 0; k < 2; ++k) \
;       acc[ai][bj][m][n] = __builtin_amdgcn_mfma_f32_16x16x32_bf16(At_[m][k], Bt_[n][k], acc[ai][bj][m][n], 0, 0, 0); \
;     __builtin_amdgcn_s_setprio(0); } while (0)
; template <int K, int LD = K>
; __device__ __forceinline__ void gemm_main(const GAS bf16* A, const GAS bf16* Bt, int brow, int bcol, f32x4 (&acc)[2][2][4][2]) {
;     ...
;   { LDB(B0, 1, 0); LDA(At, 1, 0); WAIT_V(2); BAR; WAIT_L(0); MMA(0, 0, At, B0); BAR;
;     LDB(B1, 1, 1); WAIT_V(0); BAR; WAIT_L(0); MMA(0, 1, At, B1); BAR;
;     LDA(At, 1, 1); BAR; WAIT_L(0); MMA(1, 0, At, B0); MMA(1, 1, At, B1); BAR; }
;   if (wr == 0) BAR;
	s_waitcnt lgkmcnt(0)
	s_waitcnt lgkmcnt(0)
	v_mfma_f32_16x16x32_bf16 v[74:77], v[26:29], v[2:5], v[126:129]
	v_mfma_f32_16x16x32_bf16 v[118:121], v[30:33], v[6:9], v[74:77]
	v_mfma_f32_16x16x32_bf16 v[74:77], v[26:29], v[178:181], v[122:125]
	v_mfma_f32_16x16x32_bf16 v[114:117], v[30:33], v[182:185], v[74:77]
	v_mfma_f32_16x16x32_bf16 v[74:77], v[42:45], v[2:5], v[198:201]
	v_mfma_f32_16x16x32_bf16 v[102:105], v[46:49], v[6:9], v[74:77]
	v_mfma_f32_16x16x32_bf16 v[74:77], v[42:45], v[178:181], v[202:205]
	v_mfma_f32_16x16x32_bf16 v[98:101], v[46:49], v[182:185], v[74:77]
	v_mfma_f32_16x16x32_bf16 v[74:77], v[186:189], v[2:5], v[110:113]
	v_mfma_f32_16x16x32_bf16 v[86:89], v[190:193], v[6:9], v[74:77]
	v_mfma_f32_16x16x32_bf16 v[74:77], v[186:189], v[178:181], v[106:109]
	v_mfma_f32_16x16x32_bf16 v[82:85], v[190:193], v[182:185], v[74:77]
	v_mfma_f32_16x16x32_bf16 v[74:77], v[218:221], v[2:5], v[206:209]
	v_mfma_f32_16x16x32_bf16 v[78:81], v[222:225], v[6:9], v[74:77]
	v_mfma_f32_16x16x32_bf16 v[74:77], v[218:221], v[178:181], v[210:213]
	v_mfma_f32_16x16x32_bf16 v[74:77], v[222:225], v[182:185], v[74:77]
	s_barrier
	ds_read_b128 v[198:201], v139
	ds_read_b128 v[202:205], v139 offset:1024
	ds_read_b128 v[206:209], v139 offset:2048
	ds_read_b128 v[210:213], v139 offset:3072
	s_waitcnt vmcnt(0)
	s_barrier
	s_waitcnt lgkmcnt(0)
	s_waitcnt lgkmcnt(0)
	v_mfma_f32_16x16x32_bf16 v[94:97], v[26:29], v[198:201], v[94:97]
	v_mfma_f32_16x16x32_bf16 v[26:29], v[26:29], v[206:209], v[90:93]
	v_mfma_f32_16x16x32_bf16 v[122:125], v[30:33], v[210:213], v[26:29]
	v_mfma_f32_16x16x32_bf16 v[26:29], v[42:45], v[198:201], v[142:145]
	v_mfma_f32_16x16x32_bf16 v[110:113], v[46:49], v[202:205], v[26:29]
	v_mfma_f32_16x16x32_bf16 v[26:29], v[42:45], v[206:209], v[162:165]
	v_mfma_f32_16x16x32_bf16 v[106:109], v[46:49], v[210:213], v[26:29]
	v_mfma_f32_16x16x32_bf16 v[26:29], v[186:189], v[198:201], v[166:169]
	v_mfma_f32_16x16x32_bf16 v[126:129], v[30:33], v[202:205], v[94:97]
	v_mfma_f32_16x16x32_bf16 v[94:97], v[190:193], v[202:205], v[26:29]
	v_mfma_f32_16x16x32_bf16 v[26:29], v[186:189], v[206:209], v[174:177]
	v_mfma_f32_16x16x32_bf16 v[90:93], v[190:193], v[210:213], v[26:29]
	v_mfma_f32_16x16x32_bf16 v[26:29], v[218:221], v[198:201], v[70:73]
	v_mfma_f32_16x16x32_bf16 v[70:73], v[222:225], v[202:205], v[26:29]
	v_mfma_f32_16x16x32_bf16 v[26:29], v[218:221], v[206:209], v[66:69]
	v_mfma_f32_16x16x32_bf16 v[66:69], v[222:225], v[210:213], v[26:29]
	s_barrier
	ds_read_b128 v[140:143], v138 offset:49152
	ds_read_b128 v[162:165], v138 offset:50176
	ds_read_b128 v[166:169], v137 offset:49152
	ds_read_b128 v[174:177], v137 offset:50176
	ds_read_b128 v[186:189], v136 offset:49152
	ds_read_b128 v[136:139], v136 offset:50176
	ds_read_b128 v[190:193], v135 offset:49152
	ds_read_b128 v[218:221], v135 offset:50176
	s_barrier
	s_waitcnt lgkmcnt(0)
	s_waitcnt lgkmcnt(0)
	v_mfma_f32_16x16x32_bf16 v[26:29], v[140:143], v[2:5], v[62:65]
	v_mfma_f32_16x16x32_bf16 v[62:65], v[162:165], v[6:9], v[26:29]
	v_mfma_f32_16x16x32_bf16 v[26:29], v[140:143], v[178:181], v[58:61]
	v_mfma_f32_16x16x32_bf16 v[58:61], v[162:165], v[182:185], v[26:29]
	v_mfma_f32_16x16x32_bf16 v[26:29], v[166:169], v[2:5], v[54:57]
	v_mfma_f32_16x16x32_bf16 v[46:49], v[174:177], v[6:9], v[26:29]
	v_mfma_f32_16x16x32_bf16 v[26:29], v[166:169], v[178:181], v[50:53]
	v_mfma_f32_16x16x32_bf16 v[42:45], v[174:177], v[182:185], v[26:29]
	v_mfma_f32_16x16x32_bf16 v[26:29], v[186:189], v[2:5], v[194:197]
	v_mfma_f32_16x16x32_bf16 v[2:5], v[190:193], v[2:5], v[38:41]
	v_mfma_f32_16x16x32_bf16 v[30:33], v[136:139], v[6:9], v[26:29]
	v_mfma_f32_16x16x32_bf16 v[26:29], v[186:189], v[178:181], v[214:217]
	v_mfma_f32_16x16x32_bf16 v[6:9], v[218:221], v[6:9], v[2:5]
	v_mfma_f32_16x16x32_bf16 v[2:5], v[190:193], v[178:181], v[34:37]
	v_mfma_f32_16x16x32_bf16 v[26:29], v[136:139], v[182:185], v[26:29]
	v_mfma_f32_16x16x32_bf16 v[2:5], v[218:221], v[182:185], v[2:5]
	v_mfma_f32_16x16x32_bf16 v[34:37], v[140:143], v[198:201], v[146:149]
	v_mfma_f32_16x16x32_bf16 v[54:57], v[162:165], v[202:205], v[34:37]
	v_mfma_f32_16x16x32_bf16 v[34:37], v[140:143], v[206:209], v[150:153]
	v_mfma_f32_16x16x32_bf16 v[18:21], v[166:169], v[206:209], v[18:21]
	v_mfma_f32_16x16x32_bf16 v[10:13], v[186:189], v[206:209], v[10:13]
	v_mfma_f32_16x16x32_bf16 v[50:53], v[162:165], v[210:213], v[34:37]
	v_mfma_f32_16x16x32_bf16 v[22:25], v[166:169], v[198:201], v[22:25]
	v_mfma_f32_16x16x32_bf16 v[34:37], v[174:177], v[210:213], v[18:21]
	v_mfma_f32_16x16x32_bf16 v[14:17], v[186:189], v[198:201], v[14:17]
	v_mfma_f32_16x16x32_bf16 v[18:21], v[136:139], v[210:213], v[10:13]
	v_mfma_f32_16x16x32_bf16 v[10:13], v[190:193], v[198:201], v[154:157]
	v_mfma_f32_16x16x32_bf16 v[38:41], v[174:177], v[202:205], v[22:25]
	v_mfma_f32_16x16x32_bf16 v[22:25], v[136:139], v[202:205], v[14:17]
	v_mfma_f32_16x16x32_bf16 v[14:17], v[218:221], v[202:205], v[10:13]
	v_mfma_f32_16x16x32_bf16 v[10:13], v[190:193], v[206:209], v[158:161]
	v_mfma_f32_16x16x32_bf16 v[10:13], v[218:221], v[210:213], v[10:13]
	v_cmp_gt_u32_e32 vcc, s51, v134
	s_barrier
	s_and_saveexec_b64 s[20:21], vcc
	s_cbranch_execz .LBB0_712
	s_barrier

; #define STAGE(P, GP, ktrel) do { const GAS char* _g = (GP) + (ktrel) * (BK * 2); \
;     __builtin_amdgcn_global_load_lds((const GAS unsigned*)(_g + so0), (unsigned*)((char*)(P) + tid_ * 16), 16, 0, 0); \
;     __builtin_amdgcn_global_load_lds((const GAS unsigned*)(_g + so1), (unsigned*)((char*)(P) + tid_ * 16 + 8192), 16, 0, 0); } while (0)
; #define WAIT_L(n) asm volatile("s_waitcnt lgkmcnt(" #n ")" ::: "memory")
; #define BAR __builtin_amdgcn_s_barrier()
; #define SCHED __builtin_amdgcn_sched_barrier(0)
; #define LDA(dst, b, h) for (int m = 0; m < 4; ++m) for (int k = 0; k < 2; ++k) \
;     dst[m][k] = *reinterpret_cast<const bf16x8*>((char*)SA(b, h) + lds_byte(wr * 64 + m * 16 + fr, k * 32 + fq * 8))
; #define LDB(dst, b, h) for (int n = 0; n < 2; ++n) for (int k = 0; k < 2; ++k) \
;     dst[n][k] = *reinterpret_cast<const bf16x8*>((char*)SB(b, h) + lds_byte(wc * 32 + n * 16 + fr, k * 32 + fq * 8))
; #define MMA(ai, bj, At_, Bt_) do { __builtin_amdgcn_s_setprio(1); \
;     for (int m = 0; m < 4; ++m) for (int n = 0; n < 2; ++n) for (int k = 0; k < 2; ++k) \
;       acc[ai][bj][m][n] = __builtin_amdgcn_mfma_f32_16x16x32_bf16(At_[m][k], Bt_[n][k], acc[ai][bj][m][n], 0, 0, 0); \
;     __builtin_amdgcn_s_setprio(0); } while (0)
; template <int K, int LD = K>
; __device__ __forceinline__ void gemm_main(const GAS bf16* A, const GAS bf16* Bt, int brow, int bcol, f32x4 (&acc)[2][2][4][2]) {
;     ...
;   for (int t = 0; t < nt - 2; t += 2) {
;     LDB(B0, 0, 0); SCHED; LDA(At, 0, 0); STAGE(SA(1, 1), pA1, 1);
;     WAIT_L(8); BAR; WAIT_L(0); MMA(0, 0, At, B0); BAR; SCHED;
;     LDB(B1, 0, 1); STAGE(SB(0, 0), pB0, 2);
;     BAR; WAIT_L(0); MMA(0, 1, At, B1); BAR;
;     LDA(At, 0, 1); STAGE(SA(0, 0), pA0, 2);
;     BAR; WAIT_L(0); MMA(1, 0, At, B0); BAR; SCHED;
.LBB0_715:
	ds_read_b128 v[146:149], v143
	ds_read_b128 v[150:153], v143 offset:1024
	ds_read_b128 v[154:157], v143 offset:2048
	ds_read_b128 v[158:161], v143 offset:3072
	v_add_u32_e32 v230, 0x100, v141
	v_add_u32_e32 v144, 0xc000, v230
	v_lshl_add_u64 v[214:215], s[20:21], 0, v[130:131]
	v_readfirstlane_b32 s28, v144
	v_add_u32_e32 v145, 0xe000, v230
	v_lshl_add_u64 v[198:199], v[214:215], 0, s[6:7]
	s_mov_b32 m0, s28
	v_lshl_add_u64 v[216:217], s[20:21], 0, v[132:133]
	v_readfirstlane_b32 s28, v145
	ds_read_b128 v[162:165], v138
	ds_read_b128 v[166:169], v138 offset:1024
	ds_read_b128 v[174:177], v137
	ds_read_b128 v[178:181], v137 offset:1024
	ds_read_b128 v[182:185], v136
	ds_read_b128 v[186:189], v136 offset:1024
	ds_read_b128 v[190:193], v135
	ds_read_b128 v[194:197], v135 offset:1024
	global_load_lds_dwordx4 v[198:199], off
	v_lshl_add_u64 v[198:199], v[216:217], 0, s[6:7]
	s_mov_b32 m0, s28
	s_nop 0
	global_load_lds_dwordx4 v[198:199], off
	s_waitcnt lgkmcnt(8)
	s_waitcnt vmcnt(10)
	s_barrier
	s_waitcnt lgkmcnt(0)
	s_waitcnt lgkmcnt(0)
	v_mfma_f32_16x16x32_bf16 v[126:129], v[162:165], v[146:149], v[126:129]
	v_mfma_f32_16x16x32_bf16 v[122:125], v[162:165], v[154:157], v[122:125]
	v_mfma_f32_16x16x32_bf16 v[118:121], v[174:177], v[146:149], v[118:121]
	v_mfma_f32_16x16x32_bf16 v[114:117], v[174:177], v[154:157], v[114:117]
	v_mfma_f32_16x16x32_bf16 v[110:113], v[182:185], v[146:149], v[110:113]
	v_mfma_f32_16x16x32_bf16 v[106:109], v[182:185], v[154:157], v[106:109]
	v_mfma_f32_16x16x32_bf16 v[102:105], v[190:193], v[146:149], v[102:105]
	v_mfma_f32_16x16x32_bf16 v[98:101], v[190:193], v[154:157], v[98:101]
	v_mfma_f32_16x16x32_bf16 v[126:129], v[166:169], v[150:153], v[126:129]
	v_mfma_f32_16x16x32_bf16 v[122:125], v[166:169], v[158:161], v[122:125]
	v_mfma_f32_16x16x32_bf16 v[118:121], v[178:181], v[150:153], v[118:121]
	v_mfma_f32_16x16x32_bf16 v[114:117], v[178:181], v[158:161], v[114:117]
	v_mfma_f32_16x16x32_bf16 v[110:113], v[186:189], v[150:153], v[110:113]
	v_mfma_f32_16x16x32_bf16 v[106:109], v[186:189], v[158:161], v[106:109]
	v_mfma_f32_16x16x32_bf16 v[102:105], v[194:197], v[150:153], v[102:105]
	v_mfma_f32_16x16x32_bf16 v[98:101], v[194:197], v[158:161], v[98:101]
	s_barrier
	v_add_u32_e32 v224, s47, v141
	v_lshl_add_u64 v[218:219], s[26:27], 0, v[130:131]
	v_readfirstlane_b32 s28, v224
	v_lshl_add_u64 v[220:221], v[218:219], 0, s[10:11]
	s_mov_b32 m0, s28
	v_add_u32_e32 v224, 0x2000, v224
	ds_read_b128 v[198:201], v142
	ds_read_b128 v[202:205], v142 offset:1024
	ds_read_b128 v[206:209], v142 offset:2048
	ds_read_b128 v[210:213], v142 offset:3072
	global_load_lds_dwordx4 v[220:221], off
	v_lshl_add_u64 v[220:221], s[26:27], 0, v[132:133]
	v_readfirstlane_b32 s28, v224
	v_lshl_add_u64 v[222:223], v[220:221], 0, s[10:11]
	s_mov_b32 m0, s28
	s_add_u32 s26, s26, 0x100
	global_load_lds_dwordx4 v[222:223], off
	s_waitcnt vmcnt(10)
	s_barrier
	s_waitcnt lgkmcnt(0)
	s_addc_u32 s27, s27, 0
	s_waitcnt lgkmcnt(0)
	v_mfma_f32_16x16x32_bf16 v[94:97], v[162:165], v[198:201], v[94:97]
	v_mfma_f32_16x16x32_bf16 v[90:93], v[162:165], v[206:209], v[90:93]
	v_mfma_f32_16x16x32_bf16 v[86:89], v[174:177], v[198:201], v[86:89]
	v_mfma_f32_16x16x32_bf16 v[82:85], v[174:177], v[206:209], v[82:85]
	v_mfma_f32_16x16x32_bf16 v[78:81], v[182:185], v[198:201], v[78:81]
	v_mfma_f32_16x16x32_bf16 v[74:77], v[182:185], v[206:209], v[74:77]
	v_mfma_f32_16x16x32_bf16 v[70:73], v[190:193], v[198:201], v[70:73]
	v_mfma_f32_16x16x32_bf16 v[66:69], v[190:193], v[206:209], v[66:69]
	v_mfma_f32_16x16x32_bf16 v[94:97], v[166:169], v[202:205], v[94:97]
	v_mfma_f32_16x16x32_bf16 v[90:93], v[166:169], v[210:213], v[90:93]
	v_mfma_f32_16x16x32_bf16 v[86:89], v[178:181], v[202:205], v[86:89]
	v_mfma_f32_16x16x32_bf16 v[82:85], v[178:181], v[210:213], v[82:85]
	v_mfma_f32_16x16x32_bf16 v[78:81], v[186:189], v[202:205], v[78:81]
	v_mfma_f32_16x16x32_bf16 v[74:77], v[186:189], v[210:213], v[74:77]
	v_mfma_f32_16x16x32_bf16 v[70:73], v[194:197], v[202:205], v[70:73]
	v_mfma_f32_16x16x32_bf16 v[66:69], v[194:197], v[210:213], v[66:69]
	v_lshl_add_u64 v[222:223], s[24:25], 0, v[130:131]
	v_readfirstlane_b32 s28, v230
	v_lshl_add_u64 v[224:225], v[222:223], 0, s[10:11]
	s_mov_b32 m0, s28
	v_add_u32_e32 v228, 0x2000, v230
	s_barrier
	ds_read_b128 v[162:165], v138 offset:16384
	ds_read_b128 v[166:169], v138 offset:17408
	ds_read_b128 v[174:177], v137 offset:16384
	ds_read_b128 v[178:181], v137 offset:17408
	ds_read_b128 v[182:185], v136 offset:16384
	ds_read_b128 v[186:189], v136 offset:17408
	ds_read_b128 v[190:193], v135 offset:16384
	ds_read_b128 v[194:197], v135 offset:17408
	global_load_lds_dwordx4 v[224:225], off
	v_lshl_add_u64 v[224:225], s[24:25], 0, v[132:133]
	v_readfirstlane_b32 s28, v228
	v_lshl_add_u64 v[226:227], v[224:225], 0, s[10:11]
	s_mov_b32 m0, s28
	s_add_u32 s24, s24, 0x100
	global_load_lds_dwordx4 v[226:227], off
	s_barrier
	s_waitcnt lgkmcnt(0)
	s_addc_u32 s25, s25, 0
	s_waitcnt lgkmcnt(0)
	v_mfma_f32_16x16x32_bf16 v[62:65], v[162:165], v[146:149], v[62:65]
	v_mfma_f32_16x16x32_bf16 v[58:61], v[162:165], v[154:157], v[58:61]
	v_mfma_f32_16x16x32_bf16 v[54:57], v[174:177], v[146:149], v[54:57]
	v_mfma_f32_16x16x32_bf16 v[50:53], v[174:177], v[154:157], v[50:53]
	v_mfma_f32_16x16x32_bf16 v[46:49], v[182:185], v[146:149], v[46:49]
	v_mfma_f32_16x16x32_bf16 v[42:45], v[182:185], v[154:157], v[42:45]
	v_mfma_f32_16x16x32_bf16 v[38:41], v[190:193], v[146:149], v[38:41]
	v_mfma_f32_16x16x32_bf16 v[34:37], v[190:193], v[154:157], v[34:37]
	v_mfma_f32_16x16x32_bf16 v[62:65], v[166:169], v[150:153], v[62:65]
	v_mfma_f32_16x16x32_bf16 v[58:61], v[166:169], v[158:161], v[58:61]
	v_mfma_f32_16x16x32_bf16 v[54:57], v[178:181], v[150:153], v[54:57]
	v_mfma_f32_16x16x32_bf16 v[50:53], v[178:181], v[158:161], v[50:53]
	v_mfma_f32_16x16x32_bf16 v[46:49], v[186:189], v[150:153], v[46:49]
	v_mfma_f32_16x16x32_bf16 v[42:45], v[186:189], v[158:161], v[42:45]
	v_mfma_f32_16x16x32_bf16 v[38:41], v[194:197], v[150:153], v[38:41]
	v_mfma_f32_16x16x32_bf16 v[34:37], v[194:197], v[158:161], v[34:37]
	s_barrier
; #define STAGE(P, GP, ktrel) do { const GAS char* _g = (GP) + (ktrel) * (BK * 2); \
;     __builtin_amdgcn_global_load_lds((const GAS unsigned*)(_g + so0), (unsigned*)((char*)(P) + tid_ * 16), 16, 0, 0); \
;     __builtin_amdgcn_global_load_lds((const GAS unsigned*)(_g + so1), (unsigned*)((char*)(P) + tid_ * 16 + 8192), 16, 0, 0); } while (0)
; #define WAIT_V(n) asm volatile("s_waitcnt vmcnt(" #n ")" ::: "memory")
; #define WAIT_L(n) asm volatile("s_waitcnt lgkmcnt(" #n ")" ::: "memory")
; #define BAR __builtin_amdgcn_s_barrier()
; #define SCHED __builtin_amdgcn_sched_barrier(0)
; #define LDA(dst, b, h) for (int m = 0; m < 4; ++m) for (int k = 0; k < 2; ++k) \
;     dst[m][k] = *reinterpret_cast<const bf16x8*>((char*)SA(b, h) + lds_byte(wr * 64 + m * 16 + fr, k * 32 + fq * 8))
; #define LDB(dst, b, h) for (int n = 0; n < 2; ++n) for (int k = 0; k < 2; ++k) \
;     dst[n][k] = *reinterpret_cast<const bf16x8*>((char*)SB(b, h) + lds_byte(wc * 32 + n * 16 + fr, k * 32 + fq * 8))
; #define MMA(ai, bj, At_, Bt_) do { __builtin_amdgcn_s_setprio(1); \
;     for (int m = 0; m < 4; ++m) for (int n = 0; n < 2; ++n) for (int k = 0; k < 2; ++k) \
;       acc[ai][bj][m][n] = __builtin_amdgcn_mfma_f32_16x16x32_bf16(At_[m][k], Bt_[n][k], acc[ai][bj][m][n], 0, 0, 0); \
;     __builtin_amdgcn_s_setprio(0); } while (0)
; template <int K, int LD = K>
; __device__ __forceinline__ void gemm_main(const GAS bf16* A, const GAS bf16* Bt, int brow, int bcol, f32x4 (&acc)[2][2][4][2]) {
;     ...
;     STAGE(SB(0, 1), pB1, 2);
;     WAIT_V(6); BAR; MMA(1, 1, At, B1); BAR;
;     LDB(B0, 1, 0); SCHED; LDA(At, 1, 0); STAGE(SA(0, 1), pA1, 2);
;     WAIT_L(8); BAR; WAIT_L(0); MMA(0, 0, At, B0); BAR; SCHED;
;     LDB(B1, 1, 1); STAGE(SB(1, 0), pB0, 3);
;     BAR; WAIT_L(0); MMA(0, 1, At, B1); BAR;
;     LDA(At, 1, 1); STAGE(SA(1, 0), pA0, 3);
	v_add_u32_e32 v148, s48, v141
	v_lshl_add_u64 v[226:227], s[22:23], 0, v[130:131]
	v_readfirstlane_b32 s28, v148
	v_add_u32_e32 v148, 0x2000, v148
	v_lshl_add_u64 v[146:147], v[226:227], 0, s[10:11]
	s_mov_b32 m0, s28
	v_lshl_add_u64 v[228:229], s[22:23], 0, v[132:133]
	v_readfirstlane_b32 s28, v148
	global_load_lds_dwordx4 v[146:147], off
	v_lshl_add_u64 v[146:147], v[228:229], 0, s[10:11]
	s_mov_b32 m0, s28
	s_add_u32 s22, s22, 0x100
	global_load_lds_dwordx4 v[146:147], off
	s_waitcnt vmcnt(10)
	s_addc_u32 s23, s23, 0
	s_barrier
	v_mfma_f32_16x16x32_bf16 v[30:33], v[162:165], v[198:201], v[30:33]
	v_mfma_f32_16x16x32_bf16 v[26:29], v[162:165], v[206:209], v[26:29]
	v_mfma_f32_16x16x32_bf16 v[22:25], v[174:177], v[198:201], v[22:25]
	v_mfma_f32_16x16x32_bf16 v[18:21], v[174:177], v[206:209], v[18:21]
	v_mfma_f32_16x16x32_bf16 v[14:17], v[182:185], v[198:201], v[14:17]
	v_mfma_f32_16x16x32_bf16 v[10:13], v[182:185], v[206:209], v[10:13]
	v_mfma_f32_16x16x32_bf16 v[6:9], v[190:193], v[198:201], v[6:9]
	v_mfma_f32_16x16x32_bf16 v[2:5], v[190:193], v[206:209], v[2:5]
	v_mfma_f32_16x16x32_bf16 v[30:33], v[166:169], v[202:205], v[30:33]
	v_mfma_f32_16x16x32_bf16 v[26:29], v[166:169], v[210:213], v[26:29]
	v_mfma_f32_16x16x32_bf16 v[22:25], v[178:181], v[202:205], v[22:25]
	v_mfma_f32_16x16x32_bf16 v[18:21], v[178:181], v[210:213], v[18:21]
	v_mfma_f32_16x16x32_bf16 v[14:17], v[186:189], v[202:205], v[14:17]
	v_mfma_f32_16x16x32_bf16 v[10:13], v[186:189], v[210:213], v[10:13]
	v_mfma_f32_16x16x32_bf16 v[6:9], v[194:197], v[202:205], v[6:9]
	v_mfma_f32_16x16x32_bf16 v[2:5], v[194:197], v[210:213], v[2:5]
	s_barrier
	ds_read_b128 v[146:149], v140
	ds_read_b128 v[150:153], v140 offset:1024
	ds_read_b128 v[154:157], v140 offset:2048
	ds_read_b128 v[158:161], v140 offset:3072
	v_add_u32_e32 v200, 0x4000, v230
	v_lshl_add_u64 v[198:199], v[214:215], 0, s[10:11]
	v_readfirstlane_b32 s28, v200
	v_add_u32_e32 v200, 0x6000, v230
	s_mov_b32 m0, s28
	v_readfirstlane_b32 s28, v200
	ds_read_b128 v[162:165], v138 offset:32768
	ds_read_b128 v[166:169], v138 offset:33792
	ds_read_b128 v[174:177], v137 offset:32768
	ds_read_b128 v[178:181], v137 offset:33792
	ds_read_b128 v[182:185], v136 offset:32768
	ds_read_b128 v[186:189], v136 offset:33792
	ds_read_b128 v[190:193], v135 offset:32768
	ds_read_b128 v[194:197], v135 offset:33792
	global_load_lds_dwordx4 v[198:199], off
	v_lshl_add_u64 v[198:199], v[216:217], 0, s[10:11]
	s_mov_b32 m0, s28
	s_add_u32 s20, s20, 0x100
	global_load_lds_dwordx4 v[198:199], off
	s_waitcnt lgkmcnt(8)
	s_waitcnt vmcnt(10)
	s_barrier
	s_waitcnt lgkmcnt(0)
	s_addc_u32 s21, s21, 0
	s_waitcnt lgkmcnt(0)
	v_mfma_f32_16x16x32_bf16 v[126:129], v[162:165], v[146:149], v[126:129]
	v_mfma_f32_16x16x32_bf16 v[122:125], v[162:165], v[154:157], v[122:125]
	v_mfma_f32_16x16x32_bf16 v[118:121], v[174:177], v[146:149], v[118:121]
	v_mfma_f32_16x16x32_bf16 v[114:117], v[174:177], v[154:157], v[114:117]
	v_mfma_f32_16x16x32_bf16 v[110:113], v[182:185], v[146:149], v[110:113]
	v_mfma_f32_16x16x32_bf16 v[106:109], v[182:185], v[154:157], v[106:109]
	v_mfma_f32_16x16x32_bf16 v[102:105], v[190:193], v[146:149], v[102:105]
	v_mfma_f32_16x16x32_bf16 v[98:101], v[190:193], v[154:157], v[98:101]
	v_mfma_f32_16x16x32_bf16 v[126:129], v[166:169], v[150:153], v[126:129]
	v_mfma_f32_16x16x32_bf16 v[122:125], v[166:169], v[158:161], v[122:125]
	v_mfma_f32_16x16x32_bf16 v[118:121], v[178:181], v[150:153], v[118:121]
	v_mfma_f32_16x16x32_bf16 v[114:117], v[178:181], v[158:161], v[114:117]
	v_mfma_f32_16x16x32_bf16 v[110:113], v[186:189], v[150:153], v[110:113]
	v_mfma_f32_16x16x32_bf16 v[106:109], v[186:189], v[158:161], v[106:109]
	v_mfma_f32_16x16x32_bf16 v[102:105], v[194:197], v[150:153], v[102:105]
	v_mfma_f32_16x16x32_bf16 v[98:101], v[194:197], v[158:161], v[98:101]
	s_barrier
	v_add_u32_e32 v216, s49, v141
	v_lshl_add_u64 v[214:215], v[218:219], 0, s[12:13]
	v_readfirstlane_b32 s28, v216
	v_add_u32_e32 v216, 0x2000, v216
	s_mov_b32 m0, s28
	v_readfirstlane_b32 s28, v216
	ds_read_b128 v[198:201], v139
	ds_read_b128 v[202:205], v139 offset:1024
	ds_read_b128 v[206:209], v139 offset:2048
	ds_read_b128 v[210:213], v139 offset:3072
	global_load_lds_dwordx4 v[214:215], off
	v_lshl_add_u64 v[214:215], v[220:221], 0, s[12:13]
	s_mov_b32 m0, s28
	s_nop 0
	global_load_lds_dwordx4 v[214:215], off
	s_waitcnt vmcnt(10)
	s_barrier
	s_waitcnt lgkmcnt(0)
	s_waitcnt lgkmcnt(0)
	v_mfma_f32_16x16x32_bf16 v[94:97], v[162:165], v[198:201], v[94:97]
	v_mfma_f32_16x16x32_bf16 v[90:93], v[162:165], v[206:209], v[90:93]
	v_mfma_f32_16x16x32_bf16 v[86:89], v[174:177], v[198:201], v[86:89]
	v_mfma_f32_16x16x32_bf16 v[82:85], v[174:177], v[206:209], v[82:85]
	v_mfma_f32_16x16x32_bf16 v[78:81], v[182:185], v[198:201], v[78:81]
	v_mfma_f32_16x16x32_bf16 v[74:77], v[182:185], v[206:209], v[74:77]
	v_mfma_f32_16x16x32_bf16 v[70:73], v[190:193], v[198:201], v[70:73]
	v_mfma_f32_16x16x32_bf16 v[66:69], v[190:193], v[206:209], v[66:69]
	v_mfma_f32_16x16x32_bf16 v[94:97], v[166:169], v[202:205], v[94:97]
	v_mfma_f32_16x16x32_bf16 v[90:93], v[166:169], v[210:213], v[90:93]
	v_mfma_f32_16x16x32_bf16 v[86:89], v[178:181], v[202:205], v[86:89]
	v_mfma_f32_16x16x32_bf16 v[82:85], v[178:181], v[210:213], v[82:85]
	v_mfma_f32_16x16x32_bf16 v[78:81], v[186:189], v[202:205], v[78:81]
	v_mfma_f32_16x16x32_bf16 v[74:77], v[186:189], v[210:213], v[74:77]
	v_mfma_f32_16x16x32_bf16 v[70:73], v[194:197], v[202:205], v[70:73]
	v_mfma_f32_16x16x32_bf16 v[66:69], v[194:197], v[210:213], v[66:69]
	v_add_u32_e32 v216, 0x8000, v230
	v_lshl_add_u64 v[214:215], v[222:223], 0, s[12:13]
	v_readfirstlane_b32 s28, v216
	v_add_u32_e32 v216, 0xa000, v230
	s_mov_b32 m0, s28
	v_readfirstlane_b32 s28, v216
	s_barrier
; #define STAGE(P, GP, ktrel) do { const GAS char* _g = (GP) + (ktrel) * (BK * 2); \
;     __builtin_amdgcn_global_load_lds((const GAS unsigned*)(_g + so0), (unsigned*)((char*)(P) + tid_ * 16), 16, 0, 0); \
;     __builtin_amdgcn_global_load_lds((const GAS unsigned*)(_g + so1), (unsigned*)((char*)(P) + tid_ * 16 + 8192), 16, 0, 0); } while (0)
; #define WAIT_V(n) asm volatile("s_waitcnt vmcnt(" #n ")" ::: "memory")
; #define WAIT_L(n) asm volatile("s_waitcnt lgkmcnt(" #n ")" ::: "memory")
; #define BAR __builtin_amdgcn_s_barrier()
; #define SCHED __builtin_amdgcn_sched_barrier(0)
; #define LDA(dst, b, h) for (int m = 0; m < 4; ++m) for (int k = 0; k < 2; ++k) \
;     dst[m][k] = *reinterpret_cast<const bf16x8*>((char*)SA(b, h) + lds_byte(wr * 64 + m * 16 + fr, k * 32 + fq * 8))
; #define LDB(dst, b, h) for (int n = 0; n < 2; ++n) for (int k = 0; k < 2; ++k) \
;     dst[n][k] = *reinterpret_cast<const bf16x8*>((char*)SB(b, h) + lds_byte(wc * 32 + n * 16 + fr, k * 32 + fq * 8))
; #define MMA(ai, bj, At_, Bt_) do { __builtin_amdgcn_s_setprio(1); \
;     for (int m = 0; m < 4; ++m) for (int n = 0; n < 2; ++n) for (int k = 0; k < 2; ++k) \
;       acc[ai][bj][m][n] = __builtin_amdgcn_mfma_f32_16x16x32_bf16(At_[m][k], Bt_[n][k], acc[ai][bj][m][n], 0, 0, 0); \
;     __builtin_amdgcn_s_setprio(0); } while (0)
; template <int K, int LD = K>
; __device__ __forceinline__ void gemm_main(const GAS bf16* A, const GAS bf16* Bt, int brow, int bcol, f32x4 (&acc)[2][2][4][2]) {
;     ...
;     LDA(At, 1, 1); STAGE(SA(1, 0), pA0, 3);
;     BAR; WAIT_L(0); MMA(1, 0, At, B0); BAR; SCHED;
;     STAGE(SB(1, 1), pB1, 3);
;     WAIT_V(6); BAR; MMA(1, 1, At, B1); BAR;
;     pA0 += 4 * BK; pA1 += 4 * BK; pB0 += 4 * BK; pB1 += 4 * BK;
;     asm volatile("" : "+s"(pA0), "+s"(pA1), "+s"(pB0), "+s"(pB1));
;   }
;   { LDB(B0, 0, 0); LDA(At, 0, 0); STAGE(SA(1, 1), pA1, 1);
;     BAR; WAIT_L(0); MMA(0, 0, At, B0); BAR;
;     LDB(B1, 0, 1); BAR; WAIT_L(0); MMA(0, 1, At, B1); BAR;
;     LDA(At, 0, 1); WAIT_V(4); BAR; WAIT_L(0); MMA(1, 0, At, B0); MMA(1, 1, At, B1); BAR; }
	ds_read_b128 v[162:165], v138 offset:49152
	ds_read_b128 v[166:169], v138 offset:50176
	ds_read_b128 v[174:177], v137 offset:49152
	ds_read_b128 v[178:181], v137 offset:50176
	ds_read_b128 v[182:185], v136 offset:49152
	ds_read_b128 v[186:189], v136 offset:50176
	ds_read_b128 v[190:193], v135 offset:49152
	ds_read_b128 v[194:197], v135 offset:50176
	global_load_lds_dwordx4 v[214:215], off
	v_lshl_add_u64 v[214:215], v[224:225], 0, s[12:13]
	s_mov_b32 m0, s28
	s_nop 0
	global_load_lds_dwordx4 v[214:215], off
	s_barrier
	s_waitcnt lgkmcnt(0)
	s_waitcnt lgkmcnt(0)
	v_mfma_f32_16x16x32_bf16 v[62:65], v[162:165], v[146:149], v[62:65]
	v_mfma_f32_16x16x32_bf16 v[58:61], v[162:165], v[154:157], v[58:61]
	v_mfma_f32_16x16x32_bf16 v[54:57], v[174:177], v[146:149], v[54:57]
	v_mfma_f32_16x16x32_bf16 v[50:53], v[174:177], v[154:157], v[50:53]
	v_mfma_f32_16x16x32_bf16 v[46:49], v[182:185], v[146:149], v[46:49]
	v_mfma_f32_16x16x32_bf16 v[42:45], v[182:185], v[154:157], v[42:45]
	v_mfma_f32_16x16x32_bf16 v[38:41], v[190:193], v[146:149], v[38:41]
	v_mfma_f32_16x16x32_bf16 v[34:37], v[190:193], v[154:157], v[34:37]
	v_mfma_f32_16x16x32_bf16 v[62:65], v[166:169], v[150:153], v[62:65]
	v_mfma_f32_16x16x32_bf16 v[58:61], v[166:169], v[158:161], v[58:61]
	v_mfma_f32_16x16x32_bf16 v[54:57], v[178:181], v[150:153], v[54:57]
	v_mfma_f32_16x16x32_bf16 v[50:53], v[178:181], v[158:161], v[50:53]
	v_mfma_f32_16x16x32_bf16 v[46:49], v[186:189], v[150:153], v[46:49]
	v_mfma_f32_16x16x32_bf16 v[42:45], v[186:189], v[158:161], v[42:45]
	v_mfma_f32_16x16x32_bf16 v[38:41], v[194:197], v[150:153], v[38:41]
	v_mfma_f32_16x16x32_bf16 v[34:37], v[194:197], v[158:161], v[34:37]
	s_barrier
	v_add_u32_e32 v148, s50, v141
	v_lshl_add_u64 v[146:147], v[226:227], 0, s[12:13]
	v_readfirstlane_b32 s28, v148
	v_add_u32_e32 v148, 0x2000, v148
	s_mov_b32 m0, s28
	v_readfirstlane_b32 s28, v148
	global_load_lds_dwordx4 v[146:147], off
	v_lshl_add_u64 v[146:147], v[228:229], 0, s[12:13]
	s_mov_b32 m0, s28
	s_nop 0
	global_load_lds_dwordx4 v[146:147], off
	s_waitcnt vmcnt(10)
	s_barrier
	v_mfma_f32_16x16x32_bf16 v[30:33], v[162:165], v[198:201], v[30:33]
	v_mfma_f32_16x16x32_bf16 v[26:29], v[162:165], v[206:209], v[26:29]
	v_mfma_f32_16x16x32_bf16 v[22:25], v[174:177], v[198:201], v[22:25]
	v_mfma_f32_16x16x32_bf16 v[18:21], v[174:177], v[206:209], v[18:21]
	v_mfma_f32_16x16x32_bf16 v[14:17], v[182:185], v[198:201], v[14:17]
	v_mfma_f32_16x16x32_bf16 v[10:13], v[182:185], v[206:209], v[10:13]
	v_mfma_f32_16x16x32_bf16 v[6:9], v[190:193], v[198:201], v[6:9]
	v_mfma_f32_16x16x32_bf16 v[2:5], v[190:193], v[206:209], v[2:5]
	v_mfma_f32_16x16x32_bf16 v[30:33], v[166:169], v[202:205], v[30:33]
	v_mfma_f32_16x16x32_bf16 v[26:29], v[166:169], v[210:213], v[26:29]
	v_mfma_f32_16x16x32_bf16 v[22:25], v[178:181], v[202:205], v[22:25]
	v_mfma_f32_16x16x32_bf16 v[18:21], v[178:181], v[210:213], v[18:21]
	v_mfma_f32_16x16x32_bf16 v[14:17], v[186:189], v[202:205], v[14:17]
	v_mfma_f32_16x16x32_bf16 v[10:13], v[186:189], v[210:213], v[10:13]
	v_mfma_f32_16x16x32_bf16 v[6:9], v[194:197], v[202:205], v[6:9]
	v_mfma_f32_16x16x32_bf16 v[2:5], v[194:197], v[210:213], v[2:5]
	s_add_i32 s17, s17, 2
	s_cmp_lt_u32 s17, 4
	s_barrier
	s_cbranch_scc1 .LBB0_715
	v_lshl_add_u64 v[198:199], s[20:21], 0, v[130:131]
	v_readfirstlane_b32 s17, v144
	v_lshl_add_u64 v[198:199], v[198:199], 0, s[6:7]
	s_mov_b32 m0, s17
	v_lshl_add_u64 v[132:133], s[20:21], 0, v[132:133]
	v_readfirstlane_b32 s17, v145
	ds_read_b128 v[146:149], v143
	ds_read_b128 v[150:153], v143 offset:1024
	ds_read_b128 v[154:157], v143 offset:2048
	ds_read_b128 v[158:161], v143 offset:3072
	ds_read_b128 v[162:165], v138
	ds_read_b128 v[166:169], v138 offset:1024
	ds_read_b128 v[174:177], v137
	ds_read_b128 v[178:181], v137 offset:1024
	ds_read_b128 v[182:185], v136
	ds_read_b128 v[186:189], v136 offset:1024
	ds_read_b128 v[190:193], v135
	ds_read_b128 v[194:197], v135 offset:1024
	global_load_lds_dwordx4 v[198:199], off
	v_lshl_add_u64 v[132:133], v[132:133], 0, s[6:7]
	s_mov_b32 m0, s17
	s_nop 0
	global_load_lds_dwordx4 v[132:133], off
	s_waitcnt vmcnt(10)
	s_barrier
	s_waitcnt lgkmcnt(0)
	s_waitcnt lgkmcnt(0)
	v_mfma_f32_16x16x32_bf16 v[126:129], v[162:165], v[146:149], v[126:129]
	v_mfma_f32_16x16x32_bf16 v[122:125], v[162:165], v[154:157], v[122:125]
	v_mfma_f32_16x16x32_bf16 v[110:113], v[182:185], v[146:149], v[110:113]
	v_mfma_f32_16x16x32_bf16 v[106:109], v[182:185], v[154:157], v[106:109]
	v_mfma_f32_16x16x32_bf16 v[126:129], v[166:169], v[150:153], v[126:129]
	v_mfma_f32_16x16x32_bf16 v[122:125], v[166:169], v[158:161], v[122:125]
	v_mfma_f32_16x16x32_bf16 v[118:121], v[174:177], v[146:149], v[118:121]
	v_mfma_f32_16x16x32_bf16 v[114:117], v[174:177], v[154:157], v[114:117]
	v_mfma_f32_16x16x32_bf16 v[110:113], v[186:189], v[150:153], v[110:113]
	v_mfma_f32_16x16x32_bf16 v[106:109], v[186:189], v[158:161], v[106:109]
	v_mfma_f32_16x16x32_bf16 v[102:105], v[190:193], v[146:149], v[102:105]
	v_mfma_f32_16x16x32_bf16 v[98:101], v[190:193], v[154:157], v[98:101]
	v_mfma_f32_16x16x32_bf16 v[198:201], v[178:181], v[150:153], v[118:121]
	v_mfma_f32_16x16x32_bf16 v[202:205], v[178:181], v[158:161], v[114:117]
	v_mfma_f32_16x16x32_bf16 v[206:209], v[194:197], v[150:153], v[102:105]
	v_mfma_f32_16x16x32_bf16 v[210:213], v[194:197], v[158:161], v[98:101]
	s_barrier
	s_nop 1
	ds_read_b128 v[98:101], v142
	ds_read_b128 v[102:105], v142 offset:1024
	ds_read_b128 v[114:117], v142 offset:2048
	ds_read_b128 v[118:121], v142 offset:3072
	s_waitcnt vmcnt(8)
	s_barrier
; #define WAIT_V(n) asm volatile("s_waitcnt vmcnt(" #n ")" ::: "memory")
; #define WAIT_L(n) asm volatile("s_waitcnt lgkmcnt(" #n ")" ::: "memory")
; #define BAR __builtin_amdgcn_s_barrier()
; #define LDA(dst, b, h) for (int m = 0; m < 4; ++m) for (int k = 0; k < 2; ++k) \
;     dst[m][k] = *reinterpret_cast<const bf16x8*>((char*)SA(b, h) + lds_byte(wr * 64 + m * 16 + fr, k * 32 + fq * 8))
; #define LDB(dst, b, h) for (int n = 0; n < 2; ++n) for (int k = 0; k < 2; ++k) \
;     dst[n][k] = *reinterpret_cast<const bf16x8*>((char*)SB(b, h) + lds_byte(wc * 32 + n * 16 + fr, k * 32 + fq * 8))
; #define MMA(ai, bj, At_, Bt_) do { __builtin_amdgcn_s_setprio(1); \
;     for (int m = 0; m < 4; ++m) for (int n = 0; n < 2; ++n) for (int k = 0; k < 2; ++k) \
;       acc[ai][bj][m][n] = __builtin_amdgcn_mfma_f32_16x16x32_bf16(At_[m][k], Bt_[n][k], acc[ai][bj][m][n], 0, 0, 0); \
;     __builtin_amdgcn_s_setprio(0); } while (0)
; template <int K, int LD = K>
; __device__ __forceinline__ void gemm_main(const GAS bf16* A, const GAS bf16* Bt, int brow, int bcol, f32x4 (&acc)[2][2][4][2]) {
;     ...
;     LDB(B1, 0, 1); BAR; WAIT_L(0); MMA(0, 1, At, B1); BAR;
;     LDA(At, 0, 1); WAIT_V(4); BAR; WAIT_L(0); MMA(1, 0, At, B0); MMA(1, 1, At, B1); BAR; }
;   { LDB(B0, 1, 0); LDA(At, 1, 0); WAIT_V(2); BAR; WAIT_L(0); MMA(0, 0, At, B0); BAR;
	s_waitcnt lgkmcnt(0)
	s_waitcnt lgkmcnt(0)
	v_mfma_f32_16x16x32_bf16 v[94:97], v[162:165], v[98:101], v[94:97]
	v_mfma_f32_16x16x32_bf16 v[90:93], v[162:165], v[114:117], v[90:93]
	v_mfma_f32_16x16x32_bf16 v[78:81], v[182:185], v[98:101], v[78:81]
	v_mfma_f32_16x16x32_bf16 v[74:77], v[182:185], v[114:117], v[74:77]
	v_mfma_f32_16x16x32_bf16 v[94:97], v[166:169], v[102:105], v[94:97]
	v_mfma_f32_16x16x32_bf16 v[90:93], v[166:169], v[118:121], v[90:93]
	v_mfma_f32_16x16x32_bf16 v[86:89], v[174:177], v[98:101], v[86:89]
	v_mfma_f32_16x16x32_bf16 v[82:85], v[174:177], v[114:117], v[82:85]
	v_mfma_f32_16x16x32_bf16 v[78:81], v[186:189], v[102:105], v[78:81]
	v_mfma_f32_16x16x32_bf16 v[74:77], v[186:189], v[118:121], v[74:77]
	v_mfma_f32_16x16x32_bf16 v[70:73], v[190:193], v[98:101], v[70:73]
	v_mfma_f32_16x16x32_bf16 v[66:69], v[190:193], v[114:117], v[66:69]
	v_mfma_f32_16x16x32_bf16 v[142:145], v[178:181], v[102:105], v[86:89]
	v_mfma_f32_16x16x32_bf16 v[162:165], v[178:181], v[118:121], v[82:85]
	v_mfma_f32_16x16x32_bf16 v[166:169], v[194:197], v[102:105], v[70:73]
	v_mfma_f32_16x16x32_bf16 v[174:177], v[194:197], v[118:121], v[66:69]
	s_barrier
	s_nop 1
	ds_read_b128 v[66:69], v138 offset:16384
	ds_read_b128 v[70:73], v138 offset:17408
	ds_read_b128 v[82:85], v137 offset:16384
	ds_read_b128 v[86:89], v137 offset:17408
	ds_read_b128 v[178:181], v136 offset:16384
	ds_read_b128 v[182:185], v136 offset:17408
	ds_read_b128 v[186:189], v135 offset:16384
	ds_read_b128 v[190:193], v135 offset:17408
	s_waitcnt vmcnt(4)
	s_barrier
	s_waitcnt lgkmcnt(0)
	s_waitcnt lgkmcnt(0)
	v_mfma_f32_16x16x32_bf16 v[62:65], v[66:69], v[146:149], v[62:65]
	v_mfma_f32_16x16x32_bf16 v[54:57], v[82:85], v[146:149], v[54:57]
	v_mfma_f32_16x16x32_bf16 v[46:49], v[178:181], v[146:149], v[46:49]
	v_mfma_f32_16x16x32_bf16 v[38:41], v[186:189], v[146:149], v[38:41]
	v_mfma_f32_16x16x32_bf16 v[62:65], v[70:73], v[150:153], v[62:65]
	v_mfma_f32_16x16x32_bf16 v[58:61], v[66:69], v[154:157], v[58:61]
	v_mfma_f32_16x16x32_bf16 v[54:57], v[86:89], v[150:153], v[54:57]
	v_mfma_f32_16x16x32_bf16 v[50:53], v[82:85], v[154:157], v[50:53]
	v_mfma_f32_16x16x32_bf16 v[46:49], v[182:185], v[150:153], v[46:49]
	v_mfma_f32_16x16x32_bf16 v[42:45], v[178:181], v[154:157], v[42:45]
	v_mfma_f32_16x16x32_bf16 v[38:41], v[190:193], v[150:153], v[38:41]
	v_mfma_f32_16x16x32_bf16 v[34:37], v[186:189], v[154:157], v[34:37]
	v_mfma_f32_16x16x32_bf16 v[194:197], v[70:73], v[158:161], v[58:61]
	v_mfma_f32_16x16x32_bf16 v[214:217], v[86:89], v[158:161], v[50:53]
	v_mfma_f32_16x16x32_bf16 v[218:221], v[182:185], v[158:161], v[42:45]
	v_mfma_f32_16x16x32_bf16 v[146:149], v[190:193], v[158:161], v[34:37]
	v_mfma_f32_16x16x32_bf16 v[30:33], v[66:69], v[98:101], v[30:33]
	v_mfma_f32_16x16x32_bf16 v[22:25], v[82:85], v[98:101], v[22:25]
	v_mfma_f32_16x16x32_bf16 v[14:17], v[178:181], v[98:101], v[14:17]
	v_mfma_f32_16x16x32_bf16 v[6:9], v[186:189], v[98:101], v[6:9]
	v_mfma_f32_16x16x32_bf16 v[30:33], v[70:73], v[102:105], v[30:33]
	v_mfma_f32_16x16x32_bf16 v[26:29], v[66:69], v[114:117], v[26:29]
	v_mfma_f32_16x16x32_bf16 v[22:25], v[86:89], v[102:105], v[22:25]
	v_mfma_f32_16x16x32_bf16 v[18:21], v[82:85], v[114:117], v[18:21]
	v_mfma_f32_16x16x32_bf16 v[14:17], v[182:185], v[102:105], v[14:17]
	v_mfma_f32_16x16x32_bf16 v[10:13], v[178:181], v[114:117], v[10:13]
	v_mfma_f32_16x16x32_bf16 v[6:9], v[190:193], v[102:105], v[6:9]
	v_mfma_f32_16x16x32_bf16 v[2:5], v[186:189], v[114:117], v[2:5]
	v_mfma_f32_16x16x32_bf16 v[150:153], v[70:73], v[118:121], v[26:29]
	v_mfma_f32_16x16x32_bf16 v[154:157], v[86:89], v[118:121], v[18:21]
	v_mfma_f32_16x16x32_bf16 v[158:161], v[182:185], v[118:121], v[10:13]
	v_mfma_f32_16x16x32_bf16 v[178:181], v[190:193], v[118:121], v[2:5]
	s_barrier
	s_nop 1
	ds_read_b128 v[2:5], v140
	ds_read_b128 v[10:13], v140 offset:1024
	ds_read_b128 v[182:185], v140 offset:2048
	ds_read_b128 v[186:189], v140 offset:3072
	ds_read_b128 v[18:21], v138 offset:32768
	ds_read_b128 v[26:29], v138 offset:33792
	ds_read_b128 v[34:37], v137 offset:32768
	ds_read_b128 v[42:45], v137 offset:33792
	ds_read_b128 v[50:53], v136 offset:32768
	ds_read_b128 v[58:61], v136 offset:33792
	ds_read_b128 v[190:193], v135 offset:32768
	ds_read_b128 v[222:225], v135 offset:33792
	s_waitcnt vmcnt(2)
	s_barrier
; #define WAIT_V(n) asm volatile("s_waitcnt vmcnt(" #n ")" ::: "memory")
; #define WAIT_L(n) asm volatile("s_waitcnt lgkmcnt(" #n ")" ::: "memory")
; #define BAR __builtin_amdgcn_s_barrier()
; #define LDA(dst, b, h) for (int m = 0; m < 4; ++m) for (int k = 0; k < 2; ++k) \
;     dst[m][k] = *reinterpret_cast<const bf16x8*>((char*)SA(b, h) + lds_byte(wr * 64 + m * 16 + fr, k * 32 + fq * 8))
; #define LDB(dst, b, h) for (int n = 0; n < 2; ++n) for (int k = 0; k < 2; ++k) \
;     dst[n][k] = *reinterpret_cast<const bf16x8*>((char*)SB(b, h) + lds_byte(wc * 32 + n * 16 + fr, k * 32 + fq * 8))
; #define MMA(ai, bj, At_, Bt_) do { __builtin_amdgcn_s_setprio(1); \
;     for (int m = 0; m < 4; ++m) for (int n = 0; n < 2; ++n) for (int k = 0; k < 2; ++k) \
;       acc[ai][bj][m][n] = __builtin_amdgcn_mfma_f32_16x16x32_bf16(At_[m][k], Bt_[n][k], acc[ai][bj][m][n], 0, 0, 0); \
;     __builtin_amdgcn_s_setprio(0); } while (0)
; template <int K, int LD = K>
; __device__ __forceinline__ void gemm_main(const GAS bf16* A, const GAS bf16* Bt, int brow, int bcol, f32x4 (&acc)[2][2][4][2]) {
;     ...
;   { LDB(B0, 1, 0); LDA(At, 1, 0); WAIT_V(2); BAR; WAIT_L(0); MMA(0, 0, At, B0); BAR;
;     LDB(B1, 1, 1); WAIT_V(0); BAR; WAIT_L(0); MMA(0, 1, At, B1); BAR;
;     LDA(At, 1, 1); BAR; WAIT_L(0); MMA(1, 0, At, B0); MMA(1, 1, At, B1); BAR; }
;   if (wr == 0) BAR;
	s_waitcnt lgkmcnt(0)
	s_waitcnt lgkmcnt(0)
	v_mfma_f32_16x16x32_bf16 v[66:69], v[18:21], v[2:5], v[126:129]
	v_mfma_f32_16x16x32_bf16 v[118:121], v[26:29], v[10:13], v[66:69]
	v_mfma_f32_16x16x32_bf16 v[66:69], v[18:21], v[182:185], v[122:125]
	v_mfma_f32_16x16x32_bf16 v[114:117], v[26:29], v[186:189], v[66:69]
	v_mfma_f32_16x16x32_bf16 v[66:69], v[34:37], v[2:5], v[198:201]
	v_mfma_f32_16x16x32_bf16 v[102:105], v[42:45], v[10:13], v[66:69]
	v_mfma_f32_16x16x32_bf16 v[66:69], v[34:37], v[182:185], v[202:205]
	v_mfma_f32_16x16x32_bf16 v[98:101], v[42:45], v[186:189], v[66:69]
	v_mfma_f32_16x16x32_bf16 v[66:69], v[50:53], v[2:5], v[110:113]
	v_mfma_f32_16x16x32_bf16 v[86:89], v[58:61], v[10:13], v[66:69]
	v_mfma_f32_16x16x32_bf16 v[66:69], v[50:53], v[182:185], v[106:109]
	v_mfma_f32_16x16x32_bf16 v[82:85], v[58:61], v[186:189], v[66:69]
	v_mfma_f32_16x16x32_bf16 v[66:69], v[190:193], v[2:5], v[206:209]
	v_mfma_f32_16x16x32_bf16 v[70:73], v[222:225], v[10:13], v[66:69]
	v_mfma_f32_16x16x32_bf16 v[66:69], v[190:193], v[182:185], v[210:213]
	v_mfma_f32_16x16x32_bf16 v[66:69], v[222:225], v[186:189], v[66:69]
	s_barrier
	ds_read_b128 v[198:201], v139
	ds_read_b128 v[202:205], v139 offset:1024
	ds_read_b128 v[206:209], v139 offset:2048
	ds_read_b128 v[210:213], v139 offset:3072
	s_waitcnt vmcnt(0)
	s_barrier
	s_waitcnt lgkmcnt(0)
	s_waitcnt lgkmcnt(0)
	v_mfma_f32_16x16x32_bf16 v[94:97], v[18:21], v[198:201], v[94:97]
	v_mfma_f32_16x16x32_bf16 v[18:21], v[18:21], v[206:209], v[90:93]
	v_mfma_f32_16x16x32_bf16 v[122:125], v[26:29], v[210:213], v[18:21]
	v_mfma_f32_16x16x32_bf16 v[18:21], v[34:37], v[198:201], v[142:145]
	v_mfma_f32_16x16x32_bf16 v[110:113], v[42:45], v[202:205], v[18:21]
	v_mfma_f32_16x16x32_bf16 v[18:21], v[34:37], v[206:209], v[162:165]
	v_mfma_f32_16x16x32_bf16 v[106:109], v[42:45], v[210:213], v[18:21]
	v_mfma_f32_16x16x32_bf16 v[18:21], v[50:53], v[198:201], v[78:81]
	v_mfma_f32_16x16x32_bf16 v[126:129], v[26:29], v[202:205], v[94:97]
	v_mfma_f32_16x16x32_bf16 v[94:97], v[58:61], v[202:205], v[18:21]
	v_mfma_f32_16x16x32_bf16 v[18:21], v[50:53], v[206:209], v[74:77]
	v_mfma_f32_16x16x32_bf16 v[90:93], v[58:61], v[210:213], v[18:21]
	v_mfma_f32_16x16x32_bf16 v[18:21], v[190:193], v[198:201], v[166:169]
	v_mfma_f32_16x16x32_bf16 v[78:81], v[222:225], v[202:205], v[18:21]
	v_mfma_f32_16x16x32_bf16 v[18:21], v[190:193], v[206:209], v[174:177]
	v_mfma_f32_16x16x32_bf16 v[74:77], v[222:225], v[210:213], v[18:21]
	s_barrier
	ds_read_b128 v[140:143], v138 offset:49152
	ds_read_b128 v[162:165], v138 offset:50176
	ds_read_b128 v[166:169], v137 offset:49152
	ds_read_b128 v[174:177], v137 offset:50176
	ds_read_b128 v[190:193], v136 offset:49152
	ds_read_b128 v[136:139], v136 offset:50176
	ds_read_b128 v[222:225], v135 offset:49152
	ds_read_b128 v[226:229], v135 offset:50176
	s_barrier
	s_waitcnt lgkmcnt(0)
	s_waitcnt lgkmcnt(0)
	v_mfma_f32_16x16x32_bf16 v[18:21], v[140:143], v[2:5], v[62:65]
	v_mfma_f32_16x16x32_bf16 v[58:61], v[162:165], v[10:13], v[18:21]
	v_mfma_f32_16x16x32_bf16 v[18:21], v[140:143], v[182:185], v[194:197]
	v_mfma_f32_16x16x32_bf16 v[50:53], v[162:165], v[186:189], v[18:21]
	v_mfma_f32_16x16x32_bf16 v[18:21], v[166:169], v[2:5], v[54:57]
	v_mfma_f32_16x16x32_bf16 v[42:45], v[174:177], v[10:13], v[18:21]
	v_mfma_f32_16x16x32_bf16 v[18:21], v[166:169], v[182:185], v[214:217]
	v_mfma_f32_16x16x32_bf16 v[34:37], v[174:177], v[186:189], v[18:21]
	v_mfma_f32_16x16x32_bf16 v[18:21], v[190:193], v[2:5], v[46:49]
	v_mfma_f32_16x16x32_bf16 v[2:5], v[222:225], v[2:5], v[38:41]
	v_mfma_f32_16x16x32_bf16 v[26:29], v[136:139], v[10:13], v[18:21]
	v_mfma_f32_16x16x32_bf16 v[18:21], v[190:193], v[182:185], v[218:221]
	v_mfma_f32_16x16x32_bf16 v[10:13], v[226:229], v[10:13], v[2:5]
	v_mfma_f32_16x16x32_bf16 v[2:5], v[222:225], v[182:185], v[146:149]
	v_mfma_f32_16x16x32_bf16 v[18:21], v[136:139], v[186:189], v[18:21]
	v_mfma_f32_16x16x32_bf16 v[2:5], v[226:229], v[186:189], v[2:5]
	v_mfma_f32_16x16x32_bf16 v[30:33], v[140:143], v[198:201], v[30:33]
	v_mfma_f32_16x16x32_bf16 v[62:65], v[162:165], v[202:205], v[30:33]
	v_mfma_f32_16x16x32_bf16 v[30:33], v[140:143], v[206:209], v[150:153]
	v_mfma_f32_16x16x32_bf16 v[22:25], v[166:169], v[198:201], v[22:25]
	v_mfma_f32_16x16x32_bf16 v[14:17], v[190:193], v[198:201], v[14:17]
	v_mfma_f32_16x16x32_bf16 v[54:57], v[162:165], v[210:213], v[30:33]
	v_mfma_f32_16x16x32_bf16 v[46:49], v[174:177], v[202:205], v[22:25]
	v_mfma_f32_16x16x32_bf16 v[22:25], v[166:169], v[206:209], v[154:157]
	v_mfma_f32_16x16x32_bf16 v[30:33], v[136:139], v[202:205], v[14:17]
	v_mfma_f32_16x16x32_bf16 v[14:17], v[190:193], v[206:209], v[158:161]
	v_mfma_f32_16x16x32_bf16 v[6:9], v[222:225], v[198:201], v[6:9]
	v_mfma_f32_16x16x32_bf16 v[38:41], v[174:177], v[210:213], v[22:25]
	v_mfma_f32_16x16x32_bf16 v[22:25], v[136:139], v[210:213], v[14:17]
	v_mfma_f32_16x16x32_bf16 v[14:17], v[226:229], v[202:205], v[6:9]
	v_mfma_f32_16x16x32_bf16 v[6:9], v[222:225], v[206:209], v[178:181]
	v_mfma_f32_16x16x32_bf16 v[6:9], v[226:229], v[210:213], v[6:9]
	v_cmp_gt_u32_e32 vcc, s51, v134
	s_barrier
	s_and_saveexec_b64 s[20:21], vcc
	s_cbranch_execz .LBB0_718
	s_barrier

; #define STAGE(P, GP, ktrel) do { const GAS char* _g = (GP) + (ktrel) * (BK * 2); \
;     __builtin_amdgcn_global_load_lds((const GAS unsigned*)(_g + so0), (unsigned*)((char*)(P) + tid_ * 16), 16, 0, 0); \
;     __builtin_amdgcn_global_load_lds((const GAS unsigned*)(_g + so1), (unsigned*)((char*)(P) + tid_ * 16 + 8192), 16, 0, 0); } while (0)
; #define WAIT_L(n) asm volatile("s_waitcnt lgkmcnt(" #n ")" ::: "memory")
; #define BAR __builtin_amdgcn_s_barrier()
; #define SCHED __builtin_amdgcn_sched_barrier(0)
; #define LDA(dst, b, h) for (int m = 0; m < 4; ++m) for (int k = 0; k < 2; ++k) \
;     dst[m][k] = *reinterpret_cast<const bf16x8*>((char*)SA(b, h) + lds_byte(wr * 64 + m * 16 + fr, k * 32 + fq * 8))
; #define LDB(dst, b, h) for (int n = 0; n < 2; ++n) for (int k = 0; k < 2; ++k) \
;     dst[n][k] = *reinterpret_cast<const bf16x8*>((char*)SB(b, h) + lds_byte(wc * 32 + n * 16 + fr, k * 32 + fq * 8))
; #define MMA(ai, bj, At_, Bt_) do { __builtin_amdgcn_s_setprio(1); \
;     for (int m = 0; m < 4; ++m) for (int n = 0; n < 2; ++n) for (int k = 0; k < 2; ++k) \
;       acc[ai][bj][m][n] = __builtin_amdgcn_mfma_f32_16x16x32_bf16(At_[m][k], Bt_[n][k], acc[ai][bj][m][n], 0, 0, 0); \
;     __builtin_amdgcn_s_setprio(0); } while (0)
; template <int K, int LD = K>
; __device__ __forceinline__ void gemm_main(const GAS bf16* A, const GAS bf16* Bt, int brow, int bcol, f32x4 (&acc)[2][2][4][2]) {
;     ...
;   for (int t = 0; t < nt - 2; t += 2) {
;     LDB(B0, 0, 0); SCHED; LDA(At, 0, 0); STAGE(SA(1, 1), pA1, 1);
;     WAIT_L(8); BAR; WAIT_L(0); MMA(0, 0, At, B0); BAR; SCHED;
;     LDB(B1, 0, 1); STAGE(SB(0, 0), pB0, 2);
;     BAR; WAIT_L(0); MMA(0, 1, At, B1); BAR;
;     LDA(At, 0, 1); STAGE(SA(0, 0), pA0, 2);
;     BAR; WAIT_L(0); MMA(1, 0, At, B0); BAR; SCHED;
.LBB0_767:
	ds_read_b128 v[160:163], v144
	ds_read_b128 v[164:167], v144 offset:1024
	ds_read_b128 v[174:177], v144 offset:2048
	ds_read_b128 v[178:181], v144 offset:3072
	v_lshl_add_u64 v[168:169], s[10:11], 0, v[130:131]
	v_readfirstlane_b32 s22, v143
	v_lshl_add_u64 v[214:215], v[168:169], 0, s[4:5]
	s_mov_b32 m0, s22
	v_lshl_add_u64 v[230:231], s[10:11], 0, v[132:133]
	v_readfirstlane_b32 s22, v142
	ds_read_b128 v[182:185], v138
	ds_read_b128 v[186:189], v138 offset:1024
	ds_read_b128 v[190:193], v137
	ds_read_b128 v[194:197], v137 offset:1024
	ds_read_b128 v[198:201], v136
	ds_read_b128 v[202:205], v136 offset:1024
	ds_read_b128 v[206:209], v135
	ds_read_b128 v[210:213], v135 offset:1024
	global_load_lds_dwordx4 v[214:215], off
	v_lshl_add_u64 v[214:215], v[230:231], 0, s[4:5]
	s_mov_b32 m0, s22
	s_nop 0
	global_load_lds_dwordx4 v[214:215], off
	s_waitcnt lgkmcnt(8)
	s_waitcnt vmcnt(10)
	s_barrier
	s_waitcnt lgkmcnt(0)
	s_waitcnt lgkmcnt(0)
	v_mfma_f32_16x16x32_bf16 v[126:129], v[182:185], v[160:163], v[126:129]
	v_mfma_f32_16x16x32_bf16 v[122:125], v[182:185], v[174:177], v[122:125]
	v_mfma_f32_16x16x32_bf16 v[118:121], v[190:193], v[160:163], v[118:121]
	v_mfma_f32_16x16x32_bf16 v[114:117], v[190:193], v[174:177], v[114:117]
	v_mfma_f32_16x16x32_bf16 v[110:113], v[198:201], v[160:163], v[110:113]
	v_mfma_f32_16x16x32_bf16 v[106:109], v[198:201], v[174:177], v[106:109]
	v_mfma_f32_16x16x32_bf16 v[102:105], v[206:209], v[160:163], v[102:105]
	v_mfma_f32_16x16x32_bf16 v[98:101], v[206:209], v[174:177], v[98:101]
	v_mfma_f32_16x16x32_bf16 v[126:129], v[186:189], v[164:167], v[126:129]
	v_mfma_f32_16x16x32_bf16 v[122:125], v[186:189], v[178:181], v[122:125]
	v_mfma_f32_16x16x32_bf16 v[118:121], v[194:197], v[164:167], v[118:121]
	v_mfma_f32_16x16x32_bf16 v[114:117], v[194:197], v[178:181], v[114:117]
	v_mfma_f32_16x16x32_bf16 v[110:113], v[202:205], v[164:167], v[110:113]
	v_mfma_f32_16x16x32_bf16 v[106:109], v[202:205], v[178:181], v[106:109]
	v_mfma_f32_16x16x32_bf16 v[102:105], v[210:213], v[164:167], v[102:105]
	v_mfma_f32_16x16x32_bf16 v[98:101], v[210:213], v[178:181], v[98:101]
	s_barrier
	v_lshl_add_u64 v[232:233], s[20:21], 0, v[130:131]
	v_readfirstlane_b32 s22, v151
	v_lshl_add_u64 v[234:235], v[232:233], 0, s[6:7]
	s_mov_b32 m0, s22
	ds_read_b128 v[214:217], v141
	ds_read_b128 v[218:221], v141 offset:1024
	ds_read_b128 v[222:225], v141 offset:2048
	ds_read_b128 v[226:229], v141 offset:3072
	global_load_lds_dwordx4 v[234:235], off
	v_lshl_add_u64 v[234:235], s[20:21], 0, v[132:133]
	v_readfirstlane_b32 s22, v152
	v_lshl_add_u64 v[236:237], v[234:235], 0, s[6:7]
	s_mov_b32 m0, s22
	s_add_u32 s20, s20, 0x100
	global_load_lds_dwordx4 v[236:237], off
	s_waitcnt vmcnt(10)
	s_barrier
	s_waitcnt lgkmcnt(0)
	s_addc_u32 s21, s21, 0
	s_waitcnt lgkmcnt(0)
	v_mfma_f32_16x16x32_bf16 v[94:97], v[182:185], v[214:217], v[94:97]
	v_mfma_f32_16x16x32_bf16 v[90:93], v[182:185], v[222:225], v[90:93]
	v_mfma_f32_16x16x32_bf16 v[86:89], v[190:193], v[214:217], v[86:89]
	v_mfma_f32_16x16x32_bf16 v[82:85], v[190:193], v[222:225], v[82:85]
	v_mfma_f32_16x16x32_bf16 v[78:81], v[198:201], v[214:217], v[78:81]
	v_mfma_f32_16x16x32_bf16 v[74:77], v[198:201], v[222:225], v[74:77]
	v_mfma_f32_16x16x32_bf16 v[70:73], v[206:209], v[214:217], v[70:73]
	v_mfma_f32_16x16x32_bf16 v[66:69], v[206:209], v[222:225], v[66:69]
	v_mfma_f32_16x16x32_bf16 v[94:97], v[186:189], v[218:221], v[94:97]
	v_mfma_f32_16x16x32_bf16 v[90:93], v[186:189], v[226:229], v[90:93]
	v_mfma_f32_16x16x32_bf16 v[86:89], v[194:197], v[218:221], v[86:89]
	v_mfma_f32_16x16x32_bf16 v[82:85], v[194:197], v[226:229], v[82:85]
	v_mfma_f32_16x16x32_bf16 v[78:81], v[202:205], v[218:221], v[78:81]
	v_mfma_f32_16x16x32_bf16 v[74:77], v[202:205], v[226:229], v[74:77]
	v_mfma_f32_16x16x32_bf16 v[70:73], v[210:213], v[218:221], v[70:73]
	v_mfma_f32_16x16x32_bf16 v[66:69], v[210:213], v[226:229], v[66:69]
	v_lshl_add_u64 v[236:237], s[18:19], 0, v[130:131]
	v_readfirstlane_b32 s22, v145
	v_lshl_add_u64 v[238:239], v[236:237], 0, s[6:7]
	s_mov_b32 m0, s22
	s_barrier
	ds_read_b128 v[182:185], v138 offset:16384
	ds_read_b128 v[186:189], v138 offset:17408
	ds_read_b128 v[190:193], v137 offset:16384
	ds_read_b128 v[194:197], v137 offset:17408
	ds_read_b128 v[198:201], v136 offset:16384
	ds_read_b128 v[202:205], v136 offset:17408
	ds_read_b128 v[206:209], v135 offset:16384
	ds_read_b128 v[210:213], v135 offset:17408
	global_load_lds_dwordx4 v[238:239], off
	v_lshl_add_u64 v[238:239], s[18:19], 0, v[132:133]
	v_readfirstlane_b32 s22, v146
	v_lshl_add_u64 v[240:241], v[238:239], 0, s[6:7]
	s_mov_b32 m0, s22
	s_add_u32 s18, s18, 0x100
	global_load_lds_dwordx4 v[240:241], off
	s_barrier
	s_waitcnt lgkmcnt(0)
	s_addc_u32 s19, s19, 0
	s_waitcnt lgkmcnt(0)
	v_mfma_f32_16x16x32_bf16 v[62:65], v[182:185], v[160:163], v[62:65]
	v_mfma_f32_16x16x32_bf16 v[58:61], v[182:185], v[174:177], v[58:61]
	v_mfma_f32_16x16x32_bf16 v[54:57], v[190:193], v[160:163], v[54:57]
	v_mfma_f32_16x16x32_bf16 v[50:53], v[190:193], v[174:177], v[50:53]
	v_mfma_f32_16x16x32_bf16 v[46:49], v[198:201], v[160:163], v[46:49]
	v_mfma_f32_16x16x32_bf16 v[42:45], v[198:201], v[174:177], v[42:45]
	v_mfma_f32_16x16x32_bf16 v[38:41], v[206:209], v[160:163], v[38:41]
	v_mfma_f32_16x16x32_bf16 v[34:37], v[206:209], v[174:177], v[34:37]
	v_mfma_f32_16x16x32_bf16 v[62:65], v[186:189], v[164:167], v[62:65]
	v_mfma_f32_16x16x32_bf16 v[58:61], v[186:189], v[178:181], v[58:61]
	v_mfma_f32_16x16x32_bf16 v[54:57], v[194:197], v[164:167], v[54:57]
	v_mfma_f32_16x16x32_bf16 v[50:53], v[194:197], v[178:181], v[50:53]
	v_mfma_f32_16x16x32_bf16 v[46:49], v[202:205], v[164:167], v[46:49]
	v_mfma_f32_16x16x32_bf16 v[42:45], v[202:205], v[178:181], v[42:45]
	v_mfma_f32_16x16x32_bf16 v[38:41], v[210:213], v[164:167], v[38:41]
	v_mfma_f32_16x16x32_bf16 v[34:37], v[210:213], v[178:181], v[34:37]
	s_barrier
; #define STAGE(P, GP, ktrel) do { const GAS char* _g = (GP) + (ktrel) * (BK * 2); \
;     __builtin_amdgcn_global_load_lds((const GAS unsigned*)(_g + so0), (unsigned*)((char*)(P) + tid_ * 16), 16, 0, 0); \
;     __builtin_amdgcn_global_load_lds((const GAS unsigned*)(_g + so1), (unsigned*)((char*)(P) + tid_ * 16 + 8192), 16, 0, 0); } while (0)
; #define WAIT_V(n) asm volatile("s_waitcnt vmcnt(" #n ")" ::: "memory")
; #define WAIT_L(n) asm volatile("s_waitcnt lgkmcnt(" #n ")" ::: "memory")
; #define BAR __builtin_amdgcn_s_barrier()
; #define SCHED __builtin_amdgcn_sched_barrier(0)
; #define LDA(dst, b, h) for (int m = 0; m < 4; ++m) for (int k = 0; k < 2; ++k) \
;     dst[m][k] = *reinterpret_cast<const bf16x8*>((char*)SA(b, h) + lds_byte(wr * 64 + m * 16 + fr, k * 32 + fq * 8))
; #define LDB(dst, b, h) for (int n = 0; n < 2; ++n) for (int k = 0; k < 2; ++k) \
;     dst[n][k] = *reinterpret_cast<const bf16x8*>((char*)SB(b, h) + lds_byte(wc * 32 + n * 16 + fr, k * 32 + fq * 8))
; #define MMA(ai, bj, At_, Bt_) do { __builtin_amdgcn_s_setprio(1); \
;     for (int m = 0; m < 4; ++m) for (int n = 0; n < 2; ++n) for (int k = 0; k < 2; ++k) \
;       acc[ai][bj][m][n] = __builtin_amdgcn_mfma_f32_16x16x32_bf16(At_[m][k], Bt_[n][k], acc[ai][bj][m][n], 0, 0, 0); \
;     __builtin_amdgcn_s_setprio(0); } while (0)
; template <int K, int LD = K>
; __device__ __forceinline__ void gemm_main(const GAS bf16* A, const GAS bf16* Bt, int brow, int bcol, f32x4 (&acc)[2][2][4][2]) {
;     ...
;     WAIT_V(6); BAR; MMA(1, 1, At, B1); BAR;
;     LDB(B0, 1, 0); SCHED; LDA(At, 1, 0); STAGE(SA(0, 1), pA1, 2);
;     WAIT_L(8); BAR; WAIT_L(0); MMA(0, 0, At, B0); BAR; SCHED;
;     LDB(B1, 1, 1); STAGE(SB(1, 0), pB0, 3);
;     BAR; WAIT_L(0); MMA(0, 1, At, B1); BAR;
;     LDA(At, 1, 1); STAGE(SA(1, 0), pA0, 3);
;     BAR; WAIT_L(0); MMA(1, 0, At, B0); BAR; SCHED;
;     STAGE(SB(1, 1), pB1, 3);
;     WAIT_V(6); BAR; MMA(1, 1, At, B1); BAR;
	v_lshl_add_u64 v[240:241], s[16:17], 0, v[130:131]
	v_readfirstlane_b32 s22, v153
	v_lshl_add_u64 v[160:161], v[240:241], 0, s[6:7]
	s_mov_b32 m0, s22
	v_lshl_add_u64 v[242:243], s[16:17], 0, v[132:133]
	v_readfirstlane_b32 s22, v154
	global_load_lds_dwordx4 v[160:161], off
	v_lshl_add_u64 v[160:161], v[242:243], 0, s[6:7]
	s_mov_b32 m0, s22
	s_add_u32 s16, s16, 0x100
	global_load_lds_dwordx4 v[160:161], off
	s_waitcnt vmcnt(10)
	s_addc_u32 s17, s17, 0
	s_barrier
	v_mfma_f32_16x16x32_bf16 v[30:33], v[182:185], v[214:217], v[30:33]
	v_mfma_f32_16x16x32_bf16 v[26:29], v[182:185], v[222:225], v[26:29]
	v_mfma_f32_16x16x32_bf16 v[22:25], v[190:193], v[214:217], v[22:25]
	v_mfma_f32_16x16x32_bf16 v[18:21], v[190:193], v[222:225], v[18:21]
	v_mfma_f32_16x16x32_bf16 v[14:17], v[198:201], v[214:217], v[14:17]
	v_mfma_f32_16x16x32_bf16 v[10:13], v[198:201], v[222:225], v[10:13]
	v_mfma_f32_16x16x32_bf16 v[6:9], v[206:209], v[214:217], v[6:9]
	v_mfma_f32_16x16x32_bf16 v[2:5], v[206:209], v[222:225], v[2:5]
	v_mfma_f32_16x16x32_bf16 v[30:33], v[186:189], v[218:221], v[30:33]
	v_mfma_f32_16x16x32_bf16 v[26:29], v[186:189], v[226:229], v[26:29]
	v_mfma_f32_16x16x32_bf16 v[22:25], v[194:197], v[218:221], v[22:25]
	v_mfma_f32_16x16x32_bf16 v[18:21], v[194:197], v[226:229], v[18:21]
	v_mfma_f32_16x16x32_bf16 v[14:17], v[202:205], v[218:221], v[14:17]
	v_mfma_f32_16x16x32_bf16 v[10:13], v[202:205], v[226:229], v[10:13]
	v_mfma_f32_16x16x32_bf16 v[6:9], v[210:213], v[218:221], v[6:9]
	v_mfma_f32_16x16x32_bf16 v[2:5], v[210:213], v[226:229], v[2:5]
	s_barrier
	ds_read_b128 v[160:163], v140
	ds_read_b128 v[164:167], v140 offset:1024
	ds_read_b128 v[174:177], v140 offset:2048
	ds_read_b128 v[178:181], v140 offset:3072
	v_readfirstlane_b32 s22, v147
	v_lshl_add_u64 v[168:169], v[168:169], 0, s[6:7]
	s_mov_b32 m0, s22
	v_readfirstlane_b32 s22, v148
	ds_read_b128 v[182:185], v138 offset:32768
	ds_read_b128 v[186:189], v138 offset:33792
	ds_read_b128 v[190:193], v137 offset:32768
	ds_read_b128 v[194:197], v137 offset:33792
	ds_read_b128 v[198:201], v136 offset:32768
	ds_read_b128 v[202:205], v136 offset:33792
	ds_read_b128 v[206:209], v135 offset:32768
	ds_read_b128 v[210:213], v135 offset:33792
	global_load_lds_dwordx4 v[168:169], off
	v_lshl_add_u64 v[168:169], v[230:231], 0, s[6:7]
	s_mov_b32 m0, s22
	s_add_u32 s10, s10, 0x100
	global_load_lds_dwordx4 v[168:169], off
	s_waitcnt lgkmcnt(8)
	s_waitcnt vmcnt(10)
	s_barrier
	s_waitcnt lgkmcnt(0)
	s_addc_u32 s11, s11, 0
	s_waitcnt lgkmcnt(0)
	v_mfma_f32_16x16x32_bf16 v[126:129], v[182:185], v[160:163], v[126:129]
	v_mfma_f32_16x16x32_bf16 v[122:125], v[182:185], v[174:177], v[122:125]
	v_mfma_f32_16x16x32_bf16 v[118:121], v[190:193], v[160:163], v[118:121]
	v_mfma_f32_16x16x32_bf16 v[114:117], v[190:193], v[174:177], v[114:117]
	v_mfma_f32_16x16x32_bf16 v[110:113], v[198:201], v[160:163], v[110:113]
	v_mfma_f32_16x16x32_bf16 v[106:109], v[198:201], v[174:177], v[106:109]
	v_mfma_f32_16x16x32_bf16 v[102:105], v[206:209], v[160:163], v[102:105]
	v_mfma_f32_16x16x32_bf16 v[98:101], v[206:209], v[174:177], v[98:101]
	v_mfma_f32_16x16x32_bf16 v[126:129], v[186:189], v[164:167], v[126:129]
	v_mfma_f32_16x16x32_bf16 v[122:125], v[186:189], v[178:181], v[122:125]
	v_mfma_f32_16x16x32_bf16 v[118:121], v[194:197], v[164:167], v[118:121]
	v_mfma_f32_16x16x32_bf16 v[114:117], v[194:197], v[178:181], v[114:117]
	v_mfma_f32_16x16x32_bf16 v[110:113], v[202:205], v[164:167], v[110:113]
	v_mfma_f32_16x16x32_bf16 v[106:109], v[202:205], v[178:181], v[106:109]
	v_mfma_f32_16x16x32_bf16 v[102:105], v[210:213], v[164:167], v[102:105]
	v_mfma_f32_16x16x32_bf16 v[98:101], v[210:213], v[178:181], v[98:101]
	s_barrier
	v_readfirstlane_b32 s22, v155
	v_lshl_add_u64 v[168:169], v[232:233], 0, s[8:9]
	s_mov_b32 m0, s22
	v_readfirstlane_b32 s22, v156
	ds_read_b128 v[214:217], v139
	ds_read_b128 v[218:221], v139 offset:1024
	ds_read_b128 v[222:225], v139 offset:2048
	ds_read_b128 v[226:229], v139 offset:3072
	global_load_lds_dwordx4 v[168:169], off
	v_lshl_add_u64 v[168:169], v[234:235], 0, s[8:9]
	s_mov_b32 m0, s22
	s_nop 0
	global_load_lds_dwordx4 v[168:169], off
	s_waitcnt vmcnt(10)
	s_barrier
	s_waitcnt lgkmcnt(0)
	s_waitcnt lgkmcnt(0)
	v_mfma_f32_16x16x32_bf16 v[94:97], v[182:185], v[214:217], v[94:97]
	v_mfma_f32_16x16x32_bf16 v[90:93], v[182:185], v[222:225], v[90:93]
	v_mfma_f32_16x16x32_bf16 v[86:89], v[190:193], v[214:217], v[86:89]
	v_mfma_f32_16x16x32_bf16 v[82:85], v[190:193], v[222:225], v[82:85]
	v_mfma_f32_16x16x32_bf16 v[78:81], v[198:201], v[214:217], v[78:81]
	v_mfma_f32_16x16x32_bf16 v[74:77], v[198:201], v[222:225], v[74:77]
	v_mfma_f32_16x16x32_bf16 v[70:73], v[206:209], v[214:217], v[70:73]
	v_mfma_f32_16x16x32_bf16 v[66:69], v[206:209], v[222:225], v[66:69]
	v_mfma_f32_16x16x32_bf16 v[94:97], v[186:189], v[218:221], v[94:97]
	v_mfma_f32_16x16x32_bf16 v[90:93], v[186:189], v[226:229], v[90:93]
	v_mfma_f32_16x16x32_bf16 v[86:89], v[194:197], v[218:221], v[86:89]
	v_mfma_f32_16x16x32_bf16 v[82:85], v[194:197], v[226:229], v[82:85]
	v_mfma_f32_16x16x32_bf16 v[78:81], v[202:205], v[218:221], v[78:81]
	v_mfma_f32_16x16x32_bf16 v[74:77], v[202:205], v[226:229], v[74:77]
	v_mfma_f32_16x16x32_bf16 v[70:73], v[210:213], v[218:221], v[70:73]
	v_mfma_f32_16x16x32_bf16 v[66:69], v[210:213], v[226:229], v[66:69]
	v_readfirstlane_b32 s22, v149
	v_lshl_add_u64 v[168:169], v[236:237], 0, s[8:9]
	s_mov_b32 m0, s22
	v_readfirstlane_b32 s22, v150
	s_barrier
; #define STAGE(P, GP, ktrel) do { const GAS char* _g = (GP) + (ktrel) * (BK * 2); \
;     __builtin_amdgcn_global_load_lds((const GAS unsigned*)(_g + so0), (unsigned*)((char*)(P) + tid_ * 16), 16, 0, 0); \
;     __builtin_amdgcn_global_load_lds((const GAS unsigned*)(_g + so1), (unsigned*)((char*)(P) + tid_ * 16 + 8192), 16, 0, 0); } while (0)
; #define WAIT_V(n) asm volatile("s_waitcnt vmcnt(" #n ")" ::: "memory")
; #define WAIT_L(n) asm volatile("s_waitcnt lgkmcnt(" #n ")" ::: "memory")
; #define BAR __builtin_amdgcn_s_barrier()
; #define SCHED __builtin_amdgcn_sched_barrier(0)
; #define LDA(dst, b, h) for (int m = 0; m < 4; ++m) for (int k = 0; k < 2; ++k) \
;     dst[m][k] = *reinterpret_cast<const bf16x8*>((char*)SA(b, h) + lds_byte(wr * 64 + m * 16 + fr, k * 32 + fq * 8))
; #define LDB(dst, b, h) for (int n = 0; n < 2; ++n) for (int k = 0; k < 2; ++k) \
;     dst[n][k] = *reinterpret_cast<const bf16x8*>((char*)SB(b, h) + lds_byte(wc * 32 + n * 16 + fr, k * 32 + fq * 8))
; #define MMA(ai, bj, At_, Bt_) do { __builtin_amdgcn_s_setprio(1); \
;     for (int m = 0; m < 4; ++m) for (int n = 0; n < 2; ++n) for (int k = 0; k < 2; ++k) \
;       acc[ai][bj][m][n] = __builtin_amdgcn_mfma_f32_16x16x32_bf16(At_[m][k], Bt_[n][k], acc[ai][bj][m][n], 0, 0, 0); \
;     __builtin_amdgcn_s_setprio(0); } while (0)
; template <int K, int LD = K>
; __device__ __forceinline__ void gemm_main(const GAS bf16* A, const GAS bf16* Bt, int brow, int bcol, f32x4 (&acc)[2][2][4][2]) {
;     ...
;     LDA(At, 1, 1); STAGE(SA(1, 0), pA0, 3);
;     BAR; WAIT_L(0); MMA(1, 0, At, B0); BAR; SCHED;
;     STAGE(SB(1, 1), pB1, 3);
;     WAIT_V(6); BAR; MMA(1, 1, At, B1); BAR;
;     pA0 += 4 * BK; pA1 += 4 * BK; pB0 += 4 * BK; pB1 += 4 * BK;
;     asm volatile("" : "+s"(pA0), "+s"(pA1), "+s"(pB0), "+s"(pB1));
;   }
;   { LDB(B0, 0, 0); LDA(At, 0, 0); STAGE(SA(1, 1), pA1, 1);
;     BAR; WAIT_L(0); MMA(0, 0, At, B0); BAR;
	ds_read_b128 v[182:185], v138 offset:49152
	ds_read_b128 v[186:189], v138 offset:50176
	ds_read_b128 v[190:193], v137 offset:49152
	ds_read_b128 v[194:197], v137 offset:50176
	ds_read_b128 v[198:201], v136 offset:49152
	ds_read_b128 v[202:205], v136 offset:50176
	ds_read_b128 v[206:209], v135 offset:49152
	ds_read_b128 v[210:213], v135 offset:50176
	global_load_lds_dwordx4 v[168:169], off
	v_lshl_add_u64 v[168:169], v[238:239], 0, s[8:9]
	s_mov_b32 m0, s22
	s_nop 0
	global_load_lds_dwordx4 v[168:169], off
	s_barrier
	s_waitcnt lgkmcnt(0)
	s_waitcnt lgkmcnt(0)
	v_mfma_f32_16x16x32_bf16 v[62:65], v[182:185], v[160:163], v[62:65]
	v_mfma_f32_16x16x32_bf16 v[58:61], v[182:185], v[174:177], v[58:61]
	v_mfma_f32_16x16x32_bf16 v[54:57], v[190:193], v[160:163], v[54:57]
	v_mfma_f32_16x16x32_bf16 v[50:53], v[190:193], v[174:177], v[50:53]
	v_mfma_f32_16x16x32_bf16 v[46:49], v[198:201], v[160:163], v[46:49]
	v_mfma_f32_16x16x32_bf16 v[42:45], v[198:201], v[174:177], v[42:45]
	v_mfma_f32_16x16x32_bf16 v[38:41], v[206:209], v[160:163], v[38:41]
	v_mfma_f32_16x16x32_bf16 v[34:37], v[206:209], v[174:177], v[34:37]
	v_mfma_f32_16x16x32_bf16 v[62:65], v[186:189], v[164:167], v[62:65]
	v_mfma_f32_16x16x32_bf16 v[58:61], v[186:189], v[178:181], v[58:61]
	v_mfma_f32_16x16x32_bf16 v[54:57], v[194:197], v[164:167], v[54:57]
	v_mfma_f32_16x16x32_bf16 v[50:53], v[194:197], v[178:181], v[50:53]
	v_mfma_f32_16x16x32_bf16 v[46:49], v[202:205], v[164:167], v[46:49]
	v_mfma_f32_16x16x32_bf16 v[42:45], v[202:205], v[178:181], v[42:45]
	v_mfma_f32_16x16x32_bf16 v[38:41], v[210:213], v[164:167], v[38:41]
	v_mfma_f32_16x16x32_bf16 v[34:37], v[210:213], v[178:181], v[34:37]
	s_barrier
	v_readfirstlane_b32 s22, v157
	v_lshl_add_u64 v[160:161], v[240:241], 0, s[8:9]
	s_mov_b32 m0, s22
	v_readfirstlane_b32 s22, v158
	global_load_lds_dwordx4 v[160:161], off
	v_lshl_add_u64 v[160:161], v[242:243], 0, s[8:9]
	s_mov_b32 m0, s22
	s_nop 0
	global_load_lds_dwordx4 v[160:161], off
	s_waitcnt vmcnt(10)
	s_barrier
	v_mfma_f32_16x16x32_bf16 v[30:33], v[182:185], v[214:217], v[30:33]
	v_mfma_f32_16x16x32_bf16 v[26:29], v[182:185], v[222:225], v[26:29]
	v_mfma_f32_16x16x32_bf16 v[22:25], v[190:193], v[214:217], v[22:25]
	v_mfma_f32_16x16x32_bf16 v[18:21], v[190:193], v[222:225], v[18:21]
	v_mfma_f32_16x16x32_bf16 v[14:17], v[198:201], v[214:217], v[14:17]
	v_mfma_f32_16x16x32_bf16 v[10:13], v[198:201], v[222:225], v[10:13]
	v_mfma_f32_16x16x32_bf16 v[6:9], v[206:209], v[214:217], v[6:9]
	v_mfma_f32_16x16x32_bf16 v[2:5], v[206:209], v[222:225], v[2:5]
	v_mfma_f32_16x16x32_bf16 v[30:33], v[186:189], v[218:221], v[30:33]
	v_mfma_f32_16x16x32_bf16 v[26:29], v[186:189], v[226:229], v[26:29]
	v_mfma_f32_16x16x32_bf16 v[22:25], v[194:197], v[218:221], v[22:25]
	v_mfma_f32_16x16x32_bf16 v[18:21], v[194:197], v[226:229], v[18:21]
	v_mfma_f32_16x16x32_bf16 v[14:17], v[202:205], v[218:221], v[14:17]
	v_mfma_f32_16x16x32_bf16 v[10:13], v[202:205], v[226:229], v[10:13]
	v_mfma_f32_16x16x32_bf16 v[6:9], v[210:213], v[218:221], v[6:9]
	v_mfma_f32_16x16x32_bf16 v[2:5], v[210:213], v[226:229], v[2:5]
	s_add_i32 s15, s15, 2
	s_cmp_lt_u32 s15, 12
	s_barrier
	s_cbranch_scc1 .LBB0_767
	ds_read_b128 v[146:149], v144
	ds_read_b128 v[150:153], v144 offset:1024
	ds_read_b128 v[154:157], v144 offset:2048
	ds_read_b128 v[158:161], v144 offset:3072
	ds_read_b128 v[162:165], v138
	ds_read_b128 v[166:169], v138 offset:1024
	ds_read_b128 v[174:177], v137
	ds_read_b128 v[178:181], v137 offset:1024
	ds_read_b128 v[182:185], v136
	ds_read_b128 v[186:189], v136 offset:1024
	ds_read_b128 v[190:193], v135
	ds_read_b128 v[194:197], v135 offset:1024
	v_lshl_add_u64 v[144:145], s[10:11], 0, v[130:131]
	v_readfirstlane_b32 s15, v143
	v_lshl_add_u64 v[144:145], v[144:145], 0, s[4:5]
	s_mov_b32 m0, s15
	v_lshl_add_u64 v[132:133], s[10:11], 0, v[132:133]
	v_readfirstlane_b32 s10, v142
	global_load_lds_dwordx4 v[144:145], off
	v_lshl_add_u64 v[132:133], v[132:133], 0, s[4:5]
	s_mov_b32 m0, s10
	s_nop 0
	global_load_lds_dwordx4 v[132:133], off
	s_waitcnt vmcnt(10)
	s_barrier
	s_waitcnt lgkmcnt(0)
	s_waitcnt lgkmcnt(0)
	v_mfma_f32_16x16x32_bf16 v[126:129], v[162:165], v[146:149], v[126:129]
	v_mfma_f32_16x16x32_bf16 v[122:125], v[162:165], v[154:157], v[122:125]
	v_mfma_f32_16x16x32_bf16 v[110:113], v[182:185], v[146:149], v[110:113]
	v_mfma_f32_16x16x32_bf16 v[106:109], v[182:185], v[154:157], v[106:109]
	v_mfma_f32_16x16x32_bf16 v[126:129], v[166:169], v[150:153], v[126:129]
	v_mfma_f32_16x16x32_bf16 v[122:125], v[166:169], v[158:161], v[122:125]
	v_mfma_f32_16x16x32_bf16 v[118:121], v[174:177], v[146:149], v[118:121]
	v_mfma_f32_16x16x32_bf16 v[114:117], v[174:177], v[154:157], v[114:117]
	v_mfma_f32_16x16x32_bf16 v[110:113], v[186:189], v[150:153], v[110:113]
	v_mfma_f32_16x16x32_bf16 v[106:109], v[186:189], v[158:161], v[106:109]
	v_mfma_f32_16x16x32_bf16 v[102:105], v[190:193], v[146:149], v[102:105]
	v_mfma_f32_16x16x32_bf16 v[98:101], v[190:193], v[154:157], v[98:101]
	v_mfma_f32_16x16x32_bf16 v[142:145], v[178:181], v[150:153], v[118:121]
	v_mfma_f32_16x16x32_bf16 v[198:201], v[178:181], v[158:161], v[114:117]
	v_mfma_f32_16x16x32_bf16 v[202:205], v[194:197], v[150:153], v[102:105]
	v_mfma_f32_16x16x32_bf16 v[206:209], v[194:197], v[158:161], v[98:101]
	s_barrier
	s_nop 1
	ds_read_b128 v[98:101], v141
	ds_read_b128 v[102:105], v141 offset:1024
	ds_read_b128 v[114:117], v141 offset:2048
	ds_read_b128 v[118:121], v141 offset:3072
	s_waitcnt vmcnt(8)
	s_barrier
; #define WAIT_V(n) asm volatile("s_waitcnt vmcnt(" #n ")" ::: "memory")
; #define WAIT_L(n) asm volatile("s_waitcnt lgkmcnt(" #n ")" ::: "memory")
; #define BAR __builtin_amdgcn_s_barrier()
; #define LDA(dst, b, h) for (int m = 0; m < 4; ++m) for (int k = 0; k < 2; ++k) \
;     dst[m][k] = *reinterpret_cast<const bf16x8*>((char*)SA(b, h) + lds_byte(wr * 64 + m * 16 + fr, k * 32 + fq * 8))
; #define LDB(dst, b, h) for (int n = 0; n < 2; ++n) for (int k = 0; k < 2; ++k) \
;     dst[n][k] = *reinterpret_cast<const bf16x8*>((char*)SB(b, h) + lds_byte(wc * 32 + n * 16 + fr, k * 32 + fq * 8))
; #define MMA(ai, bj, At_, Bt_) do { __builtin_amdgcn_s_setprio(1); \
;     for (int m = 0; m < 4; ++m) for (int n = 0; n < 2; ++n) for (int k = 0; k < 2; ++k) \
;       acc[ai][bj][m][n] = __builtin_amdgcn_mfma_f32_16x16x32_bf16(At_[m][k], Bt_[n][k], acc[ai][bj][m][n], 0, 0, 0); \
;     __builtin_amdgcn_s_setprio(0); } while (0)
; template <int K, int LD = K>
; __device__ __forceinline__ void gemm_main(const GAS bf16* A, const GAS bf16* Bt, int brow, int bcol, f32x4 (&acc)[2][2][4][2]) {
;     ...
;     LDB(B1, 0, 1); BAR; WAIT_L(0); MMA(0, 1, At, B1); BAR;
;     LDA(At, 0, 1); WAIT_V(4); BAR; WAIT_L(0); MMA(1, 0, At, B0); MMA(1, 1, At, B1); BAR; }
;   { LDB(B0, 1, 0); LDA(At, 1, 0); WAIT_V(2); BAR; WAIT_L(0); MMA(0, 0, At, B0); BAR;
	s_waitcnt lgkmcnt(0)
	s_waitcnt lgkmcnt(0)
	v_mfma_f32_16x16x32_bf16 v[94:97], v[162:165], v[98:101], v[94:97]
	v_mfma_f32_16x16x32_bf16 v[90:93], v[162:165], v[114:117], v[90:93]
	v_mfma_f32_16x16x32_bf16 v[78:81], v[182:185], v[98:101], v[78:81]
	v_mfma_f32_16x16x32_bf16 v[74:77], v[182:185], v[114:117], v[74:77]
	v_mfma_f32_16x16x32_bf16 v[94:97], v[166:169], v[102:105], v[94:97]
	v_mfma_f32_16x16x32_bf16 v[90:93], v[166:169], v[118:121], v[90:93]
	v_mfma_f32_16x16x32_bf16 v[86:89], v[174:177], v[98:101], v[86:89]
	v_mfma_f32_16x16x32_bf16 v[82:85], v[174:177], v[114:117], v[82:85]
	v_mfma_f32_16x16x32_bf16 v[78:81], v[186:189], v[102:105], v[78:81]
	v_mfma_f32_16x16x32_bf16 v[74:77], v[186:189], v[118:121], v[74:77]
	v_mfma_f32_16x16x32_bf16 v[70:73], v[190:193], v[98:101], v[70:73]
	v_mfma_f32_16x16x32_bf16 v[66:69], v[190:193], v[114:117], v[66:69]
	v_mfma_f32_16x16x32_bf16 v[162:165], v[178:181], v[102:105], v[86:89]
	v_mfma_f32_16x16x32_bf16 v[166:169], v[178:181], v[118:121], v[82:85]
	v_mfma_f32_16x16x32_bf16 v[174:177], v[194:197], v[102:105], v[70:73]
	v_mfma_f32_16x16x32_bf16 v[178:181], v[194:197], v[118:121], v[66:69]
	s_barrier
	s_nop 1
	ds_read_b128 v[66:69], v138 offset:16384
	ds_read_b128 v[70:73], v138 offset:17408
	ds_read_b128 v[82:85], v137 offset:16384
	ds_read_b128 v[86:89], v137 offset:17408
	ds_read_b128 v[182:185], v136 offset:16384
	ds_read_b128 v[186:189], v136 offset:17408
	ds_read_b128 v[190:193], v135 offset:16384
	ds_read_b128 v[194:197], v135 offset:17408
	s_waitcnt vmcnt(4)
	s_barrier
	s_waitcnt lgkmcnt(0)
	s_waitcnt lgkmcnt(0)
	v_mfma_f32_16x16x32_bf16 v[62:65], v[66:69], v[146:149], v[62:65]
	v_mfma_f32_16x16x32_bf16 v[58:61], v[66:69], v[154:157], v[58:61]
	v_mfma_f32_16x16x32_bf16 v[46:49], v[182:185], v[146:149], v[46:49]
	v_mfma_f32_16x16x32_bf16 v[42:45], v[182:185], v[154:157], v[42:45]
	v_mfma_f32_16x16x32_bf16 v[62:65], v[70:73], v[150:153], v[62:65]
	v_mfma_f32_16x16x32_bf16 v[58:61], v[70:73], v[158:161], v[58:61]
	v_mfma_f32_16x16x32_bf16 v[54:57], v[82:85], v[146:149], v[54:57]
	v_mfma_f32_16x16x32_bf16 v[50:53], v[82:85], v[154:157], v[50:53]
	v_mfma_f32_16x16x32_bf16 v[46:49], v[186:189], v[150:153], v[46:49]
	v_mfma_f32_16x16x32_bf16 v[42:45], v[186:189], v[158:161], v[42:45]
	v_mfma_f32_16x16x32_bf16 v[38:41], v[190:193], v[146:149], v[38:41]
	v_mfma_f32_16x16x32_bf16 v[34:37], v[190:193], v[154:157], v[34:37]
	v_mfma_f32_16x16x32_bf16 v[210:213], v[86:89], v[150:153], v[54:57]
	v_mfma_f32_16x16x32_bf16 v[214:217], v[86:89], v[158:161], v[50:53]
	v_mfma_f32_16x16x32_bf16 v[146:149], v[194:197], v[150:153], v[38:41]
	v_mfma_f32_16x16x32_bf16 v[150:153], v[194:197], v[158:161], v[34:37]
	v_mfma_f32_16x16x32_bf16 v[30:33], v[66:69], v[98:101], v[30:33]
	v_mfma_f32_16x16x32_bf16 v[26:29], v[66:69], v[114:117], v[26:29]
	v_mfma_f32_16x16x32_bf16 v[14:17], v[182:185], v[98:101], v[14:17]
	v_mfma_f32_16x16x32_bf16 v[10:13], v[182:185], v[114:117], v[10:13]
	v_mfma_f32_16x16x32_bf16 v[30:33], v[70:73], v[102:105], v[30:33]
	v_mfma_f32_16x16x32_bf16 v[26:29], v[70:73], v[118:121], v[26:29]
	v_mfma_f32_16x16x32_bf16 v[22:25], v[82:85], v[98:101], v[22:25]
	v_mfma_f32_16x16x32_bf16 v[18:21], v[82:85], v[114:117], v[18:21]
	v_mfma_f32_16x16x32_bf16 v[14:17], v[186:189], v[102:105], v[14:17]
	v_mfma_f32_16x16x32_bf16 v[10:13], v[186:189], v[118:121], v[10:13]
	v_mfma_f32_16x16x32_bf16 v[6:9], v[190:193], v[98:101], v[6:9]
	v_mfma_f32_16x16x32_bf16 v[2:5], v[190:193], v[114:117], v[2:5]
	v_mfma_f32_16x16x32_bf16 v[154:157], v[86:89], v[102:105], v[22:25]
	v_mfma_f32_16x16x32_bf16 v[158:161], v[86:89], v[118:121], v[18:21]
	v_mfma_f32_16x16x32_bf16 v[182:185], v[194:197], v[102:105], v[6:9]
	v_mfma_f32_16x16x32_bf16 v[186:189], v[194:197], v[118:121], v[2:5]
	s_barrier
	s_nop 1
	ds_read_b128 v[2:5], v140
	ds_read_b128 v[6:9], v140 offset:1024
	ds_read_b128 v[190:193], v140 offset:2048
	ds_read_b128 v[194:197], v140 offset:3072
	ds_read_b128 v[18:21], v138 offset:32768
	ds_read_b128 v[22:25], v138 offset:33792
	ds_read_b128 v[34:37], v137 offset:32768
	ds_read_b128 v[38:41], v137 offset:33792
	ds_read_b128 v[50:53], v136 offset:32768
	ds_read_b128 v[54:57], v136 offset:33792
	ds_read_b128 v[218:221], v135 offset:32768
	ds_read_b128 v[222:225], v135 offset:33792
	s_waitcnt vmcnt(2)
	s_barrier
; #define WAIT_V(n) asm volatile("s_waitcnt vmcnt(" #n ")" ::: "memory")
; #define WAIT_L(n) asm volatile("s_waitcnt lgkmcnt(" #n ")" ::: "memory")
; #define BAR __builtin_amdgcn_s_barrier()
; #define LDA(dst, b, h) for (int m = 0; m < 4; ++m) for (int k = 0; k < 2; ++k) \
;     dst[m][k] = *reinterpret_cast<const bf16x8*>((char*)SA(b, h) + lds_byte(wr * 64 + m * 16 + fr, k * 32 + fq * 8))
; #define LDB(dst, b, h) for (int n = 0; n < 2; ++n) for (int k = 0; k < 2; ++k) \
;     dst[n][k] = *reinterpret_cast<const bf16x8*>((char*)SB(b, h) + lds_byte(wc * 32 + n * 16 + fr, k * 32 + fq * 8))
; #define MMA(ai, bj, At_, Bt_) do { __builtin_amdgcn_s_setprio(1); \
;     for (int m = 0; m < 4; ++m) for (int n = 0; n < 2; ++n) for (int k = 0; k < 2; ++k) \
;       acc[ai][bj][m][n] = __builtin_amdgcn_mfma_f32_16x16x32_bf16(At_[m][k], Bt_[n][k], acc[ai][bj][m][n], 0, 0, 0); \
;     __builtin_amdgcn_s_setprio(0); } while (0)
; template <int K, int LD = K>
; __device__ __forceinline__ void gemm_main(const GAS bf16* A, const GAS bf16* Bt, int brow, int bcol, f32x4 (&acc)[2][2][4][2]) {
;     ...
;   { LDB(B0, 1, 0); LDA(At, 1, 0); WAIT_V(2); BAR; WAIT_L(0); MMA(0, 0, At, B0); BAR;
;     LDB(B1, 1, 1); WAIT_V(0); BAR; WAIT_L(0); MMA(0, 1, At, B1); BAR;
;     LDA(At, 1, 1); BAR; WAIT_L(0); MMA(1, 0, At, B0); MMA(1, 1, At, B1); BAR; }
;   if (wr == 0) BAR;
	s_waitcnt lgkmcnt(0)
	s_waitcnt lgkmcnt(0)
	v_mfma_f32_16x16x32_bf16 v[66:69], v[18:21], v[2:5], v[126:129]
	v_mfma_f32_16x16x32_bf16 v[118:121], v[22:25], v[6:9], v[66:69]
	v_mfma_f32_16x16x32_bf16 v[66:69], v[18:21], v[190:193], v[122:125]
	v_mfma_f32_16x16x32_bf16 v[114:117], v[22:25], v[194:197], v[66:69]
	v_mfma_f32_16x16x32_bf16 v[66:69], v[34:37], v[2:5], v[142:145]
	v_mfma_f32_16x16x32_bf16 v[102:105], v[38:41], v[6:9], v[66:69]
	v_mfma_f32_16x16x32_bf16 v[66:69], v[34:37], v[190:193], v[198:201]
	v_mfma_f32_16x16x32_bf16 v[98:101], v[38:41], v[194:197], v[66:69]
	v_mfma_f32_16x16x32_bf16 v[66:69], v[50:53], v[2:5], v[110:113]
	v_mfma_f32_16x16x32_bf16 v[86:89], v[54:57], v[6:9], v[66:69]
	v_mfma_f32_16x16x32_bf16 v[66:69], v[50:53], v[190:193], v[106:109]
	v_mfma_f32_16x16x32_bf16 v[82:85], v[54:57], v[194:197], v[66:69]
	v_mfma_f32_16x16x32_bf16 v[66:69], v[218:221], v[2:5], v[202:205]
	v_mfma_f32_16x16x32_bf16 v[70:73], v[222:225], v[6:9], v[66:69]
	v_mfma_f32_16x16x32_bf16 v[66:69], v[218:221], v[190:193], v[206:209]
	v_mfma_f32_16x16x32_bf16 v[66:69], v[222:225], v[194:197], v[66:69]
	s_barrier
	ds_read_b128 v[140:143], v139
	ds_read_b128 v[198:201], v139 offset:1024
	ds_read_b128 v[202:205], v139 offset:2048
	ds_read_b128 v[206:209], v139 offset:3072
	s_waitcnt vmcnt(0)
	s_barrier
	s_waitcnt lgkmcnt(0)
	s_waitcnt lgkmcnt(0)
	v_mfma_f32_16x16x32_bf16 v[94:97], v[18:21], v[140:143], v[94:97]
	v_mfma_f32_16x16x32_bf16 v[18:21], v[18:21], v[202:205], v[90:93]
	v_mfma_f32_16x16x32_bf16 v[122:125], v[22:25], v[206:209], v[18:21]
	v_mfma_f32_16x16x32_bf16 v[18:21], v[34:37], v[140:143], v[162:165]
	v_mfma_f32_16x16x32_bf16 v[110:113], v[38:41], v[198:201], v[18:21]
	v_mfma_f32_16x16x32_bf16 v[18:21], v[34:37], v[202:205], v[166:169]
	v_mfma_f32_16x16x32_bf16 v[106:109], v[38:41], v[206:209], v[18:21]
	v_mfma_f32_16x16x32_bf16 v[18:21], v[50:53], v[140:143], v[78:81]
	v_mfma_f32_16x16x32_bf16 v[126:129], v[22:25], v[198:201], v[94:97]
	v_mfma_f32_16x16x32_bf16 v[94:97], v[54:57], v[198:201], v[18:21]
	v_mfma_f32_16x16x32_bf16 v[18:21], v[50:53], v[202:205], v[74:77]
	v_mfma_f32_16x16x32_bf16 v[90:93], v[54:57], v[206:209], v[18:21]
	v_mfma_f32_16x16x32_bf16 v[18:21], v[218:221], v[140:143], v[174:177]
	v_mfma_f32_16x16x32_bf16 v[78:81], v[222:225], v[198:201], v[18:21]
	v_mfma_f32_16x16x32_bf16 v[18:21], v[218:221], v[202:205], v[178:181]
	v_mfma_f32_16x16x32_bf16 v[74:77], v[222:225], v[206:209], v[18:21]
	s_barrier
	ds_read_b128 v[162:165], v138 offset:49152
	ds_read_b128 v[166:169], v138 offset:50176
	ds_read_b128 v[174:177], v137 offset:49152
	ds_read_b128 v[178:181], v137 offset:50176
	ds_read_b128 v[218:221], v136 offset:49152
	ds_read_b128 v[136:139], v136 offset:50176
	ds_read_b128 v[222:225], v135 offset:49152
	ds_read_b128 v[226:229], v135 offset:50176
	s_barrier
	s_waitcnt lgkmcnt(0)
	s_waitcnt lgkmcnt(0)
	v_mfma_f32_16x16x32_bf16 v[18:21], v[162:165], v[2:5], v[62:65]
	v_mfma_f32_16x16x32_bf16 v[54:57], v[166:169], v[6:9], v[18:21]
	v_mfma_f32_16x16x32_bf16 v[18:21], v[162:165], v[190:193], v[58:61]
	v_mfma_f32_16x16x32_bf16 v[50:53], v[166:169], v[194:197], v[18:21]
	v_mfma_f32_16x16x32_bf16 v[18:21], v[174:177], v[2:5], v[210:213]
	v_mfma_f32_16x16x32_bf16 v[38:41], v[178:181], v[6:9], v[18:21]
	v_mfma_f32_16x16x32_bf16 v[18:21], v[174:177], v[190:193], v[214:217]
	v_mfma_f32_16x16x32_bf16 v[34:37], v[178:181], v[194:197], v[18:21]
	v_mfma_f32_16x16x32_bf16 v[18:21], v[218:221], v[2:5], v[46:49]
	v_mfma_f32_16x16x32_bf16 v[2:5], v[222:225], v[2:5], v[146:149]
	v_mfma_f32_16x16x32_bf16 v[22:25], v[136:139], v[6:9], v[18:21]
	v_mfma_f32_16x16x32_bf16 v[18:21], v[218:221], v[190:193], v[42:45]
	v_mfma_f32_16x16x32_bf16 v[6:9], v[226:229], v[6:9], v[2:5]
	v_mfma_f32_16x16x32_bf16 v[2:5], v[222:225], v[190:193], v[150:153]
	v_mfma_f32_16x16x32_bf16 v[18:21], v[136:139], v[194:197], v[18:21]
	v_mfma_f32_16x16x32_bf16 v[2:5], v[226:229], v[194:197], v[2:5]
	v_mfma_f32_16x16x32_bf16 v[26:29], v[162:165], v[202:205], v[26:29]
	v_mfma_f32_16x16x32_bf16 v[58:61], v[166:169], v[206:209], v[26:29]
	v_mfma_f32_16x16x32_bf16 v[26:29], v[174:177], v[140:143], v[154:157]
	v_mfma_f32_16x16x32_bf16 v[46:49], v[178:181], v[198:201], v[26:29]
	v_mfma_f32_16x16x32_bf16 v[26:29], v[174:177], v[202:205], v[158:161]
	v_mfma_f32_16x16x32_bf16 v[10:13], v[218:221], v[202:205], v[10:13]
	v_mfma_f32_16x16x32_bf16 v[30:33], v[162:165], v[140:143], v[30:33]
	v_mfma_f32_16x16x32_bf16 v[42:45], v[178:181], v[206:209], v[26:29]
	v_mfma_f32_16x16x32_bf16 v[14:17], v[218:221], v[140:143], v[14:17]
	v_mfma_f32_16x16x32_bf16 v[26:29], v[136:139], v[206:209], v[10:13]
	v_mfma_f32_16x16x32_bf16 v[10:13], v[222:225], v[140:143], v[182:185]
	v_mfma_f32_16x16x32_bf16 v[62:65], v[166:169], v[198:201], v[30:33]
	v_mfma_f32_16x16x32_bf16 v[30:33], v[136:139], v[198:201], v[14:17]
	v_mfma_f32_16x16x32_bf16 v[14:17], v[226:229], v[198:201], v[10:13]
	v_mfma_f32_16x16x32_bf16 v[10:13], v[222:225], v[202:205], v[186:189]
	v_mfma_f32_16x16x32_bf16 v[10:13], v[226:229], v[206:209], v[10:13]
	v_cmp_gt_u32_e32 vcc, s34, v134
	s_barrier
	s_and_saveexec_b64 s[10:11], vcc
	s_cbranch_execz .LBB0_770
	s_barrier

; #define STAGE(P, GP, ktrel) do { const GAS char* _g = (GP) + (ktrel) * (BK * 2); \
;     __builtin_amdgcn_global_load_lds((const GAS unsigned*)(_g + so0), (unsigned*)((char*)(P) + tid_ * 16), 16, 0, 0); \
;     __builtin_amdgcn_global_load_lds((const GAS unsigned*)(_g + so1), (unsigned*)((char*)(P) + tid_ * 16 + 8192), 16, 0, 0); } while (0)
; #define WAIT_L(n) asm volatile("s_waitcnt lgkmcnt(" #n ")" ::: "memory")
; #define BAR __builtin_amdgcn_s_barrier()
; #define SCHED __builtin_amdgcn_sched_barrier(0)
; #define LDA(dst, b, h) for (int m = 0; m < 4; ++m) for (int k = 0; k < 2; ++k) \
;     dst[m][k] = *reinterpret_cast<const bf16x8*>((char*)SA(b, h) + lds_byte(wr * 64 + m * 16 + fr, k * 32 + fq * 8))
; #define LDB(dst, b, h) for (int n = 0; n < 2; ++n) for (int k = 0; k < 2; ++k) \
;     dst[n][k] = *reinterpret_cast<const bf16x8*>((char*)SB(b, h) + lds_byte(wc * 32 + n * 16 + fr, k * 32 + fq * 8))
; #define MMA(ai, bj, At_, Bt_) do { __builtin_amdgcn_s_setprio(1); \
;     for (int m = 0; m < 4; ++m) for (int n = 0; n < 2; ++n) for (int k = 0; k < 2; ++k) \
;       acc[ai][bj][m][n] = __builtin_amdgcn_mfma_f32_16x16x32_bf16(At_[m][k], Bt_[n][k], acc[ai][bj][m][n], 0, 0, 0); \
;     __builtin_amdgcn_s_setprio(0); } while (0)
; template <int K, int LD = K>
; __device__ __forceinline__ void gemm_main(const GAS bf16* A, const GAS bf16* Bt, int brow, int bcol, f32x4 (&acc)[2][2][4][2]) {
;     ...
;     LDB(B0, 0, 0); SCHED; LDA(At, 0, 0); STAGE(SA(1, 1), pA1, 1);
;     WAIT_L(8); BAR; WAIT_L(0); MMA(0, 0, At, B0); BAR; SCHED;
;     LDB(B1, 0, 1); STAGE(SB(0, 0), pB0, 2);
;     BAR; WAIT_L(0); MMA(0, 1, At, B1); BAR;
;     LDA(At, 0, 1); STAGE(SA(0, 0), pA0, 2);
;     BAR; WAIT_L(0); MMA(1, 0, At, B0); BAR; SCHED;
.LBB0_884:
	ds_read_b128 v[160:163], v145
	ds_read_b128 v[164:167], v145 offset:1024
	ds_read_b128 v[174:177], v145 offset:2048
	ds_read_b128 v[178:181], v145 offset:3072
	v_lshl_add_u64 v[168:169], s[12:13], 0, v[130:131]
	v_readfirstlane_b32 s22, v144
	v_lshl_add_u64 v[214:215], v[168:169], 0, s[6:7]
	s_mov_b32 m0, s22
	v_lshl_add_u64 v[230:231], s[12:13], 0, v[132:133]
	v_readfirstlane_b32 s22, v143
	ds_read_b128 v[182:185], v139
	ds_read_b128 v[186:189], v139 offset:1024
	ds_read_b128 v[190:193], v138
	ds_read_b128 v[194:197], v138 offset:1024
	ds_read_b128 v[198:201], v137
	ds_read_b128 v[202:205], v137 offset:1024
	ds_read_b128 v[206:209], v136
	ds_read_b128 v[210:213], v136 offset:1024
	global_load_lds_dwordx4 v[214:215], off
	v_lshl_add_u64 v[214:215], v[230:231], 0, s[6:7]
	s_mov_b32 m0, s22
	s_nop 0
	global_load_lds_dwordx4 v[214:215], off
	s_waitcnt lgkmcnt(8)
	s_waitcnt vmcnt(10)
	s_barrier
	s_waitcnt lgkmcnt(0)
	s_waitcnt lgkmcnt(0)
	v_mfma_f32_16x16x32_bf16 v[126:129], v[182:185], v[160:163], v[126:129]
	v_mfma_f32_16x16x32_bf16 v[122:125], v[182:185], v[174:177], v[122:125]
	v_mfma_f32_16x16x32_bf16 v[118:121], v[190:193], v[160:163], v[118:121]
	v_mfma_f32_16x16x32_bf16 v[114:117], v[190:193], v[174:177], v[114:117]
	v_mfma_f32_16x16x32_bf16 v[110:113], v[198:201], v[160:163], v[110:113]
	v_mfma_f32_16x16x32_bf16 v[106:109], v[198:201], v[174:177], v[106:109]
	v_mfma_f32_16x16x32_bf16 v[102:105], v[206:209], v[160:163], v[102:105]
	v_mfma_f32_16x16x32_bf16 v[98:101], v[206:209], v[174:177], v[98:101]
	v_mfma_f32_16x16x32_bf16 v[126:129], v[186:189], v[164:167], v[126:129]
	v_mfma_f32_16x16x32_bf16 v[122:125], v[186:189], v[178:181], v[122:125]
	v_mfma_f32_16x16x32_bf16 v[118:121], v[194:197], v[164:167], v[118:121]
	v_mfma_f32_16x16x32_bf16 v[114:117], v[194:197], v[178:181], v[114:117]
	v_mfma_f32_16x16x32_bf16 v[110:113], v[202:205], v[164:167], v[110:113]
	v_mfma_f32_16x16x32_bf16 v[106:109], v[202:205], v[178:181], v[106:109]
	v_mfma_f32_16x16x32_bf16 v[102:105], v[210:213], v[164:167], v[102:105]
	v_mfma_f32_16x16x32_bf16 v[98:101], v[210:213], v[178:181], v[98:101]
	s_barrier
	v_lshl_add_u64 v[232:233], s[20:21], 0, v[130:131]
	v_readfirstlane_b32 s22, v152
	v_lshl_add_u64 v[234:235], v[232:233], 0, s[8:9]
	s_mov_b32 m0, s22
	ds_read_b128 v[214:217], v142
	ds_read_b128 v[218:221], v142 offset:1024
	ds_read_b128 v[222:225], v142 offset:2048
	ds_read_b128 v[226:229], v142 offset:3072
	global_load_lds_dwordx4 v[234:235], off
	v_lshl_add_u64 v[234:235], s[20:21], 0, v[132:133]
	v_readfirstlane_b32 s22, v153
	v_lshl_add_u64 v[236:237], v[234:235], 0, s[8:9]
	s_mov_b32 m0, s22
	s_add_u32 s20, s20, 0x100
	global_load_lds_dwordx4 v[236:237], off
	s_waitcnt vmcnt(10)
	s_barrier
	s_waitcnt lgkmcnt(0)
	s_addc_u32 s21, s21, 0
	s_waitcnt lgkmcnt(0)
	v_mfma_f32_16x16x32_bf16 v[94:97], v[182:185], v[214:217], v[94:97]
	v_mfma_f32_16x16x32_bf16 v[90:93], v[182:185], v[222:225], v[90:93]
	v_mfma_f32_16x16x32_bf16 v[86:89], v[190:193], v[214:217], v[86:89]
	v_mfma_f32_16x16x32_bf16 v[82:85], v[190:193], v[222:225], v[82:85]
	v_mfma_f32_16x16x32_bf16 v[78:81], v[198:201], v[214:217], v[78:81]
	v_mfma_f32_16x16x32_bf16 v[74:77], v[198:201], v[222:225], v[74:77]
	v_mfma_f32_16x16x32_bf16 v[70:73], v[206:209], v[214:217], v[70:73]
	v_mfma_f32_16x16x32_bf16 v[66:69], v[206:209], v[222:225], v[66:69]
	v_mfma_f32_16x16x32_bf16 v[94:97], v[186:189], v[218:221], v[94:97]
	v_mfma_f32_16x16x32_bf16 v[90:93], v[186:189], v[226:229], v[90:93]
	v_mfma_f32_16x16x32_bf16 v[86:89], v[194:197], v[218:221], v[86:89]
	v_mfma_f32_16x16x32_bf16 v[82:85], v[194:197], v[226:229], v[82:85]
	v_mfma_f32_16x16x32_bf16 v[78:81], v[202:205], v[218:221], v[78:81]
	v_mfma_f32_16x16x32_bf16 v[74:77], v[202:205], v[226:229], v[74:77]
	v_mfma_f32_16x16x32_bf16 v[70:73], v[210:213], v[218:221], v[70:73]
	v_mfma_f32_16x16x32_bf16 v[66:69], v[210:213], v[226:229], v[66:69]
	v_lshl_add_u64 v[236:237], s[18:19], 0, v[130:131]
	v_readfirstlane_b32 s22, v146
	v_lshl_add_u64 v[238:239], v[236:237], 0, s[8:9]
	s_mov_b32 m0, s22
	s_barrier
	ds_read_b128 v[182:185], v139 offset:16384
	ds_read_b128 v[186:189], v139 offset:17408
	ds_read_b128 v[190:193], v138 offset:16384
	ds_read_b128 v[194:197], v138 offset:17408
	ds_read_b128 v[198:201], v137 offset:16384
	ds_read_b128 v[202:205], v137 offset:17408
	ds_read_b128 v[206:209], v136 offset:16384
	ds_read_b128 v[210:213], v136 offset:17408
	global_load_lds_dwordx4 v[238:239], off
	v_lshl_add_u64 v[238:239], s[18:19], 0, v[132:133]
	v_readfirstlane_b32 s22, v147
	v_lshl_add_u64 v[240:241], v[238:239], 0, s[8:9]
	s_mov_b32 m0, s22
	s_add_u32 s18, s18, 0x100
	global_load_lds_dwordx4 v[240:241], off
	s_barrier
	s_waitcnt lgkmcnt(0)
	s_addc_u32 s19, s19, 0
	s_waitcnt lgkmcnt(0)
	v_mfma_f32_16x16x32_bf16 v[62:65], v[182:185], v[160:163], v[62:65]
	v_mfma_f32_16x16x32_bf16 v[58:61], v[182:185], v[174:177], v[58:61]
	v_mfma_f32_16x16x32_bf16 v[54:57], v[190:193], v[160:163], v[54:57]
	v_mfma_f32_16x16x32_bf16 v[50:53], v[190:193], v[174:177], v[50:53]
	v_mfma_f32_16x16x32_bf16 v[46:49], v[198:201], v[160:163], v[46:49]
	v_mfma_f32_16x16x32_bf16 v[42:45], v[198:201], v[174:177], v[42:45]
	v_mfma_f32_16x16x32_bf16 v[38:41], v[206:209], v[160:163], v[38:41]
	v_mfma_f32_16x16x32_bf16 v[34:37], v[206:209], v[174:177], v[34:37]
	v_mfma_f32_16x16x32_bf16 v[62:65], v[186:189], v[164:167], v[62:65]
	v_mfma_f32_16x16x32_bf16 v[58:61], v[186:189], v[178:181], v[58:61]
	v_mfma_f32_16x16x32_bf16 v[54:57], v[194:197], v[164:167], v[54:57]
	v_mfma_f32_16x16x32_bf16 v[50:53], v[194:197], v[178:181], v[50:53]
	v_mfma_f32_16x16x32_bf16 v[46:49], v[202:205], v[164:167], v[46:49]
	v_mfma_f32_16x16x32_bf16 v[42:45], v[202:205], v[178:181], v[42:45]
	v_mfma_f32_16x16x32_bf16 v[38:41], v[210:213], v[164:167], v[38:41]
	v_mfma_f32_16x16x32_bf16 v[34:37], v[210:213], v[178:181], v[34:37]
	s_barrier
; #define STAGE(P, GP, ktrel) do { const GAS char* _g = (GP) + (ktrel) * (BK * 2); \
;     __builtin_amdgcn_global_load_lds((const GAS unsigned*)(_g + so0), (unsigned*)((char*)(P) + tid_ * 16), 16, 0, 0); \
;     __builtin_amdgcn_global_load_lds((const GAS unsigned*)(_g + so1), (unsigned*)((char*)(P) + tid_ * 16 + 8192), 16, 0, 0); } while (0)
; #define WAIT_V(n) asm volatile("s_waitcnt vmcnt(" #n ")" ::: "memory")
; #define WAIT_L(n) asm volatile("s_waitcnt lgkmcnt(" #n ")" ::: "memory")
; #define BAR __builtin_amdgcn_s_barrier()
; #define SCHED __builtin_amdgcn_sched_barrier(0)
; #define LDA(dst, b, h) for (int m = 0; m < 4; ++m) for (int k = 0; k < 2; ++k) \
;     dst[m][k] = *reinterpret_cast<const bf16x8*>((char*)SA(b, h) + lds_byte(wr * 64 + m * 16 + fr, k * 32 + fq * 8))
; #define LDB(dst, b, h) for (int n = 0; n < 2; ++n) for (int k = 0; k < 2; ++k) \
;     dst[n][k] = *reinterpret_cast<const bf16x8*>((char*)SB(b, h) + lds_byte(wc * 32 + n * 16 + fr, k * 32 + fq * 8))
; #define MMA(ai, bj, At_, Bt_) do { __builtin_amdgcn_s_setprio(1); \
;     for (int m = 0; m < 4; ++m) for (int n = 0; n < 2; ++n) for (int k = 0; k < 2; ++k) \
;       acc[ai][bj][m][n] = __builtin_amdgcn_mfma_f32_16x16x32_bf16(At_[m][k], Bt_[n][k], acc[ai][bj][m][n], 0, 0, 0); \
;     __builtin_amdgcn_s_setprio(0); } while (0)
; template <int K, int LD = K>
; __device__ __forceinline__ void gemm_main(const GAS bf16* A, const GAS bf16* Bt, int brow, int bcol, f32x4 (&acc)[2][2][4][2]) {
;     ...
;     BAR; WAIT_L(0); MMA(1, 0, At, B0); BAR; SCHED;
;     STAGE(SB(0, 1), pB1, 2);
;     WAIT_V(6); BAR; MMA(1, 1, At, B1); BAR;
;     LDB(B0, 1, 0); SCHED; LDA(At, 1, 0); STAGE(SA(0, 1), pA1, 2);
;     WAIT_L(8); BAR; WAIT_L(0); MMA(0, 0, At, B0); BAR; SCHED;
;     LDB(B1, 1, 1); STAGE(SB(1, 0), pB0, 3);
;     BAR; WAIT_L(0); MMA(0, 1, At, B1); BAR;
	v_lshl_add_u64 v[240:241], s[16:17], 0, v[130:131]
	v_readfirstlane_b32 s22, v154
	v_lshl_add_u64 v[160:161], v[240:241], 0, s[8:9]
	s_mov_b32 m0, s22
	v_lshl_add_u64 v[242:243], s[16:17], 0, v[132:133]
	v_readfirstlane_b32 s22, v155
	global_load_lds_dwordx4 v[160:161], off
	v_lshl_add_u64 v[160:161], v[242:243], 0, s[8:9]
	s_mov_b32 m0, s22
	s_add_u32 s16, s16, 0x100
	global_load_lds_dwordx4 v[160:161], off
	s_waitcnt vmcnt(10)
	s_addc_u32 s17, s17, 0
	s_barrier
	v_mfma_f32_16x16x32_bf16 v[30:33], v[182:185], v[214:217], v[30:33]
	v_mfma_f32_16x16x32_bf16 v[26:29], v[182:185], v[222:225], v[26:29]
	v_mfma_f32_16x16x32_bf16 v[22:25], v[190:193], v[214:217], v[22:25]
	v_mfma_f32_16x16x32_bf16 v[18:21], v[190:193], v[222:225], v[18:21]
	v_mfma_f32_16x16x32_bf16 v[14:17], v[198:201], v[214:217], v[14:17]
	v_mfma_f32_16x16x32_bf16 v[10:13], v[198:201], v[222:225], v[10:13]
	v_mfma_f32_16x16x32_bf16 v[6:9], v[206:209], v[214:217], v[6:9]
	v_mfma_f32_16x16x32_bf16 v[2:5], v[206:209], v[222:225], v[2:5]
	v_mfma_f32_16x16x32_bf16 v[30:33], v[186:189], v[218:221], v[30:33]
	v_mfma_f32_16x16x32_bf16 v[26:29], v[186:189], v[226:229], v[26:29]
	v_mfma_f32_16x16x32_bf16 v[22:25], v[194:197], v[218:221], v[22:25]
	v_mfma_f32_16x16x32_bf16 v[18:21], v[194:197], v[226:229], v[18:21]
	v_mfma_f32_16x16x32_bf16 v[14:17], v[202:205], v[218:221], v[14:17]
	v_mfma_f32_16x16x32_bf16 v[10:13], v[202:205], v[226:229], v[10:13]
	v_mfma_f32_16x16x32_bf16 v[6:9], v[210:213], v[218:221], v[6:9]
	v_mfma_f32_16x16x32_bf16 v[2:5], v[210:213], v[226:229], v[2:5]
	s_barrier
	ds_read_b128 v[160:163], v141
	ds_read_b128 v[164:167], v141 offset:1024
	ds_read_b128 v[174:177], v141 offset:2048
	ds_read_b128 v[178:181], v141 offset:3072
	v_readfirstlane_b32 s22, v148
	v_lshl_add_u64 v[168:169], v[168:169], 0, s[8:9]
	s_mov_b32 m0, s22
	v_readfirstlane_b32 s22, v149
	ds_read_b128 v[182:185], v139 offset:32768
	ds_read_b128 v[186:189], v139 offset:33792
	ds_read_b128 v[190:193], v138 offset:32768
	ds_read_b128 v[194:197], v138 offset:33792
	ds_read_b128 v[198:201], v137 offset:32768
	ds_read_b128 v[202:205], v137 offset:33792
	ds_read_b128 v[206:209], v136 offset:32768
	ds_read_b128 v[210:213], v136 offset:33792
	global_load_lds_dwordx4 v[168:169], off
	v_lshl_add_u64 v[168:169], v[230:231], 0, s[8:9]
	s_mov_b32 m0, s22
	s_add_u32 s12, s12, 0x100
	global_load_lds_dwordx4 v[168:169], off
	s_waitcnt lgkmcnt(8)
	s_waitcnt vmcnt(10)
	s_barrier
	s_waitcnt lgkmcnt(0)
	s_addc_u32 s13, s13, 0
	s_waitcnt lgkmcnt(0)
	v_mfma_f32_16x16x32_bf16 v[126:129], v[182:185], v[160:163], v[126:129]
	v_mfma_f32_16x16x32_bf16 v[122:125], v[182:185], v[174:177], v[122:125]
	v_mfma_f32_16x16x32_bf16 v[118:121], v[190:193], v[160:163], v[118:121]
	v_mfma_f32_16x16x32_bf16 v[114:117], v[190:193], v[174:177], v[114:117]
	v_mfma_f32_16x16x32_bf16 v[110:113], v[198:201], v[160:163], v[110:113]
	v_mfma_f32_16x16x32_bf16 v[106:109], v[198:201], v[174:177], v[106:109]
	v_mfma_f32_16x16x32_bf16 v[102:105], v[206:209], v[160:163], v[102:105]
	v_mfma_f32_16x16x32_bf16 v[98:101], v[206:209], v[174:177], v[98:101]
	v_mfma_f32_16x16x32_bf16 v[126:129], v[186:189], v[164:167], v[126:129]
	v_mfma_f32_16x16x32_bf16 v[122:125], v[186:189], v[178:181], v[122:125]
	v_mfma_f32_16x16x32_bf16 v[118:121], v[194:197], v[164:167], v[118:121]
	v_mfma_f32_16x16x32_bf16 v[114:117], v[194:197], v[178:181], v[114:117]
	v_mfma_f32_16x16x32_bf16 v[110:113], v[202:205], v[164:167], v[110:113]
	v_mfma_f32_16x16x32_bf16 v[106:109], v[202:205], v[178:181], v[106:109]
	v_mfma_f32_16x16x32_bf16 v[102:105], v[210:213], v[164:167], v[102:105]
	v_mfma_f32_16x16x32_bf16 v[98:101], v[210:213], v[178:181], v[98:101]
	s_barrier
	v_readfirstlane_b32 s22, v156
	v_lshl_add_u64 v[168:169], v[232:233], 0, s[10:11]
	s_mov_b32 m0, s22
	v_readfirstlane_b32 s22, v157
	ds_read_b128 v[214:217], v140
	ds_read_b128 v[218:221], v140 offset:1024
	ds_read_b128 v[222:225], v140 offset:2048
	ds_read_b128 v[226:229], v140 offset:3072
	global_load_lds_dwordx4 v[168:169], off
	v_lshl_add_u64 v[168:169], v[234:235], 0, s[10:11]
	s_mov_b32 m0, s22
	s_nop 0
	global_load_lds_dwordx4 v[168:169], off
	s_waitcnt vmcnt(10)
	s_barrier
	s_waitcnt lgkmcnt(0)
	s_waitcnt lgkmcnt(0)
	v_mfma_f32_16x16x32_bf16 v[94:97], v[182:185], v[214:217], v[94:97]
	v_mfma_f32_16x16x32_bf16 v[90:93], v[182:185], v[222:225], v[90:93]
	v_mfma_f32_16x16x32_bf16 v[86:89], v[190:193], v[214:217], v[86:89]
	v_mfma_f32_16x16x32_bf16 v[82:85], v[190:193], v[222:225], v[82:85]
	v_mfma_f32_16x16x32_bf16 v[78:81], v[198:201], v[214:217], v[78:81]
	v_mfma_f32_16x16x32_bf16 v[74:77], v[198:201], v[222:225], v[74:77]
	v_mfma_f32_16x16x32_bf16 v[70:73], v[206:209], v[214:217], v[70:73]
	v_mfma_f32_16x16x32_bf16 v[66:69], v[206:209], v[222:225], v[66:69]
	v_mfma_f32_16x16x32_bf16 v[94:97], v[186:189], v[218:221], v[94:97]
	v_mfma_f32_16x16x32_bf16 v[90:93], v[186:189], v[226:229], v[90:93]
	v_mfma_f32_16x16x32_bf16 v[86:89], v[194:197], v[218:221], v[86:89]
	v_mfma_f32_16x16x32_bf16 v[82:85], v[194:197], v[226:229], v[82:85]
	v_mfma_f32_16x16x32_bf16 v[78:81], v[202:205], v[218:221], v[78:81]
	v_mfma_f32_16x16x32_bf16 v[74:77], v[202:205], v[226:229], v[74:77]
	v_mfma_f32_16x16x32_bf16 v[70:73], v[210:213], v[218:221], v[70:73]
	v_mfma_f32_16x16x32_bf16 v[66:69], v[210:213], v[226:229], v[66:69]
	v_readfirstlane_b32 s22, v150
	v_lshl_add_u64 v[168:169], v[236:237], 0, s[10:11]
	s_mov_b32 m0, s22
	v_readfirstlane_b32 s22, v151
	s_barrier
; #define STAGE(P, GP, ktrel) do { const GAS char* _g = (GP) + (ktrel) * (BK * 2); \
;     __builtin_amdgcn_global_load_lds((const GAS unsigned*)(_g + so0), (unsigned*)((char*)(P) + tid_ * 16), 16, 0, 0); \
;     __builtin_amdgcn_global_load_lds((const GAS unsigned*)(_g + so1), (unsigned*)((char*)(P) + tid_ * 16 + 8192), 16, 0, 0); } while (0)
; #define WAIT_V(n) asm volatile("s_waitcnt vmcnt(" #n ")" ::: "memory")
; #define WAIT_L(n) asm volatile("s_waitcnt lgkmcnt(" #n ")" ::: "memory")
; #define BAR __builtin_amdgcn_s_barrier()
; #define SCHED __builtin_amdgcn_sched_barrier(0)
; #define LDA(dst, b, h) for (int m = 0; m < 4; ++m) for (int k = 0; k < 2; ++k) \
;     dst[m][k] = *reinterpret_cast<const bf16x8*>((char*)SA(b, h) + lds_byte(wr * 64 + m * 16 + fr, k * 32 + fq * 8))
; #define LDB(dst, b, h) for (int n = 0; n < 2; ++n) for (int k = 0; k < 2; ++k) \
;     dst[n][k] = *reinterpret_cast<const bf16x8*>((char*)SB(b, h) + lds_byte(wc * 32 + n * 16 + fr, k * 32 + fq * 8))
; #define MMA(ai, bj, At_, Bt_) do { __builtin_amdgcn_s_setprio(1); \
;     for (int m = 0; m < 4; ++m) for (int n = 0; n < 2; ++n) for (int k = 0; k < 2; ++k) \
;       acc[ai][bj][m][n] = __builtin_amdgcn_mfma_f32_16x16x32_bf16(At_[m][k], Bt_[n][k], acc[ai][bj][m][n], 0, 0, 0); \
;     __builtin_amdgcn_s_setprio(0); } while (0)
; template <int K, int LD = K>
; __device__ __forceinline__ void gemm_main(const GAS bf16* A, const GAS bf16* Bt, int brow, int bcol, f32x4 (&acc)[2][2][4][2]) {
;     ...
;     LDA(At, 1, 1); STAGE(SA(1, 0), pA0, 3);
;     BAR; WAIT_L(0); MMA(1, 0, At, B0); BAR; SCHED;
;     STAGE(SB(1, 1), pB1, 3);
;     WAIT_V(6); BAR; MMA(1, 1, At, B1); BAR;
;     pA0 += 4 * BK; pA1 += 4 * BK; pB0 += 4 * BK; pB1 += 4 * BK;
;     asm volatile("" : "+s"(pA0), "+s"(pA1), "+s"(pB0), "+s"(pB1));
;   }
;   { LDB(B0, 0, 0); LDA(At, 0, 0); STAGE(SA(1, 1), pA1, 1);
;     BAR; WAIT_L(0); MMA(0, 0, At, B0); BAR;
	ds_read_b128 v[182:185], v139 offset:49152
	ds_read_b128 v[186:189], v139 offset:50176
	ds_read_b128 v[190:193], v138 offset:49152
	ds_read_b128 v[194:197], v138 offset:50176
	ds_read_b128 v[198:201], v137 offset:49152
	ds_read_b128 v[202:205], v137 offset:50176
	ds_read_b128 v[206:209], v136 offset:49152
	ds_read_b128 v[210:213], v136 offset:50176
	global_load_lds_dwordx4 v[168:169], off
	v_lshl_add_u64 v[168:169], v[238:239], 0, s[10:11]
	s_mov_b32 m0, s22
	s_nop 0
	global_load_lds_dwordx4 v[168:169], off
	s_barrier
	s_waitcnt lgkmcnt(0)
	s_waitcnt lgkmcnt(0)
	v_mfma_f32_16x16x32_bf16 v[62:65], v[182:185], v[160:163], v[62:65]
	v_mfma_f32_16x16x32_bf16 v[58:61], v[182:185], v[174:177], v[58:61]
	v_mfma_f32_16x16x32_bf16 v[54:57], v[190:193], v[160:163], v[54:57]
	v_mfma_f32_16x16x32_bf16 v[50:53], v[190:193], v[174:177], v[50:53]
	v_mfma_f32_16x16x32_bf16 v[46:49], v[198:201], v[160:163], v[46:49]
	v_mfma_f32_16x16x32_bf16 v[42:45], v[198:201], v[174:177], v[42:45]
	v_mfma_f32_16x16x32_bf16 v[38:41], v[206:209], v[160:163], v[38:41]
	v_mfma_f32_16x16x32_bf16 v[34:37], v[206:209], v[174:177], v[34:37]
	v_mfma_f32_16x16x32_bf16 v[62:65], v[186:189], v[164:167], v[62:65]
	v_mfma_f32_16x16x32_bf16 v[58:61], v[186:189], v[178:181], v[58:61]
	v_mfma_f32_16x16x32_bf16 v[54:57], v[194:197], v[164:167], v[54:57]
	v_mfma_f32_16x16x32_bf16 v[50:53], v[194:197], v[178:181], v[50:53]
	v_mfma_f32_16x16x32_bf16 v[46:49], v[202:205], v[164:167], v[46:49]
	v_mfma_f32_16x16x32_bf16 v[42:45], v[202:205], v[178:181], v[42:45]
	v_mfma_f32_16x16x32_bf16 v[38:41], v[210:213], v[164:167], v[38:41]
	v_mfma_f32_16x16x32_bf16 v[34:37], v[210:213], v[178:181], v[34:37]
	s_barrier
	v_readfirstlane_b32 s22, v158
	v_lshl_add_u64 v[160:161], v[240:241], 0, s[10:11]
	s_mov_b32 m0, s22
	v_readfirstlane_b32 s22, v159
	global_load_lds_dwordx4 v[160:161], off
	v_lshl_add_u64 v[160:161], v[242:243], 0, s[10:11]
	s_mov_b32 m0, s22
	s_nop 0
	global_load_lds_dwordx4 v[160:161], off
	s_waitcnt vmcnt(10)
	s_barrier
	v_mfma_f32_16x16x32_bf16 v[30:33], v[182:185], v[214:217], v[30:33]
	v_mfma_f32_16x16x32_bf16 v[26:29], v[182:185], v[222:225], v[26:29]
	v_mfma_f32_16x16x32_bf16 v[22:25], v[190:193], v[214:217], v[22:25]
	v_mfma_f32_16x16x32_bf16 v[18:21], v[190:193], v[222:225], v[18:21]
	v_mfma_f32_16x16x32_bf16 v[14:17], v[198:201], v[214:217], v[14:17]
	v_mfma_f32_16x16x32_bf16 v[10:13], v[198:201], v[222:225], v[10:13]
	v_mfma_f32_16x16x32_bf16 v[6:9], v[206:209], v[214:217], v[6:9]
	v_mfma_f32_16x16x32_bf16 v[2:5], v[206:209], v[222:225], v[2:5]
	v_mfma_f32_16x16x32_bf16 v[30:33], v[186:189], v[218:221], v[30:33]
	v_mfma_f32_16x16x32_bf16 v[26:29], v[186:189], v[226:229], v[26:29]
	v_mfma_f32_16x16x32_bf16 v[22:25], v[194:197], v[218:221], v[22:25]
	v_mfma_f32_16x16x32_bf16 v[18:21], v[194:197], v[226:229], v[18:21]
	v_mfma_f32_16x16x32_bf16 v[14:17], v[202:205], v[218:221], v[14:17]
	v_mfma_f32_16x16x32_bf16 v[10:13], v[202:205], v[226:229], v[10:13]
	v_mfma_f32_16x16x32_bf16 v[6:9], v[210:213], v[218:221], v[6:9]
	v_mfma_f32_16x16x32_bf16 v[2:5], v[210:213], v[226:229], v[2:5]
	s_add_i32 s15, s15, 2
	s_cmp_lt_u32 s15, 12
	s_barrier
	s_cbranch_scc1 .LBB0_884
	v_lshl_add_u64 v[198:199], s[12:13], 0, v[130:131]
	v_readfirstlane_b32 s15, v144
	v_lshl_add_u64 v[198:199], v[198:199], 0, s[6:7]
	s_mov_b32 m0, s15
	v_lshl_add_u64 v[132:133], s[12:13], 0, v[132:133]
	v_readfirstlane_b32 s12, v143
	ds_read_b128 v[146:149], v145
	ds_read_b128 v[150:153], v145 offset:1024
	ds_read_b128 v[154:157], v145 offset:2048
	ds_read_b128 v[158:161], v145 offset:3072
	ds_read_b128 v[162:165], v139
	ds_read_b128 v[166:169], v139 offset:1024
	ds_read_b128 v[174:177], v138
	ds_read_b128 v[178:181], v138 offset:1024
	ds_read_b128 v[182:185], v137
	ds_read_b128 v[186:189], v137 offset:1024
	ds_read_b128 v[190:193], v136
	ds_read_b128 v[194:197], v136 offset:1024
	global_load_lds_dwordx4 v[198:199], off
	v_lshl_add_u64 v[132:133], v[132:133], 0, s[6:7]
	s_mov_b32 m0, s12
	s_nop 0
	global_load_lds_dwordx4 v[132:133], off
	s_waitcnt vmcnt(10)
	s_barrier
	s_waitcnt lgkmcnt(0)
	s_waitcnt lgkmcnt(0)
	v_mfma_f32_16x16x32_bf16 v[126:129], v[162:165], v[146:149], v[126:129]
	v_mfma_f32_16x16x32_bf16 v[122:125], v[162:165], v[154:157], v[122:125]
	v_mfma_f32_16x16x32_bf16 v[110:113], v[182:185], v[146:149], v[110:113]
	v_mfma_f32_16x16x32_bf16 v[106:109], v[182:185], v[154:157], v[106:109]
	v_mfma_f32_16x16x32_bf16 v[126:129], v[166:169], v[150:153], v[126:129]
	v_mfma_f32_16x16x32_bf16 v[122:125], v[166:169], v[158:161], v[122:125]
	v_mfma_f32_16x16x32_bf16 v[118:121], v[174:177], v[146:149], v[118:121]
	v_mfma_f32_16x16x32_bf16 v[114:117], v[174:177], v[154:157], v[114:117]
	v_mfma_f32_16x16x32_bf16 v[110:113], v[186:189], v[150:153], v[110:113]
	v_mfma_f32_16x16x32_bf16 v[106:109], v[186:189], v[158:161], v[106:109]
	v_mfma_f32_16x16x32_bf16 v[102:105], v[190:193], v[146:149], v[102:105]
	v_mfma_f32_16x16x32_bf16 v[98:101], v[190:193], v[154:157], v[98:101]
	v_mfma_f32_16x16x32_bf16 v[198:201], v[178:181], v[150:153], v[118:121]
	v_mfma_f32_16x16x32_bf16 v[202:205], v[178:181], v[158:161], v[114:117]
	v_mfma_f32_16x16x32_bf16 v[206:209], v[194:197], v[150:153], v[102:105]
	v_mfma_f32_16x16x32_bf16 v[210:213], v[194:197], v[158:161], v[98:101]
	s_barrier
	s_nop 1
	ds_read_b128 v[98:101], v142
	ds_read_b128 v[102:105], v142 offset:1024
	ds_read_b128 v[114:117], v142 offset:2048
	ds_read_b128 v[118:121], v142 offset:3072
	s_waitcnt vmcnt(8)
	s_barrier
; #define WAIT_V(n) asm volatile("s_waitcnt vmcnt(" #n ")" ::: "memory")
; #define WAIT_L(n) asm volatile("s_waitcnt lgkmcnt(" #n ")" ::: "memory")
; #define BAR __builtin_amdgcn_s_barrier()
; #define LDA(dst, b, h) for (int m = 0; m < 4; ++m) for (int k = 0; k < 2; ++k) \
;     dst[m][k] = *reinterpret_cast<const bf16x8*>((char*)SA(b, h) + lds_byte(wr * 64 + m * 16 + fr, k * 32 + fq * 8))
; #define LDB(dst, b, h) for (int n = 0; n < 2; ++n) for (int k = 0; k < 2; ++k) \
;     dst[n][k] = *reinterpret_cast<const bf16x8*>((char*)SB(b, h) + lds_byte(wc * 32 + n * 16 + fr, k * 32 + fq * 8))
; #define MMA(ai, bj, At_, Bt_) do { __builtin_amdgcn_s_setprio(1); \
;     for (int m = 0; m < 4; ++m) for (int n = 0; n < 2; ++n) for (int k = 0; k < 2; ++k) \
;       acc[ai][bj][m][n] = __builtin_amdgcn_mfma_f32_16x16x32_bf16(At_[m][k], Bt_[n][k], acc[ai][bj][m][n], 0, 0, 0); \
;     __builtin_amdgcn_s_setprio(0); } while (0)
; template <int K, int LD = K>
; __device__ __forceinline__ void gemm_main(const GAS bf16* A, const GAS bf16* Bt, int brow, int bcol, f32x4 (&acc)[2][2][4][2]) {
;     ...
;     LDB(B1, 0, 1); BAR; WAIT_L(0); MMA(0, 1, At, B1); BAR;
;     LDA(At, 0, 1); WAIT_V(4); BAR; WAIT_L(0); MMA(1, 0, At, B0); MMA(1, 1, At, B1); BAR; }
;   { LDB(B0, 1, 0); LDA(At, 1, 0); WAIT_V(2); BAR; WAIT_L(0); MMA(0, 0, At, B0); BAR;
	s_waitcnt lgkmcnt(0)
	s_waitcnt lgkmcnt(0)
	v_mfma_f32_16x16x32_bf16 v[94:97], v[162:165], v[98:101], v[94:97]
	v_mfma_f32_16x16x32_bf16 v[90:93], v[162:165], v[114:117], v[90:93]
	v_mfma_f32_16x16x32_bf16 v[78:81], v[182:185], v[98:101], v[78:81]
	v_mfma_f32_16x16x32_bf16 v[74:77], v[182:185], v[114:117], v[74:77]
	v_mfma_f32_16x16x32_bf16 v[94:97], v[166:169], v[102:105], v[94:97]
	v_mfma_f32_16x16x32_bf16 v[90:93], v[166:169], v[118:121], v[90:93]
	v_mfma_f32_16x16x32_bf16 v[86:89], v[174:177], v[98:101], v[86:89]
	v_mfma_f32_16x16x32_bf16 v[82:85], v[174:177], v[114:117], v[82:85]
	v_mfma_f32_16x16x32_bf16 v[78:81], v[186:189], v[102:105], v[78:81]
	v_mfma_f32_16x16x32_bf16 v[74:77], v[186:189], v[118:121], v[74:77]
	v_mfma_f32_16x16x32_bf16 v[70:73], v[190:193], v[98:101], v[70:73]
	v_mfma_f32_16x16x32_bf16 v[66:69], v[190:193], v[114:117], v[66:69]
	v_mfma_f32_16x16x32_bf16 v[142:145], v[178:181], v[102:105], v[86:89]
	v_mfma_f32_16x16x32_bf16 v[162:165], v[178:181], v[118:121], v[82:85]
	v_mfma_f32_16x16x32_bf16 v[166:169], v[194:197], v[102:105], v[70:73]
	v_mfma_f32_16x16x32_bf16 v[174:177], v[194:197], v[118:121], v[66:69]
	s_barrier
	s_nop 1
	ds_read_b128 v[66:69], v139 offset:16384
	ds_read_b128 v[70:73], v139 offset:17408
	ds_read_b128 v[82:85], v138 offset:16384
	ds_read_b128 v[86:89], v138 offset:17408
	ds_read_b128 v[178:181], v137 offset:16384
	ds_read_b128 v[182:185], v137 offset:17408
	ds_read_b128 v[186:189], v136 offset:16384
	ds_read_b128 v[190:193], v136 offset:17408
	s_waitcnt vmcnt(4)
	s_barrier
	s_waitcnt lgkmcnt(0)
	s_waitcnt lgkmcnt(0)
	v_mfma_f32_16x16x32_bf16 v[62:65], v[66:69], v[146:149], v[62:65]
	v_mfma_f32_16x16x32_bf16 v[58:61], v[66:69], v[154:157], v[58:61]
	v_mfma_f32_16x16x32_bf16 v[46:49], v[178:181], v[146:149], v[46:49]
	v_mfma_f32_16x16x32_bf16 v[38:41], v[186:189], v[146:149], v[38:41]
	v_mfma_f32_16x16x32_bf16 v[62:65], v[70:73], v[150:153], v[62:65]
	v_mfma_f32_16x16x32_bf16 v[58:61], v[70:73], v[158:161], v[58:61]
	v_mfma_f32_16x16x32_bf16 v[54:57], v[82:85], v[146:149], v[54:57]
	v_mfma_f32_16x16x32_bf16 v[50:53], v[82:85], v[154:157], v[50:53]
	v_mfma_f32_16x16x32_bf16 v[46:49], v[182:185], v[150:153], v[46:49]
	v_mfma_f32_16x16x32_bf16 v[42:45], v[178:181], v[154:157], v[42:45]
	v_mfma_f32_16x16x32_bf16 v[38:41], v[190:193], v[150:153], v[38:41]
	v_mfma_f32_16x16x32_bf16 v[34:37], v[186:189], v[154:157], v[34:37]
	v_mfma_f32_16x16x32_bf16 v[194:197], v[86:89], v[150:153], v[54:57]
	v_mfma_f32_16x16x32_bf16 v[214:217], v[86:89], v[158:161], v[50:53]
	v_mfma_f32_16x16x32_bf16 v[218:221], v[182:185], v[158:161], v[42:45]
	v_mfma_f32_16x16x32_bf16 v[146:149], v[190:193], v[158:161], v[34:37]
	v_mfma_f32_16x16x32_bf16 v[30:33], v[66:69], v[98:101], v[30:33]
	v_mfma_f32_16x16x32_bf16 v[26:29], v[66:69], v[114:117], v[26:29]
	v_mfma_f32_16x16x32_bf16 v[14:17], v[178:181], v[98:101], v[14:17]
	v_mfma_f32_16x16x32_bf16 v[6:9], v[186:189], v[98:101], v[6:9]
	v_mfma_f32_16x16x32_bf16 v[30:33], v[70:73], v[102:105], v[30:33]
	v_mfma_f32_16x16x32_bf16 v[26:29], v[70:73], v[118:121], v[26:29]
	v_mfma_f32_16x16x32_bf16 v[22:25], v[82:85], v[98:101], v[22:25]
	v_mfma_f32_16x16x32_bf16 v[18:21], v[82:85], v[114:117], v[18:21]
	v_mfma_f32_16x16x32_bf16 v[14:17], v[182:185], v[102:105], v[14:17]
	v_mfma_f32_16x16x32_bf16 v[10:13], v[178:181], v[114:117], v[10:13]
	v_mfma_f32_16x16x32_bf16 v[6:9], v[190:193], v[102:105], v[6:9]
	v_mfma_f32_16x16x32_bf16 v[2:5], v[186:189], v[114:117], v[2:5]
	v_mfma_f32_16x16x32_bf16 v[150:153], v[86:89], v[102:105], v[22:25]
	v_mfma_f32_16x16x32_bf16 v[154:157], v[86:89], v[118:121], v[18:21]
	v_mfma_f32_16x16x32_bf16 v[158:161], v[182:185], v[118:121], v[10:13]
	v_mfma_f32_16x16x32_bf16 v[178:181], v[190:193], v[118:121], v[2:5]
	s_barrier
	s_nop 1
	ds_read_b128 v[2:5], v141
	ds_read_b128 v[10:13], v141 offset:1024
	ds_read_b128 v[182:185], v141 offset:2048
	ds_read_b128 v[186:189], v141 offset:3072
	ds_read_b128 v[18:21], v139 offset:32768
	ds_read_b128 v[22:25], v139 offset:33792
	ds_read_b128 v[34:37], v138 offset:32768
	ds_read_b128 v[42:45], v138 offset:33792
	ds_read_b128 v[50:53], v137 offset:32768
	ds_read_b128 v[54:57], v137 offset:33792
	ds_read_b128 v[190:193], v136 offset:32768
	ds_read_b128 v[222:225], v136 offset:33792
	s_waitcnt vmcnt(2)
	s_barrier
; #define WAIT_V(n) asm volatile("s_waitcnt vmcnt(" #n ")" ::: "memory")
; #define WAIT_L(n) asm volatile("s_waitcnt lgkmcnt(" #n ")" ::: "memory")
; #define BAR __builtin_amdgcn_s_barrier()
; #define LDA(dst, b, h) for (int m = 0; m < 4; ++m) for (int k = 0; k < 2; ++k) \
;     dst[m][k] = *reinterpret_cast<const bf16x8*>((char*)SA(b, h) + lds_byte(wr * 64 + m * 16 + fr, k * 32 + fq * 8))
; #define LDB(dst, b, h) for (int n = 0; n < 2; ++n) for (int k = 0; k < 2; ++k) \
;     dst[n][k] = *reinterpret_cast<const bf16x8*>((char*)SB(b, h) + lds_byte(wc * 32 + n * 16 + fr, k * 32 + fq * 8))
; #define MMA(ai, bj, At_, Bt_) do { __builtin_amdgcn_s_setprio(1); \
;     for (int m = 0; m < 4; ++m) for (int n = 0; n < 2; ++n) for (int k = 0; k < 2; ++k) \
;       acc[ai][bj][m][n] = __builtin_amdgcn_mfma_f32_16x16x32_bf16(At_[m][k], Bt_[n][k], acc[ai][bj][m][n], 0, 0, 0); \
;     __builtin_amdgcn_s_setprio(0); } while (0)
; template <int K, int LD = K>
; __device__ __forceinline__ void gemm_main(const GAS bf16* A, const GAS bf16* Bt, int brow, int bcol, f32x4 (&acc)[2][2][4][2]) {
;     ...
;   { LDB(B0, 1, 0); LDA(At, 1, 0); WAIT_V(2); BAR; WAIT_L(0); MMA(0, 0, At, B0); BAR;
;     LDB(B1, 1, 1); WAIT_V(0); BAR; WAIT_L(0); MMA(0, 1, At, B1); BAR;
;     LDA(At, 1, 1); BAR; WAIT_L(0); MMA(1, 0, At, B0); MMA(1, 1, At, B1); BAR; }
;   if (wr == 0) BAR;
	s_waitcnt lgkmcnt(0)
	s_waitcnt lgkmcnt(0)
	v_mfma_f32_16x16x32_bf16 v[66:69], v[18:21], v[2:5], v[126:129]
	v_mfma_f32_16x16x32_bf16 v[118:121], v[22:25], v[10:13], v[66:69]
	v_mfma_f32_16x16x32_bf16 v[66:69], v[18:21], v[182:185], v[122:125]
	v_mfma_f32_16x16x32_bf16 v[114:117], v[22:25], v[186:189], v[66:69]
	v_mfma_f32_16x16x32_bf16 v[66:69], v[34:37], v[2:5], v[198:201]
	v_mfma_f32_16x16x32_bf16 v[102:105], v[42:45], v[10:13], v[66:69]
	v_mfma_f32_16x16x32_bf16 v[66:69], v[34:37], v[182:185], v[202:205]
	v_mfma_f32_16x16x32_bf16 v[98:101], v[42:45], v[186:189], v[66:69]
	v_mfma_f32_16x16x32_bf16 v[66:69], v[50:53], v[2:5], v[110:113]
	v_mfma_f32_16x16x32_bf16 v[86:89], v[54:57], v[10:13], v[66:69]
	v_mfma_f32_16x16x32_bf16 v[66:69], v[50:53], v[182:185], v[106:109]
	v_mfma_f32_16x16x32_bf16 v[82:85], v[54:57], v[186:189], v[66:69]
	v_mfma_f32_16x16x32_bf16 v[66:69], v[190:193], v[2:5], v[206:209]
	v_mfma_f32_16x16x32_bf16 v[70:73], v[222:225], v[10:13], v[66:69]
	v_mfma_f32_16x16x32_bf16 v[66:69], v[190:193], v[182:185], v[210:213]
	v_mfma_f32_16x16x32_bf16 v[66:69], v[222:225], v[186:189], v[66:69]
	s_barrier
	ds_read_b128 v[198:201], v140
	ds_read_b128 v[202:205], v140 offset:1024
	ds_read_b128 v[206:209], v140 offset:2048
	ds_read_b128 v[210:213], v140 offset:3072
	s_waitcnt vmcnt(0)
	s_barrier
	s_waitcnt lgkmcnt(0)
	s_waitcnt lgkmcnt(0)
	v_mfma_f32_16x16x32_bf16 v[94:97], v[18:21], v[198:201], v[94:97]
	v_mfma_f32_16x16x32_bf16 v[18:21], v[18:21], v[206:209], v[90:93]
	v_mfma_f32_16x16x32_bf16 v[122:125], v[22:25], v[210:213], v[18:21]
	v_mfma_f32_16x16x32_bf16 v[18:21], v[34:37], v[198:201], v[142:145]
	v_mfma_f32_16x16x32_bf16 v[110:113], v[42:45], v[202:205], v[18:21]
	v_mfma_f32_16x16x32_bf16 v[18:21], v[34:37], v[206:209], v[162:165]
	v_mfma_f32_16x16x32_bf16 v[106:109], v[42:45], v[210:213], v[18:21]
	v_mfma_f32_16x16x32_bf16 v[18:21], v[50:53], v[198:201], v[78:81]
	v_mfma_f32_16x16x32_bf16 v[126:129], v[22:25], v[202:205], v[94:97]
	v_mfma_f32_16x16x32_bf16 v[94:97], v[54:57], v[202:205], v[18:21]
	v_mfma_f32_16x16x32_bf16 v[18:21], v[50:53], v[206:209], v[74:77]
	v_mfma_f32_16x16x32_bf16 v[90:93], v[54:57], v[210:213], v[18:21]
	v_mfma_f32_16x16x32_bf16 v[18:21], v[190:193], v[198:201], v[166:169]
	v_mfma_f32_16x16x32_bf16 v[78:81], v[222:225], v[202:205], v[18:21]
	v_mfma_f32_16x16x32_bf16 v[18:21], v[190:193], v[206:209], v[174:177]
	v_mfma_f32_16x16x32_bf16 v[74:77], v[222:225], v[210:213], v[18:21]
	s_barrier
	ds_read_b128 v[140:143], v139 offset:49152
	ds_read_b128 v[162:165], v139 offset:50176
	ds_read_b128 v[166:169], v138 offset:49152
	ds_read_b128 v[174:177], v138 offset:50176
	ds_read_b128 v[190:193], v137 offset:49152
	ds_read_b128 v[222:225], v137 offset:50176
	ds_read_b128 v[226:229], v136 offset:49152
	ds_read_b128 v[136:139], v136 offset:50176
	s_barrier
	s_waitcnt lgkmcnt(0)
	s_waitcnt lgkmcnt(0)
	v_mfma_f32_16x16x32_bf16 v[18:21], v[140:143], v[2:5], v[62:65]
	v_mfma_f32_16x16x32_bf16 v[54:57], v[162:165], v[10:13], v[18:21]
	v_mfma_f32_16x16x32_bf16 v[18:21], v[140:143], v[182:185], v[58:61]
	v_mfma_f32_16x16x32_bf16 v[50:53], v[162:165], v[186:189], v[18:21]
	v_mfma_f32_16x16x32_bf16 v[18:21], v[166:169], v[2:5], v[194:197]
	v_mfma_f32_16x16x32_bf16 v[42:45], v[174:177], v[10:13], v[18:21]
	v_mfma_f32_16x16x32_bf16 v[18:21], v[166:169], v[182:185], v[214:217]
	v_mfma_f32_16x16x32_bf16 v[34:37], v[174:177], v[186:189], v[18:21]
	v_mfma_f32_16x16x32_bf16 v[18:21], v[190:193], v[2:5], v[46:49]
	v_mfma_f32_16x16x32_bf16 v[2:5], v[226:229], v[2:5], v[38:41]
	v_mfma_f32_16x16x32_bf16 v[22:25], v[222:225], v[10:13], v[18:21]
	v_mfma_f32_16x16x32_bf16 v[18:21], v[190:193], v[182:185], v[218:221]
	v_mfma_f32_16x16x32_bf16 v[10:13], v[136:139], v[10:13], v[2:5]
	v_mfma_f32_16x16x32_bf16 v[2:5], v[226:229], v[182:185], v[146:149]
	v_mfma_f32_16x16x32_bf16 v[18:21], v[222:225], v[186:189], v[18:21]
	v_mfma_f32_16x16x32_bf16 v[2:5], v[136:139], v[186:189], v[2:5]
	v_mfma_f32_16x16x32_bf16 v[26:29], v[140:143], v[206:209], v[26:29]
	v_mfma_f32_16x16x32_bf16 v[30:33], v[140:143], v[198:201], v[30:33]
	v_mfma_f32_16x16x32_bf16 v[58:61], v[162:165], v[210:213], v[26:29]
	v_mfma_f32_16x16x32_bf16 v[26:29], v[166:169], v[198:201], v[150:153]
	v_mfma_f32_16x16x32_bf16 v[14:17], v[190:193], v[198:201], v[14:17]
	v_mfma_f32_16x16x32_bf16 v[62:65], v[162:165], v[202:205], v[30:33]
	v_mfma_f32_16x16x32_bf16 v[46:49], v[174:177], v[202:205], v[26:29]
	v_mfma_f32_16x16x32_bf16 v[26:29], v[166:169], v[206:209], v[154:157]
	v_mfma_f32_16x16x32_bf16 v[30:33], v[222:225], v[202:205], v[14:17]
	v_mfma_f32_16x16x32_bf16 v[14:17], v[190:193], v[206:209], v[158:161]
	v_mfma_f32_16x16x32_bf16 v[6:9], v[226:229], v[198:201], v[6:9]
	v_mfma_f32_16x16x32_bf16 v[38:41], v[174:177], v[210:213], v[26:29]
	v_mfma_f32_16x16x32_bf16 v[26:29], v[222:225], v[210:213], v[14:17]
	v_mfma_f32_16x16x32_bf16 v[14:17], v[136:139], v[202:205], v[6:9]
	v_mfma_f32_16x16x32_bf16 v[6:9], v[226:229], v[206:209], v[178:181]
	v_mfma_f32_16x16x32_bf16 v[6:9], v[136:139], v[210:213], v[6:9]
	v_cmp_gt_u32_e32 vcc, s34, v135
	s_barrier
	s_and_saveexec_b64 s[12:13], vcc
	s_cbranch_execz .LBB0_887
	s_barrier

; #define STAGE(P, GP, ktrel) do { const GAS char* _g = (GP) + (ktrel) * (BK * 2); \
;     __builtin_amdgcn_global_load_lds((const GAS unsigned*)(_g + so0), (unsigned*)((char*)(P) + tid_ * 16), 16, 0, 0); \
;     __builtin_amdgcn_global_load_lds((const GAS unsigned*)(_g + so1), (unsigned*)((char*)(P) + tid_ * 16 + 8192), 16, 0, 0); } while (0)
; #define WAIT_L(n) asm volatile("s_waitcnt lgkmcnt(" #n ")" ::: "memory")
; #define BAR __builtin_amdgcn_s_barrier()
; #define SCHED __builtin_amdgcn_sched_barrier(0)
; #define LDA(dst, b, h) for (int m = 0; m < 4; ++m) for (int k = 0; k < 2; ++k) \
;     dst[m][k] = *reinterpret_cast<const bf16x8*>((char*)SA(b, h) + lds_byte(wr * 64 + m * 16 + fr, k * 32 + fq * 8))
; #define LDB(dst, b, h) for (int n = 0; n < 2; ++n) for (int k = 0; k < 2; ++k) \
;     dst[n][k] = *reinterpret_cast<const bf16x8*>((char*)SB(b, h) + lds_byte(wc * 32 + n * 16 + fr, k * 32 + fq * 8))
; #define MMA(ai, bj, At_, Bt_) do { __builtin_amdgcn_s_setprio(1); \
;     for (int m = 0; m < 4; ++m) for (int n = 0; n < 2; ++n) for (int k = 0; k < 2; ++k) \
;       acc[ai][bj][m][n] = __builtin_amdgcn_mfma_f32_16x16x32_bf16(At_[m][k], Bt_[n][k], acc[ai][bj][m][n], 0, 0, 0); \
;     __builtin_amdgcn_s_setprio(0); } while (0)
; template <int K, int LD = K>
; __device__ __forceinline__ void gemm_main(const GAS bf16* A, const GAS bf16* Bt, int brow, int bcol, f32x4 (&acc)[2][2][4][2]) {
;     ...
;     LDB(B0, 0, 0); SCHED; LDA(At, 0, 0); STAGE(SA(1, 1), pA1, 1);
;     WAIT_L(8); BAR; WAIT_L(0); MMA(0, 0, At, B0); BAR; SCHED;
;     LDB(B1, 0, 1); STAGE(SB(0, 0), pB0, 2);
;     BAR; WAIT_L(0); MMA(0, 1, At, B1); BAR;
;     LDA(At, 0, 1); STAGE(SA(0, 0), pA0, 2);
;     BAR; WAIT_L(0); MMA(1, 0, At, B0); BAR; SCHED;
.LBB0_1105:
	ds_read_b128 v[160:163], v144
	ds_read_b128 v[164:167], v144 offset:1024
	ds_read_b128 v[174:177], v144 offset:2048
	ds_read_b128 v[178:181], v144 offset:3072
	v_lshl_add_u64 v[168:169], s[12:13], 0, v[130:131]
	v_readfirstlane_b32 s23, v143
	v_lshl_add_u64 v[214:215], v[168:169], 0, s[6:7]
	s_mov_b32 m0, s23
	v_lshl_add_u64 v[230:231], s[12:13], 0, v[132:133]
	v_readfirstlane_b32 s23, v142
	ds_read_b128 v[182:185], v138
	ds_read_b128 v[186:189], v138 offset:1024
	ds_read_b128 v[190:193], v137
	ds_read_b128 v[194:197], v137 offset:1024
	ds_read_b128 v[198:201], v136
	ds_read_b128 v[202:205], v136 offset:1024
	ds_read_b128 v[206:209], v135
	ds_read_b128 v[210:213], v135 offset:1024
	global_load_lds_dwordx4 v[214:215], off
	v_lshl_add_u64 v[214:215], v[230:231], 0, s[6:7]
	s_mov_b32 m0, s23
	s_nop 0
	global_load_lds_dwordx4 v[214:215], off
	s_waitcnt lgkmcnt(8)
	s_waitcnt vmcnt(10)
	s_barrier
	s_waitcnt lgkmcnt(0)
	s_waitcnt lgkmcnt(0)
	v_mfma_f32_16x16x32_bf16 v[126:129], v[182:185], v[160:163], v[126:129]
	v_mfma_f32_16x16x32_bf16 v[122:125], v[182:185], v[174:177], v[122:125]
	v_mfma_f32_16x16x32_bf16 v[118:121], v[190:193], v[160:163], v[118:121]
	v_mfma_f32_16x16x32_bf16 v[114:117], v[190:193], v[174:177], v[114:117]
	v_mfma_f32_16x16x32_bf16 v[110:113], v[198:201], v[160:163], v[110:113]
	v_mfma_f32_16x16x32_bf16 v[106:109], v[198:201], v[174:177], v[106:109]
	v_mfma_f32_16x16x32_bf16 v[102:105], v[206:209], v[160:163], v[102:105]
	v_mfma_f32_16x16x32_bf16 v[98:101], v[206:209], v[174:177], v[98:101]
	v_mfma_f32_16x16x32_bf16 v[126:129], v[186:189], v[164:167], v[126:129]
	v_mfma_f32_16x16x32_bf16 v[122:125], v[186:189], v[178:181], v[122:125]
	v_mfma_f32_16x16x32_bf16 v[118:121], v[194:197], v[164:167], v[118:121]
	v_mfma_f32_16x16x32_bf16 v[114:117], v[194:197], v[178:181], v[114:117]
	v_mfma_f32_16x16x32_bf16 v[110:113], v[202:205], v[164:167], v[110:113]
	v_mfma_f32_16x16x32_bf16 v[106:109], v[202:205], v[178:181], v[106:109]
	v_mfma_f32_16x16x32_bf16 v[102:105], v[210:213], v[164:167], v[102:105]
	v_mfma_f32_16x16x32_bf16 v[98:101], v[210:213], v[178:181], v[98:101]
	s_barrier
	v_lshl_add_u64 v[232:233], s[20:21], 0, v[130:131]
	v_readfirstlane_b32 s23, v151
	v_lshl_add_u64 v[234:235], v[232:233], 0, s[8:9]
	s_mov_b32 m0, s23
	ds_read_b128 v[214:217], v141
	ds_read_b128 v[218:221], v141 offset:1024
	ds_read_b128 v[222:225], v141 offset:2048
	ds_read_b128 v[226:229], v141 offset:3072
	global_load_lds_dwordx4 v[234:235], off
	v_lshl_add_u64 v[234:235], s[20:21], 0, v[132:133]
	v_readfirstlane_b32 s23, v152
	v_lshl_add_u64 v[236:237], v[234:235], 0, s[8:9]
	s_mov_b32 m0, s23
	s_add_u32 s20, s20, 0x100
	global_load_lds_dwordx4 v[236:237], off
	s_waitcnt vmcnt(10)
	s_barrier
	s_waitcnt lgkmcnt(0)
	s_addc_u32 s21, s21, 0
	s_waitcnt lgkmcnt(0)
	v_mfma_f32_16x16x32_bf16 v[94:97], v[182:185], v[214:217], v[94:97]
	v_mfma_f32_16x16x32_bf16 v[90:93], v[182:185], v[222:225], v[90:93]
	v_mfma_f32_16x16x32_bf16 v[86:89], v[190:193], v[214:217], v[86:89]
	v_mfma_f32_16x16x32_bf16 v[82:85], v[190:193], v[222:225], v[82:85]
	v_mfma_f32_16x16x32_bf16 v[78:81], v[198:201], v[214:217], v[78:81]
	v_mfma_f32_16x16x32_bf16 v[74:77], v[198:201], v[222:225], v[74:77]
	v_mfma_f32_16x16x32_bf16 v[70:73], v[206:209], v[214:217], v[70:73]
	v_mfma_f32_16x16x32_bf16 v[66:69], v[206:209], v[222:225], v[66:69]
	v_mfma_f32_16x16x32_bf16 v[94:97], v[186:189], v[218:221], v[94:97]
	v_mfma_f32_16x16x32_bf16 v[90:93], v[186:189], v[226:229], v[90:93]
	v_mfma_f32_16x16x32_bf16 v[86:89], v[194:197], v[218:221], v[86:89]
	v_mfma_f32_16x16x32_bf16 v[82:85], v[194:197], v[226:229], v[82:85]
	v_mfma_f32_16x16x32_bf16 v[78:81], v[202:205], v[218:221], v[78:81]
	v_mfma_f32_16x16x32_bf16 v[74:77], v[202:205], v[226:229], v[74:77]
	v_mfma_f32_16x16x32_bf16 v[70:73], v[210:213], v[218:221], v[70:73]
	v_mfma_f32_16x16x32_bf16 v[66:69], v[210:213], v[226:229], v[66:69]
	v_lshl_add_u64 v[236:237], s[18:19], 0, v[130:131]
	v_readfirstlane_b32 s23, v145
	v_lshl_add_u64 v[238:239], v[236:237], 0, s[8:9]
	s_mov_b32 m0, s23
	s_barrier
	ds_read_b128 v[182:185], v138 offset:16384
	ds_read_b128 v[186:189], v138 offset:17408
	ds_read_b128 v[190:193], v137 offset:16384
	ds_read_b128 v[194:197], v137 offset:17408
	ds_read_b128 v[198:201], v136 offset:16384
	ds_read_b128 v[202:205], v136 offset:17408
	ds_read_b128 v[206:209], v135 offset:16384
	ds_read_b128 v[210:213], v135 offset:17408
	global_load_lds_dwordx4 v[238:239], off
	v_lshl_add_u64 v[238:239], s[18:19], 0, v[132:133]
	v_readfirstlane_b32 s23, v146
	v_lshl_add_u64 v[240:241], v[238:239], 0, s[8:9]
	s_mov_b32 m0, s23
	s_add_u32 s18, s18, 0x100
	global_load_lds_dwordx4 v[240:241], off
	s_barrier
	s_waitcnt lgkmcnt(0)
	s_addc_u32 s19, s19, 0
	s_waitcnt lgkmcnt(0)
	v_mfma_f32_16x16x32_bf16 v[62:65], v[182:185], v[160:163], v[62:65]
	v_mfma_f32_16x16x32_bf16 v[58:61], v[182:185], v[174:177], v[58:61]
	v_mfma_f32_16x16x32_bf16 v[54:57], v[190:193], v[160:163], v[54:57]
	v_mfma_f32_16x16x32_bf16 v[50:53], v[190:193], v[174:177], v[50:53]
	v_mfma_f32_16x16x32_bf16 v[46:49], v[198:201], v[160:163], v[46:49]
	v_mfma_f32_16x16x32_bf16 v[42:45], v[198:201], v[174:177], v[42:45]
	v_mfma_f32_16x16x32_bf16 v[38:41], v[206:209], v[160:163], v[38:41]
	v_mfma_f32_16x16x32_bf16 v[34:37], v[206:209], v[174:177], v[34:37]
	v_mfma_f32_16x16x32_bf16 v[62:65], v[186:189], v[164:167], v[62:65]
	v_mfma_f32_16x16x32_bf16 v[58:61], v[186:189], v[178:181], v[58:61]
	v_mfma_f32_16x16x32_bf16 v[54:57], v[194:197], v[164:167], v[54:57]
	v_mfma_f32_16x16x32_bf16 v[50:53], v[194:197], v[178:181], v[50:53]
	v_mfma_f32_16x16x32_bf16 v[46:49], v[202:205], v[164:167], v[46:49]
	v_mfma_f32_16x16x32_bf16 v[42:45], v[202:205], v[178:181], v[42:45]
	v_mfma_f32_16x16x32_bf16 v[38:41], v[210:213], v[164:167], v[38:41]
	v_mfma_f32_16x16x32_bf16 v[34:37], v[210:213], v[178:181], v[34:37]
	s_barrier
; #define STAGE(P, GP, ktrel) do { const GAS char* _g = (GP) + (ktrel) * (BK * 2); \
;     __builtin_amdgcn_global_load_lds((const GAS unsigned*)(_g + so0), (unsigned*)((char*)(P) + tid_ * 16), 16, 0, 0); \
;     __builtin_amdgcn_global_load_lds((const GAS unsigned*)(_g + so1), (unsigned*)((char*)(P) + tid_ * 16 + 8192), 16, 0, 0); } while (0)
; #define WAIT_V(n) asm volatile("s_waitcnt vmcnt(" #n ")" ::: "memory")
; #define WAIT_L(n) asm volatile("s_waitcnt lgkmcnt(" #n ")" ::: "memory")
; #define BAR __builtin_amdgcn_s_barrier()
; #define SCHED __builtin_amdgcn_sched_barrier(0)
; #define LDA(dst, b, h) for (int m = 0; m < 4; ++m) for (int k = 0; k < 2; ++k) \
;     dst[m][k] = *reinterpret_cast<const bf16x8*>((char*)SA(b, h) + lds_byte(wr * 64 + m * 16 + fr, k * 32 + fq * 8))
; #define LDB(dst, b, h) for (int n = 0; n < 2; ++n) for (int k = 0; k < 2; ++k) \
;     dst[n][k] = *reinterpret_cast<const bf16x8*>((char*)SB(b, h) + lds_byte(wc * 32 + n * 16 + fr, k * 32 + fq * 8))
; #define MMA(ai, bj, At_, Bt_) do { __builtin_amdgcn_s_setprio(1); \
;     for (int m = 0; m < 4; ++m) for (int n = 0; n < 2; ++n) for (int k = 0; k < 2; ++k) \
;       acc[ai][bj][m][n] = __builtin_amdgcn_mfma_f32_16x16x32_bf16(At_[m][k], Bt_[n][k], acc[ai][bj][m][n], 0, 0, 0); \
;     __builtin_amdgcn_s_setprio(0); } while (0)
; template <int K, int LD = K>
; __device__ __forceinline__ void gemm_main(const GAS bf16* A, const GAS bf16* Bt, int brow, int bcol, f32x4 (&acc)[2][2][4][2]) {
;     ...
;     BAR; WAIT_L(0); MMA(1, 0, At, B0); BAR; SCHED;
;     STAGE(SB(0, 1), pB1, 2);
;     WAIT_V(6); BAR; MMA(1, 1, At, B1); BAR;
;     LDB(B0, 1, 0); SCHED; LDA(At, 1, 0); STAGE(SA(0, 1), pA1, 2);
;     WAIT_L(8); BAR; WAIT_L(0); MMA(0, 0, At, B0); BAR; SCHED;
;     LDB(B1, 1, 1); STAGE(SB(1, 0), pB0, 3);
;     BAR; WAIT_L(0); MMA(0, 1, At, B1); BAR;
	v_lshl_add_u64 v[240:241], s[16:17], 0, v[130:131]
	v_readfirstlane_b32 s23, v153
	v_lshl_add_u64 v[160:161], v[240:241], 0, s[8:9]
	s_mov_b32 m0, s23
	v_lshl_add_u64 v[242:243], s[16:17], 0, v[132:133]
	v_readfirstlane_b32 s23, v154
	global_load_lds_dwordx4 v[160:161], off
	v_lshl_add_u64 v[160:161], v[242:243], 0, s[8:9]
	s_mov_b32 m0, s23
	s_add_u32 s16, s16, 0x100
	global_load_lds_dwordx4 v[160:161], off
	s_waitcnt vmcnt(10)
	s_addc_u32 s17, s17, 0
	s_barrier
	v_mfma_f32_16x16x32_bf16 v[30:33], v[182:185], v[214:217], v[30:33]
	v_mfma_f32_16x16x32_bf16 v[26:29], v[182:185], v[222:225], v[26:29]
	v_mfma_f32_16x16x32_bf16 v[22:25], v[190:193], v[214:217], v[22:25]
	v_mfma_f32_16x16x32_bf16 v[18:21], v[190:193], v[222:225], v[18:21]
	v_mfma_f32_16x16x32_bf16 v[14:17], v[198:201], v[214:217], v[14:17]
	v_mfma_f32_16x16x32_bf16 v[10:13], v[198:201], v[222:225], v[10:13]
	v_mfma_f32_16x16x32_bf16 v[6:9], v[206:209], v[214:217], v[6:9]
	v_mfma_f32_16x16x32_bf16 v[2:5], v[206:209], v[222:225], v[2:5]
	v_mfma_f32_16x16x32_bf16 v[30:33], v[186:189], v[218:221], v[30:33]
	v_mfma_f32_16x16x32_bf16 v[26:29], v[186:189], v[226:229], v[26:29]
	v_mfma_f32_16x16x32_bf16 v[22:25], v[194:197], v[218:221], v[22:25]
	v_mfma_f32_16x16x32_bf16 v[18:21], v[194:197], v[226:229], v[18:21]
	v_mfma_f32_16x16x32_bf16 v[14:17], v[202:205], v[218:221], v[14:17]
	v_mfma_f32_16x16x32_bf16 v[10:13], v[202:205], v[226:229], v[10:13]
	v_mfma_f32_16x16x32_bf16 v[6:9], v[210:213], v[218:221], v[6:9]
	v_mfma_f32_16x16x32_bf16 v[2:5], v[210:213], v[226:229], v[2:5]
	s_barrier
	ds_read_b128 v[160:163], v140
	ds_read_b128 v[164:167], v140 offset:1024
	ds_read_b128 v[174:177], v140 offset:2048
	ds_read_b128 v[178:181], v140 offset:3072
	v_readfirstlane_b32 s23, v147
	v_lshl_add_u64 v[168:169], v[168:169], 0, s[8:9]
	s_mov_b32 m0, s23
	v_readfirstlane_b32 s23, v148
	ds_read_b128 v[182:185], v138 offset:32768
	ds_read_b128 v[186:189], v138 offset:33792
	ds_read_b128 v[190:193], v137 offset:32768
	ds_read_b128 v[194:197], v137 offset:33792
	ds_read_b128 v[198:201], v136 offset:32768
	ds_read_b128 v[202:205], v136 offset:33792
	ds_read_b128 v[206:209], v135 offset:32768
	ds_read_b128 v[210:213], v135 offset:33792
	global_load_lds_dwordx4 v[168:169], off
	v_lshl_add_u64 v[168:169], v[230:231], 0, s[8:9]
	s_mov_b32 m0, s23
	s_add_u32 s12, s12, 0x100
	global_load_lds_dwordx4 v[168:169], off
	s_waitcnt lgkmcnt(8)
	s_waitcnt vmcnt(10)
	s_barrier
	s_waitcnt lgkmcnt(0)
	s_addc_u32 s13, s13, 0
	s_waitcnt lgkmcnt(0)
	v_mfma_f32_16x16x32_bf16 v[126:129], v[182:185], v[160:163], v[126:129]
	v_mfma_f32_16x16x32_bf16 v[122:125], v[182:185], v[174:177], v[122:125]
	v_mfma_f32_16x16x32_bf16 v[118:121], v[190:193], v[160:163], v[118:121]
	v_mfma_f32_16x16x32_bf16 v[114:117], v[190:193], v[174:177], v[114:117]
	v_mfma_f32_16x16x32_bf16 v[110:113], v[198:201], v[160:163], v[110:113]
	v_mfma_f32_16x16x32_bf16 v[106:109], v[198:201], v[174:177], v[106:109]
	v_mfma_f32_16x16x32_bf16 v[102:105], v[206:209], v[160:163], v[102:105]
	v_mfma_f32_16x16x32_bf16 v[98:101], v[206:209], v[174:177], v[98:101]
	v_mfma_f32_16x16x32_bf16 v[126:129], v[186:189], v[164:167], v[126:129]
	v_mfma_f32_16x16x32_bf16 v[122:125], v[186:189], v[178:181], v[122:125]
	v_mfma_f32_16x16x32_bf16 v[118:121], v[194:197], v[164:167], v[118:121]
	v_mfma_f32_16x16x32_bf16 v[114:117], v[194:197], v[178:181], v[114:117]
	v_mfma_f32_16x16x32_bf16 v[110:113], v[202:205], v[164:167], v[110:113]
	v_mfma_f32_16x16x32_bf16 v[106:109], v[202:205], v[178:181], v[106:109]
	v_mfma_f32_16x16x32_bf16 v[102:105], v[210:213], v[164:167], v[102:105]
	v_mfma_f32_16x16x32_bf16 v[98:101], v[210:213], v[178:181], v[98:101]
	s_barrier
	v_readfirstlane_b32 s23, v155
	v_lshl_add_u64 v[168:169], v[232:233], 0, s[10:11]
	s_mov_b32 m0, s23
	v_readfirstlane_b32 s23, v156
	ds_read_b128 v[214:217], v139
	ds_read_b128 v[218:221], v139 offset:1024
	ds_read_b128 v[222:225], v139 offset:2048
	ds_read_b128 v[226:229], v139 offset:3072
	global_load_lds_dwordx4 v[168:169], off
	v_lshl_add_u64 v[168:169], v[234:235], 0, s[10:11]
	s_mov_b32 m0, s23
	s_nop 0
	global_load_lds_dwordx4 v[168:169], off
	s_waitcnt vmcnt(10)
	s_barrier
	s_waitcnt lgkmcnt(0)
	s_waitcnt lgkmcnt(0)
	v_mfma_f32_16x16x32_bf16 v[94:97], v[182:185], v[214:217], v[94:97]
	v_mfma_f32_16x16x32_bf16 v[90:93], v[182:185], v[222:225], v[90:93]
	v_mfma_f32_16x16x32_bf16 v[86:89], v[190:193], v[214:217], v[86:89]
	v_mfma_f32_16x16x32_bf16 v[82:85], v[190:193], v[222:225], v[82:85]
	v_mfma_f32_16x16x32_bf16 v[78:81], v[198:201], v[214:217], v[78:81]
	v_mfma_f32_16x16x32_bf16 v[74:77], v[198:201], v[222:225], v[74:77]
	v_mfma_f32_16x16x32_bf16 v[70:73], v[206:209], v[214:217], v[70:73]
	v_mfma_f32_16x16x32_bf16 v[66:69], v[206:209], v[222:225], v[66:69]
	v_mfma_f32_16x16x32_bf16 v[94:97], v[186:189], v[218:221], v[94:97]
	v_mfma_f32_16x16x32_bf16 v[90:93], v[186:189], v[226:229], v[90:93]
	v_mfma_f32_16x16x32_bf16 v[86:89], v[194:197], v[218:221], v[86:89]
	v_mfma_f32_16x16x32_bf16 v[82:85], v[194:197], v[226:229], v[82:85]
	v_mfma_f32_16x16x32_bf16 v[78:81], v[202:205], v[218:221], v[78:81]
	v_mfma_f32_16x16x32_bf16 v[74:77], v[202:205], v[226:229], v[74:77]
	v_mfma_f32_16x16x32_bf16 v[70:73], v[210:213], v[218:221], v[70:73]
	v_mfma_f32_16x16x32_bf16 v[66:69], v[210:213], v[226:229], v[66:69]
	v_readfirstlane_b32 s23, v149
	v_lshl_add_u64 v[168:169], v[236:237], 0, s[10:11]
	s_mov_b32 m0, s23
	v_readfirstlane_b32 s23, v150
	s_barrier
; #define STAGE(P, GP, ktrel) do { const GAS char* _g = (GP) + (ktrel) * (BK * 2); \
;     __builtin_amdgcn_global_load_lds((const GAS unsigned*)(_g + so0), (unsigned*)((char*)(P) + tid_ * 16), 16, 0, 0); \
;     __builtin_amdgcn_global_load_lds((const GAS unsigned*)(_g + so1), (unsigned*)((char*)(P) + tid_ * 16 + 8192), 16, 0, 0); } while (0)
; #define WAIT_V(n) asm volatile("s_waitcnt vmcnt(" #n ")" ::: "memory")
; #define WAIT_L(n) asm volatile("s_waitcnt lgkmcnt(" #n ")" ::: "memory")
; #define BAR __builtin_amdgcn_s_barrier()
; #define SCHED __builtin_amdgcn_sched_barrier(0)
; #define LDA(dst, b, h) for (int m = 0; m < 4; ++m) for (int k = 0; k < 2; ++k) \
;     dst[m][k] = *reinterpret_cast<const bf16x8*>((char*)SA(b, h) + lds_byte(wr * 64 + m * 16 + fr, k * 32 + fq * 8))
; #define LDB(dst, b, h) for (int n = 0; n < 2; ++n) for (int k = 0; k < 2; ++k) \
;     dst[n][k] = *reinterpret_cast<const bf16x8*>((char*)SB(b, h) + lds_byte(wc * 32 + n * 16 + fr, k * 32 + fq * 8))
; #define MMA(ai, bj, At_, Bt_) do { __builtin_amdgcn_s_setprio(1); \
;     for (int m = 0; m < 4; ++m) for (int n = 0; n < 2; ++n) for (int k = 0; k < 2; ++k) \
;       acc[ai][bj][m][n] = __builtin_amdgcn_mfma_f32_16x16x32_bf16(At_[m][k], Bt_[n][k], acc[ai][bj][m][n], 0, 0, 0); \
;     __builtin_amdgcn_s_setprio(0); } while (0)
; template <int K, int LD = K>
; __device__ __forceinline__ void gemm_main(const GAS bf16* A, const GAS bf16* Bt, int brow, int bcol, f32x4 (&acc)[2][2][4][2]) {
;     ...
;     LDA(At, 1, 1); STAGE(SA(1, 0), pA0, 3);
;     BAR; WAIT_L(0); MMA(1, 0, At, B0); BAR; SCHED;
;     STAGE(SB(1, 1), pB1, 3);
;     WAIT_V(6); BAR; MMA(1, 1, At, B1); BAR;
;     pA0 += 4 * BK; pA1 += 4 * BK; pB0 += 4 * BK; pB1 += 4 * BK;
;     asm volatile("" : "+s"(pA0), "+s"(pA1), "+s"(pB0), "+s"(pB1));
;   }
;   { LDB(B0, 0, 0); LDA(At, 0, 0); STAGE(SA(1, 1), pA1, 1);
;     BAR; WAIT_L(0); MMA(0, 0, At, B0); BAR;
	ds_read_b128 v[182:185], v138 offset:49152
	ds_read_b128 v[186:189], v138 offset:50176
	ds_read_b128 v[190:193], v137 offset:49152
	ds_read_b128 v[194:197], v137 offset:50176
	ds_read_b128 v[198:201], v136 offset:49152
	ds_read_b128 v[202:205], v136 offset:50176
	ds_read_b128 v[206:209], v135 offset:49152
	ds_read_b128 v[210:213], v135 offset:50176
	global_load_lds_dwordx4 v[168:169], off
	v_lshl_add_u64 v[168:169], v[238:239], 0, s[10:11]
	s_mov_b32 m0, s23
	s_nop 0
	global_load_lds_dwordx4 v[168:169], off
	s_barrier
	s_waitcnt lgkmcnt(0)
	s_waitcnt lgkmcnt(0)
	v_mfma_f32_16x16x32_bf16 v[62:65], v[182:185], v[160:163], v[62:65]
	v_mfma_f32_16x16x32_bf16 v[58:61], v[182:185], v[174:177], v[58:61]
	v_mfma_f32_16x16x32_bf16 v[54:57], v[190:193], v[160:163], v[54:57]
	v_mfma_f32_16x16x32_bf16 v[50:53], v[190:193], v[174:177], v[50:53]
	v_mfma_f32_16x16x32_bf16 v[46:49], v[198:201], v[160:163], v[46:49]
	v_mfma_f32_16x16x32_bf16 v[42:45], v[198:201], v[174:177], v[42:45]
	v_mfma_f32_16x16x32_bf16 v[38:41], v[206:209], v[160:163], v[38:41]
	v_mfma_f32_16x16x32_bf16 v[34:37], v[206:209], v[174:177], v[34:37]
	v_mfma_f32_16x16x32_bf16 v[62:65], v[186:189], v[164:167], v[62:65]
	v_mfma_f32_16x16x32_bf16 v[58:61], v[186:189], v[178:181], v[58:61]
	v_mfma_f32_16x16x32_bf16 v[54:57], v[194:197], v[164:167], v[54:57]
	v_mfma_f32_16x16x32_bf16 v[50:53], v[194:197], v[178:181], v[50:53]
	v_mfma_f32_16x16x32_bf16 v[46:49], v[202:205], v[164:167], v[46:49]
	v_mfma_f32_16x16x32_bf16 v[42:45], v[202:205], v[178:181], v[42:45]
	v_mfma_f32_16x16x32_bf16 v[38:41], v[210:213], v[164:167], v[38:41]
	v_mfma_f32_16x16x32_bf16 v[34:37], v[210:213], v[178:181], v[34:37]
	s_barrier
	v_readfirstlane_b32 s23, v157
	v_lshl_add_u64 v[160:161], v[240:241], 0, s[10:11]
	s_mov_b32 m0, s23
	v_readfirstlane_b32 s23, v158
	global_load_lds_dwordx4 v[160:161], off
	v_lshl_add_u64 v[160:161], v[242:243], 0, s[10:11]
	s_mov_b32 m0, s23
	s_nop 0
	global_load_lds_dwordx4 v[160:161], off
	s_waitcnt vmcnt(10)
	s_barrier
	v_mfma_f32_16x16x32_bf16 v[30:33], v[182:185], v[214:217], v[30:33]
	v_mfma_f32_16x16x32_bf16 v[26:29], v[182:185], v[222:225], v[26:29]
	v_mfma_f32_16x16x32_bf16 v[22:25], v[190:193], v[214:217], v[22:25]
	v_mfma_f32_16x16x32_bf16 v[18:21], v[190:193], v[222:225], v[18:21]
	v_mfma_f32_16x16x32_bf16 v[14:17], v[198:201], v[214:217], v[14:17]
	v_mfma_f32_16x16x32_bf16 v[10:13], v[198:201], v[222:225], v[10:13]
	v_mfma_f32_16x16x32_bf16 v[6:9], v[206:209], v[214:217], v[6:9]
	v_mfma_f32_16x16x32_bf16 v[2:5], v[206:209], v[222:225], v[2:5]
	v_mfma_f32_16x16x32_bf16 v[30:33], v[186:189], v[218:221], v[30:33]
	v_mfma_f32_16x16x32_bf16 v[26:29], v[186:189], v[226:229], v[26:29]
	v_mfma_f32_16x16x32_bf16 v[22:25], v[194:197], v[218:221], v[22:25]
	v_mfma_f32_16x16x32_bf16 v[18:21], v[194:197], v[226:229], v[18:21]
	v_mfma_f32_16x16x32_bf16 v[14:17], v[202:205], v[218:221], v[14:17]
	v_mfma_f32_16x16x32_bf16 v[10:13], v[202:205], v[226:229], v[10:13]
	v_mfma_f32_16x16x32_bf16 v[6:9], v[210:213], v[218:221], v[6:9]
	v_mfma_f32_16x16x32_bf16 v[2:5], v[210:213], v[226:229], v[2:5]
	s_add_i32 s22, s22, 2
	s_cmp_lt_u32 s22, 40
	s_barrier
	s_cbranch_scc1 .LBB0_1105
	ds_read_b128 v[146:149], v144
	ds_read_b128 v[150:153], v144 offset:1024
	ds_read_b128 v[154:157], v144 offset:2048
	ds_read_b128 v[158:161], v144 offset:3072
	ds_read_b128 v[162:165], v138
	ds_read_b128 v[166:169], v138 offset:1024
	ds_read_b128 v[174:177], v137
	ds_read_b128 v[178:181], v137 offset:1024
	ds_read_b128 v[182:185], v136
	ds_read_b128 v[186:189], v136 offset:1024
	ds_read_b128 v[190:193], v135
	ds_read_b128 v[194:197], v135 offset:1024
	v_lshl_add_u64 v[144:145], s[12:13], 0, v[130:131]
	v_readfirstlane_b32 s16, v143
	v_lshl_add_u64 v[144:145], v[144:145], 0, s[6:7]
	s_mov_b32 m0, s16
	v_lshl_add_u64 v[132:133], s[12:13], 0, v[132:133]
	v_readfirstlane_b32 s12, v142
	global_load_lds_dwordx4 v[144:145], off
	v_lshl_add_u64 v[132:133], v[132:133], 0, s[6:7]
	s_mov_b32 m0, s12
	s_nop 0
	global_load_lds_dwordx4 v[132:133], off
	s_waitcnt vmcnt(10)
	s_barrier
	s_waitcnt lgkmcnt(0)
	s_waitcnt lgkmcnt(0)
	v_mfma_f32_16x16x32_bf16 v[126:129], v[162:165], v[146:149], v[126:129]
	v_mfma_f32_16x16x32_bf16 v[122:125], v[162:165], v[154:157], v[122:125]
	v_mfma_f32_16x16x32_bf16 v[110:113], v[182:185], v[146:149], v[110:113]
	v_mfma_f32_16x16x32_bf16 v[106:109], v[182:185], v[154:157], v[106:109]
	v_mfma_f32_16x16x32_bf16 v[126:129], v[166:169], v[150:153], v[126:129]
	v_mfma_f32_16x16x32_bf16 v[122:125], v[166:169], v[158:161], v[122:125]
	v_mfma_f32_16x16x32_bf16 v[118:121], v[174:177], v[146:149], v[118:121]
	v_mfma_f32_16x16x32_bf16 v[114:117], v[174:177], v[154:157], v[114:117]
	v_mfma_f32_16x16x32_bf16 v[110:113], v[186:189], v[150:153], v[110:113]
	v_mfma_f32_16x16x32_bf16 v[106:109], v[186:189], v[158:161], v[106:109]
	v_mfma_f32_16x16x32_bf16 v[102:105], v[190:193], v[146:149], v[102:105]
	v_mfma_f32_16x16x32_bf16 v[98:101], v[190:193], v[154:157], v[98:101]
	v_mfma_f32_16x16x32_bf16 v[142:145], v[178:181], v[150:153], v[118:121]
	v_mfma_f32_16x16x32_bf16 v[198:201], v[178:181], v[158:161], v[114:117]
	v_mfma_f32_16x16x32_bf16 v[202:205], v[194:197], v[150:153], v[102:105]
	v_mfma_f32_16x16x32_bf16 v[206:209], v[194:197], v[158:161], v[98:101]
	s_barrier
	s_nop 1
	ds_read_b128 v[98:101], v141
	ds_read_b128 v[102:105], v141 offset:1024
	ds_read_b128 v[114:117], v141 offset:2048
	ds_read_b128 v[118:121], v141 offset:3072
	s_waitcnt vmcnt(8)
	s_barrier
; #define WAIT_V(n) asm volatile("s_waitcnt vmcnt(" #n ")" ::: "memory")
; #define WAIT_L(n) asm volatile("s_waitcnt lgkmcnt(" #n ")" ::: "memory")
; #define BAR __builtin_amdgcn_s_barrier()
; #define LDA(dst, b, h) for (int m = 0; m < 4; ++m) for (int k = 0; k < 2; ++k) \
;     dst[m][k] = *reinterpret_cast<const bf16x8*>((char*)SA(b, h) + lds_byte(wr * 64 + m * 16 + fr, k * 32 + fq * 8))
; #define LDB(dst, b, h) for (int n = 0; n < 2; ++n) for (int k = 0; k < 2; ++k) \
;     dst[n][k] = *reinterpret_cast<const bf16x8*>((char*)SB(b, h) + lds_byte(wc * 32 + n * 16 + fr, k * 32 + fq * 8))
; #define MMA(ai, bj, At_, Bt_) do { __builtin_amdgcn_s_setprio(1); \
;     for (int m = 0; m < 4; ++m) for (int n = 0; n < 2; ++n) for (int k = 0; k < 2; ++k) \
;       acc[ai][bj][m][n] = __builtin_amdgcn_mfma_f32_16x16x32_bf16(At_[m][k], Bt_[n][k], acc[ai][bj][m][n], 0, 0, 0); \
;     __builtin_amdgcn_s_setprio(0); } while (0)
; template <int K, int LD = K>
; __device__ __forceinline__ void gemm_main(const GAS bf16* A, const GAS bf16* Bt, int brow, int bcol, f32x4 (&acc)[2][2][4][2]) {
;     ...
;     LDB(B1, 0, 1); BAR; WAIT_L(0); MMA(0, 1, At, B1); BAR;
;     LDA(At, 0, 1); WAIT_V(4); BAR; WAIT_L(0); MMA(1, 0, At, B0); MMA(1, 1, At, B1); BAR; }
;   { LDB(B0, 1, 0); LDA(At, 1, 0); WAIT_V(2); BAR; WAIT_L(0); MMA(0, 0, At, B0); BAR;
	s_waitcnt lgkmcnt(0)
	s_waitcnt lgkmcnt(0)
	v_mfma_f32_16x16x32_bf16 v[94:97], v[162:165], v[98:101], v[94:97]
	v_mfma_f32_16x16x32_bf16 v[90:93], v[162:165], v[114:117], v[90:93]
	v_mfma_f32_16x16x32_bf16 v[78:81], v[182:185], v[98:101], v[78:81]
	v_mfma_f32_16x16x32_bf16 v[74:77], v[182:185], v[114:117], v[74:77]
	v_mfma_f32_16x16x32_bf16 v[94:97], v[166:169], v[102:105], v[94:97]
	v_mfma_f32_16x16x32_bf16 v[90:93], v[166:169], v[118:121], v[90:93]
	v_mfma_f32_16x16x32_bf16 v[86:89], v[174:177], v[98:101], v[86:89]
	v_mfma_f32_16x16x32_bf16 v[82:85], v[174:177], v[114:117], v[82:85]
	v_mfma_f32_16x16x32_bf16 v[78:81], v[186:189], v[102:105], v[78:81]
	v_mfma_f32_16x16x32_bf16 v[74:77], v[186:189], v[118:121], v[74:77]
	v_mfma_f32_16x16x32_bf16 v[70:73], v[190:193], v[98:101], v[70:73]
	v_mfma_f32_16x16x32_bf16 v[66:69], v[190:193], v[114:117], v[66:69]
	v_mfma_f32_16x16x32_bf16 v[162:165], v[178:181], v[102:105], v[86:89]
	v_mfma_f32_16x16x32_bf16 v[166:169], v[178:181], v[118:121], v[82:85]
	v_mfma_f32_16x16x32_bf16 v[174:177], v[194:197], v[102:105], v[70:73]
	v_mfma_f32_16x16x32_bf16 v[178:181], v[194:197], v[118:121], v[66:69]
	s_barrier
	s_nop 1
	ds_read_b128 v[66:69], v138 offset:16384
	ds_read_b128 v[70:73], v138 offset:17408
	ds_read_b128 v[82:85], v137 offset:16384
	ds_read_b128 v[86:89], v137 offset:17408
	ds_read_b128 v[182:185], v136 offset:16384
	ds_read_b128 v[186:189], v136 offset:17408
	ds_read_b128 v[190:193], v135 offset:16384
	ds_read_b128 v[194:197], v135 offset:17408
	s_waitcnt vmcnt(4)
	s_barrier
	s_waitcnt lgkmcnt(0)
	s_waitcnt lgkmcnt(0)
	v_mfma_f32_16x16x32_bf16 v[62:65], v[66:69], v[146:149], v[62:65]
	v_mfma_f32_16x16x32_bf16 v[58:61], v[66:69], v[154:157], v[58:61]
	v_mfma_f32_16x16x32_bf16 v[46:49], v[182:185], v[146:149], v[46:49]
	v_mfma_f32_16x16x32_bf16 v[42:45], v[182:185], v[154:157], v[42:45]
	v_mfma_f32_16x16x32_bf16 v[62:65], v[70:73], v[150:153], v[62:65]
	v_mfma_f32_16x16x32_bf16 v[58:61], v[70:73], v[158:161], v[58:61]
	v_mfma_f32_16x16x32_bf16 v[54:57], v[82:85], v[146:149], v[54:57]
	v_mfma_f32_16x16x32_bf16 v[50:53], v[82:85], v[154:157], v[50:53]
	v_mfma_f32_16x16x32_bf16 v[46:49], v[186:189], v[150:153], v[46:49]
	v_mfma_f32_16x16x32_bf16 v[42:45], v[186:189], v[158:161], v[42:45]
	v_mfma_f32_16x16x32_bf16 v[38:41], v[190:193], v[146:149], v[38:41]
	v_mfma_f32_16x16x32_bf16 v[34:37], v[190:193], v[154:157], v[34:37]
	v_mfma_f32_16x16x32_bf16 v[210:213], v[86:89], v[150:153], v[54:57]
	v_mfma_f32_16x16x32_bf16 v[214:217], v[86:89], v[158:161], v[50:53]
	v_mfma_f32_16x16x32_bf16 v[146:149], v[194:197], v[150:153], v[38:41]
	v_mfma_f32_16x16x32_bf16 v[150:153], v[194:197], v[158:161], v[34:37]
	v_mfma_f32_16x16x32_bf16 v[30:33], v[66:69], v[98:101], v[30:33]
	v_mfma_f32_16x16x32_bf16 v[26:29], v[66:69], v[114:117], v[26:29]
	v_mfma_f32_16x16x32_bf16 v[14:17], v[182:185], v[98:101], v[14:17]
	v_mfma_f32_16x16x32_bf16 v[10:13], v[182:185], v[114:117], v[10:13]
	v_mfma_f32_16x16x32_bf16 v[30:33], v[70:73], v[102:105], v[30:33]
	v_mfma_f32_16x16x32_bf16 v[26:29], v[70:73], v[118:121], v[26:29]
	v_mfma_f32_16x16x32_bf16 v[22:25], v[82:85], v[98:101], v[22:25]
	v_mfma_f32_16x16x32_bf16 v[18:21], v[82:85], v[114:117], v[18:21]
	v_mfma_f32_16x16x32_bf16 v[14:17], v[186:189], v[102:105], v[14:17]
	v_mfma_f32_16x16x32_bf16 v[10:13], v[186:189], v[118:121], v[10:13]
	v_mfma_f32_16x16x32_bf16 v[6:9], v[190:193], v[98:101], v[6:9]
	v_mfma_f32_16x16x32_bf16 v[2:5], v[190:193], v[114:117], v[2:5]
	v_mfma_f32_16x16x32_bf16 v[154:157], v[86:89], v[102:105], v[22:25]
	v_mfma_f32_16x16x32_bf16 v[158:161], v[86:89], v[118:121], v[18:21]
	v_mfma_f32_16x16x32_bf16 v[182:185], v[194:197], v[102:105], v[6:9]
	v_mfma_f32_16x16x32_bf16 v[186:189], v[194:197], v[118:121], v[2:5]
	s_barrier
	s_nop 1
	ds_read_b128 v[2:5], v140
	ds_read_b128 v[6:9], v140 offset:1024
	ds_read_b128 v[190:193], v140 offset:2048
	ds_read_b128 v[194:197], v140 offset:3072
	ds_read_b128 v[18:21], v138 offset:32768
	ds_read_b128 v[22:25], v138 offset:33792
	ds_read_b128 v[34:37], v137 offset:32768
	ds_read_b128 v[38:41], v137 offset:33792
	ds_read_b128 v[50:53], v136 offset:32768
	ds_read_b128 v[54:57], v136 offset:33792
	ds_read_b128 v[218:221], v135 offset:32768
	ds_read_b128 v[222:225], v135 offset:33792
	s_waitcnt vmcnt(2)
	s_barrier
; #define WAIT_V(n) asm volatile("s_waitcnt vmcnt(" #n ")" ::: "memory")
; #define WAIT_L(n) asm volatile("s_waitcnt lgkmcnt(" #n ")" ::: "memory")
; #define BAR __builtin_amdgcn_s_barrier()
; #define LDA(dst, b, h) for (int m = 0; m < 4; ++m) for (int k = 0; k < 2; ++k) \
;     dst[m][k] = *reinterpret_cast<const bf16x8*>((char*)SA(b, h) + lds_byte(wr * 64 + m * 16 + fr, k * 32 + fq * 8))
; #define LDB(dst, b, h) for (int n = 0; n < 2; ++n) for (int k = 0; k < 2; ++k) \
;     dst[n][k] = *reinterpret_cast<const bf16x8*>((char*)SB(b, h) + lds_byte(wc * 32 + n * 16 + fr, k * 32 + fq * 8))
; #define MMA(ai, bj, At_, Bt_) do { __builtin_amdgcn_s_setprio(1); \
;     for (int m = 0; m < 4; ++m) for (int n = 0; n < 2; ++n) for (int k = 0; k < 2; ++k) \
;       acc[ai][bj][m][n] = __builtin_amdgcn_mfma_f32_16x16x32_bf16(At_[m][k], Bt_[n][k], acc[ai][bj][m][n], 0, 0, 0); \
;     __builtin_amdgcn_s_setprio(0); } while (0)
; template <int K, int LD = K>
; __device__ __forceinline__ void gemm_main(const GAS bf16* A, const GAS bf16* Bt, int brow, int bcol, f32x4 (&acc)[2][2][4][2]) {
;     ...
;   { LDB(B0, 1, 0); LDA(At, 1, 0); WAIT_V(2); BAR; WAIT_L(0); MMA(0, 0, At, B0); BAR;
;     LDB(B1, 1, 1); WAIT_V(0); BAR; WAIT_L(0); MMA(0, 1, At, B1); BAR;
;     LDA(At, 1, 1); BAR; WAIT_L(0); MMA(1, 0, At, B0); MMA(1, 1, At, B1); BAR; }
;   if (wr == 0) BAR;
	s_waitcnt lgkmcnt(0)
	s_waitcnt lgkmcnt(0)
	v_mfma_f32_16x16x32_bf16 v[66:69], v[18:21], v[2:5], v[126:129]
	v_mfma_f32_16x16x32_bf16 v[118:121], v[22:25], v[6:9], v[66:69]
	v_mfma_f32_16x16x32_bf16 v[66:69], v[18:21], v[190:193], v[122:125]
	v_mfma_f32_16x16x32_bf16 v[114:117], v[22:25], v[194:197], v[66:69]
	v_mfma_f32_16x16x32_bf16 v[66:69], v[34:37], v[2:5], v[142:145]
	v_mfma_f32_16x16x32_bf16 v[102:105], v[38:41], v[6:9], v[66:69]
	v_mfma_f32_16x16x32_bf16 v[66:69], v[34:37], v[190:193], v[198:201]
	v_mfma_f32_16x16x32_bf16 v[98:101], v[38:41], v[194:197], v[66:69]
	v_mfma_f32_16x16x32_bf16 v[66:69], v[50:53], v[2:5], v[110:113]
	v_mfma_f32_16x16x32_bf16 v[86:89], v[54:57], v[6:9], v[66:69]
	v_mfma_f32_16x16x32_bf16 v[66:69], v[50:53], v[190:193], v[106:109]
	v_mfma_f32_16x16x32_bf16 v[82:85], v[54:57], v[194:197], v[66:69]
	v_mfma_f32_16x16x32_bf16 v[66:69], v[218:221], v[2:5], v[202:205]
	v_mfma_f32_16x16x32_bf16 v[70:73], v[222:225], v[6:9], v[66:69]
	v_mfma_f32_16x16x32_bf16 v[66:69], v[218:221], v[190:193], v[206:209]
	v_mfma_f32_16x16x32_bf16 v[66:69], v[222:225], v[194:197], v[66:69]
	s_barrier
	ds_read_b128 v[140:143], v139
	ds_read_b128 v[198:201], v139 offset:1024
	ds_read_b128 v[202:205], v139 offset:2048
	ds_read_b128 v[206:209], v139 offset:3072
	s_waitcnt vmcnt(0)
	s_barrier
	s_waitcnt lgkmcnt(0)
	s_waitcnt lgkmcnt(0)
	v_mfma_f32_16x16x32_bf16 v[94:97], v[18:21], v[140:143], v[94:97]
	v_mfma_f32_16x16x32_bf16 v[18:21], v[18:21], v[202:205], v[90:93]
	v_mfma_f32_16x16x32_bf16 v[122:125], v[22:25], v[206:209], v[18:21]
	v_mfma_f32_16x16x32_bf16 v[18:21], v[34:37], v[140:143], v[162:165]
	v_mfma_f32_16x16x32_bf16 v[110:113], v[38:41], v[198:201], v[18:21]
	v_mfma_f32_16x16x32_bf16 v[18:21], v[34:37], v[202:205], v[166:169]
	v_mfma_f32_16x16x32_bf16 v[106:109], v[38:41], v[206:209], v[18:21]
	v_mfma_f32_16x16x32_bf16 v[18:21], v[50:53], v[140:143], v[78:81]
	v_mfma_f32_16x16x32_bf16 v[126:129], v[22:25], v[198:201], v[94:97]
	v_mfma_f32_16x16x32_bf16 v[94:97], v[54:57], v[198:201], v[18:21]
	v_mfma_f32_16x16x32_bf16 v[18:21], v[50:53], v[202:205], v[74:77]
	v_mfma_f32_16x16x32_bf16 v[90:93], v[54:57], v[206:209], v[18:21]
	v_mfma_f32_16x16x32_bf16 v[18:21], v[218:221], v[140:143], v[174:177]
	v_mfma_f32_16x16x32_bf16 v[78:81], v[222:225], v[198:201], v[18:21]
	v_mfma_f32_16x16x32_bf16 v[18:21], v[218:221], v[202:205], v[178:181]
	v_mfma_f32_16x16x32_bf16 v[74:77], v[222:225], v[206:209], v[18:21]
	s_barrier
	ds_read_b128 v[162:165], v138 offset:49152
	ds_read_b128 v[166:169], v138 offset:50176
	ds_read_b128 v[174:177], v137 offset:49152
	ds_read_b128 v[178:181], v137 offset:50176
	ds_read_b128 v[218:221], v136 offset:49152
	ds_read_b128 v[136:139], v136 offset:50176
	ds_read_b128 v[222:225], v135 offset:49152
	ds_read_b128 v[226:229], v135 offset:50176
	s_barrier
	s_waitcnt lgkmcnt(0)
	s_waitcnt lgkmcnt(0)
	v_mfma_f32_16x16x32_bf16 v[18:21], v[162:165], v[2:5], v[62:65]
	v_mfma_f32_16x16x32_bf16 v[54:57], v[166:169], v[6:9], v[18:21]
	v_mfma_f32_16x16x32_bf16 v[18:21], v[162:165], v[190:193], v[58:61]
	v_mfma_f32_16x16x32_bf16 v[50:53], v[166:169], v[194:197], v[18:21]
	v_mfma_f32_16x16x32_bf16 v[18:21], v[174:177], v[2:5], v[210:213]
	v_mfma_f32_16x16x32_bf16 v[38:41], v[178:181], v[6:9], v[18:21]
	v_mfma_f32_16x16x32_bf16 v[18:21], v[174:177], v[190:193], v[214:217]
	v_mfma_f32_16x16x32_bf16 v[34:37], v[178:181], v[194:197], v[18:21]
	v_mfma_f32_16x16x32_bf16 v[18:21], v[218:221], v[2:5], v[46:49]
	v_mfma_f32_16x16x32_bf16 v[2:5], v[222:225], v[2:5], v[146:149]
	v_mfma_f32_16x16x32_bf16 v[22:25], v[136:139], v[6:9], v[18:21]
	v_mfma_f32_16x16x32_bf16 v[18:21], v[218:221], v[190:193], v[42:45]
	v_mfma_f32_16x16x32_bf16 v[6:9], v[226:229], v[6:9], v[2:5]
	v_mfma_f32_16x16x32_bf16 v[2:5], v[222:225], v[190:193], v[150:153]
	v_mfma_f32_16x16x32_bf16 v[18:21], v[136:139], v[194:197], v[18:21]
	v_mfma_f32_16x16x32_bf16 v[2:5], v[226:229], v[194:197], v[2:5]
	v_mfma_f32_16x16x32_bf16 v[26:29], v[162:165], v[202:205], v[26:29]
	v_mfma_f32_16x16x32_bf16 v[58:61], v[166:169], v[206:209], v[26:29]
	v_mfma_f32_16x16x32_bf16 v[26:29], v[174:177], v[140:143], v[154:157]
	v_mfma_f32_16x16x32_bf16 v[46:49], v[178:181], v[198:201], v[26:29]
	v_mfma_f32_16x16x32_bf16 v[26:29], v[174:177], v[202:205], v[158:161]
	v_mfma_f32_16x16x32_bf16 v[10:13], v[218:221], v[202:205], v[10:13]
	v_mfma_f32_16x16x32_bf16 v[30:33], v[162:165], v[140:143], v[30:33]
	v_mfma_f32_16x16x32_bf16 v[42:45], v[178:181], v[206:209], v[26:29]
	v_mfma_f32_16x16x32_bf16 v[14:17], v[218:221], v[140:143], v[14:17]
	v_mfma_f32_16x16x32_bf16 v[26:29], v[136:139], v[206:209], v[10:13]
	v_mfma_f32_16x16x32_bf16 v[10:13], v[222:225], v[140:143], v[182:185]
	v_mfma_f32_16x16x32_bf16 v[62:65], v[166:169], v[198:201], v[30:33]
	v_mfma_f32_16x16x32_bf16 v[30:33], v[136:139], v[198:201], v[14:17]
	v_mfma_f32_16x16x32_bf16 v[14:17], v[226:229], v[198:201], v[10:13]
	v_mfma_f32_16x16x32_bf16 v[10:13], v[222:225], v[202:205], v[186:189]
	v_mfma_f32_16x16x32_bf16 v[10:13], v[226:229], v[206:209], v[10:13]
	v_cmp_gt_u32_e32 vcc, s33, v134
	s_barrier
	s_and_saveexec_b64 s[12:13], vcc
	s_cbranch_execz .LBB0_1108
	s_barrier

; #define GAS __attribute__((address_space(1)))
; #define STAGE(P, GP, ktrel) do { const GAS char* _g = (GP) + (ktrel) * (BK * 2); \
;     __builtin_amdgcn_global_load_lds((const GAS unsigned*)(_g + so0), (unsigned*)((char*)(P) + tid_ * 16), 16, 0, 0); \
;     __builtin_amdgcn_global_load_lds((const GAS unsigned*)(_g + so1), (unsigned*)((char*)(P) + tid_ * 16 + 8192), 16, 0, 0); } while (0)
; #define WAIT_V(n) asm volatile("s_waitcnt vmcnt(" #n ")" ::: "memory")
; #define WAIT_L(n) asm volatile("s_waitcnt lgkmcnt(" #n ")" ::: "memory")
; #define BAR __builtin_amdgcn_s_barrier()
; #define SCHED __builtin_amdgcn_sched_barrier(0)
; #define LDA(dst, b, h) for (int m = 0; m < 4; ++m) for (int k = 0; k < 2; ++k) \
;     dst[m][k] = *reinterpret_cast<const bf16x8*>((char*)SA(b, h) + lds_byte(wr * 64 + m * 16 + fr, k * 32 + fq * 8))
; #define LDB(dst, b, h) for (int n = 0; n < 2; ++n) for (int k = 0; k < 2; ++k) \
;     dst[n][k] = *reinterpret_cast<const bf16x8*>((char*)SB(b, h) + lds_byte(wc * 32 + n * 16 + fr, k * 32 + fq * 8))
; #define MMA(ai, bj, At_, Bt_) do { __builtin_amdgcn_s_setprio(1); \
;     for (int m = 0; m < 4; ++m) for (int n = 0; n < 2; ++n) for (int k = 0; k < 2; ++k) \
;       acc[ai][bj][m][n] = __builtin_amdgcn_mfma_f32_16x16x32_bf16(At_[m][k], Bt_[n][k], acc[ai][bj][m][n], 0, 0, 0); \
;     __builtin_amdgcn_s_setprio(0); } while (0)
; template <int K, int LD = K>
; __device__ __forceinline__ void gemm_main(const GAS bf16* A, const GAS bf16* Bt, int brow, int bcol, f32x4 (&acc)[2][2][4][2]) {
;     ...
;   unsigned so0, so1;
;   { int r_, c_; stage_rc(tid_ * 16, r_, c_); so0 = (unsigned)(r_ * LD + c_) * 2u; stage_rc(tid_ * 16 + 8192, r_, c_); so1 = (unsigned)(r_ * LD + c_) * 2u; }
;   const GAS char* pA0 = (const GAS char*)A + (long)brow * LD * 2; const GAS char* pA1 = pA0 + (long)HALF * LD * 2;
;   const GAS char* pB0 = (const GAS char*)Bt + (long)bcol * LD * 2; const GAS char* pB1 = pB0 + (long)HALF * LD * 2;
;   asm volatile("" : "+s"(pA0), "+s"(pA1), "+s"(pB0), "+s"(pB1));
;   constexpr int nt = K / BK;
;   static_assert(K % 128 == 0 && K >= 256, "K");
;   if (wr == 1) BAR;
;   WAIT_V(0); BAR;
;   BAR;
;   for (int t = 0; t < nt - 2; t += 2) {
;     LDB(B0, 0, 0); SCHED; LDA(At, 0, 0); STAGE(SA(1, 1), pA1, 1);
;     WAIT_L(8); BAR; WAIT_L(0); MMA(0, 0, At, B0); BAR; SCHED;
;     LDB(B1, 0, 1); STAGE(SB(0, 0), pB0, 2);
.LBB0_1221:
	s_or_b64 exec, exec, s[30:31]
	v_bfe_i32 v5, v130, 27, 1
	v_lshlrev_b32_e32 v20, 4, v130
	v_lshrrev_b32_e32 v5, 22, v5
	v_add_u32_e32 v5, v20, v5
	v_and_b32_e32 v5, 0xfffffc00, v5
	v_sub_u32_e32 v5, v20, v5
	v_lshrrev_b32_e32 v6, 4, v5
	v_bitop3_b32 v6, v6, v5, 32 bitop3:0x6c
	v_ashrrev_i32_e32 v5, 31, v5
	v_ashrrev_i32_e32 v2, 31, v130
	v_lshrrev_b32_e32 v5, 26, v5
	v_lshrrev_b32_e32 v2, 26, v2
	v_add_u32_e32 v5, v6, v5
	v_add_u32_e32 v2, v130, v2
	v_ashrrev_i32_e32 v5, 6, v5
	v_ashrrev_i32_e32 v2, 6, v2
	v_mul_i32_i24_e32 v8, 64, v5
	v_lshlrev_b32_e32 v7, 3, v2
	v_lshlrev_b32_e32 v2, 5, v2
	v_sub_u32_e32 v6, v6, v8
	v_and_b32_e32 v7, 0x7ffff0, v7
	v_and_b32_e32 v2, 32, v2
	v_ashrrev_i16_sdwa v6, v1, sext(v6) dst_sel:DWORD dst_unused:UNUSED_PAD src0_sel:DWORD src1_sel:BYTE_0
	v_add_u32_sdwa v2, v2, sext(v6) dst_sel:DWORD dst_unused:UNUSED_PAD src0_sel:DWORD src1_sel:WORD_0
	v_add_lshl_u32 v5, v5, v7, 9
	v_lshl_add_u32 v2, v2, 1, v5
	v_add_u32_e32 v5, 0x2000, v20
	v_ashrrev_i32_e32 v6, 31, v5
	v_lshrrev_b32_e32 v6, 22, v6
	v_add_u32_e32 v6, v5, v6
	v_ashrrev_i32_e32 v6, 10, v6
	v_mul_i32_i24_e32 v7, 0x400, v6
	v_sub_u32_e32 v5, v5, v7
	v_lshrrev_b32_e32 v7, 4, v5
	v_bitop3_b32 v5, v7, v5, 32 bitop3:0x6c
	v_ashrrev_i32_e32 v8, 31, v5
	v_lshrrev_b32_e32 v8, 26, v8
	v_add_u32_e32 v8, v5, v8
	v_lshrrev_b32_e32 v9, 6, v8
	v_and_b32_e32 v8, 0xc0, v8
	v_lshlrev_b32_e32 v7, 3, v6
	v_lshlrev_b32_e32 v6, 5, v6
	v_sub_u32_e32 v5, v5, v8
	v_and_b32_e32 v7, 0x7ffff0, v7
	v_and_b32_e32 v6, 32, v6
	v_ashrrev_i16_sdwa v5, v1, sext(v5) dst_sel:DWORD dst_unused:UNUSED_PAD src0_sel:DWORD src1_sel:BYTE_0
	v_add_u32_sdwa v5, v6, sext(v5) dst_sel:DWORD dst_unused:UNUSED_PAD src0_sel:DWORD src1_sel:WORD_0
	v_add_lshl_u32 v6, v9, v7, 9
	v_and_b32_e32 v4, 15, v130
	v_lshl_add_u32 v138, v5, 1, v6
	v_lshlrev_b32_e32 v5, 2, v130
	v_and_b32_e32 v28, 48, v130
	v_lshlrev_b32_e32 v4, 6, v4
	v_and_b32_e32 v29, 32, v5
	v_lshlrev_b32_e32 v30, 6, v130
	v_bitop3_b32 v131, v4, v29, v28 bitop3:0x36
	v_and_b32_e32 v200, 0x3000, v30
	v_add3_u32 v225, s38, v131, v200
	s_waitcnt vmcnt(0)
	s_barrier
	s_barrier
	ds_read_b128 v[4:7], v225
	ds_read_b128 v[8:11], v225 offset:1024
	ds_read_b128 v[12:15], v225 offset:2048
	ds_read_b128 v[16:19], v225 offset:3072
	v_add_u32_e32 v142, 0x100, v20
	v_add_u32_e32 v102, s38, v20
	v_add_u32_e32 v54, 0xc000, v142
	v_add_u32_e32 v55, 0xe000, v142
	v_add_u32_e32 v103, 0x2000, v102
	v_add_u32_e32 v155, s39, v20
	v_add_u32_e32 v222, s40, v20
	v_add_u32_e32 v227, s41, v20
	v_add_u32_e32 v143, 0x2000, v142
	v_add_u32_e32 v198, 0x4000, v142
	v_add_u32_e32 v199, 0x6000, v142
	v_add_u32_e32 v223, 0x2000, v222
	v_add_u32_e32 v224, 0x8000, v142
	v_add_u32_e32 v226, 0xa000, v142
	v_add_u32_e32 v228, 0x2000, v227
	v_add_u32_e32 v174, 0x2000, v155
	v_and_b32_e32 v30, 0x3c0, v30
	v_lshlrev_b32_e32 v3, 13, v3
	v_bitop3_b32 v28, v30, v29, v28 bitop3:0x36
	v_add3_u32 v246, s42, v131, v3
	v_add3_u32 v247, s42, v28, v3
	v_mov_b32_e32 v3, v139
	v_lshl_add_u64 v[128:129], s[18:19], 0, v[2:3]
	v_readfirstlane_b32 s31, v54
	v_lshl_add_u64 v[52:53], v[128:129], 0, s[8:9]
	s_mov_b32 m0, s31
	v_lshl_add_u64 v[136:137], s[18:19], 0, v[138:139]
	v_readfirstlane_b32 s30, v55
	ds_read_b128 v[20:23], v246
	ds_read_b128 v[24:27], v246 offset:1024
	ds_read_b128 v[28:31], v247 offset:2048
	ds_read_b128 v[32:35], v247 offset:3072
	ds_read_b128 v[36:39], v247 offset:4096
	ds_read_b128 v[40:43], v247 offset:5120
	ds_read_b128 v[44:47], v247 offset:6144
	ds_read_b128 v[48:51], v247 offset:7168
	global_load_lds_dwordx4 v[52:53], off
	v_lshl_add_u64 v[52:53], v[136:137], 0, s[8:9]
	s_mov_b32 m0, s30
	s_nop 0
	global_load_lds_dwordx4 v[52:53], off
	s_waitcnt lgkmcnt(8)
	s_barrier
	s_waitcnt lgkmcnt(0)
	s_waitcnt lgkmcnt(0)
	v_mfma_f32_16x16x32_bf16 v[52:55], v[20:23], v[4:7], 0
	v_mfma_f32_16x16x32_bf16 v[56:59], v[20:23], v[12:15], 0
	v_mfma_f32_16x16x32_bf16 v[60:63], v[28:31], v[4:7], 0
	v_mfma_f32_16x16x32_bf16 v[64:67], v[28:31], v[12:15], 0
	v_mfma_f32_16x16x32_bf16 v[68:71], v[36:39], v[4:7], 0
	v_mfma_f32_16x16x32_bf16 v[72:75], v[36:39], v[12:15], 0
	v_mfma_f32_16x16x32_bf16 v[76:79], v[44:47], v[4:7], 0
	v_mfma_f32_16x16x32_bf16 v[80:83], v[44:47], v[12:15], 0
	v_mfma_f32_16x16x32_bf16 v[52:55], v[24:27], v[8:11], v[52:55]
	v_mfma_f32_16x16x32_bf16 v[56:59], v[24:27], v[16:19], v[56:59]
	v_mfma_f32_16x16x32_bf16 v[60:63], v[32:35], v[8:11], v[60:63]
	v_mfma_f32_16x16x32_bf16 v[64:67], v[32:35], v[16:19], v[64:67]
	v_mfma_f32_16x16x32_bf16 v[68:71], v[40:43], v[8:11], v[68:71]
	v_mfma_f32_16x16x32_bf16 v[72:75], v[40:43], v[16:19], v[72:75]
	v_mfma_f32_16x16x32_bf16 v[76:79], v[48:51], v[8:11], v[76:79]
	v_mfma_f32_16x16x32_bf16 v[80:83], v[48:51], v[16:19], v[80:83]
	s_barrier
	v_lshl_add_u64 v[152:153], s[24:25], 0, v[2:3]
	v_readfirstlane_b32 s48, v102
	v_add3_u32 v229, s39, v131, v200
	v_lshl_add_u64 v[100:101], v[152:153], 0, s[14:15]
	s_mov_b32 m0, s48
	v_lshl_add_u64 v[168:169], s[24:25], 0, v[138:139]
	v_readfirstlane_b32 s48, v103
	ds_read_b128 v[84:87], v229
	ds_read_b128 v[88:91], v229 offset:1024
	ds_read_b128 v[92:95], v229 offset:2048
	ds_read_b128 v[96:99], v229 offset:3072
	global_load_lds_dwordx4 v[100:101], off
	v_lshl_add_u64 v[100:101], v[168:169], 0, s[14:15]
	s_mov_b32 m0, s48
	s_add_u32 s24, s24, 0x100
	global_load_lds_dwordx4 v[100:101], off
	s_barrier
; #define STAGE(P, GP, ktrel) do { const GAS char* _g = (GP) + (ktrel) * (BK * 2); \
;     __builtin_amdgcn_global_load_lds((const GAS unsigned*)(_g + so0), (unsigned*)((char*)(P) + tid_ * 16), 16, 0, 0); \
;     __builtin_amdgcn_global_load_lds((const GAS unsigned*)(_g + so1), (unsigned*)((char*)(P) + tid_ * 16 + 8192), 16, 0, 0); } while (0)
; #define WAIT_V(n) asm volatile("s_waitcnt vmcnt(" #n ")" ::: "memory")
; #define WAIT_L(n) asm volatile("s_waitcnt lgkmcnt(" #n ")" ::: "memory")
; #define BAR __builtin_amdgcn_s_barrier()
; #define SCHED __builtin_amdgcn_sched_barrier(0)
; #define LDA(dst, b, h) for (int m = 0; m < 4; ++m) for (int k = 0; k < 2; ++k) \
;     dst[m][k] = *reinterpret_cast<const bf16x8*>((char*)SA(b, h) + lds_byte(wr * 64 + m * 16 + fr, k * 32 + fq * 8))
; #define LDB(dst, b, h) for (int n = 0; n < 2; ++n) for (int k = 0; k < 2; ++k) \
;     dst[n][k] = *reinterpret_cast<const bf16x8*>((char*)SB(b, h) + lds_byte(wc * 32 + n * 16 + fr, k * 32 + fq * 8))
; #define MMA(ai, bj, At_, Bt_) do { __builtin_amdgcn_s_setprio(1); \
;     for (int m = 0; m < 4; ++m) for (int n = 0; n < 2; ++n) for (int k = 0; k < 2; ++k) \
;       acc[ai][bj][m][n] = __builtin_amdgcn_mfma_f32_16x16x32_bf16(At_[m][k], Bt_[n][k], acc[ai][bj][m][n], 0, 0, 0); \
;     __builtin_amdgcn_s_setprio(0); } while (0)
; template <int K, int LD = K>
; __device__ __forceinline__ void gemm_main(const GAS bf16* A, const GAS bf16* Bt, int brow, int bcol, f32x4 (&acc)[2][2][4][2]) {
;     ...
;     WAIT_L(8); BAR; WAIT_L(0); MMA(0, 0, At, B0); BAR; SCHED;
;     LDB(B1, 0, 1); STAGE(SB(0, 0), pB0, 2);
;     BAR; WAIT_L(0); MMA(0, 1, At, B1); BAR;
;     LDA(At, 0, 1); STAGE(SA(0, 0), pA0, 2);
;     BAR; WAIT_L(0); MMA(1, 0, At, B0); BAR; SCHED;
;     STAGE(SB(0, 1), pB1, 2);
;     WAIT_V(6); BAR; MMA(1, 1, At, B1); BAR;
;     LDB(B0, 1, 0); SCHED; LDA(At, 1, 0); STAGE(SA(0, 1), pA1, 2);
;     WAIT_L(8); BAR; WAIT_L(0); MMA(0, 0, At, B0); BAR; SCHED;
	s_waitcnt lgkmcnt(0)
	s_addc_u32 s25, s25, 0
	s_waitcnt lgkmcnt(0)
	v_mfma_f32_16x16x32_bf16 v[100:103], v[20:23], v[84:87], 0
	v_mfma_f32_16x16x32_bf16 v[20:23], v[20:23], v[92:95], 0
	v_mfma_f32_16x16x32_bf16 v[100:103], v[24:27], v[88:91], v[100:103]
	v_mfma_f32_16x16x32_bf16 v[20:23], v[24:27], v[96:99], v[20:23]
	v_mfma_f32_16x16x32_bf16 v[24:27], v[28:31], v[84:87], 0
	v_mfma_f32_16x16x32_bf16 v[28:31], v[28:31], v[92:95], 0
	v_mfma_f32_16x16x32_bf16 v[24:27], v[32:35], v[88:91], v[24:27]
	v_mfma_f32_16x16x32_bf16 v[28:31], v[32:35], v[96:99], v[28:31]
	v_mfma_f32_16x16x32_bf16 v[32:35], v[36:39], v[84:87], 0
	v_mfma_f32_16x16x32_bf16 v[36:39], v[36:39], v[92:95], 0
	v_mfma_f32_16x16x32_bf16 v[32:35], v[40:43], v[88:91], v[32:35]
	v_mfma_f32_16x16x32_bf16 v[36:39], v[40:43], v[96:99], v[36:39]
	v_mfma_f32_16x16x32_bf16 v[40:43], v[44:47], v[84:87], 0
	v_mfma_f32_16x16x32_bf16 v[44:47], v[44:47], v[92:95], 0
	v_mfma_f32_16x16x32_bf16 v[40:43], v[48:51], v[88:91], v[40:43]
	v_mfma_f32_16x16x32_bf16 v[44:47], v[48:51], v[96:99], v[44:47]
	v_lshl_add_u64 v[214:215], s[28:29], 0, v[2:3]
	v_readfirstlane_b32 s48, v142
	v_lshl_add_u64 v[140:141], v[214:215], 0, s[14:15]
	s_mov_b32 m0, s48
	v_lshl_add_u64 v[216:217], s[28:29], 0, v[138:139]
	v_readfirstlane_b32 s48, v143
	s_barrier
	ds_read_b128 v[48:51], v246 offset:16384
	ds_read_b128 v[104:107], v246 offset:17408
	ds_read_b128 v[108:111], v247 offset:18432
	ds_read_b128 v[112:115], v247 offset:19456
	ds_read_b128 v[116:119], v247 offset:20480
	ds_read_b128 v[120:123], v247 offset:21504
	ds_read_b128 v[124:127], v247 offset:22528
	ds_read_b128 v[132:135], v247 offset:23552
	global_load_lds_dwordx4 v[140:141], off
	v_lshl_add_u64 v[140:141], v[216:217], 0, s[14:15]
	s_mov_b32 m0, s48
	s_add_u32 s28, s28, 0x100
	global_load_lds_dwordx4 v[140:141], off
	s_barrier
	s_waitcnt lgkmcnt(0)
	s_addc_u32 s29, s29, 0
	s_waitcnt lgkmcnt(0)
	v_mfma_f32_16x16x32_bf16 v[140:143], v[48:51], v[4:7], 0
	v_mfma_f32_16x16x32_bf16 v[148:151], v[108:111], v[4:7], 0
	v_mfma_f32_16x16x32_bf16 v[160:163], v[116:119], v[4:7], 0
	v_mfma_f32_16x16x32_bf16 v[4:7], v[124:127], v[4:7], 0
	v_mfma_f32_16x16x32_bf16 v[140:143], v[104:107], v[8:11], v[140:143]
	v_mfma_f32_16x16x32_bf16 v[148:151], v[112:115], v[8:11], v[148:151]
	v_mfma_f32_16x16x32_bf16 v[160:163], v[120:123], v[8:11], v[160:163]
	v_mfma_f32_16x16x32_bf16 v[4:7], v[132:135], v[8:11], v[4:7]
	v_mfma_f32_16x16x32_bf16 v[8:11], v[124:127], v[12:15], 0
	v_mfma_f32_16x16x32_bf16 v[144:147], v[48:51], v[12:15], 0
	v_mfma_f32_16x16x32_bf16 v[156:159], v[108:111], v[12:15], 0
	v_mfma_f32_16x16x32_bf16 v[164:167], v[116:119], v[12:15], 0
	v_mfma_f32_16x16x32_bf16 v[8:11], v[132:135], v[16:19], v[8:11]
	v_mfma_f32_16x16x32_bf16 v[144:147], v[104:107], v[16:19], v[144:147]
	v_mfma_f32_16x16x32_bf16 v[156:159], v[112:115], v[16:19], v[156:159]
	v_mfma_f32_16x16x32_bf16 v[164:167], v[120:123], v[16:19], v[164:167]
	s_barrier
	v_lshl_add_u64 v[218:219], s[26:27], 0, v[2:3]
	v_readfirstlane_b32 s48, v155
	v_lshl_add_u64 v[12:13], v[218:219], 0, s[14:15]
	s_mov_b32 m0, s48
	v_lshl_add_u64 v[220:221], s[26:27], 0, v[138:139]
	v_readfirstlane_b32 s48, v174
	global_load_lds_dwordx4 v[12:13], off
	v_lshl_add_u64 v[12:13], v[220:221], 0, s[14:15]
	s_mov_b32 m0, s48
	s_add_u32 s26, s26, 0x100
	global_load_lds_dwordx4 v[12:13], off
	s_waitcnt vmcnt(6)
	s_addc_u32 s27, s27, 0
	s_barrier
	v_mfma_f32_16x16x32_bf16 v[12:15], v[48:51], v[84:87], 0
	v_mfma_f32_16x16x32_bf16 v[16:19], v[48:51], v[92:95], 0
	v_mfma_f32_16x16x32_bf16 v[12:15], v[104:107], v[88:91], v[12:15]
	v_mfma_f32_16x16x32_bf16 v[16:19], v[104:107], v[96:99], v[16:19]
	v_mfma_f32_16x16x32_bf16 v[48:51], v[108:111], v[84:87], 0
	v_mfma_f32_16x16x32_bf16 v[104:107], v[108:111], v[92:95], 0
	v_mfma_f32_16x16x32_bf16 v[108:111], v[116:119], v[84:87], 0
	v_mfma_f32_16x16x32_bf16 v[84:87], v[124:127], v[84:87], 0
	v_mfma_f32_16x16x32_bf16 v[48:51], v[112:115], v[88:91], v[48:51]
	v_mfma_f32_16x16x32_bf16 v[104:107], v[112:115], v[96:99], v[104:107]
	v_mfma_f32_16x16x32_bf16 v[108:111], v[120:123], v[88:91], v[108:111]
	v_mfma_f32_16x16x32_bf16 v[112:115], v[116:119], v[92:95], 0
	v_mfma_f32_16x16x32_bf16 v[84:87], v[132:135], v[88:91], v[84:87]
	v_mfma_f32_16x16x32_bf16 v[88:91], v[124:127], v[92:95], 0
	v_mfma_f32_16x16x32_bf16 v[112:115], v[120:123], v[96:99], v[112:115]
	v_mfma_f32_16x16x32_bf16 v[88:91], v[132:135], v[96:99], v[88:91]
	v_add3_u32 v155, s40, v131, v200
	s_barrier
	ds_read_b128 v[92:95], v155
	ds_read_b128 v[96:99], v155 offset:1024
	ds_read_b128 v[116:119], v155 offset:2048
	ds_read_b128 v[120:123], v155 offset:3072
	v_readfirstlane_b32 s48, v198
	v_lshl_add_u64 v[128:129], v[128:129], 0, s[14:15]
	s_mov_b32 m0, s48
	v_readfirstlane_b32 s48, v199
	ds_read_b128 v[124:127], v246 offset:32768
	ds_read_b128 v[132:135], v246 offset:33792
	ds_read_b128 v[174:177], v247 offset:34816
	ds_read_b128 v[178:181], v247 offset:35840
	ds_read_b128 v[182:185], v247 offset:36864
	ds_read_b128 v[186:189], v247 offset:37888
	ds_read_b128 v[190:193], v247 offset:38912
	ds_read_b128 v[194:197], v247 offset:39936
	global_load_lds_dwordx4 v[128:129], off
	v_lshl_add_u64 v[128:129], v[136:137], 0, s[14:15]
	s_mov_b32 m0, s48
	s_add_u32 s18, s18, 0x100
	global_load_lds_dwordx4 v[128:129], off
	s_waitcnt lgkmcnt(8)
	s_barrier
; #define STAGE(P, GP, ktrel) do { const GAS char* _g = (GP) + (ktrel) * (BK * 2); \
;     __builtin_amdgcn_global_load_lds((const GAS unsigned*)(_g + so0), (unsigned*)((char*)(P) + tid_ * 16), 16, 0, 0); \
;     __builtin_amdgcn_global_load_lds((const GAS unsigned*)(_g + so1), (unsigned*)((char*)(P) + tid_ * 16 + 8192), 16, 0, 0); } while (0)
; #define WAIT_V(n) asm volatile("s_waitcnt vmcnt(" #n ")" ::: "memory")
; #define WAIT_L(n) asm volatile("s_waitcnt lgkmcnt(" #n ")" ::: "memory")
; #define BAR __builtin_amdgcn_s_barrier()
; #define SCHED __builtin_amdgcn_sched_barrier(0)
; #define LDA(dst, b, h) for (int m = 0; m < 4; ++m) for (int k = 0; k < 2; ++k) \
;     dst[m][k] = *reinterpret_cast<const bf16x8*>((char*)SA(b, h) + lds_byte(wr * 64 + m * 16 + fr, k * 32 + fq * 8))
; #define LDB(dst, b, h) for (int n = 0; n < 2; ++n) for (int k = 0; k < 2; ++k) \
;     dst[n][k] = *reinterpret_cast<const bf16x8*>((char*)SB(b, h) + lds_byte(wc * 32 + n * 16 + fr, k * 32 + fq * 8))
; #define MMA(ai, bj, At_, Bt_) do { __builtin_amdgcn_s_setprio(1); \
;     for (int m = 0; m < 4; ++m) for (int n = 0; n < 2; ++n) for (int k = 0; k < 2; ++k) \
;       acc[ai][bj][m][n] = __builtin_amdgcn_mfma_f32_16x16x32_bf16(At_[m][k], Bt_[n][k], acc[ai][bj][m][n], 0, 0, 0); \
;     __builtin_amdgcn_s_setprio(0); } while (0)
; template <int K, int LD = K>
; __device__ __forceinline__ void gemm_main(const GAS bf16* A, const GAS bf16* Bt, int brow, int bcol, f32x4 (&acc)[2][2][4][2]) {
;     ...
;     WAIT_V(6); BAR; MMA(1, 1, At, B1); BAR;
;     LDB(B0, 1, 0); SCHED; LDA(At, 1, 0); STAGE(SA(0, 1), pA1, 2);
;     WAIT_L(8); BAR; WAIT_L(0); MMA(0, 0, At, B0); BAR; SCHED;
;     LDB(B1, 1, 1); STAGE(SB(1, 0), pB0, 3);
;     BAR; WAIT_L(0); MMA(0, 1, At, B1); BAR;
;     LDA(At, 1, 1); STAGE(SA(1, 0), pA0, 3);
;     BAR; WAIT_L(0); MMA(1, 0, At, B0); BAR; SCHED;
;     STAGE(SB(1, 1), pB1, 3);
;     WAIT_V(6); BAR; MMA(1, 1, At, B1); BAR;
	s_waitcnt lgkmcnt(0)
	s_addc_u32 s19, s19, 0
	s_waitcnt lgkmcnt(0)
	v_mfma_f32_16x16x32_bf16 v[52:55], v[124:127], v[92:95], v[52:55]
	v_mfma_f32_16x16x32_bf16 v[56:59], v[124:127], v[116:119], v[56:59]
	v_mfma_f32_16x16x32_bf16 v[60:63], v[174:177], v[92:95], v[60:63]
	v_mfma_f32_16x16x32_bf16 v[64:67], v[174:177], v[116:119], v[64:67]
	v_mfma_f32_16x16x32_bf16 v[68:71], v[182:185], v[92:95], v[68:71]
	v_mfma_f32_16x16x32_bf16 v[72:75], v[182:185], v[116:119], v[72:75]
	v_mfma_f32_16x16x32_bf16 v[76:79], v[190:193], v[92:95], v[76:79]
	v_mfma_f32_16x16x32_bf16 v[80:83], v[190:193], v[116:119], v[80:83]
	v_mfma_f32_16x16x32_bf16 v[52:55], v[132:135], v[96:99], v[52:55]
	v_mfma_f32_16x16x32_bf16 v[56:59], v[132:135], v[120:123], v[56:59]
	v_mfma_f32_16x16x32_bf16 v[60:63], v[178:181], v[96:99], v[60:63]
	v_mfma_f32_16x16x32_bf16 v[64:67], v[178:181], v[120:123], v[64:67]
	v_mfma_f32_16x16x32_bf16 v[68:71], v[186:189], v[96:99], v[68:71]
	v_mfma_f32_16x16x32_bf16 v[72:75], v[186:189], v[120:123], v[72:75]
	v_mfma_f32_16x16x32_bf16 v[76:79], v[194:197], v[96:99], v[76:79]
	v_mfma_f32_16x16x32_bf16 v[80:83], v[194:197], v[120:123], v[80:83]
	s_barrier
	v_readfirstlane_b32 s48, v222
	v_add3_u32 v131, s41, v131, v200
	v_lshl_add_u64 v[128:129], v[152:153], 0, s[16:17]
	s_mov_b32 m0, s48
	v_readfirstlane_b32 s48, v223
	ds_read_b128 v[198:201], v131
	ds_read_b128 v[202:205], v131 offset:1024
	ds_read_b128 v[206:209], v131 offset:2048
	ds_read_b128 v[210:213], v131 offset:3072
	global_load_lds_dwordx4 v[128:129], off
	v_lshl_add_u64 v[128:129], v[168:169], 0, s[16:17]
	s_mov_b32 m0, s48
	s_nop 0
	global_load_lds_dwordx4 v[128:129], off
	s_barrier
	s_waitcnt lgkmcnt(0)
	s_waitcnt lgkmcnt(0)
	v_mfma_f32_16x16x32_bf16 v[100:103], v[124:127], v[198:201], v[100:103]
	v_mfma_f32_16x16x32_bf16 v[20:23], v[124:127], v[206:209], v[20:23]
	v_mfma_f32_16x16x32_bf16 v[24:27], v[174:177], v[198:201], v[24:27]
	v_mfma_f32_16x16x32_bf16 v[28:31], v[174:177], v[206:209], v[28:31]
	v_mfma_f32_16x16x32_bf16 v[32:35], v[182:185], v[198:201], v[32:35]
	v_mfma_f32_16x16x32_bf16 v[36:39], v[182:185], v[206:209], v[36:39]
	v_mfma_f32_16x16x32_bf16 v[40:43], v[190:193], v[198:201], v[40:43]
	v_mfma_f32_16x16x32_bf16 v[44:47], v[190:193], v[206:209], v[44:47]
	v_mfma_f32_16x16x32_bf16 v[100:103], v[132:135], v[202:205], v[100:103]
	v_mfma_f32_16x16x32_bf16 v[20:23], v[132:135], v[210:213], v[20:23]
	v_mfma_f32_16x16x32_bf16 v[24:27], v[178:181], v[202:205], v[24:27]
	v_mfma_f32_16x16x32_bf16 v[28:31], v[178:181], v[210:213], v[28:31]
	v_mfma_f32_16x16x32_bf16 v[32:35], v[186:189], v[202:205], v[32:35]
	v_mfma_f32_16x16x32_bf16 v[36:39], v[186:189], v[210:213], v[36:39]
	v_mfma_f32_16x16x32_bf16 v[40:43], v[194:197], v[202:205], v[40:43]
	v_mfma_f32_16x16x32_bf16 v[44:47], v[194:197], v[210:213], v[44:47]
	v_readfirstlane_b32 s48, v224
	v_lshl_add_u64 v[128:129], v[214:215], 0, s[16:17]
	s_mov_b32 m0, s48
	v_readfirstlane_b32 s48, v226
	s_barrier
	ds_read_b128 v[124:127], v246 offset:49152
	ds_read_b128 v[132:135], v246 offset:50176
	ds_read_b128 v[174:177], v247 offset:51200
	ds_read_b128 v[178:181], v247 offset:52224
	ds_read_b128 v[182:185], v247 offset:53248
	ds_read_b128 v[186:189], v247 offset:54272
	ds_read_b128 v[190:193], v247 offset:55296
	ds_read_b128 v[194:197], v247 offset:56320
	global_load_lds_dwordx4 v[128:129], off
	v_lshl_add_u64 v[128:129], v[216:217], 0, s[16:17]
	s_mov_b32 m0, s48
	s_nop 0
	global_load_lds_dwordx4 v[128:129], off
	s_barrier
	s_waitcnt lgkmcnt(0)
	s_waitcnt lgkmcnt(0)
	v_mfma_f32_16x16x32_bf16 v[4:7], v[190:193], v[92:95], v[4:7]
	v_mfma_f32_16x16x32_bf16 v[8:11], v[190:193], v[116:119], v[8:11]
	v_mfma_f32_16x16x32_bf16 v[140:143], v[124:127], v[92:95], v[140:143]
	v_mfma_f32_16x16x32_bf16 v[144:147], v[124:127], v[116:119], v[144:147]
	v_mfma_f32_16x16x32_bf16 v[148:151], v[174:177], v[92:95], v[148:151]
	v_mfma_f32_16x16x32_bf16 v[156:159], v[174:177], v[116:119], v[156:159]
	v_mfma_f32_16x16x32_bf16 v[160:163], v[182:185], v[92:95], v[160:163]
	v_mfma_f32_16x16x32_bf16 v[164:167], v[182:185], v[116:119], v[164:167]
	v_mfma_f32_16x16x32_bf16 v[4:7], v[194:197], v[96:99], v[4:7]
	v_mfma_f32_16x16x32_bf16 v[8:11], v[194:197], v[120:123], v[8:11]
	v_mfma_f32_16x16x32_bf16 v[140:143], v[132:135], v[96:99], v[140:143]
	v_mfma_f32_16x16x32_bf16 v[144:147], v[132:135], v[120:123], v[144:147]
	v_mfma_f32_16x16x32_bf16 v[148:151], v[178:181], v[96:99], v[148:151]
	v_mfma_f32_16x16x32_bf16 v[156:159], v[178:181], v[120:123], v[156:159]
	v_mfma_f32_16x16x32_bf16 v[160:163], v[186:189], v[96:99], v[160:163]
	v_mfma_f32_16x16x32_bf16 v[164:167], v[186:189], v[120:123], v[164:167]
	s_barrier
	v_readfirstlane_b32 s48, v227
	v_lshl_add_u64 v[92:93], v[218:219], 0, s[16:17]
	s_mov_b32 m0, s48
	v_readfirstlane_b32 s48, v228
	global_load_lds_dwordx4 v[92:93], off
	v_lshl_add_u64 v[92:93], v[220:221], 0, s[16:17]
	s_mov_b32 m0, s48
	s_nop 0
	global_load_lds_dwordx4 v[92:93], off
	s_waitcnt vmcnt(6)
	s_barrier
	v_mfma_f32_16x16x32_bf16 v[12:15], v[124:127], v[198:201], v[12:15]
	v_mfma_f32_16x16x32_bf16 v[16:19], v[124:127], v[206:209], v[16:19]
	v_mfma_f32_16x16x32_bf16 v[48:51], v[174:177], v[198:201], v[48:51]
	v_mfma_f32_16x16x32_bf16 v[92:95], v[174:177], v[206:209], v[104:107]
	v_mfma_f32_16x16x32_bf16 v[96:99], v[182:185], v[198:201], v[108:111]
	v_mfma_f32_16x16x32_bf16 v[104:107], v[182:185], v[206:209], v[112:115]
	v_mfma_f32_16x16x32_bf16 v[84:87], v[190:193], v[198:201], v[84:87]
	v_mfma_f32_16x16x32_bf16 v[88:91], v[190:193], v[206:209], v[88:91]
	v_mfma_f32_16x16x32_bf16 v[12:15], v[132:135], v[202:205], v[12:15]
	v_mfma_f32_16x16x32_bf16 v[16:19], v[132:135], v[210:213], v[16:19]
	v_mfma_f32_16x16x32_bf16 v[48:51], v[178:181], v[202:205], v[48:51]
	v_mfma_f32_16x16x32_bf16 v[92:95], v[178:181], v[210:213], v[92:95]
	v_mfma_f32_16x16x32_bf16 v[96:99], v[186:189], v[202:205], v[96:99]
	v_mfma_f32_16x16x32_bf16 v[104:107], v[186:189], v[210:213], v[104:107]
	v_mfma_f32_16x16x32_bf16 v[84:87], v[194:197], v[202:205], v[84:87]
	v_mfma_f32_16x16x32_bf16 v[88:91], v[194:197], v[210:213], v[88:91]
	s_barrier
; #define STAGE(P, GP, ktrel) do { const GAS char* _g = (GP) + (ktrel) * (BK * 2); \
;     __builtin_amdgcn_global_load_lds((const GAS unsigned*)(_g + so0), (unsigned*)((char*)(P) + tid_ * 16), 16, 0, 0); \
;     __builtin_amdgcn_global_load_lds((const GAS unsigned*)(_g + so1), (unsigned*)((char*)(P) + tid_ * 16 + 8192), 16, 0, 0); } while (0)
; #define WAIT_V(n) asm volatile("s_waitcnt vmcnt(" #n ")" ::: "memory")
; #define WAIT_L(n) asm volatile("s_waitcnt lgkmcnt(" #n ")" ::: "memory")
; #define BAR __builtin_amdgcn_s_barrier()
; #define LDA(dst, b, h) for (int m = 0; m < 4; ++m) for (int k = 0; k < 2; ++k) \
;     dst[m][k] = *reinterpret_cast<const bf16x8*>((char*)SA(b, h) + lds_byte(wr * 64 + m * 16 + fr, k * 32 + fq * 8))
; #define LDB(dst, b, h) for (int n = 0; n < 2; ++n) for (int k = 0; k < 2; ++k) \
;     dst[n][k] = *reinterpret_cast<const bf16x8*>((char*)SB(b, h) + lds_byte(wc * 32 + n * 16 + fr, k * 32 + fq * 8))
; #define MMA(ai, bj, At_, Bt_) do { __builtin_amdgcn_s_setprio(1); \
;     for (int m = 0; m < 4; ++m) for (int n = 0; n < 2; ++n) for (int k = 0; k < 2; ++k) \
;       acc[ai][bj][m][n] = __builtin_amdgcn_mfma_f32_16x16x32_bf16(At_[m][k], Bt_[n][k], acc[ai][bj][m][n], 0, 0, 0); \
;     __builtin_amdgcn_s_setprio(0); } while (0)
; template <int K, int LD = K>
; __device__ __forceinline__ void gemm_main(const GAS bf16* A, const GAS bf16* Bt, int brow, int bcol, f32x4 (&acc)[2][2][4][2]) {
;     ...
;   { LDB(B0, 0, 0); LDA(At, 0, 0); STAGE(SA(1, 1), pA1, 1);
;     BAR; WAIT_L(0); MMA(0, 0, At, B0); BAR;
;     LDB(B1, 0, 1); BAR; WAIT_L(0); MMA(0, 1, At, B1); BAR;
;     LDA(At, 0, 1); WAIT_V(4); BAR; WAIT_L(0); MMA(1, 0, At, B0); MMA(1, 1, At, B1); BAR; }
	s_mov_b32 m0, s31
	v_lshl_add_u64 v[2:3], s[18:19], 0, v[2:3]
	v_lshl_add_u64 v[2:3], v[2:3], 0, s[8:9]
	ds_read_b128 v[108:111], v225
	ds_read_b128 v[112:115], v225 offset:1024
	ds_read_b128 v[116:119], v225 offset:2048
	ds_read_b128 v[120:123], v225 offset:3072
	ds_read_b128 v[124:127], v246
	ds_read_b128 v[132:135], v246 offset:1024
	ds_read_b128 v[174:177], v247 offset:2048
	ds_read_b128 v[178:181], v247 offset:3072
	ds_read_b128 v[182:185], v247 offset:4096
	ds_read_b128 v[186:189], v247 offset:5120
	ds_read_b128 v[190:193], v247 offset:6144
	ds_read_b128 v[194:197], v247 offset:7168
	global_load_lds_dwordx4 v[2:3], off
	v_lshl_add_u64 v[2:3], s[18:19], 0, v[138:139]
	v_lshl_add_u64 v[2:3], v[2:3], 0, s[8:9]
	s_mov_b32 m0, s30
	s_nop 0
	global_load_lds_dwordx4 v[2:3], off
	s_barrier
	s_waitcnt lgkmcnt(0)
	s_waitcnt lgkmcnt(0)
	v_mfma_f32_16x16x32_bf16 v[52:55], v[124:127], v[108:111], v[52:55]
	v_mfma_f32_16x16x32_bf16 v[56:59], v[124:127], v[116:119], v[56:59]
	v_mfma_f32_16x16x32_bf16 v[60:63], v[174:177], v[108:111], v[60:63]
	v_mfma_f32_16x16x32_bf16 v[64:67], v[174:177], v[116:119], v[64:67]
	v_mfma_f32_16x16x32_bf16 v[68:71], v[182:185], v[108:111], v[68:71]
	v_mfma_f32_16x16x32_bf16 v[72:75], v[182:185], v[116:119], v[72:75]
	v_mfma_f32_16x16x32_bf16 v[76:79], v[190:193], v[108:111], v[76:79]
	v_mfma_f32_16x16x32_bf16 v[52:55], v[132:135], v[112:115], v[52:55]
	v_mfma_f32_16x16x32_bf16 v[56:59], v[132:135], v[120:123], v[56:59]
	v_mfma_f32_16x16x32_bf16 v[60:63], v[178:181], v[112:115], v[60:63]
	v_mfma_f32_16x16x32_bf16 v[64:67], v[178:181], v[120:123], v[64:67]
	v_mfma_f32_16x16x32_bf16 v[68:71], v[186:189], v[112:115], v[68:71]
	v_mfma_f32_16x16x32_bf16 v[72:75], v[186:189], v[120:123], v[72:75]
	v_mfma_f32_16x16x32_bf16 v[76:79], v[194:197], v[112:115], v[76:79]
	v_mfma_f32_16x16x32_bf16 v[80:83], v[190:193], v[116:119], v[80:83]
	v_mfma_f32_16x16x32_bf16 v[198:201], v[194:197], v[120:123], v[80:83]
	s_barrier
	s_nop 4
	ds_read_b128 v[80:83], v229
	ds_read_b128 v[202:205], v229 offset:1024
	ds_read_b128 v[206:209], v229 offset:2048
	ds_read_b128 v[210:213], v229 offset:3072
	s_barrier
	s_waitcnt lgkmcnt(0)
	s_waitcnt lgkmcnt(0)
	v_mfma_f32_16x16x32_bf16 v[20:23], v[124:127], v[206:209], v[20:23]
	v_mfma_f32_16x16x32_bf16 v[24:27], v[174:177], v[80:83], v[24:27]
	v_mfma_f32_16x16x32_bf16 v[28:31], v[174:177], v[206:209], v[28:31]
	v_mfma_f32_16x16x32_bf16 v[32:35], v[182:185], v[80:83], v[32:35]
	v_mfma_f32_16x16x32_bf16 v[36:39], v[182:185], v[206:209], v[36:39]
	v_mfma_f32_16x16x32_bf16 v[40:43], v[190:193], v[80:83], v[40:43]
	v_mfma_f32_16x16x32_bf16 v[44:47], v[190:193], v[206:209], v[44:47]
	v_mfma_f32_16x16x32_bf16 v[100:103], v[124:127], v[80:83], v[100:103]
	v_mfma_f32_16x16x32_bf16 v[20:23], v[132:135], v[210:213], v[20:23]
	v_mfma_f32_16x16x32_bf16 v[24:27], v[178:181], v[202:205], v[24:27]
	v_mfma_f32_16x16x32_bf16 v[28:31], v[178:181], v[210:213], v[28:31]
	v_mfma_f32_16x16x32_bf16 v[32:35], v[186:189], v[202:205], v[32:35]
	v_mfma_f32_16x16x32_bf16 v[36:39], v[186:189], v[210:213], v[36:39]
	v_mfma_f32_16x16x32_bf16 v[40:43], v[194:197], v[202:205], v[40:43]
	v_mfma_f32_16x16x32_bf16 v[44:47], v[194:197], v[210:213], v[44:47]
	v_mfma_f32_16x16x32_bf16 v[214:217], v[132:135], v[202:205], v[100:103]
	s_barrier
	s_nop 0
	ds_read_b128 v[100:103], v246 offset:16384
	ds_read_b128 v[124:127], v246 offset:17408
	ds_read_b128 v[132:135], v247 offset:18432
	ds_read_b128 v[174:177], v247 offset:19456
	ds_read_b128 v[178:181], v247 offset:20480
	ds_read_b128 v[182:185], v247 offset:21504
	ds_read_b128 v[186:189], v247 offset:22528
	ds_read_b128 v[190:193], v247 offset:23552
	s_waitcnt vmcnt(4)
	s_barrier
	s_waitcnt lgkmcnt(0)
	s_waitcnt lgkmcnt(0)
	v_mfma_f32_16x16x32_bf16 v[2:5], v[186:189], v[108:111], v[4:7]
	v_mfma_f32_16x16x32_bf16 v[140:143], v[100:103], v[108:111], v[140:143]
	v_mfma_f32_16x16x32_bf16 v[144:147], v[100:103], v[116:119], v[144:147]
	v_mfma_f32_16x16x32_bf16 v[148:151], v[132:135], v[108:111], v[148:151]
	v_mfma_f32_16x16x32_bf16 v[156:159], v[132:135], v[116:119], v[156:159]
	v_mfma_f32_16x16x32_bf16 v[160:163], v[178:181], v[108:111], v[160:163]
	v_mfma_f32_16x16x32_bf16 v[164:167], v[178:181], v[116:119], v[164:167]
	v_mfma_f32_16x16x32_bf16 v[2:5], v[190:193], v[112:115], v[2:5]
	v_mfma_f32_16x16x32_bf16 v[6:9], v[186:189], v[116:119], v[8:11]
	v_mfma_f32_16x16x32_bf16 v[140:143], v[124:127], v[112:115], v[140:143]
	v_mfma_f32_16x16x32_bf16 v[144:147], v[124:127], v[120:123], v[144:147]
	v_mfma_f32_16x16x32_bf16 v[148:151], v[174:177], v[112:115], v[148:151]
	v_mfma_f32_16x16x32_bf16 v[156:159], v[174:177], v[120:123], v[156:159]
	v_mfma_f32_16x16x32_bf16 v[160:163], v[182:185], v[112:115], v[160:163]
	v_mfma_f32_16x16x32_bf16 v[164:167], v[182:185], v[120:123], v[164:167]
	v_mfma_f32_16x16x32_bf16 v[194:197], v[190:193], v[120:123], v[6:9]
	v_mfma_f32_16x16x32_bf16 v[6:9], v[100:103], v[80:83], v[12:15]
	v_mfma_f32_16x16x32_bf16 v[10:13], v[124:127], v[202:205], v[6:9]
	v_mfma_f32_16x16x32_bf16 v[6:9], v[100:103], v[206:209], v[16:19]
	v_mfma_f32_16x16x32_bf16 v[14:17], v[124:127], v[210:213], v[6:9]
	v_mfma_f32_16x16x32_bf16 v[6:9], v[132:135], v[80:83], v[48:51]
	v_mfma_f32_16x16x32_bf16 v[218:221], v[174:177], v[202:205], v[6:9]
	v_mfma_f32_16x16x32_bf16 v[6:9], v[132:135], v[206:209], v[92:95]
	v_mfma_f32_16x16x32_bf16 v[132:135], v[174:177], v[210:213], v[6:9]
	v_mfma_f32_16x16x32_bf16 v[6:9], v[178:181], v[80:83], v[96:99]
	v_mfma_f32_16x16x32_bf16 v[174:177], v[182:185], v[202:205], v[6:9]
	v_mfma_f32_16x16x32_bf16 v[6:9], v[178:181], v[206:209], v[104:107]
	v_mfma_f32_16x16x32_bf16 v[178:181], v[182:185], v[210:213], v[6:9]
	v_mfma_f32_16x16x32_bf16 v[6:9], v[186:189], v[80:83], v[84:87]
	v_mfma_f32_16x16x32_bf16 v[182:185], v[190:193], v[202:205], v[6:9]
	v_mfma_f32_16x16x32_bf16 v[6:9], v[186:189], v[206:209], v[88:91]
	v_mfma_f32_16x16x32_bf16 v[186:189], v[190:193], v[210:213], v[6:9]
	s_barrier
; #define WAIT_V(n) asm volatile("s_waitcnt vmcnt(" #n ")" ::: "memory")
; #define WAIT_L(n) asm volatile("s_waitcnt lgkmcnt(" #n ")" ::: "memory")
; #define BAR __builtin_amdgcn_s_barrier()
; #define LDA(dst, b, h) for (int m = 0; m < 4; ++m) for (int k = 0; k < 2; ++k) \
;     dst[m][k] = *reinterpret_cast<const bf16x8*>((char*)SA(b, h) + lds_byte(wr * 64 + m * 16 + fr, k * 32 + fq * 8))
; #define LDB(dst, b, h) for (int n = 0; n < 2; ++n) for (int k = 0; k < 2; ++k) \
;     dst[n][k] = *reinterpret_cast<const bf16x8*>((char*)SB(b, h) + lds_byte(wc * 32 + n * 16 + fr, k * 32 + fq * 8))
; #define MMA(ai, bj, At_, Bt_) do { __builtin_amdgcn_s_setprio(1); \
;     for (int m = 0; m < 4; ++m) for (int n = 0; n < 2; ++n) for (int k = 0; k < 2; ++k) \
;       acc[ai][bj][m][n] = __builtin_amdgcn_mfma_f32_16x16x32_bf16(At_[m][k], Bt_[n][k], acc[ai][bj][m][n], 0, 0, 0); \
;     __builtin_amdgcn_s_setprio(0); } while (0)
; template <int K, int LD = K>
; __device__ __forceinline__ void gemm_main(const GAS bf16* A, const GAS bf16* Bt, int brow, int bcol, f32x4 (&acc)[2][2][4][2]) {
;     ...
;     LDA(At, 0, 1); WAIT_V(4); BAR; WAIT_L(0); MMA(1, 0, At, B0); MMA(1, 1, At, B1); BAR; }
;   { LDB(B0, 1, 0); LDA(At, 1, 0); WAIT_V(2); BAR; WAIT_L(0); MMA(0, 0, At, B0); BAR;
;     LDB(B1, 1, 1); WAIT_V(0); BAR; WAIT_L(0); MMA(0, 1, At, B1); BAR;
;     LDA(At, 1, 1); BAR; WAIT_L(0); MMA(1, 0, At, B0); MMA(1, 1, At, B1); BAR; }
;   if (wr == 0) BAR;
	s_nop 4
	ds_read_b128 v[6:9], v155
	ds_read_b128 v[190:193], v155 offset:1024
	ds_read_b128 v[202:205], v155 offset:2048
	ds_read_b128 v[206:209], v155 offset:3072
	ds_read_b128 v[48:51], v246 offset:32768
	ds_read_b128 v[90:93], v246 offset:33792
	ds_read_b128 v[94:97], v247 offset:34816
	ds_read_b128 v[106:109], v247 offset:35840
	ds_read_b128 v[210:213], v247 offset:36864
	ds_read_b128 v[222:225], v247 offset:37888
	ds_read_b128 v[226:229], v247 offset:38912
	ds_read_b128 v[230:233], v247 offset:39936
	s_waitcnt vmcnt(2)
	s_barrier
	s_waitcnt lgkmcnt(0)
	s_waitcnt lgkmcnt(0)
	v_mfma_f32_16x16x32_bf16 v[52:55], v[48:51], v[6:9], v[52:55]
	v_mfma_f32_16x16x32_bf16 v[118:121], v[90:93], v[190:193], v[52:55]
	v_mfma_f32_16x16x32_bf16 v[52:55], v[48:51], v[202:205], v[56:59]
	v_mfma_f32_16x16x32_bf16 v[114:117], v[90:93], v[206:209], v[52:55]
	v_mfma_f32_16x16x32_bf16 v[52:55], v[94:97], v[6:9], v[60:63]
	v_mfma_f32_16x16x32_bf16 v[102:105], v[106:109], v[190:193], v[52:55]
	v_mfma_f32_16x16x32_bf16 v[52:55], v[94:97], v[202:205], v[64:67]
	v_mfma_f32_16x16x32_bf16 v[98:101], v[106:109], v[206:209], v[52:55]
	v_mfma_f32_16x16x32_bf16 v[52:55], v[210:213], v[6:9], v[68:71]
	v_mfma_f32_16x16x32_bf16 v[86:89], v[222:225], v[190:193], v[52:55]
	v_mfma_f32_16x16x32_bf16 v[52:55], v[210:213], v[202:205], v[72:75]
	v_mfma_f32_16x16x32_bf16 v[82:85], v[222:225], v[206:209], v[52:55]
	v_mfma_f32_16x16x32_bf16 v[52:55], v[226:229], v[6:9], v[76:79]
	v_mfma_f32_16x16x32_bf16 v[70:73], v[230:233], v[190:193], v[52:55]
	v_mfma_f32_16x16x32_bf16 v[52:55], v[226:229], v[202:205], v[198:201]
	v_mfma_f32_16x16x32_bf16 v[66:69], v[230:233], v[206:209], v[52:55]
	s_barrier
	ds_read_b128 v[198:201], v131
	ds_read_b128 v[234:237], v131 offset:1024
	ds_read_b128 v[238:241], v131 offset:2048
	ds_read_b128 v[242:245], v131 offset:3072
	s_waitcnt vmcnt(0)
	s_barrier
	s_waitcnt lgkmcnt(0)
	s_waitcnt lgkmcnt(0)
	v_mfma_f32_16x16x32_bf16 v[18:21], v[48:51], v[238:241], v[20:23]
	v_mfma_f32_16x16x32_bf16 v[122:125], v[90:93], v[242:245], v[18:21]
	v_mfma_f32_16x16x32_bf16 v[18:21], v[94:97], v[198:201], v[24:27]
	v_mfma_f32_16x16x32_bf16 v[110:113], v[106:109], v[234:237], v[18:21]
	v_mfma_f32_16x16x32_bf16 v[18:21], v[94:97], v[238:241], v[28:31]
	v_mfma_f32_16x16x32_bf16 v[106:109], v[106:109], v[242:245], v[18:21]
	v_mfma_f32_16x16x32_bf16 v[18:21], v[210:213], v[198:201], v[32:35]
	v_mfma_f32_16x16x32_bf16 v[52:55], v[48:51], v[198:201], v[214:217]
	v_mfma_f32_16x16x32_bf16 v[94:97], v[222:225], v[234:237], v[18:21]
	v_mfma_f32_16x16x32_bf16 v[18:21], v[210:213], v[238:241], v[36:39]
	v_mfma_f32_16x16x32_bf16 v[126:129], v[90:93], v[234:237], v[52:55]
	v_mfma_f32_16x16x32_bf16 v[90:93], v[222:225], v[242:245], v[18:21]
	v_mfma_f32_16x16x32_bf16 v[18:21], v[226:229], v[198:201], v[40:43]
	v_mfma_f32_16x16x32_bf16 v[78:81], v[230:233], v[234:237], v[18:21]
	v_mfma_f32_16x16x32_bf16 v[18:21], v[226:229], v[238:241], v[44:47]
	v_mfma_f32_16x16x32_bf16 v[74:77], v[230:233], v[242:245], v[18:21]
	s_barrier
	ds_read_b128 v[26:29], v246 offset:49152
	ds_read_b128 v[30:33], v246 offset:50176
	ds_read_b128 v[42:45], v247 offset:51200
	ds_read_b128 v[210:213], v247 offset:52224
	ds_read_b128 v[214:217], v247 offset:53248
	ds_read_b128 v[222:225], v247 offset:54272
	ds_read_b128 v[226:229], v247 offset:55296
	ds_read_b128 v[230:233], v247 offset:56320
	s_barrier
	s_waitcnt lgkmcnt(0)
	s_waitcnt lgkmcnt(0)
	v_mfma_f32_16x16x32_bf16 v[18:21], v[26:29], v[6:9], v[140:143]
	v_mfma_f32_16x16x32_bf16 v[54:57], v[30:33], v[190:193], v[18:21]
	v_mfma_f32_16x16x32_bf16 v[18:21], v[26:29], v[202:205], v[144:147]
	v_mfma_f32_16x16x32_bf16 v[50:53], v[30:33], v[206:209], v[18:21]
	v_mfma_f32_16x16x32_bf16 v[18:21], v[42:45], v[6:9], v[148:151]
	v_mfma_f32_16x16x32_bf16 v[38:41], v[210:213], v[190:193], v[18:21]
	v_mfma_f32_16x16x32_bf16 v[18:21], v[42:45], v[202:205], v[156:159]
	v_mfma_f32_16x16x32_bf16 v[34:37], v[210:213], v[206:209], v[18:21]
	v_mfma_f32_16x16x32_bf16 v[18:21], v[214:217], v[6:9], v[160:163]
	v_mfma_f32_16x16x32_bf16 v[2:5], v[226:229], v[6:9], v[2:5]
	v_mfma_f32_16x16x32_bf16 v[22:25], v[222:225], v[190:193], v[18:21]
	v_mfma_f32_16x16x32_bf16 v[18:21], v[214:217], v[202:205], v[164:167]
	v_mfma_f32_16x16x32_bf16 v[6:9], v[230:233], v[190:193], v[2:5]
	v_mfma_f32_16x16x32_bf16 v[2:5], v[226:229], v[202:205], v[194:197]
	v_mfma_f32_16x16x32_bf16 v[18:21], v[222:225], v[206:209], v[18:21]
	v_mfma_f32_16x16x32_bf16 v[2:5], v[230:233], v[206:209], v[2:5]
	v_mfma_f32_16x16x32_bf16 v[10:13], v[26:29], v[198:201], v[10:13]
	v_mfma_f32_16x16x32_bf16 v[62:65], v[30:33], v[234:237], v[10:13]
	v_mfma_f32_16x16x32_bf16 v[10:13], v[26:29], v[238:241], v[14:17]
	v_mfma_f32_16x16x32_bf16 v[58:61], v[30:33], v[242:245], v[10:13]
	v_mfma_f32_16x16x32_bf16 v[10:13], v[42:45], v[198:201], v[218:221]
	v_mfma_f32_16x16x32_bf16 v[46:49], v[210:213], v[234:237], v[10:13]
	v_mfma_f32_16x16x32_bf16 v[10:13], v[42:45], v[238:241], v[132:135]
	v_mfma_f32_16x16x32_bf16 v[42:45], v[210:213], v[242:245], v[10:13]
	v_mfma_f32_16x16x32_bf16 v[10:13], v[214:217], v[198:201], v[174:177]
	v_mfma_f32_16x16x32_bf16 v[30:33], v[222:225], v[234:237], v[10:13]
	v_mfma_f32_16x16x32_bf16 v[10:13], v[214:217], v[238:241], v[178:181]
	v_mfma_f32_16x16x32_bf16 v[26:29], v[222:225], v[242:245], v[10:13]
	v_mfma_f32_16x16x32_bf16 v[10:13], v[226:229], v[198:201], v[182:185]
	v_mfma_f32_16x16x32_bf16 v[14:17], v[230:233], v[234:237], v[10:13]
	v_mfma_f32_16x16x32_bf16 v[10:13], v[226:229], v[238:241], v[186:189]
	v_mfma_f32_16x16x32_bf16 v[10:13], v[230:233], v[242:245], v[10:13]
	v_cmp_gt_u32_e32 vcc, s42, v130
	s_barrier
	s_and_saveexec_b64 s[18:19], vcc
	s_cbranch_execz .LBB0_1223
	s_barrier

; #define STAGE(P, GP, ktrel) do { const GAS char* _g = (GP) + (ktrel) * (BK * 2); \
;     __builtin_amdgcn_global_load_lds((const GAS unsigned*)(_g + so0), (unsigned*)((char*)(P) + tid_ * 16), 16, 0, 0); \
;     __builtin_amdgcn_global_load_lds((const GAS unsigned*)(_g + so1), (unsigned*)((char*)(P) + tid_ * 16 + 8192), 16, 0, 0); } while (0)
; #define WAIT_L(n) asm volatile("s_waitcnt lgkmcnt(" #n ")" ::: "memory")
; #define BAR __builtin_amdgcn_s_barrier()
; #define SCHED __builtin_amdgcn_sched_barrier(0)
; #define LDA(dst, b, h) for (int m = 0; m < 4; ++m) for (int k = 0; k < 2; ++k) \
;     dst[m][k] = *reinterpret_cast<const bf16x8*>((char*)SA(b, h) + lds_byte(wr * 64 + m * 16 + fr, k * 32 + fq * 8))
; #define LDB(dst, b, h) for (int n = 0; n < 2; ++n) for (int k = 0; k < 2; ++k) \
;     dst[n][k] = *reinterpret_cast<const bf16x8*>((char*)SB(b, h) + lds_byte(wc * 32 + n * 16 + fr, k * 32 + fq * 8))
; #define MMA(ai, bj, At_, Bt_) do { __builtin_amdgcn_s_setprio(1); \
;     for (int m = 0; m < 4; ++m) for (int n = 0; n < 2; ++n) for (int k = 0; k < 2; ++k) \
;       acc[ai][bj][m][n] = __builtin_amdgcn_mfma_f32_16x16x32_bf16(At_[m][k], Bt_[n][k], acc[ai][bj][m][n], 0, 0, 0); \
;     __builtin_amdgcn_s_setprio(0); } while (0)
; template <int K, int LD = K>
; __device__ __forceinline__ void gemm_main(const GAS bf16* A, const GAS bf16* Bt, int brow, int bcol, f32x4 (&acc)[2][2][4][2]) {
;     ...
;     LDB(B0, 0, 0); SCHED; LDA(At, 0, 0); STAGE(SA(1, 1), pA1, 1);
;     WAIT_L(8); BAR; WAIT_L(0); MMA(0, 0, At, B0); BAR; SCHED;
;     LDB(B1, 0, 1); STAGE(SB(0, 0), pB0, 2);
;     BAR; WAIT_L(0); MMA(0, 1, At, B1); BAR;
;     LDA(At, 0, 1); STAGE(SA(0, 0), pA0, 2);
;     BAR; WAIT_L(0); MMA(1, 0, At, B0); BAR; SCHED;
.LBB0_1226:
	ds_read_b128 v[146:149], v143
	ds_read_b128 v[150:153], v143 offset:1024
	ds_read_b128 v[156:159], v143 offset:2048
	ds_read_b128 v[160:163], v143 offset:3072
	v_add_u32_e32 v155, 0x100, v141
	v_add_u32_e32 v144, 0xc000, v155
	v_lshl_add_u64 v[168:169], s[18:19], 0, v[138:139]
	v_readfirstlane_b32 s30, v144
	v_add_u32_e32 v145, 0xe000, v155
	v_lshl_add_u64 v[202:203], v[168:169], 0, s[8:9]
	s_mov_b32 m0, s30
	v_lshl_add_u64 v[218:219], s[18:19], 0, v[130:131]
	v_readfirstlane_b32 s30, v145
	ds_read_b128 v[164:167], v136
	ds_read_b128 v[174:177], v136 offset:1024
	ds_read_b128 v[178:181], v135
	ds_read_b128 v[182:185], v135 offset:1024
	ds_read_b128 v[186:189], v134
	ds_read_b128 v[190:193], v134 offset:1024
	ds_read_b128 v[194:197], v133
	ds_read_b128 v[198:201], v133 offset:1024
	global_load_lds_dwordx4 v[202:203], off
	v_lshl_add_u64 v[202:203], v[218:219], 0, s[8:9]
	s_mov_b32 m0, s30
	s_nop 0
	global_load_lds_dwordx4 v[202:203], off
	s_waitcnt lgkmcnt(8)
	s_waitcnt vmcnt(10)
	s_barrier
	s_waitcnt lgkmcnt(0)
	s_waitcnt lgkmcnt(0)
	v_mfma_f32_16x16x32_bf16 v[126:129], v[164:167], v[146:149], v[126:129]
	v_mfma_f32_16x16x32_bf16 v[122:125], v[164:167], v[156:159], v[122:125]
	v_mfma_f32_16x16x32_bf16 v[118:121], v[178:181], v[146:149], v[118:121]
	v_mfma_f32_16x16x32_bf16 v[114:117], v[178:181], v[156:159], v[114:117]
	v_mfma_f32_16x16x32_bf16 v[110:113], v[186:189], v[146:149], v[110:113]
	v_mfma_f32_16x16x32_bf16 v[106:109], v[186:189], v[156:159], v[106:109]
	v_mfma_f32_16x16x32_bf16 v[102:105], v[194:197], v[146:149], v[102:105]
	v_mfma_f32_16x16x32_bf16 v[98:101], v[194:197], v[156:159], v[98:101]
	v_mfma_f32_16x16x32_bf16 v[126:129], v[174:177], v[150:153], v[126:129]
	v_mfma_f32_16x16x32_bf16 v[122:125], v[174:177], v[160:163], v[122:125]
	v_mfma_f32_16x16x32_bf16 v[118:121], v[182:185], v[150:153], v[118:121]
	v_mfma_f32_16x16x32_bf16 v[114:117], v[182:185], v[160:163], v[114:117]
	v_mfma_f32_16x16x32_bf16 v[110:113], v[190:193], v[150:153], v[110:113]
	v_mfma_f32_16x16x32_bf16 v[106:109], v[190:193], v[160:163], v[106:109]
	v_mfma_f32_16x16x32_bf16 v[102:105], v[198:201], v[150:153], v[102:105]
	v_mfma_f32_16x16x32_bf16 v[98:101], v[198:201], v[160:163], v[98:101]
	s_barrier
	v_add_u32_e32 v226, s38, v141
	v_lshl_add_u64 v[220:221], s[28:29], 0, v[138:139]
	v_readfirstlane_b32 s30, v226
	v_lshl_add_u64 v[222:223], v[220:221], 0, s[14:15]
	s_mov_b32 m0, s30
	v_add_u32_e32 v226, 0x2000, v226
	ds_read_b128 v[202:205], v142
	ds_read_b128 v[206:209], v142 offset:1024
	ds_read_b128 v[210:213], v142 offset:2048
	ds_read_b128 v[214:217], v142 offset:3072
	global_load_lds_dwordx4 v[222:223], off
	v_lshl_add_u64 v[222:223], s[28:29], 0, v[130:131]
	v_readfirstlane_b32 s30, v226
	v_lshl_add_u64 v[224:225], v[222:223], 0, s[14:15]
	s_mov_b32 m0, s30
	s_add_u32 s28, s28, 0x100
	global_load_lds_dwordx4 v[224:225], off
	s_waitcnt vmcnt(10)
	s_barrier
	s_waitcnt lgkmcnt(0)
	s_addc_u32 s29, s29, 0
	s_waitcnt lgkmcnt(0)
	v_mfma_f32_16x16x32_bf16 v[94:97], v[164:167], v[202:205], v[94:97]
	v_mfma_f32_16x16x32_bf16 v[90:93], v[164:167], v[210:213], v[90:93]
	v_mfma_f32_16x16x32_bf16 v[86:89], v[178:181], v[202:205], v[86:89]
	v_mfma_f32_16x16x32_bf16 v[82:85], v[178:181], v[210:213], v[82:85]
	v_mfma_f32_16x16x32_bf16 v[78:81], v[186:189], v[202:205], v[78:81]
	v_mfma_f32_16x16x32_bf16 v[74:77], v[186:189], v[210:213], v[74:77]
	v_mfma_f32_16x16x32_bf16 v[70:73], v[194:197], v[202:205], v[70:73]
	v_mfma_f32_16x16x32_bf16 v[66:69], v[194:197], v[210:213], v[66:69]
	v_mfma_f32_16x16x32_bf16 v[94:97], v[174:177], v[206:209], v[94:97]
	v_mfma_f32_16x16x32_bf16 v[90:93], v[174:177], v[214:217], v[90:93]
	v_mfma_f32_16x16x32_bf16 v[86:89], v[182:185], v[206:209], v[86:89]
	v_mfma_f32_16x16x32_bf16 v[82:85], v[182:185], v[214:217], v[82:85]
	v_mfma_f32_16x16x32_bf16 v[78:81], v[190:193], v[206:209], v[78:81]
	v_mfma_f32_16x16x32_bf16 v[74:77], v[190:193], v[214:217], v[74:77]
	v_mfma_f32_16x16x32_bf16 v[70:73], v[198:201], v[206:209], v[70:73]
	v_mfma_f32_16x16x32_bf16 v[66:69], v[198:201], v[214:217], v[66:69]
	v_lshl_add_u64 v[224:225], s[26:27], 0, v[138:139]
	v_readfirstlane_b32 s30, v155
	v_lshl_add_u64 v[226:227], v[224:225], 0, s[14:15]
	s_mov_b32 m0, s30
	v_add_u32_e32 v230, 0x2000, v155
	s_barrier
	ds_read_b128 v[164:167], v136 offset:16384
	ds_read_b128 v[174:177], v136 offset:17408
	ds_read_b128 v[178:181], v135 offset:16384
	ds_read_b128 v[182:185], v135 offset:17408
	ds_read_b128 v[186:189], v134 offset:16384
	ds_read_b128 v[190:193], v134 offset:17408
	ds_read_b128 v[194:197], v133 offset:16384
	ds_read_b128 v[198:201], v133 offset:17408
	global_load_lds_dwordx4 v[226:227], off
	v_lshl_add_u64 v[226:227], s[26:27], 0, v[130:131]
	v_readfirstlane_b32 s30, v230
	v_lshl_add_u64 v[228:229], v[226:227], 0, s[14:15]
	s_mov_b32 m0, s30
	s_add_u32 s26, s26, 0x100
	global_load_lds_dwordx4 v[228:229], off
	s_barrier
	s_waitcnt lgkmcnt(0)
	s_addc_u32 s27, s27, 0
	s_waitcnt lgkmcnt(0)
	v_mfma_f32_16x16x32_bf16 v[62:65], v[164:167], v[146:149], v[62:65]
	v_mfma_f32_16x16x32_bf16 v[58:61], v[164:167], v[156:159], v[58:61]
	v_mfma_f32_16x16x32_bf16 v[54:57], v[178:181], v[146:149], v[54:57]
	v_mfma_f32_16x16x32_bf16 v[50:53], v[178:181], v[156:159], v[50:53]
	v_mfma_f32_16x16x32_bf16 v[46:49], v[186:189], v[146:149], v[46:49]
	v_mfma_f32_16x16x32_bf16 v[42:45], v[186:189], v[156:159], v[42:45]
	v_mfma_f32_16x16x32_bf16 v[38:41], v[194:197], v[146:149], v[38:41]
	v_mfma_f32_16x16x32_bf16 v[34:37], v[194:197], v[156:159], v[34:37]
	v_mfma_f32_16x16x32_bf16 v[62:65], v[174:177], v[150:153], v[62:65]
	v_mfma_f32_16x16x32_bf16 v[58:61], v[174:177], v[160:163], v[58:61]
	v_mfma_f32_16x16x32_bf16 v[54:57], v[182:185], v[150:153], v[54:57]
	v_mfma_f32_16x16x32_bf16 v[50:53], v[182:185], v[160:163], v[50:53]
	v_mfma_f32_16x16x32_bf16 v[46:49], v[190:193], v[150:153], v[46:49]
	v_mfma_f32_16x16x32_bf16 v[42:45], v[190:193], v[160:163], v[42:45]
	v_mfma_f32_16x16x32_bf16 v[38:41], v[198:201], v[150:153], v[38:41]
	v_mfma_f32_16x16x32_bf16 v[34:37], v[198:201], v[160:163], v[34:37]
	s_barrier
; #define STAGE(P, GP, ktrel) do { const GAS char* _g = (GP) + (ktrel) * (BK * 2); \
;     __builtin_amdgcn_global_load_lds((const GAS unsigned*)(_g + so0), (unsigned*)((char*)(P) + tid_ * 16), 16, 0, 0); \
;     __builtin_amdgcn_global_load_lds((const GAS unsigned*)(_g + so1), (unsigned*)((char*)(P) + tid_ * 16 + 8192), 16, 0, 0); } while (0)
; #define WAIT_V(n) asm volatile("s_waitcnt vmcnt(" #n ")" ::: "memory")
; #define WAIT_L(n) asm volatile("s_waitcnt lgkmcnt(" #n ")" ::: "memory")
; #define BAR __builtin_amdgcn_s_barrier()
; #define SCHED __builtin_amdgcn_sched_barrier(0)
; #define LDA(dst, b, h) for (int m = 0; m < 4; ++m) for (int k = 0; k < 2; ++k) \
;     dst[m][k] = *reinterpret_cast<const bf16x8*>((char*)SA(b, h) + lds_byte(wr * 64 + m * 16 + fr, k * 32 + fq * 8))
; #define LDB(dst, b, h) for (int n = 0; n < 2; ++n) for (int k = 0; k < 2; ++k) \
;     dst[n][k] = *reinterpret_cast<const bf16x8*>((char*)SB(b, h) + lds_byte(wc * 32 + n * 16 + fr, k * 32 + fq * 8))
; #define MMA(ai, bj, At_, Bt_) do { __builtin_amdgcn_s_setprio(1); \
;     for (int m = 0; m < 4; ++m) for (int n = 0; n < 2; ++n) for (int k = 0; k < 2; ++k) \
;       acc[ai][bj][m][n] = __builtin_amdgcn_mfma_f32_16x16x32_bf16(At_[m][k], Bt_[n][k], acc[ai][bj][m][n], 0, 0, 0); \
;     __builtin_amdgcn_s_setprio(0); } while (0)
; template <int K, int LD = K>
; __device__ __forceinline__ void gemm_main(const GAS bf16* A, const GAS bf16* Bt, int brow, int bcol, f32x4 (&acc)[2][2][4][2]) {
;     ...
;     BAR; WAIT_L(0); MMA(1, 0, At, B0); BAR; SCHED;
;     STAGE(SB(0, 1), pB1, 2);
;     WAIT_V(6); BAR; MMA(1, 1, At, B1); BAR;
;     LDB(B0, 1, 0); SCHED; LDA(At, 1, 0); STAGE(SA(0, 1), pA1, 2);
;     WAIT_L(8); BAR; WAIT_L(0); MMA(0, 0, At, B0); BAR; SCHED;
;     LDB(B1, 1, 1); STAGE(SB(1, 0), pB0, 3);
;     BAR; WAIT_L(0); MMA(0, 1, At, B1); BAR;
	v_add_u32_e32 v148, s39, v141
	v_lshl_add_u64 v[228:229], s[24:25], 0, v[138:139]
	v_readfirstlane_b32 s30, v148
	v_add_u32_e32 v148, 0x2000, v148
	v_lshl_add_u64 v[146:147], v[228:229], 0, s[14:15]
	s_mov_b32 m0, s30
	v_lshl_add_u64 v[230:231], s[24:25], 0, v[130:131]
	v_readfirstlane_b32 s30, v148
	global_load_lds_dwordx4 v[146:147], off
	v_lshl_add_u64 v[146:147], v[230:231], 0, s[14:15]
	s_mov_b32 m0, s30
	s_add_u32 s24, s24, 0x100
	global_load_lds_dwordx4 v[146:147], off
	s_waitcnt vmcnt(10)
	s_addc_u32 s25, s25, 0
	s_barrier
	v_mfma_f32_16x16x32_bf16 v[30:33], v[164:167], v[202:205], v[30:33]
	v_mfma_f32_16x16x32_bf16 v[26:29], v[164:167], v[210:213], v[26:29]
	v_mfma_f32_16x16x32_bf16 v[22:25], v[178:181], v[202:205], v[22:25]
	v_mfma_f32_16x16x32_bf16 v[18:21], v[178:181], v[210:213], v[18:21]
	v_mfma_f32_16x16x32_bf16 v[14:17], v[186:189], v[202:205], v[14:17]
	v_mfma_f32_16x16x32_bf16 v[10:13], v[186:189], v[210:213], v[10:13]
	v_mfma_f32_16x16x32_bf16 v[6:9], v[194:197], v[202:205], v[6:9]
	v_mfma_f32_16x16x32_bf16 v[2:5], v[194:197], v[210:213], v[2:5]
	v_mfma_f32_16x16x32_bf16 v[30:33], v[174:177], v[206:209], v[30:33]
	v_mfma_f32_16x16x32_bf16 v[26:29], v[174:177], v[214:217], v[26:29]
	v_mfma_f32_16x16x32_bf16 v[22:25], v[182:185], v[206:209], v[22:25]
	v_mfma_f32_16x16x32_bf16 v[18:21], v[182:185], v[214:217], v[18:21]
	v_mfma_f32_16x16x32_bf16 v[14:17], v[190:193], v[206:209], v[14:17]
	v_mfma_f32_16x16x32_bf16 v[10:13], v[190:193], v[214:217], v[10:13]
	v_mfma_f32_16x16x32_bf16 v[6:9], v[198:201], v[206:209], v[6:9]
	v_mfma_f32_16x16x32_bf16 v[2:5], v[198:201], v[214:217], v[2:5]
	s_barrier
	ds_read_b128 v[146:149], v140
	ds_read_b128 v[150:153], v140 offset:1024
	ds_read_b128 v[156:159], v140 offset:2048
	ds_read_b128 v[160:163], v140 offset:3072
	v_add_u32_e32 v202, 0x4000, v155
	v_lshl_add_u64 v[168:169], v[168:169], 0, s[14:15]
	v_readfirstlane_b32 s30, v202
	v_add_u32_e32 v202, 0x6000, v155
	s_mov_b32 m0, s30
	v_readfirstlane_b32 s30, v202
	ds_read_b128 v[164:167], v136 offset:32768
	ds_read_b128 v[174:177], v136 offset:33792
	ds_read_b128 v[178:181], v135 offset:32768
	ds_read_b128 v[182:185], v135 offset:33792
	ds_read_b128 v[186:189], v134 offset:32768
	ds_read_b128 v[190:193], v134 offset:33792
	ds_read_b128 v[194:197], v133 offset:32768
	ds_read_b128 v[198:201], v133 offset:33792
	global_load_lds_dwordx4 v[168:169], off
	v_lshl_add_u64 v[168:169], v[218:219], 0, s[14:15]
	s_mov_b32 m0, s30
	s_add_u32 s18, s18, 0x100
	global_load_lds_dwordx4 v[168:169], off
	s_waitcnt lgkmcnt(8)
	s_waitcnt vmcnt(10)
	s_barrier
	s_waitcnt lgkmcnt(0)
	s_addc_u32 s19, s19, 0
	s_waitcnt lgkmcnt(0)
	v_mfma_f32_16x16x32_bf16 v[126:129], v[164:167], v[146:149], v[126:129]
	v_mfma_f32_16x16x32_bf16 v[122:125], v[164:167], v[156:159], v[122:125]
	v_mfma_f32_16x16x32_bf16 v[118:121], v[178:181], v[146:149], v[118:121]
	v_mfma_f32_16x16x32_bf16 v[114:117], v[178:181], v[156:159], v[114:117]
	v_mfma_f32_16x16x32_bf16 v[110:113], v[186:189], v[146:149], v[110:113]
	v_mfma_f32_16x16x32_bf16 v[106:109], v[186:189], v[156:159], v[106:109]
	v_mfma_f32_16x16x32_bf16 v[102:105], v[194:197], v[146:149], v[102:105]
	v_mfma_f32_16x16x32_bf16 v[98:101], v[194:197], v[156:159], v[98:101]
	v_mfma_f32_16x16x32_bf16 v[126:129], v[174:177], v[150:153], v[126:129]
	v_mfma_f32_16x16x32_bf16 v[122:125], v[174:177], v[160:163], v[122:125]
	v_mfma_f32_16x16x32_bf16 v[118:121], v[182:185], v[150:153], v[118:121]
	v_mfma_f32_16x16x32_bf16 v[114:117], v[182:185], v[160:163], v[114:117]
	v_mfma_f32_16x16x32_bf16 v[110:113], v[190:193], v[150:153], v[110:113]
	v_mfma_f32_16x16x32_bf16 v[106:109], v[190:193], v[160:163], v[106:109]
	v_mfma_f32_16x16x32_bf16 v[102:105], v[198:201], v[150:153], v[102:105]
	v_mfma_f32_16x16x32_bf16 v[98:101], v[198:201], v[160:163], v[98:101]
	s_barrier
	v_add_u32_e32 v218, s40, v141
	v_lshl_add_u64 v[168:169], v[220:221], 0, s[16:17]
	v_readfirstlane_b32 s30, v218
	v_add_u32_e32 v218, 0x2000, v218
	s_mov_b32 m0, s30
	v_readfirstlane_b32 s30, v218
	ds_read_b128 v[202:205], v137
	ds_read_b128 v[206:209], v137 offset:1024
	ds_read_b128 v[210:213], v137 offset:2048
	ds_read_b128 v[214:217], v137 offset:3072
	global_load_lds_dwordx4 v[168:169], off
	v_lshl_add_u64 v[168:169], v[222:223], 0, s[16:17]
	s_mov_b32 m0, s30
	s_nop 0
	global_load_lds_dwordx4 v[168:169], off
	s_waitcnt vmcnt(10)
	s_barrier
	s_waitcnt lgkmcnt(0)
	s_waitcnt lgkmcnt(0)
	v_mfma_f32_16x16x32_bf16 v[94:97], v[164:167], v[202:205], v[94:97]
	v_mfma_f32_16x16x32_bf16 v[90:93], v[164:167], v[210:213], v[90:93]
	v_mfma_f32_16x16x32_bf16 v[86:89], v[178:181], v[202:205], v[86:89]
	v_mfma_f32_16x16x32_bf16 v[82:85], v[178:181], v[210:213], v[82:85]
	v_mfma_f32_16x16x32_bf16 v[78:81], v[186:189], v[202:205], v[78:81]
	v_mfma_f32_16x16x32_bf16 v[74:77], v[186:189], v[210:213], v[74:77]
	v_mfma_f32_16x16x32_bf16 v[70:73], v[194:197], v[202:205], v[70:73]
	v_mfma_f32_16x16x32_bf16 v[66:69], v[194:197], v[210:213], v[66:69]
	v_mfma_f32_16x16x32_bf16 v[94:97], v[174:177], v[206:209], v[94:97]
	v_mfma_f32_16x16x32_bf16 v[90:93], v[174:177], v[214:217], v[90:93]
	v_mfma_f32_16x16x32_bf16 v[86:89], v[182:185], v[206:209], v[86:89]
	v_mfma_f32_16x16x32_bf16 v[82:85], v[182:185], v[214:217], v[82:85]
	v_mfma_f32_16x16x32_bf16 v[78:81], v[190:193], v[206:209], v[78:81]
	v_mfma_f32_16x16x32_bf16 v[74:77], v[190:193], v[214:217], v[74:77]
	v_mfma_f32_16x16x32_bf16 v[70:73], v[198:201], v[206:209], v[70:73]
	v_mfma_f32_16x16x32_bf16 v[66:69], v[198:201], v[214:217], v[66:69]
	v_add_u32_e32 v218, 0x8000, v155
	v_add_u32_e32 v155, 0xa000, v155
	v_readfirstlane_b32 s30, v218
	v_lshl_add_u64 v[168:169], v[224:225], 0, s[16:17]
	s_mov_b32 m0, s30
	v_readfirstlane_b32 s30, v155
	s_barrier
; #define STAGE(P, GP, ktrel) do { const GAS char* _g = (GP) + (ktrel) * (BK * 2); \
;     __builtin_amdgcn_global_load_lds((const GAS unsigned*)(_g + so0), (unsigned*)((char*)(P) + tid_ * 16), 16, 0, 0); \
;     __builtin_amdgcn_global_load_lds((const GAS unsigned*)(_g + so1), (unsigned*)((char*)(P) + tid_ * 16 + 8192), 16, 0, 0); } while (0)
; #define WAIT_V(n) asm volatile("s_waitcnt vmcnt(" #n ")" ::: "memory")
; #define WAIT_L(n) asm volatile("s_waitcnt lgkmcnt(" #n ")" ::: "memory")
; #define BAR __builtin_amdgcn_s_barrier()
; #define SCHED __builtin_amdgcn_sched_barrier(0)
; #define LDA(dst, b, h) for (int m = 0; m < 4; ++m) for (int k = 0; k < 2; ++k) \
;     dst[m][k] = *reinterpret_cast<const bf16x8*>((char*)SA(b, h) + lds_byte(wr * 64 + m * 16 + fr, k * 32 + fq * 8))
; #define LDB(dst, b, h) for (int n = 0; n < 2; ++n) for (int k = 0; k < 2; ++k) \
;     dst[n][k] = *reinterpret_cast<const bf16x8*>((char*)SB(b, h) + lds_byte(wc * 32 + n * 16 + fr, k * 32 + fq * 8))
; #define MMA(ai, bj, At_, Bt_) do { __builtin_amdgcn_s_setprio(1); \
;     for (int m = 0; m < 4; ++m) for (int n = 0; n < 2; ++n) for (int k = 0; k < 2; ++k) \
;       acc[ai][bj][m][n] = __builtin_amdgcn_mfma_f32_16x16x32_bf16(At_[m][k], Bt_[n][k], acc[ai][bj][m][n], 0, 0, 0); \
;     __builtin_amdgcn_s_setprio(0); } while (0)
; template <int K, int LD = K>
; __device__ __forceinline__ void gemm_main(const GAS bf16* A, const GAS bf16* Bt, int brow, int bcol, f32x4 (&acc)[2][2][4][2]) {
;     ...
;     LDA(At, 1, 1); STAGE(SA(1, 0), pA0, 3);
;     BAR; WAIT_L(0); MMA(1, 0, At, B0); BAR; SCHED;
;     STAGE(SB(1, 1), pB1, 3);
;     WAIT_V(6); BAR; MMA(1, 1, At, B1); BAR;
;     pA0 += 4 * BK; pA1 += 4 * BK; pB0 += 4 * BK; pB1 += 4 * BK;
;     asm volatile("" : "+s"(pA0), "+s"(pA1), "+s"(pB0), "+s"(pB1));
;   }
;   { LDB(B0, 0, 0); LDA(At, 0, 0); STAGE(SA(1, 1), pA1, 1);
;     BAR; WAIT_L(0); MMA(0, 0, At, B0); BAR;
	ds_read_b128 v[164:167], v136 offset:49152
	ds_read_b128 v[174:177], v136 offset:50176
	ds_read_b128 v[178:181], v135 offset:49152
	ds_read_b128 v[182:185], v135 offset:50176
	ds_read_b128 v[186:189], v134 offset:49152
	ds_read_b128 v[190:193], v134 offset:50176
	ds_read_b128 v[194:197], v133 offset:49152
	ds_read_b128 v[198:201], v133 offset:50176
	global_load_lds_dwordx4 v[168:169], off
	v_lshl_add_u64 v[168:169], v[226:227], 0, s[16:17]
	s_mov_b32 m0, s30
	s_nop 0
	global_load_lds_dwordx4 v[168:169], off
	s_barrier
	s_waitcnt lgkmcnt(0)
	s_waitcnt lgkmcnt(0)
	v_mfma_f32_16x16x32_bf16 v[62:65], v[164:167], v[146:149], v[62:65]
	v_mfma_f32_16x16x32_bf16 v[58:61], v[164:167], v[156:159], v[58:61]
	v_mfma_f32_16x16x32_bf16 v[54:57], v[178:181], v[146:149], v[54:57]
	v_mfma_f32_16x16x32_bf16 v[50:53], v[178:181], v[156:159], v[50:53]
	v_mfma_f32_16x16x32_bf16 v[46:49], v[186:189], v[146:149], v[46:49]
	v_mfma_f32_16x16x32_bf16 v[42:45], v[186:189], v[156:159], v[42:45]
	v_mfma_f32_16x16x32_bf16 v[38:41], v[194:197], v[146:149], v[38:41]
	v_mfma_f32_16x16x32_bf16 v[34:37], v[194:197], v[156:159], v[34:37]
	v_mfma_f32_16x16x32_bf16 v[62:65], v[174:177], v[150:153], v[62:65]
	v_mfma_f32_16x16x32_bf16 v[58:61], v[174:177], v[160:163], v[58:61]
	v_mfma_f32_16x16x32_bf16 v[54:57], v[182:185], v[150:153], v[54:57]
	v_mfma_f32_16x16x32_bf16 v[50:53], v[182:185], v[160:163], v[50:53]
	v_mfma_f32_16x16x32_bf16 v[46:49], v[190:193], v[150:153], v[46:49]
	v_mfma_f32_16x16x32_bf16 v[42:45], v[190:193], v[160:163], v[42:45]
	v_mfma_f32_16x16x32_bf16 v[38:41], v[198:201], v[150:153], v[38:41]
	v_mfma_f32_16x16x32_bf16 v[34:37], v[198:201], v[160:163], v[34:37]
	s_barrier
	v_add_u32_e32 v148, s41, v141
	v_lshl_add_u64 v[146:147], v[228:229], 0, s[16:17]
	v_readfirstlane_b32 s30, v148
	v_add_u32_e32 v148, 0x2000, v148
	s_mov_b32 m0, s30
	v_readfirstlane_b32 s30, v148
	global_load_lds_dwordx4 v[146:147], off
	v_lshl_add_u64 v[146:147], v[230:231], 0, s[16:17]
	s_mov_b32 m0, s30
	s_nop 0
	global_load_lds_dwordx4 v[146:147], off
	s_waitcnt vmcnt(10)
	s_barrier
	v_mfma_f32_16x16x32_bf16 v[30:33], v[164:167], v[202:205], v[30:33]
	v_mfma_f32_16x16x32_bf16 v[26:29], v[164:167], v[210:213], v[26:29]
	v_mfma_f32_16x16x32_bf16 v[22:25], v[178:181], v[202:205], v[22:25]
	v_mfma_f32_16x16x32_bf16 v[18:21], v[178:181], v[210:213], v[18:21]
	v_mfma_f32_16x16x32_bf16 v[14:17], v[186:189], v[202:205], v[14:17]
	v_mfma_f32_16x16x32_bf16 v[10:13], v[186:189], v[210:213], v[10:13]
	v_mfma_f32_16x16x32_bf16 v[6:9], v[194:197], v[202:205], v[6:9]
	v_mfma_f32_16x16x32_bf16 v[2:5], v[194:197], v[210:213], v[2:5]
	v_mfma_f32_16x16x32_bf16 v[30:33], v[174:177], v[206:209], v[30:33]
	v_mfma_f32_16x16x32_bf16 v[26:29], v[174:177], v[214:217], v[26:29]
	v_mfma_f32_16x16x32_bf16 v[22:25], v[182:185], v[206:209], v[22:25]
	v_mfma_f32_16x16x32_bf16 v[18:21], v[182:185], v[214:217], v[18:21]
	v_mfma_f32_16x16x32_bf16 v[14:17], v[190:193], v[206:209], v[14:17]
	v_mfma_f32_16x16x32_bf16 v[10:13], v[190:193], v[214:217], v[10:13]
	v_mfma_f32_16x16x32_bf16 v[6:9], v[198:201], v[206:209], v[6:9]
	v_mfma_f32_16x16x32_bf16 v[2:5], v[198:201], v[214:217], v[2:5]
	s_add_i32 s21, s21, 2
	s_cmp_lt_u32 s21, 12
	s_barrier
	s_cbranch_scc1 .LBB0_1226
	v_lshl_add_u64 v[168:169], s[18:19], 0, v[138:139]
	v_readfirstlane_b32 s21, v144
	v_lshl_add_u64 v[168:169], v[168:169], 0, s[8:9]
	s_mov_b32 m0, s21
	v_lshl_add_u64 v[130:131], s[18:19], 0, v[130:131]
	v_readfirstlane_b32 s18, v145
	ds_read_b128 v[146:149], v143
	ds_read_b128 v[150:153], v143 offset:1024
	ds_read_b128 v[156:159], v143 offset:2048
	ds_read_b128 v[160:163], v143 offset:3072
	ds_read_b128 v[164:167], v136
	ds_read_b128 v[174:177], v136 offset:1024
	ds_read_b128 v[178:181], v135
	ds_read_b128 v[182:185], v135 offset:1024
	ds_read_b128 v[186:189], v134
	ds_read_b128 v[190:193], v134 offset:1024
	ds_read_b128 v[194:197], v133
	ds_read_b128 v[198:201], v133 offset:1024
	global_load_lds_dwordx4 v[168:169], off
	v_lshl_add_u64 v[130:131], v[130:131], 0, s[8:9]
	s_mov_b32 m0, s18
	s_nop 0
	global_load_lds_dwordx4 v[130:131], off
	s_waitcnt vmcnt(10)
	s_barrier
	s_waitcnt lgkmcnt(0)
	s_waitcnt lgkmcnt(0)
	v_mfma_f32_16x16x32_bf16 v[126:129], v[164:167], v[146:149], v[126:129]
	v_mfma_f32_16x16x32_bf16 v[122:125], v[164:167], v[156:159], v[122:125]
	v_mfma_f32_16x16x32_bf16 v[110:113], v[186:189], v[146:149], v[110:113]
	v_mfma_f32_16x16x32_bf16 v[106:109], v[186:189], v[156:159], v[106:109]
	v_mfma_f32_16x16x32_bf16 v[126:129], v[174:177], v[150:153], v[126:129]
	v_mfma_f32_16x16x32_bf16 v[122:125], v[174:177], v[160:163], v[122:125]
	v_mfma_f32_16x16x32_bf16 v[118:121], v[178:181], v[146:149], v[118:121]
	v_mfma_f32_16x16x32_bf16 v[114:117], v[178:181], v[156:159], v[114:117]
	v_mfma_f32_16x16x32_bf16 v[110:113], v[190:193], v[150:153], v[110:113]
	v_mfma_f32_16x16x32_bf16 v[106:109], v[190:193], v[160:163], v[106:109]
	v_mfma_f32_16x16x32_bf16 v[102:105], v[194:197], v[146:149], v[102:105]
	v_mfma_f32_16x16x32_bf16 v[98:101], v[194:197], v[156:159], v[98:101]
	v_mfma_f32_16x16x32_bf16 v[202:205], v[182:185], v[150:153], v[118:121]
	v_mfma_f32_16x16x32_bf16 v[206:209], v[182:185], v[160:163], v[114:117]
	v_mfma_f32_16x16x32_bf16 v[210:213], v[198:201], v[150:153], v[102:105]
	v_mfma_f32_16x16x32_bf16 v[214:217], v[198:201], v[160:163], v[98:101]
	s_barrier
	s_nop 1
	ds_read_b128 v[98:101], v142
	ds_read_b128 v[102:105], v142 offset:1024
	ds_read_b128 v[114:117], v142 offset:2048
	ds_read_b128 v[118:121], v142 offset:3072
	s_waitcnt vmcnt(8)
	s_barrier
; #define WAIT_V(n) asm volatile("s_waitcnt vmcnt(" #n ")" ::: "memory")
; #define WAIT_L(n) asm volatile("s_waitcnt lgkmcnt(" #n ")" ::: "memory")
; #define BAR __builtin_amdgcn_s_barrier()
; #define LDA(dst, b, h) for (int m = 0; m < 4; ++m) for (int k = 0; k < 2; ++k) \
;     dst[m][k] = *reinterpret_cast<const bf16x8*>((char*)SA(b, h) + lds_byte(wr * 64 + m * 16 + fr, k * 32 + fq * 8))
; #define LDB(dst, b, h) for (int n = 0; n < 2; ++n) for (int k = 0; k < 2; ++k) \
;     dst[n][k] = *reinterpret_cast<const bf16x8*>((char*)SB(b, h) + lds_byte(wc * 32 + n * 16 + fr, k * 32 + fq * 8))
; #define MMA(ai, bj, At_, Bt_) do { __builtin_amdgcn_s_setprio(1); \
;     for (int m = 0; m < 4; ++m) for (int n = 0; n < 2; ++n) for (int k = 0; k < 2; ++k) \
;       acc[ai][bj][m][n] = __builtin_amdgcn_mfma_f32_16x16x32_bf16(At_[m][k], Bt_[n][k], acc[ai][bj][m][n], 0, 0, 0); \
;     __builtin_amdgcn_s_setprio(0); } while (0)
; template <int K, int LD = K>
; __device__ __forceinline__ void gemm_main(const GAS bf16* A, const GAS bf16* Bt, int brow, int bcol, f32x4 (&acc)[2][2][4][2]) {
;     ...
;     LDB(B1, 0, 1); BAR; WAIT_L(0); MMA(0, 1, At, B1); BAR;
;     LDA(At, 0, 1); WAIT_V(4); BAR; WAIT_L(0); MMA(1, 0, At, B0); MMA(1, 1, At, B1); BAR; }
;   { LDB(B0, 1, 0); LDA(At, 1, 0); WAIT_V(2); BAR; WAIT_L(0); MMA(0, 0, At, B0); BAR;
	s_waitcnt lgkmcnt(0)
	s_waitcnt lgkmcnt(0)
	v_mfma_f32_16x16x32_bf16 v[94:97], v[164:167], v[98:101], v[94:97]
	v_mfma_f32_16x16x32_bf16 v[90:93], v[164:167], v[114:117], v[90:93]
	v_mfma_f32_16x16x32_bf16 v[78:81], v[186:189], v[98:101], v[78:81]
	v_mfma_f32_16x16x32_bf16 v[74:77], v[186:189], v[114:117], v[74:77]
	v_mfma_f32_16x16x32_bf16 v[94:97], v[174:177], v[102:105], v[94:97]
	v_mfma_f32_16x16x32_bf16 v[90:93], v[174:177], v[118:121], v[90:93]
	v_mfma_f32_16x16x32_bf16 v[86:89], v[178:181], v[98:101], v[86:89]
	v_mfma_f32_16x16x32_bf16 v[82:85], v[178:181], v[114:117], v[82:85]
	v_mfma_f32_16x16x32_bf16 v[78:81], v[190:193], v[102:105], v[78:81]
	v_mfma_f32_16x16x32_bf16 v[74:77], v[190:193], v[118:121], v[74:77]
	v_mfma_f32_16x16x32_bf16 v[70:73], v[194:197], v[98:101], v[70:73]
	v_mfma_f32_16x16x32_bf16 v[66:69], v[194:197], v[114:117], v[66:69]
	v_mfma_f32_16x16x32_bf16 v[142:145], v[182:185], v[102:105], v[86:89]
	v_mfma_f32_16x16x32_bf16 v[164:167], v[182:185], v[118:121], v[82:85]
	v_mfma_f32_16x16x32_bf16 v[174:177], v[198:201], v[102:105], v[70:73]
	v_mfma_f32_16x16x32_bf16 v[178:181], v[198:201], v[118:121], v[66:69]
	s_barrier
	s_nop 1
	ds_read_b128 v[66:69], v136 offset:16384
	ds_read_b128 v[70:73], v136 offset:17408
	ds_read_b128 v[82:85], v135 offset:16384
	ds_read_b128 v[86:89], v135 offset:17408
	ds_read_b128 v[182:185], v134 offset:16384
	ds_read_b128 v[186:189], v134 offset:17408
	ds_read_b128 v[190:193], v133 offset:16384
	ds_read_b128 v[194:197], v133 offset:17408
	s_waitcnt vmcnt(4)
	s_barrier
	s_waitcnt lgkmcnt(0)
	s_waitcnt lgkmcnt(0)
	v_mfma_f32_16x16x32_bf16 v[62:65], v[66:69], v[146:149], v[62:65]
	v_mfma_f32_16x16x32_bf16 v[58:61], v[66:69], v[156:159], v[58:61]
	v_mfma_f32_16x16x32_bf16 v[46:49], v[182:185], v[146:149], v[46:49]
	v_mfma_f32_16x16x32_bf16 v[42:45], v[182:185], v[156:159], v[42:45]
	v_mfma_f32_16x16x32_bf16 v[62:65], v[70:73], v[150:153], v[62:65]
	v_mfma_f32_16x16x32_bf16 v[58:61], v[70:73], v[160:163], v[58:61]
	v_mfma_f32_16x16x32_bf16 v[54:57], v[82:85], v[146:149], v[54:57]
	v_mfma_f32_16x16x32_bf16 v[50:53], v[82:85], v[156:159], v[50:53]
	v_mfma_f32_16x16x32_bf16 v[46:49], v[186:189], v[150:153], v[46:49]
	v_mfma_f32_16x16x32_bf16 v[42:45], v[186:189], v[160:163], v[42:45]
	v_mfma_f32_16x16x32_bf16 v[38:41], v[190:193], v[146:149], v[38:41]
	v_mfma_f32_16x16x32_bf16 v[34:37], v[190:193], v[156:159], v[34:37]
	v_mfma_f32_16x16x32_bf16 v[198:201], v[86:89], v[150:153], v[54:57]
	v_mfma_f32_16x16x32_bf16 v[218:221], v[86:89], v[160:163], v[50:53]
	v_mfma_f32_16x16x32_bf16 v[146:149], v[194:197], v[150:153], v[38:41]
	v_mfma_f32_16x16x32_bf16 v[150:153], v[194:197], v[160:163], v[34:37]
	v_mfma_f32_16x16x32_bf16 v[30:33], v[66:69], v[98:101], v[30:33]
	v_mfma_f32_16x16x32_bf16 v[26:29], v[66:69], v[114:117], v[26:29]
	v_mfma_f32_16x16x32_bf16 v[10:13], v[182:185], v[114:117], v[10:13]
	v_mfma_f32_16x16x32_bf16 v[2:5], v[190:193], v[114:117], v[2:5]
	v_mfma_f32_16x16x32_bf16 v[30:33], v[70:73], v[102:105], v[30:33]
	v_mfma_f32_16x16x32_bf16 v[26:29], v[70:73], v[118:121], v[26:29]
	v_mfma_f32_16x16x32_bf16 v[22:25], v[82:85], v[98:101], v[22:25]
	v_mfma_f32_16x16x32_bf16 v[18:21], v[82:85], v[114:117], v[18:21]
	v_mfma_f32_16x16x32_bf16 v[14:17], v[182:185], v[98:101], v[14:17]
	v_mfma_f32_16x16x32_bf16 v[10:13], v[186:189], v[118:121], v[10:13]
	v_mfma_f32_16x16x32_bf16 v[6:9], v[190:193], v[98:101], v[6:9]
	v_mfma_f32_16x16x32_bf16 v[2:5], v[194:197], v[118:121], v[2:5]
	v_mfma_f32_16x16x32_bf16 v[156:159], v[86:89], v[102:105], v[22:25]
	v_mfma_f32_16x16x32_bf16 v[160:163], v[86:89], v[118:121], v[18:21]
	v_mfma_f32_16x16x32_bf16 v[222:225], v[186:189], v[102:105], v[14:17]
	v_mfma_f32_16x16x32_bf16 v[182:185], v[194:197], v[102:105], v[6:9]
	s_barrier
	s_nop 0
	ds_read_b128 v[6:9], v140
	ds_read_b128 v[14:17], v140 offset:1024
	ds_read_b128 v[186:189], v140 offset:2048
	ds_read_b128 v[190:193], v140 offset:3072
	ds_read_b128 v[18:21], v136 offset:32768
	ds_read_b128 v[22:25], v136 offset:33792
	ds_read_b128 v[34:37], v135 offset:32768
	ds_read_b128 v[38:41], v135 offset:33792
	ds_read_b128 v[50:53], v134 offset:32768
	ds_read_b128 v[54:57], v134 offset:33792
	ds_read_b128 v[194:197], v133 offset:32768
	ds_read_b128 v[226:229], v133 offset:33792
	s_waitcnt vmcnt(2)
	s_barrier
; #define WAIT_V(n) asm volatile("s_waitcnt vmcnt(" #n ")" ::: "memory")
; #define WAIT_L(n) asm volatile("s_waitcnt lgkmcnt(" #n ")" ::: "memory")
; #define BAR __builtin_amdgcn_s_barrier()
; #define LDA(dst, b, h) for (int m = 0; m < 4; ++m) for (int k = 0; k < 2; ++k) \
;     dst[m][k] = *reinterpret_cast<const bf16x8*>((char*)SA(b, h) + lds_byte(wr * 64 + m * 16 + fr, k * 32 + fq * 8))
; #define LDB(dst, b, h) for (int n = 0; n < 2; ++n) for (int k = 0; k < 2; ++k) \
;     dst[n][k] = *reinterpret_cast<const bf16x8*>((char*)SB(b, h) + lds_byte(wc * 32 + n * 16 + fr, k * 32 + fq * 8))
; #define MMA(ai, bj, At_, Bt_) do { __builtin_amdgcn_s_setprio(1); \
;     for (int m = 0; m < 4; ++m) for (int n = 0; n < 2; ++n) for (int k = 0; k < 2; ++k) \
;       acc[ai][bj][m][n] = __builtin_amdgcn_mfma_f32_16x16x32_bf16(At_[m][k], Bt_[n][k], acc[ai][bj][m][n], 0, 0, 0); \
;     __builtin_amdgcn_s_setprio(0); } while (0)
; template <int K, int LD = K>
; __device__ __forceinline__ void gemm_main(const GAS bf16* A, const GAS bf16* Bt, int brow, int bcol, f32x4 (&acc)[2][2][4][2]) {
;     ...
;   { LDB(B0, 1, 0); LDA(At, 1, 0); WAIT_V(2); BAR; WAIT_L(0); MMA(0, 0, At, B0); BAR;
;     LDB(B1, 1, 1); WAIT_V(0); BAR; WAIT_L(0); MMA(0, 1, At, B1); BAR;
;     LDA(At, 1, 1); BAR; WAIT_L(0); MMA(1, 0, At, B0); MMA(1, 1, At, B1); BAR; }
;   if (wr == 0) BAR;
	s_waitcnt lgkmcnt(0)
	s_waitcnt lgkmcnt(0)
	v_mfma_f32_16x16x32_bf16 v[66:69], v[18:21], v[6:9], v[126:129]
	v_mfma_f32_16x16x32_bf16 v[118:121], v[22:25], v[14:17], v[66:69]
	v_mfma_f32_16x16x32_bf16 v[66:69], v[18:21], v[186:189], v[122:125]
	v_mfma_f32_16x16x32_bf16 v[114:117], v[22:25], v[190:193], v[66:69]
	v_mfma_f32_16x16x32_bf16 v[66:69], v[34:37], v[6:9], v[202:205]
	v_mfma_f32_16x16x32_bf16 v[102:105], v[38:41], v[14:17], v[66:69]
	v_mfma_f32_16x16x32_bf16 v[66:69], v[34:37], v[186:189], v[206:209]
	v_mfma_f32_16x16x32_bf16 v[98:101], v[38:41], v[190:193], v[66:69]
	v_mfma_f32_16x16x32_bf16 v[66:69], v[50:53], v[6:9], v[110:113]
	v_mfma_f32_16x16x32_bf16 v[86:89], v[54:57], v[14:17], v[66:69]
	v_mfma_f32_16x16x32_bf16 v[66:69], v[50:53], v[186:189], v[106:109]
	v_mfma_f32_16x16x32_bf16 v[82:85], v[54:57], v[190:193], v[66:69]
	v_mfma_f32_16x16x32_bf16 v[66:69], v[194:197], v[6:9], v[210:213]
	v_mfma_f32_16x16x32_bf16 v[70:73], v[226:229], v[14:17], v[66:69]
	v_mfma_f32_16x16x32_bf16 v[66:69], v[194:197], v[186:189], v[214:217]
	v_mfma_f32_16x16x32_bf16 v[66:69], v[226:229], v[190:193], v[66:69]
	s_barrier
	ds_read_b128 v[202:205], v137
	ds_read_b128 v[206:209], v137 offset:1024
	ds_read_b128 v[210:213], v137 offset:2048
	ds_read_b128 v[214:217], v137 offset:3072
	s_waitcnt vmcnt(0)
	s_barrier
	s_waitcnt lgkmcnt(0)
	s_waitcnt lgkmcnt(0)
	v_mfma_f32_16x16x32_bf16 v[94:97], v[18:21], v[202:205], v[94:97]
	v_mfma_f32_16x16x32_bf16 v[18:21], v[18:21], v[210:213], v[90:93]
	v_mfma_f32_16x16x32_bf16 v[122:125], v[22:25], v[214:217], v[18:21]
	v_mfma_f32_16x16x32_bf16 v[18:21], v[34:37], v[202:205], v[142:145]
	v_mfma_f32_16x16x32_bf16 v[110:113], v[38:41], v[206:209], v[18:21]
	v_mfma_f32_16x16x32_bf16 v[18:21], v[34:37], v[210:213], v[164:167]
	v_mfma_f32_16x16x32_bf16 v[106:109], v[38:41], v[214:217], v[18:21]
	v_mfma_f32_16x16x32_bf16 v[18:21], v[50:53], v[202:205], v[78:81]
	v_mfma_f32_16x16x32_bf16 v[126:129], v[22:25], v[206:209], v[94:97]
	v_mfma_f32_16x16x32_bf16 v[94:97], v[54:57], v[206:209], v[18:21]
	v_mfma_f32_16x16x32_bf16 v[18:21], v[50:53], v[210:213], v[74:77]
	v_mfma_f32_16x16x32_bf16 v[90:93], v[54:57], v[214:217], v[18:21]
	v_mfma_f32_16x16x32_bf16 v[18:21], v[194:197], v[202:205], v[174:177]
	v_mfma_f32_16x16x32_bf16 v[78:81], v[226:229], v[206:209], v[18:21]
	v_mfma_f32_16x16x32_bf16 v[18:21], v[194:197], v[210:213], v[178:181]
	v_mfma_f32_16x16x32_bf16 v[74:77], v[226:229], v[214:217], v[18:21]
	s_barrier
	ds_read_b128 v[140:143], v136 offset:49152
	ds_read_b128 v[164:167], v136 offset:50176
	ds_read_b128 v[174:177], v135 offset:49152
	ds_read_b128 v[178:181], v135 offset:50176
	ds_read_b128 v[194:197], v134 offset:49152
	ds_read_b128 v[134:137], v134 offset:50176
	ds_read_b128 v[226:229], v133 offset:49152
	ds_read_b128 v[230:233], v133 offset:50176
	s_barrier
	s_waitcnt lgkmcnt(0)
	s_waitcnt lgkmcnt(0)
	v_mfma_f32_16x16x32_bf16 v[18:21], v[140:143], v[6:9], v[62:65]
	v_mfma_f32_16x16x32_bf16 v[54:57], v[164:167], v[14:17], v[18:21]
	v_mfma_f32_16x16x32_bf16 v[18:21], v[140:143], v[186:189], v[58:61]
	v_mfma_f32_16x16x32_bf16 v[50:53], v[164:167], v[190:193], v[18:21]
	v_mfma_f32_16x16x32_bf16 v[18:21], v[174:177], v[6:9], v[198:201]
	v_mfma_f32_16x16x32_bf16 v[38:41], v[178:181], v[14:17], v[18:21]
	v_mfma_f32_16x16x32_bf16 v[18:21], v[174:177], v[186:189], v[218:221]
	v_mfma_f32_16x16x32_bf16 v[34:37], v[178:181], v[190:193], v[18:21]
	v_mfma_f32_16x16x32_bf16 v[18:21], v[194:197], v[6:9], v[46:49]
	v_mfma_f32_16x16x32_bf16 v[6:9], v[226:229], v[6:9], v[146:149]
	v_mfma_f32_16x16x32_bf16 v[22:25], v[134:137], v[14:17], v[18:21]
	v_mfma_f32_16x16x32_bf16 v[18:21], v[194:197], v[186:189], v[42:45]
	v_mfma_f32_16x16x32_bf16 v[14:17], v[230:233], v[14:17], v[6:9]
	v_mfma_f32_16x16x32_bf16 v[6:9], v[226:229], v[186:189], v[150:153]
	v_mfma_f32_16x16x32_bf16 v[18:21], v[134:137], v[190:193], v[18:21]
	v_mfma_f32_16x16x32_bf16 v[6:9], v[230:233], v[190:193], v[6:9]
	v_mfma_f32_16x16x32_bf16 v[26:29], v[140:143], v[210:213], v[26:29]
	v_mfma_f32_16x16x32_bf16 v[58:61], v[164:167], v[214:217], v[26:29]
	v_mfma_f32_16x16x32_bf16 v[26:29], v[174:177], v[202:205], v[156:159]
	v_mfma_f32_16x16x32_bf16 v[46:49], v[178:181], v[206:209], v[26:29]
	v_mfma_f32_16x16x32_bf16 v[26:29], v[174:177], v[210:213], v[160:163]
	v_mfma_f32_16x16x32_bf16 v[30:33], v[140:143], v[202:205], v[30:33]
	v_mfma_f32_16x16x32_bf16 v[42:45], v[178:181], v[214:217], v[26:29]
	v_mfma_f32_16x16x32_bf16 v[26:29], v[194:197], v[202:205], v[222:225]
	v_mfma_f32_16x16x32_bf16 v[10:13], v[194:197], v[210:213], v[10:13]
	v_mfma_f32_16x16x32_bf16 v[62:65], v[164:167], v[206:209], v[30:33]
	v_mfma_f32_16x16x32_bf16 v[30:33], v[134:137], v[206:209], v[26:29]
	v_mfma_f32_16x16x32_bf16 v[26:29], v[134:137], v[214:217], v[10:13]
	v_mfma_f32_16x16x32_bf16 v[10:13], v[226:229], v[202:205], v[182:185]
	v_mfma_f32_16x16x32_bf16 v[2:5], v[226:229], v[210:213], v[2:5]
	v_mfma_f32_16x16x32_bf16 v[10:13], v[230:233], v[206:209], v[10:13]
	v_mfma_f32_16x16x32_bf16 v[2:5], v[230:233], v[214:217], v[2:5]
	v_cmp_gt_u32_e32 vcc, s42, v132
	s_barrier
	s_and_saveexec_b64 s[18:19], vcc
	s_cbranch_execz .LBB0_1229
	s_barrier
